# K-loops: removed no-op counted lgkmcnt waits and the setprio 0/1 pair inside each 32-MFMA block (on top of mods GEMV batching + hand-written rg epilogue)
# speedup vs baseline: 1.0129x; 1.0004x over previous
; #define PG8_STAGE(bufoff, gbase, voff, p64) do { _Pragma("unroll") for (int _i = 0; _i < 2; ++_i) { \
;         const char* _gb = (const char*)(gbase) + (size_t)_i * (p64); const unsigned _la = ldsbase + (unsigned)(bufoff) + (unsigned)_i * 8192u; \
;         asm volatile("s_mov_b32 m0, %0\n\ts_nop 0\n\tglobal_load_lds_dwordx4 %1, %2" :: "s"(_la), "v"(voff), "s"(_gb) : "memory"); } } while (0)
; #define PG8_LDA(dst, b, h) do { _Pragma("unroll") for (int m = 0; m < 4; ++m) _Pragma("unroll") for (int k = 0; k < 2; ++k) dst[m][k] = *(const LAS bf16x8*)(lds + PG8_SA(b, h) + aoff + m * 2048 + k * 1024); } while (0)
; #define PG8_LDB(dst, b, h) do { _Pragma("unroll") for (int n = 0; n < 2; ++n) _Pragma("unroll") for (int k = 0; k < 2; ++k) dst[n][k] = *(const LAS bf16x8*)(lds + PG8_SB(b, h) + boff + n * 2048 + k * 1024); } while (0)
; #define PG8_MMA(ai, bj, At, Bt) do { __builtin_amdgcn_s_setprio(1); _Pragma("unroll") for (int m = 0; m < 4; ++m) _Pragma("unroll") for (int n = 0; n < 2; ++n) _Pragma("unroll") for (int k = 0; k < 2; ++k) \
;         acc[ai][bj][m][n] = __builtin_amdgcn_mfma_f32_16x16x32_bf16(Bt[n][k], At[m][k], acc[ai][bj][m][n], 0, 0, 0); __builtin_amdgcn_s_setprio(0); } while (0)
; #define PG8_WAIT_V(n) asm volatile("s_waitcnt vmcnt(" #n ")" ::: "memory")
; #define PG8_WAIT_L(n) asm volatile("s_waitcnt lgkmcnt(" #n ")" ::: "memory")
; #define PG8_BAR __builtin_amdgcn_s_barrier()
; #define PG8_SCHED __builtin_amdgcn_sched_barrier(0)
; template <class Epi, class Sched>
; __device__ __forceinline__ void gemm_phase(LAS unsigned char* lds, const Sched& S, const Epi& E) {
;     ...
;             PG8_LDB(B0, 0, 0); PG8_LDB(B1, 0, 1); PG8_SCHED; PG8_LDA(At, 0, 0); PG8_STAGE(PG8_SA(1, 1), a1 + hA, voffA, hA / 2);
;             PG8_WAIT_V(8); PG8_WAIT_L(0); PG8_BAR; PG8_MMA(0, 0, At, B0); PG8_MMA(0, 1, At, B1); PG8_BAR; PG8_SCHED;
;             PG8_LDA(At, 0, 1); PG8_STAGE(PG8_SB(0, 0), b2, vB2, hB2 / 2); PG8_STAGE(PG8_SB(0, 1), b2 + hB2, vB2, hB2 / 2); PG8_STAGE(PG8_SA(0, 0), a2, vA2, hA2 / 2);
;             PG8_WAIT_V(8); PG8_WAIT_L(0); PG8_BAR; PG8_MMA(1, 0, At, B0); PG8_MMA(1, 1, At, B1); PG8_BAR; PG8_SCHED;
;             PG8_LDB(B0, 1, 0); PG8_LDB(B1, 1, 1); PG8_SCHED; PG8_LDA(At, 1, 0); PG8_STAGE(PG8_SA(0, 1), a2 + hA2, vA2, hA2 / 2);
;             PG8_WAIT_V(8); PG8_WAIT_L(0); PG8_BAR; PG8_MMA(0, 0, At, B0); PG8_MMA(0, 1, At, B1); PG8_BAR; PG8_SCHED;
.LBB0_304:
	ds_read_b128 v[144:147], v138
	ds_read_b128 v[148:151], v138 offset:1024
	ds_read_b128 v[152:155], v138 offset:2048
	ds_read_b128 v[156:159], v138 offset:3072
	ds_read_b128 v[160:163], v139
	ds_read_b128 v[164:167], v139 offset:1024
	ds_read_b128 v[168:171], v139 offset:2048
	ds_read_b128 v[172:175], v139 offset:3072
	s_add_u32 s30, s38, 0xfffc0080
	s_addc_u32 s31, s39, -1
	s_cmp_eq_u32 s64, 12
	s_cselect_b32 s40, s24, s30
	s_cselect_b32 s41, s25, s31
	s_cselect_b32 s44, s26, s62
	s_cselect_b32 s45, s27, s63
	s_add_u32 s42, s40, 0x80
	s_addc_u32 s43, s41, 0
	ds_read_b128 v[178:181], v140
	ds_read_b128 v[182:185], v140 offset:1024
	ds_read_b128 v[186:189], v140 offset:2048
	ds_read_b128 v[190:193], v140 offset:3072
	ds_read_b128 v[194:197], v140 offset:4096
	ds_read_b128 v[198:201], v140 offset:5120
	ds_read_b128 v[202:205], v140 offset:6144
	ds_read_b128 v[206:209], v140 offset:7168
	s_mov_b32 m0, s55
	s_nop 0
	global_load_lds_dwordx4 v134, s[38:39]
	s_add_u32 s66, s38, 0x20000
	s_addc_u32 s67, s39, 0
	s_mov_b32 m0, s56
	s_nop 0
	global_load_lds_dwordx4 v134, s[66:67]
	s_waitcnt vmcnt(8)
	s_waitcnt lgkmcnt(0)
	s_barrier
	s_setprio 1
	v_mfma_f32_16x16x32_bf16 v[124:127], v[144:147], v[178:181], v[124:127]
	v_mfma_f32_16x16x32_bf16 v[120:123], v[152:155], v[178:181], v[120:123]
	v_mfma_f32_16x16x32_bf16 v[108:111], v[144:147], v[186:189], v[108:111]
	v_mfma_f32_16x16x32_bf16 v[104:107], v[152:155], v[186:189], v[104:107]
	v_mfma_f32_16x16x32_bf16 v[92:95], v[144:147], v[194:197], v[92:95]
	v_mfma_f32_16x16x32_bf16 v[88:91], v[152:155], v[194:197], v[88:91]
	v_mfma_f32_16x16x32_bf16 v[76:79], v[144:147], v[202:205], v[76:79]
	v_mfma_f32_16x16x32_bf16 v[72:75], v[152:155], v[202:205], v[72:75]
	v_mfma_f32_16x16x32_bf16 v[124:127], v[148:151], v[182:185], v[124:127]
	v_mfma_f32_16x16x32_bf16 v[120:123], v[156:159], v[182:185], v[120:123]
	v_mfma_f32_16x16x32_bf16 v[108:111], v[148:151], v[190:193], v[108:111]
	v_mfma_f32_16x16x32_bf16 v[104:107], v[156:159], v[190:193], v[104:107]
	v_mfma_f32_16x16x32_bf16 v[92:95], v[148:151], v[198:201], v[92:95]
	v_mfma_f32_16x16x32_bf16 v[88:91], v[156:159], v[198:201], v[88:91]
	v_mfma_f32_16x16x32_bf16 v[76:79], v[148:151], v[206:209], v[76:79]
	v_mfma_f32_16x16x32_bf16 v[72:75], v[156:159], v[206:209], v[72:75]
	v_mfma_f32_16x16x32_bf16 v[116:119], v[160:163], v[178:181], v[116:119]
	v_mfma_f32_16x16x32_bf16 v[112:115], v[168:171], v[178:181], v[112:115]
	v_mfma_f32_16x16x32_bf16 v[100:103], v[160:163], v[186:189], v[100:103]
	v_mfma_f32_16x16x32_bf16 v[96:99], v[168:171], v[186:189], v[96:99]
	v_mfma_f32_16x16x32_bf16 v[84:87], v[160:163], v[194:197], v[84:87]
	v_mfma_f32_16x16x32_bf16 v[80:83], v[168:171], v[194:197], v[80:83]
	v_mfma_f32_16x16x32_bf16 v[68:71], v[160:163], v[202:205], v[68:71]
	v_mfma_f32_16x16x32_bf16 v[64:67], v[168:171], v[202:205], v[64:67]
	v_mfma_f32_16x16x32_bf16 v[116:119], v[164:167], v[182:185], v[116:119]
	v_mfma_f32_16x16x32_bf16 v[112:115], v[172:175], v[182:185], v[112:115]
	v_mfma_f32_16x16x32_bf16 v[100:103], v[164:167], v[190:193], v[100:103]
	v_mfma_f32_16x16x32_bf16 v[96:99], v[172:175], v[190:193], v[96:99]
	v_mfma_f32_16x16x32_bf16 v[84:87], v[164:167], v[198:201], v[84:87]
	v_mfma_f32_16x16x32_bf16 v[80:83], v[172:175], v[198:201], v[80:83]
	v_mfma_f32_16x16x32_bf16 v[68:71], v[164:167], v[206:209], v[68:71]
	v_mfma_f32_16x16x32_bf16 v[64:67], v[172:175], v[206:209], v[64:67]
	s_setprio 0
	s_barrier
	s_add_u32 s66, s44, 0x20000
	ds_read_b128 v[178:181], v140 offset:16384
	ds_read_b128 v[182:185], v140 offset:17408
	ds_read_b128 v[186:189], v140 offset:18432
	ds_read_b128 v[190:193], v140 offset:19456
	ds_read_b128 v[194:197], v140 offset:20480
	ds_read_b128 v[198:201], v140 offset:21504
	ds_read_b128 v[202:205], v140 offset:22528
	ds_read_b128 v[206:209], v140 offset:23552
	s_mov_b32 m0, s33
	s_nop 0
	global_load_lds_dwordx4 v135, s[44:45]
	s_addc_u32 s67, s45, 0
	s_mov_b32 m0, s34
	s_nop 0
	global_load_lds_dwordx4 v135, s[66:67]
	s_add_u32 s66, s44, 0x40000
	s_addc_u32 s67, s45, 0
	s_mov_b32 m0, s35
	s_nop 0
	global_load_lds_dwordx4 v135, s[66:67]
	s_add_u32 s66, s44, 0x60000
	s_addc_u32 s67, s45, 0
	s_mov_b32 m0, s36
	s_nop 0
	global_load_lds_dwordx4 v135, s[66:67]
	s_mov_b32 m0, s12
	s_nop 0
	global_load_lds_dwordx4 v134, s[40:41]
	s_add_u32 s66, s40, 0x20000
	s_addc_u32 s67, s41, 0
	s_mov_b32 m0, s37
	s_nop 0
	global_load_lds_dwordx4 v134, s[66:67]
	s_waitcnt vmcnt(8)
	s_waitcnt lgkmcnt(0)
	s_barrier
	s_setprio 1
	v_mfma_f32_16x16x32_bf16 v[60:63], v[144:147], v[178:181], v[60:63]
	v_mfma_f32_16x16x32_bf16 v[56:59], v[152:155], v[178:181], v[56:59]
	v_mfma_f32_16x16x32_bf16 v[44:47], v[144:147], v[186:189], v[44:47]
	v_mfma_f32_16x16x32_bf16 v[40:43], v[152:155], v[186:189], v[40:43]
	v_mfma_f32_16x16x32_bf16 v[28:31], v[144:147], v[194:197], v[28:31]
	v_mfma_f32_16x16x32_bf16 v[24:27], v[152:155], v[194:197], v[24:27]
	v_mfma_f32_16x16x32_bf16 v[12:15], v[144:147], v[202:205], v[12:15]
	v_mfma_f32_16x16x32_bf16 v[8:11], v[152:155], v[202:205], v[8:11]
	v_mfma_f32_16x16x32_bf16 v[60:63], v[148:151], v[182:185], v[60:63]
	v_mfma_f32_16x16x32_bf16 v[56:59], v[156:159], v[182:185], v[56:59]
	v_mfma_f32_16x16x32_bf16 v[44:47], v[148:151], v[190:193], v[44:47]
	v_mfma_f32_16x16x32_bf16 v[40:43], v[156:159], v[190:193], v[40:43]
	v_mfma_f32_16x16x32_bf16 v[28:31], v[148:151], v[198:201], v[28:31]
	v_mfma_f32_16x16x32_bf16 v[24:27], v[156:159], v[198:201], v[24:27]
	v_mfma_f32_16x16x32_bf16 v[12:15], v[148:151], v[206:209], v[12:15]
	v_mfma_f32_16x16x32_bf16 v[8:11], v[156:159], v[206:209], v[8:11]
	v_mfma_f32_16x16x32_bf16 v[52:55], v[160:163], v[178:181], v[52:55]
	v_mfma_f32_16x16x32_bf16 v[48:51], v[168:171], v[178:181], v[48:51]
	v_mfma_f32_16x16x32_bf16 v[36:39], v[160:163], v[186:189], v[36:39]
	v_mfma_f32_16x16x32_bf16 v[32:35], v[168:171], v[186:189], v[32:35]
	v_mfma_f32_16x16x32_bf16 v[20:23], v[160:163], v[194:197], v[20:23]
	v_mfma_f32_16x16x32_bf16 v[16:19], v[168:171], v[194:197], v[16:19]
	v_mfma_f32_16x16x32_bf16 v[4:7], v[160:163], v[202:205], v[4:7]
	v_mfma_f32_16x16x32_bf16 v[0:3], v[168:171], v[202:205], v[0:3]
	v_mfma_f32_16x16x32_bf16 v[52:55], v[164:167], v[182:185], v[52:55]
	v_mfma_f32_16x16x32_bf16 v[48:51], v[172:175], v[182:185], v[48:51]
	v_mfma_f32_16x16x32_bf16 v[36:39], v[164:167], v[190:193], v[36:39]
	v_mfma_f32_16x16x32_bf16 v[32:35], v[172:175], v[190:193], v[32:35]
	v_mfma_f32_16x16x32_bf16 v[20:23], v[164:167], v[198:201], v[20:23]
	v_mfma_f32_16x16x32_bf16 v[16:19], v[172:175], v[198:201], v[16:19]
	v_mfma_f32_16x16x32_bf16 v[4:7], v[164:167], v[206:209], v[4:7]
	v_mfma_f32_16x16x32_bf16 v[0:3], v[172:175], v[206:209], v[0:3]
	s_setprio 0
	s_barrier
; #define PG8_STAGE(bufoff, gbase, voff, p64) do { _Pragma("unroll") for (int _i = 0; _i < 2; ++_i) { \
;         const char* _gb = (const char*)(gbase) + (size_t)_i * (p64); const unsigned _la = ldsbase + (unsigned)(bufoff) + (unsigned)_i * 8192u; \
;         asm volatile("s_mov_b32 m0, %0\n\ts_nop 0\n\tglobal_load_lds_dwordx4 %1, %2" :: "s"(_la), "v"(voff), "s"(_gb) : "memory"); } } while (0)
; #define PG8_LDA(dst, b, h) do { _Pragma("unroll") for (int m = 0; m < 4; ++m) _Pragma("unroll") for (int k = 0; k < 2; ++k) dst[m][k] = *(const LAS bf16x8*)(lds + PG8_SA(b, h) + aoff + m * 2048 + k * 1024); } while (0)
; #define PG8_LDB(dst, b, h) do { _Pragma("unroll") for (int n = 0; n < 2; ++n) _Pragma("unroll") for (int k = 0; k < 2; ++k) dst[n][k] = *(const LAS bf16x8*)(lds + PG8_SB(b, h) + boff + n * 2048 + k * 1024); } while (0)
; #define PG8_MMA(ai, bj, At, Bt) do { __builtin_amdgcn_s_setprio(1); _Pragma("unroll") for (int m = 0; m < 4; ++m) _Pragma("unroll") for (int n = 0; n < 2; ++n) _Pragma("unroll") for (int k = 0; k < 2; ++k) \
;         acc[ai][bj][m][n] = __builtin_amdgcn_mfma_f32_16x16x32_bf16(Bt[n][k], At[m][k], acc[ai][bj][m][n], 0, 0, 0); __builtin_amdgcn_s_setprio(0); } while (0)
; #define PG8_WAIT_V(n) asm volatile("s_waitcnt vmcnt(" #n ")" ::: "memory")
; #define PG8_WAIT_L(n) asm volatile("s_waitcnt lgkmcnt(" #n ")" ::: "memory")
; #define PG8_BAR __builtin_amdgcn_s_barrier()
; #define PG8_SCHED __builtin_amdgcn_sched_barrier(0)
; template <class Epi, class Sched>
; __device__ __forceinline__ void gemm_phase(LAS unsigned char* lds, const Sched& S, const Epi& E) {
;     ...
;             PG8_LDB(B0, 1, 0); PG8_LDB(B1, 1, 1); PG8_SCHED; PG8_LDA(At, 1, 0); PG8_STAGE(PG8_SA(0, 1), a2 + hA2, vA2, hA2 / 2);
;             PG8_WAIT_V(8); PG8_WAIT_L(0); PG8_BAR; PG8_MMA(0, 0, At, B0); PG8_MMA(0, 1, At, B1); PG8_BAR; PG8_SCHED;
;             PG8_LDA(At, 1, 1); PG8_STAGE(PG8_SB(1, 0), b3, vB2, hB2 / 2); PG8_STAGE(PG8_SB(1, 1), b3 + hB2, vB2, hB2 / 2); PG8_STAGE(PG8_SA(1, 0), a3, vA2, hA2 / 2);
;             PG8_WAIT_V(8); PG8_WAIT_L(0); PG8_BAR; PG8_MMA(1, 0, At, B0); PG8_MMA(1, 1, At, B1); PG8_BAR; PG8_SCHED;
	ds_read_b128 v[144:147], v141
	ds_read_b128 v[148:151], v141 offset:1024
	ds_read_b128 v[152:155], v141 offset:2048
	ds_read_b128 v[156:159], v141 offset:3072
	ds_read_b128 v[160:163], v142
	ds_read_b128 v[164:167], v142 offset:1024
	ds_read_b128 v[168:171], v142 offset:2048
	ds_read_b128 v[172:175], v142 offset:3072
	ds_read_b128 v[178:181], v140 offset:32768
	ds_read_b128 v[182:185], v140 offset:33792
	ds_read_b128 v[186:189], v140 offset:34816
	ds_read_b128 v[190:193], v140 offset:35840
	ds_read_b128 v[194:197], v140 offset:36864
	ds_read_b128 v[198:201], v140 offset:37888
	ds_read_b128 v[202:205], v140 offset:38912
	ds_read_b128 v[206:209], v140 offset:39936
	s_add_u32 s66, s40, 0x40000
	s_addc_u32 s67, s41, 0
	s_mov_b32 m0, s46
	s_nop 0
	global_load_lds_dwordx4 v134, s[66:67]
	s_add_u32 s66, s40, 0x60000
	s_addc_u32 s67, s41, 0
	s_mov_b32 m0, s47
	s_nop 0
	global_load_lds_dwordx4 v134, s[66:67]
	s_waitcnt vmcnt(8)
	s_waitcnt lgkmcnt(0)
	s_barrier
	s_setprio 1
	v_mfma_f32_16x16x32_bf16 v[124:127], v[144:147], v[178:181], v[124:127]
	v_mfma_f32_16x16x32_bf16 v[120:123], v[152:155], v[178:181], v[120:123]
	v_mfma_f32_16x16x32_bf16 v[108:111], v[144:147], v[186:189], v[108:111]
	v_mfma_f32_16x16x32_bf16 v[104:107], v[152:155], v[186:189], v[104:107]
	v_mfma_f32_16x16x32_bf16 v[92:95], v[144:147], v[194:197], v[92:95]
	v_mfma_f32_16x16x32_bf16 v[88:91], v[152:155], v[194:197], v[88:91]
	v_mfma_f32_16x16x32_bf16 v[76:79], v[144:147], v[202:205], v[76:79]
	v_mfma_f32_16x16x32_bf16 v[72:75], v[152:155], v[202:205], v[72:75]
	v_mfma_f32_16x16x32_bf16 v[124:127], v[148:151], v[182:185], v[124:127]
	v_mfma_f32_16x16x32_bf16 v[120:123], v[156:159], v[182:185], v[120:123]
	v_mfma_f32_16x16x32_bf16 v[108:111], v[148:151], v[190:193], v[108:111]
	v_mfma_f32_16x16x32_bf16 v[104:107], v[156:159], v[190:193], v[104:107]
	v_mfma_f32_16x16x32_bf16 v[92:95], v[148:151], v[198:201], v[92:95]
	v_mfma_f32_16x16x32_bf16 v[88:91], v[156:159], v[198:201], v[88:91]
	v_mfma_f32_16x16x32_bf16 v[76:79], v[148:151], v[206:209], v[76:79]
	v_mfma_f32_16x16x32_bf16 v[72:75], v[156:159], v[206:209], v[72:75]
	v_mfma_f32_16x16x32_bf16 v[116:119], v[160:163], v[178:181], v[116:119]
	v_mfma_f32_16x16x32_bf16 v[112:115], v[168:171], v[178:181], v[112:115]
	v_mfma_f32_16x16x32_bf16 v[100:103], v[160:163], v[186:189], v[100:103]
	v_mfma_f32_16x16x32_bf16 v[96:99], v[168:171], v[186:189], v[96:99]
	v_mfma_f32_16x16x32_bf16 v[84:87], v[160:163], v[194:197], v[84:87]
	v_mfma_f32_16x16x32_bf16 v[80:83], v[168:171], v[194:197], v[80:83]
	v_mfma_f32_16x16x32_bf16 v[68:71], v[160:163], v[202:205], v[68:71]
	v_mfma_f32_16x16x32_bf16 v[64:67], v[168:171], v[202:205], v[64:67]
	v_mfma_f32_16x16x32_bf16 v[116:119], v[164:167], v[182:185], v[116:119]
	v_mfma_f32_16x16x32_bf16 v[112:115], v[172:175], v[182:185], v[112:115]
	v_mfma_f32_16x16x32_bf16 v[100:103], v[164:167], v[190:193], v[100:103]
	v_mfma_f32_16x16x32_bf16 v[96:99], v[172:175], v[190:193], v[96:99]
	v_mfma_f32_16x16x32_bf16 v[84:87], v[164:167], v[198:201], v[84:87]
	v_mfma_f32_16x16x32_bf16 v[80:83], v[172:175], v[198:201], v[80:83]
	v_mfma_f32_16x16x32_bf16 v[68:71], v[164:167], v[206:209], v[68:71]
	v_mfma_f32_16x16x32_bf16 v[64:67], v[172:175], v[206:209], v[64:67]
	s_setprio 0
	s_barrier
	s_add_u32 s66, s44, 0x80
	s_addc_u32 s67, s45, 0
	ds_read_b128 v[178:181], v140 offset:49152
	ds_read_b128 v[182:185], v140 offset:50176
	ds_read_b128 v[186:189], v140 offset:51200
	ds_read_b128 v[190:193], v140 offset:52224
	ds_read_b128 v[194:197], v140 offset:53248
	ds_read_b128 v[198:201], v140 offset:54272
	ds_read_b128 v[202:205], v140 offset:55296
	ds_read_b128 v[206:209], v140 offset:56320
	s_mov_b32 m0, s49
	s_nop 0
	global_load_lds_dwordx4 v135, s[66:67]
	s_add_u32 s66, s44, 0x20080
	s_addc_u32 s67, s45, 0
	s_mov_b32 m0, s50
	s_nop 0
	global_load_lds_dwordx4 v135, s[66:67]
	s_add_u32 s66, s44, 0x40080
	s_addc_u32 s67, s45, 0
	s_mov_b32 m0, s53
	s_nop 0
	global_load_lds_dwordx4 v135, s[66:67]
	s_add_u32 s44, s44, 0x60080
	s_addc_u32 s45, s45, 0
	s_mov_b32 m0, s54
	s_nop 0
	global_load_lds_dwordx4 v135, s[44:45]
	s_mov_b32 m0, s51
	s_nop 0
	global_load_lds_dwordx4 v134, s[42:43]
	s_add_u32 s40, s40, 0x20080
	s_addc_u32 s41, s41, 0
	s_mov_b32 m0, s52
	s_nop 0
	global_load_lds_dwordx4 v134, s[40:41]
	s_waitcnt vmcnt(8)
	s_waitcnt lgkmcnt(0)
	s_barrier
	s_setprio 1
	v_mfma_f32_16x16x32_bf16 v[60:63], v[144:147], v[178:181], v[60:63]
	v_mfma_f32_16x16x32_bf16 v[56:59], v[152:155], v[178:181], v[56:59]
	v_mfma_f32_16x16x32_bf16 v[44:47], v[144:147], v[186:189], v[44:47]
	v_mfma_f32_16x16x32_bf16 v[40:43], v[152:155], v[186:189], v[40:43]
	v_mfma_f32_16x16x32_bf16 v[28:31], v[144:147], v[194:197], v[28:31]
	v_mfma_f32_16x16x32_bf16 v[24:27], v[152:155], v[194:197], v[24:27]
	v_mfma_f32_16x16x32_bf16 v[12:15], v[144:147], v[202:205], v[12:15]
	v_mfma_f32_16x16x32_bf16 v[8:11], v[152:155], v[202:205], v[8:11]
	v_mfma_f32_16x16x32_bf16 v[60:63], v[148:151], v[182:185], v[60:63]
	v_mfma_f32_16x16x32_bf16 v[56:59], v[156:159], v[182:185], v[56:59]
	v_mfma_f32_16x16x32_bf16 v[44:47], v[148:151], v[190:193], v[44:47]
	v_mfma_f32_16x16x32_bf16 v[40:43], v[156:159], v[190:193], v[40:43]
	v_mfma_f32_16x16x32_bf16 v[28:31], v[148:151], v[198:201], v[28:31]
	v_mfma_f32_16x16x32_bf16 v[24:27], v[156:159], v[198:201], v[24:27]
	v_mfma_f32_16x16x32_bf16 v[12:15], v[148:151], v[206:209], v[12:15]
	v_mfma_f32_16x16x32_bf16 v[8:11], v[156:159], v[206:209], v[8:11]
	v_mfma_f32_16x16x32_bf16 v[52:55], v[160:163], v[178:181], v[52:55]
	v_mfma_f32_16x16x32_bf16 v[48:51], v[168:171], v[178:181], v[48:51]
	v_mfma_f32_16x16x32_bf16 v[36:39], v[160:163], v[186:189], v[36:39]
	v_mfma_f32_16x16x32_bf16 v[32:35], v[168:171], v[186:189], v[32:35]
	v_mfma_f32_16x16x32_bf16 v[20:23], v[160:163], v[194:197], v[20:23]
	v_mfma_f32_16x16x32_bf16 v[16:19], v[168:171], v[194:197], v[16:19]
	v_mfma_f32_16x16x32_bf16 v[4:7], v[160:163], v[202:205], v[4:7]
	v_mfma_f32_16x16x32_bf16 v[0:3], v[168:171], v[202:205], v[0:3]
	v_mfma_f32_16x16x32_bf16 v[52:55], v[164:167], v[182:185], v[52:55]
	v_mfma_f32_16x16x32_bf16 v[48:51], v[172:175], v[182:185], v[48:51]
	v_mfma_f32_16x16x32_bf16 v[36:39], v[164:167], v[190:193], v[36:39]
	v_mfma_f32_16x16x32_bf16 v[32:35], v[172:175], v[190:193], v[32:35]
	v_mfma_f32_16x16x32_bf16 v[20:23], v[164:167], v[198:201], v[20:23]
	v_mfma_f32_16x16x32_bf16 v[16:19], v[172:175], v[198:201], v[16:19]
	v_mfma_f32_16x16x32_bf16 v[4:7], v[164:167], v[206:209], v[4:7]
	v_mfma_f32_16x16x32_bf16 v[0:3], v[172:175], v[206:209], v[0:3]
	s_setprio 0
	s_barrier
	s_add_i32 s64, s64, 2
	s_add_u32 s38, s38, 0x100
	s_addc_u32 s39, s39, 0
	s_add_u32 s62, s62, 0x100
	s_addc_u32 s63, s63, 0
	s_cmp_gt_u32 s64, 13
	s_cbranch_scc0 .LBB0_304
	s_and_b64 vcc, exec, s[18:19]
	s_cbranch_vccz .LBB0_307
	s_barrier

; #define PG8_STAGE(bufoff, gbase, voff, p64) do { _Pragma("unroll") for (int _i = 0; _i < 2; ++_i) { \
;         const char* _gb = (const char*)(gbase) + (size_t)_i * (p64); const unsigned _la = ldsbase + (unsigned)(bufoff) + (unsigned)_i * 8192u; \
;         asm volatile("s_mov_b32 m0, %0\n\ts_nop 0\n\tglobal_load_lds_dwordx4 %1, %2" :: "s"(_la), "v"(voff), "s"(_gb) : "memory"); } } while (0)
; #define PG8_LDA(dst, b, h) do { _Pragma("unroll") for (int m = 0; m < 4; ++m) _Pragma("unroll") for (int k = 0; k < 2; ++k) dst[m][k] = *(const LAS bf16x8*)(lds + PG8_SA(b, h) + aoff + m * 2048 + k * 1024); } while (0)
; #define PG8_LDB(dst, b, h) do { _Pragma("unroll") for (int n = 0; n < 2; ++n) _Pragma("unroll") for (int k = 0; k < 2; ++k) dst[n][k] = *(const LAS bf16x8*)(lds + PG8_SB(b, h) + boff + n * 2048 + k * 1024); } while (0)
; #define PG8_MMA(ai, bj, At, Bt) do { __builtin_amdgcn_s_setprio(1); _Pragma("unroll") for (int m = 0; m < 4; ++m) _Pragma("unroll") for (int n = 0; n < 2; ++n) _Pragma("unroll") for (int k = 0; k < 2; ++k) \
;         acc[ai][bj][m][n] = __builtin_amdgcn_mfma_f32_16x16x32_bf16(Bt[n][k], At[m][k], acc[ai][bj][m][n], 0, 0, 0); __builtin_amdgcn_s_setprio(0); } while (0)
; #define PG8_WAIT_V(n) asm volatile("s_waitcnt vmcnt(" #n ")" ::: "memory")
; #define PG8_WAIT_L(n) asm volatile("s_waitcnt lgkmcnt(" #n ")" ::: "memory")
; #define PG8_BAR __builtin_amdgcn_s_barrier()
; #define PG8_SCHED __builtin_amdgcn_sched_barrier(0)
; template <class Epi, class Sched>
; __device__ __forceinline__ void gemm_phase(LAS unsigned char* lds, const Sched& S, const Epi& E) {
;     ...
;             PG8_LDB(B0, 0, 0); PG8_LDB(B1, 0, 1); PG8_SCHED; PG8_LDA(At, 0, 0); PG8_STAGE(PG8_SA(1, 1), a1 + hA, voffA, hA / 2);
;             PG8_WAIT_V(8); PG8_WAIT_L(0); PG8_BAR; PG8_MMA(0, 0, At, B0); PG8_MMA(0, 1, At, B1); PG8_BAR; PG8_SCHED;
;             PG8_LDA(At, 0, 1); PG8_STAGE(PG8_SB(0, 0), b2, vB2, hB2 / 2); PG8_STAGE(PG8_SB(0, 1), b2 + hB2, vB2, hB2 / 2); PG8_STAGE(PG8_SA(0, 0), a2, vA2, hA2 / 2);
;             PG8_WAIT_V(8); PG8_WAIT_L(0); PG8_BAR; PG8_MMA(1, 0, At, B0); PG8_MMA(1, 1, At, B1); PG8_BAR; PG8_SCHED;
;             PG8_LDB(B0, 1, 0); PG8_LDB(B1, 1, 1); PG8_SCHED; PG8_LDA(At, 1, 0); PG8_STAGE(PG8_SA(0, 1), a2 + hA2, vA2, hA2 / 2);
;             PG8_WAIT_V(8); PG8_WAIT_L(0); PG8_BAR; PG8_MMA(0, 0, At, B0); PG8_MMA(0, 1, At, B1); PG8_BAR; PG8_SCHED;
.LBB0_398:
	ds_read_b128 v[130:133], v164
	ds_read_b128 v[134:137], v164 offset:1024
	ds_read_b128 v[138:141], v164 offset:2048
	ds_read_b128 v[142:145], v164 offset:3072
	ds_read_b128 v[146:149], v165
	ds_read_b128 v[150:153], v165 offset:1024
	ds_read_b128 v[154:157], v165 offset:2048
	ds_read_b128 v[158:161], v165 offset:3072
	s_add_i32 s73, s38, 2
	s_cmp_eq_u32 s68, s38
	s_cselect_b32 s38, s67, s69
	s_cselect_b32 s39, s66, s70
	s_cselect_b32 s42, s45, s71
	s_cselect_b32 s43, s44, s72
	s_add_u32 s40, s38, 0x80
	s_addc_u32 s41, s39, 0
	ds_read_b128 v[170:173], v166
	ds_read_b128 v[178:181], v166 offset:1024
	ds_read_b128 v[182:185], v166 offset:2048
	ds_read_b128 v[186:189], v166 offset:3072
	ds_read_b128 v[190:193], v166 offset:4096
	ds_read_b128 v[194:197], v166 offset:5120
	ds_read_b128 v[198:201], v166 offset:6144
	ds_read_b128 v[202:205], v166 offset:7168
	s_add_u32 s74, s69, 0xaff80
	s_addc_u32 s75, s70, 0
	s_mov_b32 m0, s59
	s_nop 0
	global_load_lds_dwordx4 v128, s[74:75]
	s_add_u32 s74, s69, 0x107f80
	s_addc_u32 s75, s70, 0
	s_mov_b32 m0, s60
	s_nop 0
	global_load_lds_dwordx4 v128, s[74:75]
	s_waitcnt vmcnt(8)
	s_waitcnt lgkmcnt(0)
	s_barrier
	s_setprio 1
	v_mfma_f32_16x16x32_bf16 v[124:127], v[130:133], v[170:173], v[124:127]
	v_mfma_f32_16x16x32_bf16 v[120:123], v[138:141], v[170:173], v[120:123]
	v_mfma_f32_16x16x32_bf16 v[116:119], v[130:133], v[182:185], v[116:119]
	v_mfma_f32_16x16x32_bf16 v[112:115], v[138:141], v[182:185], v[112:115]
	v_mfma_f32_16x16x32_bf16 v[108:111], v[130:133], v[190:193], v[108:111]
	v_mfma_f32_16x16x32_bf16 v[104:107], v[138:141], v[190:193], v[104:107]
	v_mfma_f32_16x16x32_bf16 v[100:103], v[130:133], v[198:201], v[100:103]
	v_mfma_f32_16x16x32_bf16 v[96:99], v[138:141], v[198:201], v[96:99]
	v_mfma_f32_16x16x32_bf16 v[124:127], v[134:137], v[178:181], v[124:127]
	v_mfma_f32_16x16x32_bf16 v[120:123], v[142:145], v[178:181], v[120:123]
	v_mfma_f32_16x16x32_bf16 v[116:119], v[134:137], v[186:189], v[116:119]
	v_mfma_f32_16x16x32_bf16 v[112:115], v[142:145], v[186:189], v[112:115]
	v_mfma_f32_16x16x32_bf16 v[108:111], v[134:137], v[194:197], v[108:111]
	v_mfma_f32_16x16x32_bf16 v[104:107], v[142:145], v[194:197], v[104:107]
	v_mfma_f32_16x16x32_bf16 v[100:103], v[134:137], v[202:205], v[100:103]
	v_mfma_f32_16x16x32_bf16 v[96:99], v[142:145], v[202:205], v[96:99]
	v_mfma_f32_16x16x32_bf16 v[60:63], v[146:149], v[170:173], v[60:63]
	v_mfma_f32_16x16x32_bf16 v[56:59], v[154:157], v[170:173], v[56:59]
	v_mfma_f32_16x16x32_bf16 v[52:55], v[146:149], v[182:185], v[52:55]
	v_mfma_f32_16x16x32_bf16 v[48:51], v[154:157], v[182:185], v[48:51]
	v_mfma_f32_16x16x32_bf16 v[44:47], v[146:149], v[190:193], v[44:47]
	v_mfma_f32_16x16x32_bf16 v[40:43], v[154:157], v[190:193], v[40:43]
	v_mfma_f32_16x16x32_bf16 v[36:39], v[146:149], v[198:201], v[36:39]
	v_mfma_f32_16x16x32_bf16 v[32:35], v[154:157], v[198:201], v[32:35]
	v_mfma_f32_16x16x32_bf16 v[60:63], v[150:153], v[178:181], v[60:63]
	v_mfma_f32_16x16x32_bf16 v[56:59], v[158:161], v[178:181], v[56:59]
	v_mfma_f32_16x16x32_bf16 v[52:55], v[150:153], v[186:189], v[52:55]
	v_mfma_f32_16x16x32_bf16 v[48:51], v[158:161], v[186:189], v[48:51]
	v_mfma_f32_16x16x32_bf16 v[44:47], v[150:153], v[194:197], v[44:47]
	v_mfma_f32_16x16x32_bf16 v[40:43], v[158:161], v[194:197], v[40:43]
	v_mfma_f32_16x16x32_bf16 v[36:39], v[150:153], v[202:205], v[36:39]
	v_mfma_f32_16x16x32_bf16 v[32:35], v[158:161], v[202:205], v[32:35]
	s_setprio 0
	s_barrier
	s_add_u32 s74, s42, 0x58000
	ds_read_b128 v[170:173], v166 offset:16384
	ds_read_b128 v[178:181], v166 offset:17408
	ds_read_b128 v[182:185], v166 offset:18432
	ds_read_b128 v[186:189], v166 offset:19456
	ds_read_b128 v[190:193], v166 offset:20480
	ds_read_b128 v[194:197], v166 offset:21504
	ds_read_b128 v[198:201], v166 offset:22528
	ds_read_b128 v[202:205], v166 offset:23552
	s_mov_b32 m0, s15
	s_nop 0
	global_load_lds_dwordx4 v129, s[42:43]
	s_addc_u32 s75, s43, 0
	s_mov_b32 m0, s33
	s_nop 0
	global_load_lds_dwordx4 v129, s[74:75]
	s_add_u32 s74, s42, 0xb0000
	s_addc_u32 s75, s43, 0
	s_mov_b32 m0, s34
	s_nop 0
	global_load_lds_dwordx4 v129, s[74:75]
	s_add_u32 s74, s42, 0x108000
	s_addc_u32 s75, s43, 0
	s_mov_b32 m0, s35
	s_nop 0
	global_load_lds_dwordx4 v129, s[74:75]
	s_mov_b32 m0, s14
	s_nop 0
	global_load_lds_dwordx4 v128, s[38:39]
	s_add_u32 s74, s38, 0x58000
	s_addc_u32 s75, s39, 0
	s_mov_b32 m0, s36
	s_nop 0
	global_load_lds_dwordx4 v128, s[74:75]
	s_waitcnt vmcnt(8)
	s_waitcnt lgkmcnt(0)
	s_barrier
	s_setprio 1
	v_mfma_f32_16x16x32_bf16 v[92:95], v[130:133], v[170:173], v[92:95]
	v_mfma_f32_16x16x32_bf16 v[88:91], v[138:141], v[170:173], v[88:91]
	v_mfma_f32_16x16x32_bf16 v[84:87], v[130:133], v[182:185], v[84:87]
	v_mfma_f32_16x16x32_bf16 v[80:83], v[138:141], v[182:185], v[80:83]
	v_mfma_f32_16x16x32_bf16 v[76:79], v[130:133], v[190:193], v[76:79]
	v_mfma_f32_16x16x32_bf16 v[72:75], v[138:141], v[190:193], v[72:75]
	v_mfma_f32_16x16x32_bf16 v[68:71], v[130:133], v[198:201], v[68:71]
	v_mfma_f32_16x16x32_bf16 v[64:67], v[138:141], v[198:201], v[64:67]
	v_mfma_f32_16x16x32_bf16 v[92:95], v[134:137], v[178:181], v[92:95]
	v_mfma_f32_16x16x32_bf16 v[88:91], v[142:145], v[178:181], v[88:91]
	v_mfma_f32_16x16x32_bf16 v[84:87], v[134:137], v[186:189], v[84:87]
	v_mfma_f32_16x16x32_bf16 v[80:83], v[142:145], v[186:189], v[80:83]
	v_mfma_f32_16x16x32_bf16 v[76:79], v[134:137], v[194:197], v[76:79]
	v_mfma_f32_16x16x32_bf16 v[72:75], v[142:145], v[194:197], v[72:75]
	v_mfma_f32_16x16x32_bf16 v[68:71], v[134:137], v[202:205], v[68:71]
	v_mfma_f32_16x16x32_bf16 v[64:67], v[142:145], v[202:205], v[64:67]
	v_mfma_f32_16x16x32_bf16 v[28:31], v[146:149], v[170:173], v[28:31]
	v_mfma_f32_16x16x32_bf16 v[24:27], v[154:157], v[170:173], v[24:27]
	v_mfma_f32_16x16x32_bf16 v[20:23], v[146:149], v[182:185], v[20:23]
	v_mfma_f32_16x16x32_bf16 v[16:19], v[154:157], v[182:185], v[16:19]
	v_mfma_f32_16x16x32_bf16 v[12:15], v[146:149], v[190:193], v[12:15]
	v_mfma_f32_16x16x32_bf16 v[8:11], v[154:157], v[190:193], v[8:11]
	v_mfma_f32_16x16x32_bf16 v[4:7], v[146:149], v[198:201], v[4:7]
	v_mfma_f32_16x16x32_bf16 v[0:3], v[154:157], v[198:201], v[0:3]
	v_mfma_f32_16x16x32_bf16 v[28:31], v[150:153], v[178:181], v[28:31]
	v_mfma_f32_16x16x32_bf16 v[24:27], v[158:161], v[178:181], v[24:27]
	v_mfma_f32_16x16x32_bf16 v[20:23], v[150:153], v[186:189], v[20:23]
	v_mfma_f32_16x16x32_bf16 v[16:19], v[158:161], v[186:189], v[16:19]
	v_mfma_f32_16x16x32_bf16 v[12:15], v[150:153], v[194:197], v[12:15]
	v_mfma_f32_16x16x32_bf16 v[8:11], v[158:161], v[194:197], v[8:11]
	v_mfma_f32_16x16x32_bf16 v[4:7], v[150:153], v[202:205], v[4:7]
	v_mfma_f32_16x16x32_bf16 v[0:3], v[158:161], v[202:205], v[0:3]
	s_setprio 0
	s_barrier
; #define PG8_STAGE(bufoff, gbase, voff, p64) do { _Pragma("unroll") for (int _i = 0; _i < 2; ++_i) { \
;         const char* _gb = (const char*)(gbase) + (size_t)_i * (p64); const unsigned _la = ldsbase + (unsigned)(bufoff) + (unsigned)_i * 8192u; \
;         asm volatile("s_mov_b32 m0, %0\n\ts_nop 0\n\tglobal_load_lds_dwordx4 %1, %2" :: "s"(_la), "v"(voff), "s"(_gb) : "memory"); } } while (0)
; #define PG8_LDA(dst, b, h) do { _Pragma("unroll") for (int m = 0; m < 4; ++m) _Pragma("unroll") for (int k = 0; k < 2; ++k) dst[m][k] = *(const LAS bf16x8*)(lds + PG8_SA(b, h) + aoff + m * 2048 + k * 1024); } while (0)
; #define PG8_LDB(dst, b, h) do { _Pragma("unroll") for (int n = 0; n < 2; ++n) _Pragma("unroll") for (int k = 0; k < 2; ++k) dst[n][k] = *(const LAS bf16x8*)(lds + PG8_SB(b, h) + boff + n * 2048 + k * 1024); } while (0)
; #define PG8_MMA(ai, bj, At, Bt) do { __builtin_amdgcn_s_setprio(1); _Pragma("unroll") for (int m = 0; m < 4; ++m) _Pragma("unroll") for (int n = 0; n < 2; ++n) _Pragma("unroll") for (int k = 0; k < 2; ++k) \
;         acc[ai][bj][m][n] = __builtin_amdgcn_mfma_f32_16x16x32_bf16(Bt[n][k], At[m][k], acc[ai][bj][m][n], 0, 0, 0); __builtin_amdgcn_s_setprio(0); } while (0)
; #define PG8_WAIT_V(n) asm volatile("s_waitcnt vmcnt(" #n ")" ::: "memory")
; #define PG8_WAIT_L(n) asm volatile("s_waitcnt lgkmcnt(" #n ")" ::: "memory")
; #define PG8_BAR __builtin_amdgcn_s_barrier()
; #define PG8_SCHED __builtin_amdgcn_sched_barrier(0)
; template <class Epi, class Sched>
; __device__ __forceinline__ void gemm_phase(LAS unsigned char* lds, const Sched& S, const Epi& E) {
;     ...
;             PG8_LDB(B0, 1, 0); PG8_LDB(B1, 1, 1); PG8_SCHED; PG8_LDA(At, 1, 0); PG8_STAGE(PG8_SA(0, 1), a2 + hA2, vA2, hA2 / 2);
;             PG8_WAIT_V(8); PG8_WAIT_L(0); PG8_BAR; PG8_MMA(0, 0, At, B0); PG8_MMA(0, 1, At, B1); PG8_BAR; PG8_SCHED;
;             PG8_LDA(At, 1, 1); PG8_STAGE(PG8_SB(1, 0), b3, vB2, hB2 / 2); PG8_STAGE(PG8_SB(1, 1), b3 + hB2, vB2, hB2 / 2); PG8_STAGE(PG8_SA(1, 0), a3, vA2, hA2 / 2);
;             PG8_WAIT_V(8); PG8_WAIT_L(0); PG8_BAR; PG8_MMA(1, 0, At, B0); PG8_MMA(1, 1, At, B1); PG8_BAR; PG8_SCHED;
	ds_read_b128 v[130:133], v167
	ds_read_b128 v[134:137], v167 offset:1024
	ds_read_b128 v[138:141], v167 offset:2048
	ds_read_b128 v[142:145], v167 offset:3072
	ds_read_b128 v[146:149], v168
	ds_read_b128 v[150:153], v168 offset:1024
	ds_read_b128 v[154:157], v168 offset:2048
	ds_read_b128 v[158:161], v168 offset:3072
	ds_read_b128 v[170:173], v166 offset:32768
	ds_read_b128 v[178:181], v166 offset:33792
	ds_read_b128 v[182:185], v166 offset:34816
	ds_read_b128 v[186:189], v166 offset:35840
	ds_read_b128 v[190:193], v166 offset:36864
	ds_read_b128 v[194:197], v166 offset:37888
	ds_read_b128 v[198:201], v166 offset:38912
	ds_read_b128 v[202:205], v166 offset:39936
	s_add_u32 s74, s38, 0xb0000
	s_addc_u32 s75, s39, 0
	s_mov_b32 m0, s37
	s_nop 0
	global_load_lds_dwordx4 v128, s[74:75]
	s_add_u32 s74, s38, 0x108000
	s_addc_u32 s75, s39, 0
	s_mov_b32 m0, s46
	s_nop 0
	global_load_lds_dwordx4 v128, s[74:75]
	s_waitcnt vmcnt(8)
	s_waitcnt lgkmcnt(0)
	s_barrier
	s_setprio 1
	v_mfma_f32_16x16x32_bf16 v[124:127], v[130:133], v[170:173], v[124:127]
	v_mfma_f32_16x16x32_bf16 v[120:123], v[138:141], v[170:173], v[120:123]
	v_mfma_f32_16x16x32_bf16 v[116:119], v[130:133], v[182:185], v[116:119]
	v_mfma_f32_16x16x32_bf16 v[112:115], v[138:141], v[182:185], v[112:115]
	v_mfma_f32_16x16x32_bf16 v[108:111], v[130:133], v[190:193], v[108:111]
	v_mfma_f32_16x16x32_bf16 v[104:107], v[138:141], v[190:193], v[104:107]
	v_mfma_f32_16x16x32_bf16 v[100:103], v[130:133], v[198:201], v[100:103]
	v_mfma_f32_16x16x32_bf16 v[96:99], v[138:141], v[198:201], v[96:99]
	v_mfma_f32_16x16x32_bf16 v[124:127], v[134:137], v[178:181], v[124:127]
	v_mfma_f32_16x16x32_bf16 v[120:123], v[142:145], v[178:181], v[120:123]
	v_mfma_f32_16x16x32_bf16 v[116:119], v[134:137], v[186:189], v[116:119]
	v_mfma_f32_16x16x32_bf16 v[112:115], v[142:145], v[186:189], v[112:115]
	v_mfma_f32_16x16x32_bf16 v[108:111], v[134:137], v[194:197], v[108:111]
	v_mfma_f32_16x16x32_bf16 v[104:107], v[142:145], v[194:197], v[104:107]
	v_mfma_f32_16x16x32_bf16 v[100:103], v[134:137], v[202:205], v[100:103]
	v_mfma_f32_16x16x32_bf16 v[96:99], v[142:145], v[202:205], v[96:99]
	v_mfma_f32_16x16x32_bf16 v[60:63], v[146:149], v[170:173], v[60:63]
	v_mfma_f32_16x16x32_bf16 v[56:59], v[154:157], v[170:173], v[56:59]
	v_mfma_f32_16x16x32_bf16 v[52:55], v[146:149], v[182:185], v[52:55]
	v_mfma_f32_16x16x32_bf16 v[48:51], v[154:157], v[182:185], v[48:51]
	v_mfma_f32_16x16x32_bf16 v[44:47], v[146:149], v[190:193], v[44:47]
	v_mfma_f32_16x16x32_bf16 v[40:43], v[154:157], v[190:193], v[40:43]
	v_mfma_f32_16x16x32_bf16 v[36:39], v[146:149], v[198:201], v[36:39]
	v_mfma_f32_16x16x32_bf16 v[32:35], v[154:157], v[198:201], v[32:35]
	v_mfma_f32_16x16x32_bf16 v[60:63], v[150:153], v[178:181], v[60:63]
	v_mfma_f32_16x16x32_bf16 v[56:59], v[158:161], v[178:181], v[56:59]
	v_mfma_f32_16x16x32_bf16 v[52:55], v[150:153], v[186:189], v[52:55]
	v_mfma_f32_16x16x32_bf16 v[48:51], v[158:161], v[186:189], v[48:51]
	v_mfma_f32_16x16x32_bf16 v[44:47], v[150:153], v[194:197], v[44:47]
	v_mfma_f32_16x16x32_bf16 v[40:43], v[158:161], v[194:197], v[40:43]
	v_mfma_f32_16x16x32_bf16 v[36:39], v[150:153], v[202:205], v[36:39]
	v_mfma_f32_16x16x32_bf16 v[32:35], v[158:161], v[202:205], v[32:35]
	s_setprio 0
	s_barrier
	s_add_u32 s74, s42, 0x80
	s_addc_u32 s75, s43, 0
	ds_read_b128 v[170:173], v166 offset:49152
	ds_read_b128 v[178:181], v166 offset:50176
	ds_read_b128 v[182:185], v166 offset:51200
	ds_read_b128 v[186:189], v166 offset:52224
	ds_read_b128 v[190:193], v166 offset:53248
	ds_read_b128 v[194:197], v166 offset:54272
	ds_read_b128 v[198:201], v166 offset:55296
	ds_read_b128 v[202:205], v166 offset:56320
	s_mov_b32 m0, s53
	s_nop 0
	global_load_lds_dwordx4 v129, s[74:75]
	s_add_u32 s74, s42, 0x58080
	s_addc_u32 s75, s43, 0
	s_mov_b32 m0, s54
	s_nop 0
	global_load_lds_dwordx4 v129, s[74:75]
	s_add_u32 s74, s42, 0xb0080
	s_addc_u32 s75, s43, 0
	s_mov_b32 m0, s57
	s_nop 0
	global_load_lds_dwordx4 v129, s[74:75]
	s_add_u32 s42, s42, 0x108080
	s_addc_u32 s43, s43, 0
	s_mov_b32 m0, s58
	s_nop 0
	global_load_lds_dwordx4 v129, s[42:43]
	s_mov_b32 m0, s55
	s_nop 0
	global_load_lds_dwordx4 v128, s[40:41]
	s_add_u32 s38, s38, 0x58080
	s_addc_u32 s39, s39, 0
	s_mov_b32 m0, s56
	s_nop 0
	global_load_lds_dwordx4 v128, s[38:39]
	s_waitcnt vmcnt(8)
	s_waitcnt lgkmcnt(0)
	s_barrier
	s_setprio 1
	v_mfma_f32_16x16x32_bf16 v[92:95], v[130:133], v[170:173], v[92:95]
	v_mfma_f32_16x16x32_bf16 v[88:91], v[138:141], v[170:173], v[88:91]
	v_mfma_f32_16x16x32_bf16 v[84:87], v[130:133], v[182:185], v[84:87]
	v_mfma_f32_16x16x32_bf16 v[80:83], v[138:141], v[182:185], v[80:83]
	v_mfma_f32_16x16x32_bf16 v[76:79], v[130:133], v[190:193], v[76:79]
	v_mfma_f32_16x16x32_bf16 v[72:75], v[138:141], v[190:193], v[72:75]
	v_mfma_f32_16x16x32_bf16 v[68:71], v[130:133], v[198:201], v[68:71]
	v_mfma_f32_16x16x32_bf16 v[64:67], v[138:141], v[198:201], v[64:67]
	v_mfma_f32_16x16x32_bf16 v[92:95], v[134:137], v[178:181], v[92:95]
	v_mfma_f32_16x16x32_bf16 v[88:91], v[142:145], v[178:181], v[88:91]
	v_mfma_f32_16x16x32_bf16 v[84:87], v[134:137], v[186:189], v[84:87]
	v_mfma_f32_16x16x32_bf16 v[80:83], v[142:145], v[186:189], v[80:83]
	v_mfma_f32_16x16x32_bf16 v[76:79], v[134:137], v[194:197], v[76:79]
	v_mfma_f32_16x16x32_bf16 v[72:75], v[142:145], v[194:197], v[72:75]
	v_mfma_f32_16x16x32_bf16 v[68:71], v[134:137], v[202:205], v[68:71]
	v_mfma_f32_16x16x32_bf16 v[64:67], v[142:145], v[202:205], v[64:67]
	v_mfma_f32_16x16x32_bf16 v[28:31], v[146:149], v[170:173], v[28:31]
	v_mfma_f32_16x16x32_bf16 v[24:27], v[154:157], v[170:173], v[24:27]
	v_mfma_f32_16x16x32_bf16 v[20:23], v[146:149], v[182:185], v[20:23]
	v_mfma_f32_16x16x32_bf16 v[16:19], v[154:157], v[182:185], v[16:19]
	v_mfma_f32_16x16x32_bf16 v[12:15], v[146:149], v[190:193], v[12:15]
	v_mfma_f32_16x16x32_bf16 v[8:11], v[154:157], v[190:193], v[8:11]
	v_mfma_f32_16x16x32_bf16 v[4:7], v[146:149], v[198:201], v[4:7]
	v_mfma_f32_16x16x32_bf16 v[0:3], v[154:157], v[198:201], v[0:3]
	v_mfma_f32_16x16x32_bf16 v[28:31], v[150:153], v[178:181], v[28:31]
	v_mfma_f32_16x16x32_bf16 v[24:27], v[158:161], v[178:181], v[24:27]
	v_mfma_f32_16x16x32_bf16 v[20:23], v[150:153], v[186:189], v[20:23]
	v_mfma_f32_16x16x32_bf16 v[16:19], v[158:161], v[186:189], v[16:19]
	v_mfma_f32_16x16x32_bf16 v[12:15], v[150:153], v[194:197], v[12:15]
	v_mfma_f32_16x16x32_bf16 v[8:11], v[158:161], v[194:197], v[8:11]
	v_mfma_f32_16x16x32_bf16 v[4:7], v[150:153], v[202:205], v[4:7]
	v_mfma_f32_16x16x32_bf16 v[0:3], v[158:161], v[202:205], v[0:3]
	s_setprio 0
	s_barrier
	s_add_u32 s69, s69, 0x100
	s_addc_u32 s70, s70, 0
	s_add_u32 s71, s71, 0x100
	s_addc_u32 s72, s72, 0
	s_cmp_ge_i32 s73, s21
	s_mov_b32 s38, s73
	s_cbranch_scc0 .LBB0_398
	s_and_b64 vcc, exec, s[18:19]
	s_cbranch_vccz .LBB0_401
	s_barrier

; #define PG8_STAGE(bufoff, gbase, voff, p64) do { _Pragma("unroll") for (int _i = 0; _i < 2; ++_i) { \
;         const char* _gb = (const char*)(gbase) + (size_t)_i * (p64); const unsigned _la = ldsbase + (unsigned)(bufoff) + (unsigned)_i * 8192u; \
;         asm volatile("s_mov_b32 m0, %0\n\ts_nop 0\n\tglobal_load_lds_dwordx4 %1, %2" :: "s"(_la), "v"(voff), "s"(_gb) : "memory"); } } while (0)
; #define PG8_LDA(dst, b, h) do { _Pragma("unroll") for (int m = 0; m < 4; ++m) _Pragma("unroll") for (int k = 0; k < 2; ++k) dst[m][k] = *(const LAS bf16x8*)(lds + PG8_SA(b, h) + aoff + m * 2048 + k * 1024); } while (0)
; #define PG8_LDB(dst, b, h) do { _Pragma("unroll") for (int n = 0; n < 2; ++n) _Pragma("unroll") for (int k = 0; k < 2; ++k) dst[n][k] = *(const LAS bf16x8*)(lds + PG8_SB(b, h) + boff + n * 2048 + k * 1024); } while (0)
; #define PG8_MMA(ai, bj, At, Bt) do { __builtin_amdgcn_s_setprio(1); _Pragma("unroll") for (int m = 0; m < 4; ++m) _Pragma("unroll") for (int n = 0; n < 2; ++n) _Pragma("unroll") for (int k = 0; k < 2; ++k) \
;         acc[ai][bj][m][n] = __builtin_amdgcn_mfma_f32_16x16x32_bf16(Bt[n][k], At[m][k], acc[ai][bj][m][n], 0, 0, 0); __builtin_amdgcn_s_setprio(0); } while (0)
; #define PG8_WAIT_V(n) asm volatile("s_waitcnt vmcnt(" #n ")" ::: "memory")
; #define PG8_WAIT_L(n) asm volatile("s_waitcnt lgkmcnt(" #n ")" ::: "memory")
; #define PG8_BAR __builtin_amdgcn_s_barrier()
; #define PG8_SCHED __builtin_amdgcn_sched_barrier(0)
; template <class Epi, class Sched>
; __device__ __forceinline__ void gemm_phase(LAS unsigned char* lds, const Sched& S, const Epi& E) {
;     ...
;             PG8_LDB(B0, 0, 0); PG8_LDB(B1, 0, 1); PG8_SCHED; PG8_LDA(At, 0, 0); PG8_STAGE(PG8_SA(1, 1), a1 + hA, voffA, hA / 2);
;             PG8_WAIT_V(8); PG8_WAIT_L(0); PG8_BAR; PG8_MMA(0, 0, At, B0); PG8_MMA(0, 1, At, B1); PG8_BAR; PG8_SCHED;
;             PG8_LDA(At, 0, 1); PG8_STAGE(PG8_SB(0, 0), b2, vB2, hB2 / 2); PG8_STAGE(PG8_SB(0, 1), b2 + hB2, vB2, hB2 / 2); PG8_STAGE(PG8_SA(0, 0), a2, vA2, hA2 / 2);
;             PG8_WAIT_V(8); PG8_WAIT_L(0); PG8_BAR; PG8_MMA(1, 0, At, B0); PG8_MMA(1, 1, At, B1); PG8_BAR; PG8_SCHED;
.LBB0_553:
	v_add_u32_e32 v128, 0x10000, v154
	ds_read_b128 v[138:141], v128
	ds_read_b128 v[142:145], v128 offset:1024
	ds_read_b128 v[146:149], v128 offset:2048
	ds_read_b128 v[172:175], v128 offset:3072
	v_add_u32_e32 v128, 0x14000, v154
	ds_read_b128 v[178:181], v128
	ds_read_b128 v[182:185], v128 offset:1024
	ds_read_b128 v[186:189], v128 offset:2048
	ds_read_b128 v[190:193], v128 offset:3072
	s_add_u32 s16, s74, 0xfffc0080
	s_addc_u32 s17, s75, -1
	s_cmp_eq_u32 s81, 12
	s_cselect_b32 s16, s58, s16
	s_cselect_b32 s17, s59, s17
	s_cselect_b32 s76, s62, s57
	s_cselect_b32 s77, s63, s80
	s_add_u32 s22, s16, 0x80
	s_addc_u32 s23, s17, 0
	ds_read_b128 v[194:197], v155
	ds_read_b128 v[198:201], v155 offset:1024
	ds_read_b128 v[202:205], v155 offset:2048
	ds_read_b128 v[206:209], v155 offset:3072
	ds_read_b128 v[210:213], v155 offset:4096
	ds_read_b128 v[214:217], v155 offset:5120
	ds_read_b128 v[218:221], v155 offset:6144
	ds_read_b128 v[222:225], v155 offset:7168
	s_mov_b32 m0, s67
	s_nop 0
	global_load_lds_dwordx4 v150, s[74:75]
	s_add_u32 s82, s74, 0x20000
	s_addc_u32 s83, s75, 0
	s_mov_b32 m0, s69
	s_nop 0
	global_load_lds_dwordx4 v150, s[82:83]
	s_waitcnt vmcnt(8)
	s_waitcnt lgkmcnt(0)
	s_barrier
	s_setprio 1
	v_mfma_f32_16x16x32_bf16 v[124:127], v[138:141], v[194:197], v[124:127]
	v_mfma_f32_16x16x32_bf16 v[120:123], v[146:149], v[194:197], v[120:123]
	v_mfma_f32_16x16x32_bf16 v[112:115], v[138:141], v[202:205], v[112:115]
	v_mfma_f32_16x16x32_bf16 v[104:107], v[146:149], v[202:205], v[104:107]
	v_mfma_f32_16x16x32_bf16 v[96:99], v[138:141], v[210:213], v[96:99]
	v_mfma_f32_16x16x32_bf16 v[88:91], v[146:149], v[210:213], v[88:91]
	v_mfma_f32_16x16x32_bf16 v[80:83], v[138:141], v[218:221], v[80:83]
	v_mfma_f32_16x16x32_bf16 v[72:75], v[146:149], v[218:221], v[72:75]
	v_mfma_f32_16x16x32_bf16 v[124:127], v[142:145], v[198:201], v[124:127]
	v_mfma_f32_16x16x32_bf16 v[120:123], v[172:175], v[198:201], v[120:123]
	v_mfma_f32_16x16x32_bf16 v[112:115], v[142:145], v[206:209], v[112:115]
	v_mfma_f32_16x16x32_bf16 v[104:107], v[172:175], v[206:209], v[104:107]
	v_mfma_f32_16x16x32_bf16 v[96:99], v[142:145], v[214:217], v[96:99]
	v_mfma_f32_16x16x32_bf16 v[88:91], v[172:175], v[214:217], v[88:91]
	v_mfma_f32_16x16x32_bf16 v[80:83], v[142:145], v[222:225], v[80:83]
	v_mfma_f32_16x16x32_bf16 v[72:75], v[172:175], v[222:225], v[72:75]
	v_mfma_f32_16x16x32_bf16 v[116:119], v[178:181], v[194:197], v[116:119]
	v_mfma_f32_16x16x32_bf16 v[108:111], v[186:189], v[194:197], v[108:111]
	v_mfma_f32_16x16x32_bf16 v[100:103], v[178:181], v[202:205], v[100:103]
	v_mfma_f32_16x16x32_bf16 v[92:95], v[186:189], v[202:205], v[92:95]
	v_mfma_f32_16x16x32_bf16 v[84:87], v[178:181], v[210:213], v[84:87]
	v_mfma_f32_16x16x32_bf16 v[76:79], v[186:189], v[210:213], v[76:79]
	v_mfma_f32_16x16x32_bf16 v[68:71], v[178:181], v[218:221], v[68:71]
	v_mfma_f32_16x16x32_bf16 v[64:67], v[186:189], v[218:221], v[64:67]
	v_mfma_f32_16x16x32_bf16 v[116:119], v[182:185], v[198:201], v[116:119]
	v_mfma_f32_16x16x32_bf16 v[108:111], v[190:193], v[198:201], v[108:111]
	v_mfma_f32_16x16x32_bf16 v[100:103], v[182:185], v[206:209], v[100:103]
	v_mfma_f32_16x16x32_bf16 v[92:95], v[190:193], v[206:209], v[92:95]
	v_mfma_f32_16x16x32_bf16 v[84:87], v[182:185], v[214:217], v[84:87]
	v_mfma_f32_16x16x32_bf16 v[76:79], v[190:193], v[214:217], v[76:79]
	v_mfma_f32_16x16x32_bf16 v[68:71], v[182:185], v[222:225], v[68:71]
	v_mfma_f32_16x16x32_bf16 v[64:67], v[190:193], v[222:225], v[64:67]
	s_setprio 0
	s_barrier
	s_add_u32 s82, s76, 0x20000
	ds_read_b128 v[194:197], v155 offset:16384
	ds_read_b128 v[198:201], v155 offset:17408
	ds_read_b128 v[202:205], v155 offset:18432
	ds_read_b128 v[206:209], v155 offset:19456
	ds_read_b128 v[210:213], v155 offset:20480
	ds_read_b128 v[214:217], v155 offset:21504
	ds_read_b128 v[218:221], v155 offset:22528
	ds_read_b128 v[222:225], v155 offset:23552
	s_mov_b32 m0, s24
	s_nop 0
	global_load_lds_dwordx4 v151, s[76:77]
	s_addc_u32 s83, s77, 0
	s_mov_b32 m0, s33
	s_nop 0
	global_load_lds_dwordx4 v151, s[82:83]
	s_add_u32 s82, s76, 0x40000
	s_addc_u32 s83, s77, 0
	s_mov_b32 m0, s34
	s_nop 0
	global_load_lds_dwordx4 v151, s[82:83]
	s_add_u32 s82, s76, 0x60000
	s_addc_u32 s83, s77, 0
	s_mov_b32 m0, s35
	s_nop 0
	global_load_lds_dwordx4 v151, s[82:83]
	s_mov_b32 m0, s15
	s_nop 0
	global_load_lds_dwordx4 v150, s[16:17]
	s_add_u32 s82, s16, 0x20000
	s_addc_u32 s83, s17, 0
	s_mov_b32 m0, s36
	s_nop 0
	global_load_lds_dwordx4 v150, s[82:83]
	s_waitcnt vmcnt(8)
	s_waitcnt lgkmcnt(0)
	s_barrier
; #define PG8_STAGE(bufoff, gbase, voff, p64) do { _Pragma("unroll") for (int _i = 0; _i < 2; ++_i) { \
;         const char* _gb = (const char*)(gbase) + (size_t)_i * (p64); const unsigned _la = ldsbase + (unsigned)(bufoff) + (unsigned)_i * 8192u; \
;         asm volatile("s_mov_b32 m0, %0\n\ts_nop 0\n\tglobal_load_lds_dwordx4 %1, %2" :: "s"(_la), "v"(voff), "s"(_gb) : "memory"); } } while (0)
; #define PG8_LDA(dst, b, h) do { _Pragma("unroll") for (int m = 0; m < 4; ++m) _Pragma("unroll") for (int k = 0; k < 2; ++k) dst[m][k] = *(const LAS bf16x8*)(lds + PG8_SA(b, h) + aoff + m * 2048 + k * 1024); } while (0)
; #define PG8_LDB(dst, b, h) do { _Pragma("unroll") for (int n = 0; n < 2; ++n) _Pragma("unroll") for (int k = 0; k < 2; ++k) dst[n][k] = *(const LAS bf16x8*)(lds + PG8_SB(b, h) + boff + n * 2048 + k * 1024); } while (0)
; #define PG8_MMA(ai, bj, At, Bt) do { __builtin_amdgcn_s_setprio(1); _Pragma("unroll") for (int m = 0; m < 4; ++m) _Pragma("unroll") for (int n = 0; n < 2; ++n) _Pragma("unroll") for (int k = 0; k < 2; ++k) \
;         acc[ai][bj][m][n] = __builtin_amdgcn_mfma_f32_16x16x32_bf16(Bt[n][k], At[m][k], acc[ai][bj][m][n], 0, 0, 0); __builtin_amdgcn_s_setprio(0); } while (0)
; #define PG8_WAIT_V(n) asm volatile("s_waitcnt vmcnt(" #n ")" ::: "memory")
; #define PG8_WAIT_L(n) asm volatile("s_waitcnt lgkmcnt(" #n ")" ::: "memory")
; #define PG8_BAR __builtin_amdgcn_s_barrier()
; #define PG8_SCHED __builtin_amdgcn_sched_barrier(0)
; template <class Epi, class Sched>
; __device__ __forceinline__ void gemm_phase(LAS unsigned char* lds, const Sched& S, const Epi& E) {
;     ...
;             PG8_WAIT_V(8); PG8_WAIT_L(0); PG8_BAR; PG8_MMA(0, 0, At, B0); PG8_MMA(0, 1, At, B1); PG8_BAR; PG8_SCHED;
;             PG8_LDA(At, 0, 1); PG8_STAGE(PG8_SB(0, 0), b2, vB2, hB2 / 2); PG8_STAGE(PG8_SB(0, 1), b2 + hB2, vB2, hB2 / 2); PG8_STAGE(PG8_SA(0, 0), a2, vA2, hA2 / 2);
;             PG8_WAIT_V(8); PG8_WAIT_L(0); PG8_BAR; PG8_MMA(1, 0, At, B0); PG8_MMA(1, 1, At, B1); PG8_BAR; PG8_SCHED;
;             PG8_LDB(B0, 1, 0); PG8_LDB(B1, 1, 1); PG8_SCHED; PG8_LDA(At, 1, 0); PG8_STAGE(PG8_SA(0, 1), a2 + hA2, vA2, hA2 / 2);
;             PG8_WAIT_V(8); PG8_WAIT_L(0); PG8_BAR; PG8_MMA(0, 0, At, B0); PG8_MMA(0, 1, At, B1); PG8_BAR; PG8_SCHED;
	s_setprio 1
	v_mfma_f32_16x16x32_bf16 v[60:63], v[138:141], v[194:197], v[60:63]
	v_mfma_f32_16x16x32_bf16 v[56:59], v[146:149], v[194:197], v[56:59]
	v_mfma_f32_16x16x32_bf16 v[48:51], v[138:141], v[202:205], v[48:51]
	v_mfma_f32_16x16x32_bf16 v[40:43], v[146:149], v[202:205], v[40:43]
	v_mfma_f32_16x16x32_bf16 v[32:35], v[138:141], v[210:213], v[32:35]
	v_mfma_f32_16x16x32_bf16 v[24:27], v[146:149], v[210:213], v[24:27]
	v_mfma_f32_16x16x32_bf16 v[16:19], v[138:141], v[218:221], v[16:19]
	v_mfma_f32_16x16x32_bf16 v[8:11], v[146:149], v[218:221], v[8:11]
	v_mfma_f32_16x16x32_bf16 v[60:63], v[142:145], v[198:201], v[60:63]
	v_mfma_f32_16x16x32_bf16 v[56:59], v[172:175], v[198:201], v[56:59]
	v_mfma_f32_16x16x32_bf16 v[48:51], v[142:145], v[206:209], v[48:51]
	v_mfma_f32_16x16x32_bf16 v[40:43], v[172:175], v[206:209], v[40:43]
	v_mfma_f32_16x16x32_bf16 v[32:35], v[142:145], v[214:217], v[32:35]
	v_mfma_f32_16x16x32_bf16 v[24:27], v[172:175], v[214:217], v[24:27]
	v_mfma_f32_16x16x32_bf16 v[16:19], v[142:145], v[222:225], v[16:19]
	v_mfma_f32_16x16x32_bf16 v[8:11], v[172:175], v[222:225], v[8:11]
	v_mfma_f32_16x16x32_bf16 v[52:55], v[178:181], v[194:197], v[52:55]
	v_mfma_f32_16x16x32_bf16 v[44:47], v[186:189], v[194:197], v[44:47]
	v_mfma_f32_16x16x32_bf16 v[36:39], v[178:181], v[202:205], v[36:39]
	v_mfma_f32_16x16x32_bf16 v[28:31], v[186:189], v[202:205], v[28:31]
	v_mfma_f32_16x16x32_bf16 v[20:23], v[178:181], v[210:213], v[20:23]
	v_mfma_f32_16x16x32_bf16 v[12:15], v[186:189], v[210:213], v[12:15]
	v_mfma_f32_16x16x32_bf16 v[4:7], v[178:181], v[218:221], v[4:7]
	v_mfma_f32_16x16x32_bf16 v[0:3], v[186:189], v[218:221], v[0:3]
	v_mfma_f32_16x16x32_bf16 v[52:55], v[182:185], v[198:201], v[52:55]
	v_mfma_f32_16x16x32_bf16 v[44:47], v[190:193], v[198:201], v[44:47]
	v_mfma_f32_16x16x32_bf16 v[36:39], v[182:185], v[206:209], v[36:39]
	v_mfma_f32_16x16x32_bf16 v[28:31], v[190:193], v[206:209], v[28:31]
	v_mfma_f32_16x16x32_bf16 v[20:23], v[182:185], v[214:217], v[20:23]
	v_mfma_f32_16x16x32_bf16 v[12:15], v[190:193], v[214:217], v[12:15]
	v_mfma_f32_16x16x32_bf16 v[4:7], v[182:185], v[222:225], v[4:7]
	v_mfma_f32_16x16x32_bf16 v[0:3], v[190:193], v[222:225], v[0:3]
	s_setprio 0
	s_barrier
	v_add_u32_e32 v128, 0x18000, v154
	ds_read_b128 v[138:141], v128
	ds_read_b128 v[142:145], v128 offset:1024
	ds_read_b128 v[146:149], v128 offset:2048
	ds_read_b128 v[172:175], v128 offset:3072
	v_add_u32_e32 v128, 0x1c000, v154
	ds_read_b128 v[178:181], v128
	ds_read_b128 v[182:185], v128 offset:1024
	ds_read_b128 v[186:189], v128 offset:2048
	ds_read_b128 v[190:193], v128 offset:3072
	ds_read_b128 v[194:197], v155 offset:32768
	ds_read_b128 v[198:201], v155 offset:33792
	ds_read_b128 v[202:205], v155 offset:34816
	ds_read_b128 v[206:209], v155 offset:35840
	ds_read_b128 v[210:213], v155 offset:36864
	ds_read_b128 v[214:217], v155 offset:37888
	ds_read_b128 v[218:221], v155 offset:38912
	ds_read_b128 v[222:225], v155 offset:39936
	s_add_u32 s82, s16, 0x40000
	s_addc_u32 s83, s17, 0
	s_mov_b32 m0, s37
	s_nop 0
	global_load_lds_dwordx4 v150, s[82:83]
	s_add_u32 s82, s16, 0x60000
	s_addc_u32 s83, s17, 0
	s_mov_b32 m0, s42
	s_nop 0
	global_load_lds_dwordx4 v150, s[82:83]
	s_waitcnt vmcnt(8)
	s_waitcnt lgkmcnt(0)
	s_barrier
	s_setprio 1
	v_mfma_f32_16x16x32_bf16 v[124:127], v[138:141], v[194:197], v[124:127]
	v_mfma_f32_16x16x32_bf16 v[120:123], v[146:149], v[194:197], v[120:123]
	v_mfma_f32_16x16x32_bf16 v[112:115], v[138:141], v[202:205], v[112:115]
	v_mfma_f32_16x16x32_bf16 v[104:107], v[146:149], v[202:205], v[104:107]
	v_mfma_f32_16x16x32_bf16 v[96:99], v[138:141], v[210:213], v[96:99]
	v_mfma_f32_16x16x32_bf16 v[88:91], v[146:149], v[210:213], v[88:91]
	v_mfma_f32_16x16x32_bf16 v[80:83], v[138:141], v[218:221], v[80:83]
	v_mfma_f32_16x16x32_bf16 v[72:75], v[146:149], v[218:221], v[72:75]
	v_mfma_f32_16x16x32_bf16 v[124:127], v[142:145], v[198:201], v[124:127]
	v_mfma_f32_16x16x32_bf16 v[120:123], v[172:175], v[198:201], v[120:123]
	v_mfma_f32_16x16x32_bf16 v[112:115], v[142:145], v[206:209], v[112:115]
	v_mfma_f32_16x16x32_bf16 v[104:107], v[172:175], v[206:209], v[104:107]
	v_mfma_f32_16x16x32_bf16 v[96:99], v[142:145], v[214:217], v[96:99]
	v_mfma_f32_16x16x32_bf16 v[88:91], v[172:175], v[214:217], v[88:91]
	v_mfma_f32_16x16x32_bf16 v[80:83], v[142:145], v[222:225], v[80:83]
	v_mfma_f32_16x16x32_bf16 v[72:75], v[172:175], v[222:225], v[72:75]
	v_mfma_f32_16x16x32_bf16 v[116:119], v[178:181], v[194:197], v[116:119]
	v_mfma_f32_16x16x32_bf16 v[108:111], v[186:189], v[194:197], v[108:111]
	v_mfma_f32_16x16x32_bf16 v[100:103], v[178:181], v[202:205], v[100:103]
	v_mfma_f32_16x16x32_bf16 v[92:95], v[186:189], v[202:205], v[92:95]
	v_mfma_f32_16x16x32_bf16 v[84:87], v[178:181], v[210:213], v[84:87]
	v_mfma_f32_16x16x32_bf16 v[76:79], v[186:189], v[210:213], v[76:79]
	v_mfma_f32_16x16x32_bf16 v[68:71], v[178:181], v[218:221], v[68:71]
	v_mfma_f32_16x16x32_bf16 v[64:67], v[186:189], v[218:221], v[64:67]
	v_mfma_f32_16x16x32_bf16 v[116:119], v[182:185], v[198:201], v[116:119]
	v_mfma_f32_16x16x32_bf16 v[108:111], v[190:193], v[198:201], v[108:111]
	v_mfma_f32_16x16x32_bf16 v[100:103], v[182:185], v[206:209], v[100:103]
	v_mfma_f32_16x16x32_bf16 v[92:95], v[190:193], v[206:209], v[92:95]
	v_mfma_f32_16x16x32_bf16 v[84:87], v[182:185], v[214:217], v[84:87]
	v_mfma_f32_16x16x32_bf16 v[76:79], v[190:193], v[214:217], v[76:79]
	v_mfma_f32_16x16x32_bf16 v[68:71], v[182:185], v[222:225], v[68:71]
	v_mfma_f32_16x16x32_bf16 v[64:67], v[190:193], v[222:225], v[64:67]
	s_setprio 0
	s_barrier
; #define PG8_STAGE(bufoff, gbase, voff, p64) do { _Pragma("unroll") for (int _i = 0; _i < 2; ++_i) { \
;         const char* _gb = (const char*)(gbase) + (size_t)_i * (p64); const unsigned _la = ldsbase + (unsigned)(bufoff) + (unsigned)_i * 8192u; \
;         asm volatile("s_mov_b32 m0, %0\n\ts_nop 0\n\tglobal_load_lds_dwordx4 %1, %2" :: "s"(_la), "v"(voff), "s"(_gb) : "memory"); } } while (0)
; #define PG8_LDA(dst, b, h) do { _Pragma("unroll") for (int m = 0; m < 4; ++m) _Pragma("unroll") for (int k = 0; k < 2; ++k) dst[m][k] = *(const LAS bf16x8*)(lds + PG8_SA(b, h) + aoff + m * 2048 + k * 1024); } while (0)
; #define PG8_MMA(ai, bj, At, Bt) do { __builtin_amdgcn_s_setprio(1); _Pragma("unroll") for (int m = 0; m < 4; ++m) _Pragma("unroll") for (int n = 0; n < 2; ++n) _Pragma("unroll") for (int k = 0; k < 2; ++k) \
;         acc[ai][bj][m][n] = __builtin_amdgcn_mfma_f32_16x16x32_bf16(Bt[n][k], At[m][k], acc[ai][bj][m][n], 0, 0, 0); __builtin_amdgcn_s_setprio(0); } while (0)
; #define PG8_WAIT_V(n) asm volatile("s_waitcnt vmcnt(" #n ")" ::: "memory")
; #define PG8_WAIT_L(n) asm volatile("s_waitcnt lgkmcnt(" #n ")" ::: "memory")
; #define PG8_BAR __builtin_amdgcn_s_barrier()
; #define PG8_SCHED __builtin_amdgcn_sched_barrier(0)
; template <class Epi, class Sched>
; __device__ __forceinline__ void gemm_phase(LAS unsigned char* lds, const Sched& S, const Epi& E) {
;     ...
;             PG8_LDA(At, 1, 1); PG8_STAGE(PG8_SB(1, 0), b3, vB2, hB2 / 2); PG8_STAGE(PG8_SB(1, 1), b3 + hB2, vB2, hB2 / 2); PG8_STAGE(PG8_SA(1, 0), a3, vA2, hA2 / 2);
;             PG8_WAIT_V(8); PG8_WAIT_L(0); PG8_BAR; PG8_MMA(1, 0, At, B0); PG8_MMA(1, 1, At, B1); PG8_BAR; PG8_SCHED;
	s_add_u32 s82, s76, 0x80
	s_addc_u32 s83, s77, 0
	ds_read_b128 v[194:197], v155 offset:49152
	ds_read_b128 v[198:201], v155 offset:50176
	ds_read_b128 v[202:205], v155 offset:51200
	ds_read_b128 v[206:209], v155 offset:52224
	ds_read_b128 v[210:213], v155 offset:53248
	ds_read_b128 v[214:217], v155 offset:54272
	ds_read_b128 v[218:221], v155 offset:55296
	ds_read_b128 v[222:225], v155 offset:56320
	s_mov_b32 m0, s50
	s_nop 0
	global_load_lds_dwordx4 v151, s[82:83]
	s_add_u32 s82, s76, 0x20080
	s_addc_u32 s83, s77, 0
	s_mov_b32 m0, s51
	s_nop 0
	global_load_lds_dwordx4 v151, s[82:83]
	s_add_u32 s82, s76, 0x40080
	s_addc_u32 s83, s77, 0
	s_mov_b32 m0, s65
	s_nop 0
	global_load_lds_dwordx4 v151, s[82:83]
	s_add_u32 s76, s76, 0x60080
	s_addc_u32 s77, s77, 0
	s_mov_b32 m0, s66
	s_nop 0
	global_load_lds_dwordx4 v151, s[76:77]
	s_mov_b32 m0, s61
	s_nop 0
	global_load_lds_dwordx4 v150, s[22:23]
	s_add_u32 s16, s16, 0x20080
	s_addc_u32 s17, s17, 0
	s_mov_b32 m0, s64
	s_nop 0
	global_load_lds_dwordx4 v150, s[16:17]
	s_waitcnt vmcnt(8)
	s_waitcnt lgkmcnt(0)
	s_barrier
	s_setprio 1
	v_mfma_f32_16x16x32_bf16 v[60:63], v[138:141], v[194:197], v[60:63]
	v_mfma_f32_16x16x32_bf16 v[56:59], v[146:149], v[194:197], v[56:59]
	v_mfma_f32_16x16x32_bf16 v[48:51], v[138:141], v[202:205], v[48:51]
	v_mfma_f32_16x16x32_bf16 v[40:43], v[146:149], v[202:205], v[40:43]
	v_mfma_f32_16x16x32_bf16 v[32:35], v[138:141], v[210:213], v[32:35]
	v_mfma_f32_16x16x32_bf16 v[24:27], v[146:149], v[210:213], v[24:27]
	v_mfma_f32_16x16x32_bf16 v[16:19], v[138:141], v[218:221], v[16:19]
	v_mfma_f32_16x16x32_bf16 v[8:11], v[146:149], v[218:221], v[8:11]
	v_mfma_f32_16x16x32_bf16 v[60:63], v[142:145], v[198:201], v[60:63]
	v_mfma_f32_16x16x32_bf16 v[56:59], v[172:175], v[198:201], v[56:59]
	v_mfma_f32_16x16x32_bf16 v[48:51], v[142:145], v[206:209], v[48:51]
	v_mfma_f32_16x16x32_bf16 v[40:43], v[172:175], v[206:209], v[40:43]
	v_mfma_f32_16x16x32_bf16 v[32:35], v[142:145], v[214:217], v[32:35]
	v_mfma_f32_16x16x32_bf16 v[24:27], v[172:175], v[214:217], v[24:27]
	v_mfma_f32_16x16x32_bf16 v[16:19], v[142:145], v[222:225], v[16:19]
	v_mfma_f32_16x16x32_bf16 v[8:11], v[172:175], v[222:225], v[8:11]
	v_mfma_f32_16x16x32_bf16 v[52:55], v[178:181], v[194:197], v[52:55]
	v_mfma_f32_16x16x32_bf16 v[44:47], v[186:189], v[194:197], v[44:47]
	v_mfma_f32_16x16x32_bf16 v[36:39], v[178:181], v[202:205], v[36:39]
	v_mfma_f32_16x16x32_bf16 v[28:31], v[186:189], v[202:205], v[28:31]
	v_mfma_f32_16x16x32_bf16 v[20:23], v[178:181], v[210:213], v[20:23]
	v_mfma_f32_16x16x32_bf16 v[12:15], v[186:189], v[210:213], v[12:15]
	v_mfma_f32_16x16x32_bf16 v[4:7], v[178:181], v[218:221], v[4:7]
	v_mfma_f32_16x16x32_bf16 v[0:3], v[186:189], v[218:221], v[0:3]
	v_mfma_f32_16x16x32_bf16 v[52:55], v[182:185], v[198:201], v[52:55]
	v_mfma_f32_16x16x32_bf16 v[44:47], v[190:193], v[198:201], v[44:47]
	v_mfma_f32_16x16x32_bf16 v[36:39], v[182:185], v[206:209], v[36:39]
	v_mfma_f32_16x16x32_bf16 v[28:31], v[190:193], v[206:209], v[28:31]
	v_mfma_f32_16x16x32_bf16 v[20:23], v[182:185], v[214:217], v[20:23]
	v_mfma_f32_16x16x32_bf16 v[12:15], v[190:193], v[214:217], v[12:15]
	v_mfma_f32_16x16x32_bf16 v[4:7], v[182:185], v[222:225], v[4:7]
	v_mfma_f32_16x16x32_bf16 v[0:3], v[190:193], v[222:225], v[0:3]
	s_setprio 0
	s_barrier
	s_add_i32 s81, s81, 2
	s_add_u32 s74, s74, 0x100
	s_addc_u32 s75, s75, 0
	s_add_u32 s57, s57, 0x100
	s_addc_u32 s80, s80, 0
	s_cmp_gt_u32 s81, 13
	s_cbranch_scc0 .LBB0_553
	s_and_b64 vcc, exec, s[6:7]
	s_cbranch_vccz .LBB0_556
	s_barrier

; #define PG8_STAGE(bufoff, gbase, voff, p64) do { _Pragma("unroll") for (int _i = 0; _i < 2; ++_i) { \
;         const char* _gb = (const char*)(gbase) + (size_t)_i * (p64); const unsigned _la = ldsbase + (unsigned)(bufoff) + (unsigned)_i * 8192u; \
;         asm volatile("s_mov_b32 m0, %0\n\ts_nop 0\n\tglobal_load_lds_dwordx4 %1, %2" :: "s"(_la), "v"(voff), "s"(_gb) : "memory"); } } while (0)
; #define PG8_LDA(dst, b, h) do { _Pragma("unroll") for (int m = 0; m < 4; ++m) _Pragma("unroll") for (int k = 0; k < 2; ++k) dst[m][k] = *(const LAS bf16x8*)(lds + PG8_SA(b, h) + aoff + m * 2048 + k * 1024); } while (0)
; #define PG8_LDB(dst, b, h) do { _Pragma("unroll") for (int n = 0; n < 2; ++n) _Pragma("unroll") for (int k = 0; k < 2; ++k) dst[n][k] = *(const LAS bf16x8*)(lds + PG8_SB(b, h) + boff + n * 2048 + k * 1024); } while (0)
; #define PG8_MMA(ai, bj, At, Bt) do { __builtin_amdgcn_s_setprio(1); _Pragma("unroll") for (int m = 0; m < 4; ++m) _Pragma("unroll") for (int n = 0; n < 2; ++n) _Pragma("unroll") for (int k = 0; k < 2; ++k) \
;         acc[ai][bj][m][n] = __builtin_amdgcn_mfma_f32_16x16x32_bf16(Bt[n][k], At[m][k], acc[ai][bj][m][n], 0, 0, 0); __builtin_amdgcn_s_setprio(0); } while (0)
; #define PG8_WAIT_V(n) asm volatile("s_waitcnt vmcnt(" #n ")" ::: "memory")
; #define PG8_BAR __builtin_amdgcn_s_barrier()
; template <class Epi, class Sched>
; __device__ __forceinline__ void gemm_phase(LAS unsigned char* lds, const Sched& S, const Epi& E) {
;     ...
;             const bool last = (t == nt - 2);
;             const char* a1 = cA + (size_t)(t + 1) * kstep;
;             const char* a2 = last ? nA : cA + (size_t)(t + 2) * kstep; const char* b2 = last ? nB : cB + (size_t)(t + 2) * kstep;
;             const char* a3 = a2 + kstep; const char* b3 = b2 + kstep;
;             const unsigned vA2 = voffA, vB2 = voffB, hA2 = hA, hB2 = hB;
;             PG8_LDB(B0, 0, 0); PG8_LDB(B1, 0, 1); PG8_SCHED; PG8_LDA(At, 0, 0); PG8_STAGE(PG8_SA(1, 1), a1 + hA, voffA, hA / 2);
;             PG8_WAIT_V(8); PG8_WAIT_L(0); PG8_BAR; PG8_MMA(0, 0, At, B0); PG8_MMA(0, 1, At, B1); PG8_BAR; PG8_SCHED;
;             PG8_LDA(At, 0, 1); PG8_STAGE(PG8_SB(0, 0), b2, vB2, hB2 / 2); PG8_STAGE(PG8_SB(0, 1), b2 + hB2, vB2, hB2 / 2); PG8_STAGE(PG8_SA(0, 0), a2, vA2, hA2 / 2);
;             PG8_WAIT_V(8); PG8_WAIT_L(0); PG8_BAR; PG8_MMA(1, 0, At, B0); PG8_MMA(1, 1, At, B1); PG8_BAR; PG8_SCHED;
.LBB0_582:
	v_add_u32_e32 v130, 0x10000, v153
	ds_read_b128 v[138:141], v130
	ds_read_b128 v[142:145], v130 offset:1024
	ds_read_b128 v[146:149], v130 offset:2048
	ds_read_b128 v[172:175], v130 offset:3072
	v_add_u32_e32 v130, 0x14000, v153
	ds_read_b128 v[178:181], v130
	ds_read_b128 v[182:185], v130 offset:1024
	ds_read_b128 v[186:189], v130 offset:2048
	ds_read_b128 v[190:193], v130 offset:3072
	s_add_u32 s16, s62, 0xfffc0080
	s_addc_u32 s17, s63, -1
	s_cmp_eq_u32 s75, 12
	s_cselect_b32 s16, s56, s16
	s_cselect_b32 s17, s57, s17
	s_cselect_b32 s72, s58, s55
	s_cselect_b32 s73, s59, s74
	s_add_u32 s22, s16, 0x80
	s_addc_u32 s23, s17, 0
	ds_read_b128 v[194:197], v154
	ds_read_b128 v[198:201], v154 offset:1024
	ds_read_b128 v[202:205], v154 offset:2048
	ds_read_b128 v[206:209], v154 offset:3072
	ds_read_b128 v[210:213], v154 offset:4096
	ds_read_b128 v[214:217], v154 offset:5120
	ds_read_b128 v[218:221], v154 offset:6144
	ds_read_b128 v[222:225], v154 offset:7168
	s_mov_b32 m0, s78
	s_nop 0
	global_load_lds_dwordx4 v128, s[62:63]
	s_add_u32 s82, s62, 0x20000
	s_addc_u32 s83, s63, 0
	s_mov_b32 m0, s80
	s_nop 0
	global_load_lds_dwordx4 v128, s[82:83]
	s_waitcnt vmcnt(8)
	s_waitcnt lgkmcnt(0)
	s_barrier
	s_setprio 1
	v_mfma_f32_16x16x32_bf16 v[124:127], v[138:141], v[194:197], v[124:127]
	v_mfma_f32_16x16x32_bf16 v[120:123], v[146:149], v[194:197], v[120:123]
	v_mfma_f32_16x16x32_bf16 v[116:119], v[138:141], v[202:205], v[116:119]
	v_mfma_f32_16x16x32_bf16 v[108:111], v[146:149], v[202:205], v[108:111]
	v_mfma_f32_16x16x32_bf16 v[100:103], v[138:141], v[210:213], v[100:103]
	v_mfma_f32_16x16x32_bf16 v[92:95], v[146:149], v[210:213], v[92:95]
	v_mfma_f32_16x16x32_bf16 v[84:87], v[138:141], v[218:221], v[84:87]
	v_mfma_f32_16x16x32_bf16 v[76:79], v[146:149], v[218:221], v[76:79]
	v_mfma_f32_16x16x32_bf16 v[124:127], v[142:145], v[198:201], v[124:127]
	v_mfma_f32_16x16x32_bf16 v[120:123], v[172:175], v[198:201], v[120:123]
	v_mfma_f32_16x16x32_bf16 v[116:119], v[142:145], v[206:209], v[116:119]
	v_mfma_f32_16x16x32_bf16 v[108:111], v[172:175], v[206:209], v[108:111]
	v_mfma_f32_16x16x32_bf16 v[100:103], v[142:145], v[214:217], v[100:103]
	v_mfma_f32_16x16x32_bf16 v[92:95], v[172:175], v[214:217], v[92:95]
	v_mfma_f32_16x16x32_bf16 v[84:87], v[142:145], v[222:225], v[84:87]
	v_mfma_f32_16x16x32_bf16 v[76:79], v[172:175], v[222:225], v[76:79]
	v_mfma_f32_16x16x32_bf16 v[112:115], v[178:181], v[194:197], v[112:115]
	v_mfma_f32_16x16x32_bf16 v[104:107], v[186:189], v[194:197], v[104:107]
	v_mfma_f32_16x16x32_bf16 v[96:99], v[178:181], v[202:205], v[96:99]
	v_mfma_f32_16x16x32_bf16 v[88:91], v[186:189], v[202:205], v[88:91]
	v_mfma_f32_16x16x32_bf16 v[80:83], v[178:181], v[210:213], v[80:83]
	v_mfma_f32_16x16x32_bf16 v[72:75], v[186:189], v[210:213], v[72:75]
	v_mfma_f32_16x16x32_bf16 v[68:71], v[178:181], v[218:221], v[68:71]
	v_mfma_f32_16x16x32_bf16 v[64:67], v[186:189], v[218:221], v[64:67]
	v_mfma_f32_16x16x32_bf16 v[112:115], v[182:185], v[198:201], v[112:115]
	v_mfma_f32_16x16x32_bf16 v[104:107], v[190:193], v[198:201], v[104:107]
	v_mfma_f32_16x16x32_bf16 v[96:99], v[182:185], v[206:209], v[96:99]
	v_mfma_f32_16x16x32_bf16 v[88:91], v[190:193], v[206:209], v[88:91]
	v_mfma_f32_16x16x32_bf16 v[80:83], v[182:185], v[214:217], v[80:83]
	v_mfma_f32_16x16x32_bf16 v[72:75], v[190:193], v[214:217], v[72:75]
	v_mfma_f32_16x16x32_bf16 v[68:71], v[182:185], v[222:225], v[68:71]
	v_mfma_f32_16x16x32_bf16 v[64:67], v[190:193], v[222:225], v[64:67]
	s_setprio 0
	s_barrier
	s_add_u32 s82, s72, 0x20000
	ds_read_b128 v[194:197], v154 offset:16384
	ds_read_b128 v[198:201], v154 offset:17408
	ds_read_b128 v[202:205], v154 offset:18432
	ds_read_b128 v[206:209], v154 offset:19456
	ds_read_b128 v[210:213], v154 offset:20480
	ds_read_b128 v[214:217], v154 offset:21504
	ds_read_b128 v[218:221], v154 offset:22528
	ds_read_b128 v[222:225], v154 offset:23552
	s_mov_b32 m0, s20
	s_nop 0
	global_load_lds_dwordx4 v150, s[72:73]
	s_addc_u32 s83, s73, 0
	s_mov_b32 m0, s24
	s_nop 0
	global_load_lds_dwordx4 v150, s[82:83]
	s_add_u32 s82, s72, 0x40000
	s_addc_u32 s83, s73, 0
	s_mov_b32 m0, s33
	s_nop 0
	global_load_lds_dwordx4 v150, s[82:83]
	s_add_u32 s82, s72, 0x60000
	s_addc_u32 s83, s73, 0
	s_mov_b32 m0, s34
	s_nop 0
	global_load_lds_dwordx4 v150, s[82:83]
	s_mov_b32 m0, s15
	s_nop 0
	global_load_lds_dwordx4 v128, s[16:17]
	s_add_u32 s82, s16, 0x20000
	s_addc_u32 s83, s17, 0
	s_mov_b32 m0, s35
	s_nop 0
	global_load_lds_dwordx4 v128, s[82:83]
	s_waitcnt vmcnt(8)
	s_waitcnt lgkmcnt(0)
	s_barrier
; #define PG8_STAGE(bufoff, gbase, voff, p64) do { _Pragma("unroll") for (int _i = 0; _i < 2; ++_i) { \
;         const char* _gb = (const char*)(gbase) + (size_t)_i * (p64); const unsigned _la = ldsbase + (unsigned)(bufoff) + (unsigned)_i * 8192u; \
;         asm volatile("s_mov_b32 m0, %0\n\ts_nop 0\n\tglobal_load_lds_dwordx4 %1, %2" :: "s"(_la), "v"(voff), "s"(_gb) : "memory"); } } while (0)
; #define PG8_LDA(dst, b, h) do { _Pragma("unroll") for (int m = 0; m < 4; ++m) _Pragma("unroll") for (int k = 0; k < 2; ++k) dst[m][k] = *(const LAS bf16x8*)(lds + PG8_SA(b, h) + aoff + m * 2048 + k * 1024); } while (0)
; #define PG8_LDB(dst, b, h) do { _Pragma("unroll") for (int n = 0; n < 2; ++n) _Pragma("unroll") for (int k = 0; k < 2; ++k) dst[n][k] = *(const LAS bf16x8*)(lds + PG8_SB(b, h) + boff + n * 2048 + k * 1024); } while (0)
; #define PG8_MMA(ai, bj, At, Bt) do { __builtin_amdgcn_s_setprio(1); _Pragma("unroll") for (int m = 0; m < 4; ++m) _Pragma("unroll") for (int n = 0; n < 2; ++n) _Pragma("unroll") for (int k = 0; k < 2; ++k) \
;         acc[ai][bj][m][n] = __builtin_amdgcn_mfma_f32_16x16x32_bf16(Bt[n][k], At[m][k], acc[ai][bj][m][n], 0, 0, 0); __builtin_amdgcn_s_setprio(0); } while (0)
; #define PG8_WAIT_V(n) asm volatile("s_waitcnt vmcnt(" #n ")" ::: "memory")
; #define PG8_WAIT_L(n) asm volatile("s_waitcnt lgkmcnt(" #n ")" ::: "memory")
; #define PG8_BAR __builtin_amdgcn_s_barrier()
; #define PG8_SCHED __builtin_amdgcn_sched_barrier(0)
; template <class Epi, class Sched>
; __device__ __forceinline__ void gemm_phase(LAS unsigned char* lds, const Sched& S, const Epi& E) {
;     ...
;             PG8_WAIT_V(8); PG8_WAIT_L(0); PG8_BAR; PG8_MMA(1, 0, At, B0); PG8_MMA(1, 1, At, B1); PG8_BAR; PG8_SCHED;
;             PG8_LDB(B0, 1, 0); PG8_LDB(B1, 1, 1); PG8_SCHED; PG8_LDA(At, 1, 0); PG8_STAGE(PG8_SA(0, 1), a2 + hA2, vA2, hA2 / 2);
;             PG8_WAIT_V(8); PG8_WAIT_L(0); PG8_BAR; PG8_MMA(0, 0, At, B0); PG8_MMA(0, 1, At, B1); PG8_BAR; PG8_SCHED;
	s_setprio 1
	v_mfma_f32_16x16x32_bf16 v[60:63], v[138:141], v[194:197], v[60:63]
	v_mfma_f32_16x16x32_bf16 v[56:59], v[146:149], v[194:197], v[56:59]
	v_mfma_f32_16x16x32_bf16 v[52:55], v[138:141], v[202:205], v[52:55]
	v_mfma_f32_16x16x32_bf16 v[44:47], v[146:149], v[202:205], v[44:47]
	v_mfma_f32_16x16x32_bf16 v[36:39], v[138:141], v[210:213], v[36:39]
	v_mfma_f32_16x16x32_bf16 v[28:31], v[146:149], v[210:213], v[28:31]
	v_mfma_f32_16x16x32_bf16 v[20:23], v[138:141], v[218:221], v[20:23]
	v_mfma_f32_16x16x32_bf16 v[12:15], v[146:149], v[218:221], v[12:15]
	v_mfma_f32_16x16x32_bf16 v[60:63], v[142:145], v[198:201], v[60:63]
	v_mfma_f32_16x16x32_bf16 v[56:59], v[172:175], v[198:201], v[56:59]
	v_mfma_f32_16x16x32_bf16 v[52:55], v[142:145], v[206:209], v[52:55]
	v_mfma_f32_16x16x32_bf16 v[44:47], v[172:175], v[206:209], v[44:47]
	v_mfma_f32_16x16x32_bf16 v[36:39], v[142:145], v[214:217], v[36:39]
	v_mfma_f32_16x16x32_bf16 v[28:31], v[172:175], v[214:217], v[28:31]
	v_mfma_f32_16x16x32_bf16 v[20:23], v[142:145], v[222:225], v[20:23]
	v_mfma_f32_16x16x32_bf16 v[12:15], v[172:175], v[222:225], v[12:15]
	v_mfma_f32_16x16x32_bf16 v[48:51], v[178:181], v[194:197], v[48:51]
	v_mfma_f32_16x16x32_bf16 v[40:43], v[186:189], v[194:197], v[40:43]
	v_mfma_f32_16x16x32_bf16 v[32:35], v[178:181], v[202:205], v[32:35]
	v_mfma_f32_16x16x32_bf16 v[24:27], v[186:189], v[202:205], v[24:27]
	v_mfma_f32_16x16x32_bf16 v[16:19], v[178:181], v[210:213], v[16:19]
	v_mfma_f32_16x16x32_bf16 v[8:11], v[186:189], v[210:213], v[8:11]
	v_mfma_f32_16x16x32_bf16 v[4:7], v[178:181], v[218:221], v[4:7]
	v_mfma_f32_16x16x32_bf16 v[0:3], v[186:189], v[218:221], v[0:3]
	v_mfma_f32_16x16x32_bf16 v[48:51], v[182:185], v[198:201], v[48:51]
	v_mfma_f32_16x16x32_bf16 v[40:43], v[190:193], v[198:201], v[40:43]
	v_mfma_f32_16x16x32_bf16 v[32:35], v[182:185], v[206:209], v[32:35]
	v_mfma_f32_16x16x32_bf16 v[24:27], v[190:193], v[206:209], v[24:27]
	v_mfma_f32_16x16x32_bf16 v[16:19], v[182:185], v[214:217], v[16:19]
	v_mfma_f32_16x16x32_bf16 v[8:11], v[190:193], v[214:217], v[8:11]
	v_mfma_f32_16x16x32_bf16 v[4:7], v[182:185], v[222:225], v[4:7]
	v_mfma_f32_16x16x32_bf16 v[0:3], v[190:193], v[222:225], v[0:3]
	s_setprio 0
	s_barrier
	v_add_u32_e32 v130, 0x18000, v153
	ds_read_b128 v[138:141], v130
	ds_read_b128 v[142:145], v130 offset:1024
	ds_read_b128 v[146:149], v130 offset:2048
	ds_read_b128 v[172:175], v130 offset:3072
	v_add_u32_e32 v130, 0x1c000, v153
	ds_read_b128 v[178:181], v130
	ds_read_b128 v[182:185], v130 offset:1024
	ds_read_b128 v[186:189], v130 offset:2048
	ds_read_b128 v[190:193], v130 offset:3072
	ds_read_b128 v[194:197], v154 offset:32768
	ds_read_b128 v[198:201], v154 offset:33792
	ds_read_b128 v[202:205], v154 offset:34816
	ds_read_b128 v[206:209], v154 offset:35840
	ds_read_b128 v[210:213], v154 offset:36864
	ds_read_b128 v[214:217], v154 offset:37888
	ds_read_b128 v[218:221], v154 offset:38912
	ds_read_b128 v[222:225], v154 offset:39936
	s_add_u32 s82, s16, 0x40000
	s_addc_u32 s83, s17, 0
	s_mov_b32 m0, s36
	s_nop 0
	global_load_lds_dwordx4 v128, s[82:83]
	s_add_u32 s82, s16, 0x60000
	s_addc_u32 s83, s17, 0
	s_mov_b32 m0, s37
	s_nop 0
	global_load_lds_dwordx4 v128, s[82:83]
	s_waitcnt vmcnt(8)
	s_waitcnt lgkmcnt(0)
	s_barrier
	s_setprio 1
	v_mfma_f32_16x16x32_bf16 v[124:127], v[138:141], v[194:197], v[124:127]
	v_mfma_f32_16x16x32_bf16 v[120:123], v[146:149], v[194:197], v[120:123]
	v_mfma_f32_16x16x32_bf16 v[116:119], v[138:141], v[202:205], v[116:119]
	v_mfma_f32_16x16x32_bf16 v[108:111], v[146:149], v[202:205], v[108:111]
	v_mfma_f32_16x16x32_bf16 v[100:103], v[138:141], v[210:213], v[100:103]
	v_mfma_f32_16x16x32_bf16 v[92:95], v[146:149], v[210:213], v[92:95]
	v_mfma_f32_16x16x32_bf16 v[84:87], v[138:141], v[218:221], v[84:87]
	v_mfma_f32_16x16x32_bf16 v[76:79], v[146:149], v[218:221], v[76:79]
	v_mfma_f32_16x16x32_bf16 v[124:127], v[142:145], v[198:201], v[124:127]
	v_mfma_f32_16x16x32_bf16 v[120:123], v[172:175], v[198:201], v[120:123]
	v_mfma_f32_16x16x32_bf16 v[116:119], v[142:145], v[206:209], v[116:119]
	v_mfma_f32_16x16x32_bf16 v[108:111], v[172:175], v[206:209], v[108:111]
	v_mfma_f32_16x16x32_bf16 v[100:103], v[142:145], v[214:217], v[100:103]
	v_mfma_f32_16x16x32_bf16 v[92:95], v[172:175], v[214:217], v[92:95]
	v_mfma_f32_16x16x32_bf16 v[84:87], v[142:145], v[222:225], v[84:87]
	v_mfma_f32_16x16x32_bf16 v[76:79], v[172:175], v[222:225], v[76:79]
	v_mfma_f32_16x16x32_bf16 v[112:115], v[178:181], v[194:197], v[112:115]
	v_mfma_f32_16x16x32_bf16 v[104:107], v[186:189], v[194:197], v[104:107]
	v_mfma_f32_16x16x32_bf16 v[96:99], v[178:181], v[202:205], v[96:99]
	v_mfma_f32_16x16x32_bf16 v[88:91], v[186:189], v[202:205], v[88:91]
	v_mfma_f32_16x16x32_bf16 v[80:83], v[178:181], v[210:213], v[80:83]
	v_mfma_f32_16x16x32_bf16 v[72:75], v[186:189], v[210:213], v[72:75]
	v_mfma_f32_16x16x32_bf16 v[68:71], v[178:181], v[218:221], v[68:71]
	v_mfma_f32_16x16x32_bf16 v[64:67], v[186:189], v[218:221], v[64:67]
	v_mfma_f32_16x16x32_bf16 v[112:115], v[182:185], v[198:201], v[112:115]
	v_mfma_f32_16x16x32_bf16 v[104:107], v[190:193], v[198:201], v[104:107]
	v_mfma_f32_16x16x32_bf16 v[96:99], v[182:185], v[206:209], v[96:99]
	v_mfma_f32_16x16x32_bf16 v[88:91], v[190:193], v[206:209], v[88:91]
	v_mfma_f32_16x16x32_bf16 v[80:83], v[182:185], v[214:217], v[80:83]
	v_mfma_f32_16x16x32_bf16 v[72:75], v[190:193], v[214:217], v[72:75]
	v_mfma_f32_16x16x32_bf16 v[68:71], v[182:185], v[222:225], v[68:71]
	v_mfma_f32_16x16x32_bf16 v[64:67], v[190:193], v[222:225], v[64:67]
	s_setprio 0
	s_barrier
; #define PG8_STAGE(bufoff, gbase, voff, p64) do { _Pragma("unroll") for (int _i = 0; _i < 2; ++_i) { \
;         const char* _gb = (const char*)(gbase) + (size_t)_i * (p64); const unsigned _la = ldsbase + (unsigned)(bufoff) + (unsigned)_i * 8192u; \
;         asm volatile("s_mov_b32 m0, %0\n\ts_nop 0\n\tglobal_load_lds_dwordx4 %1, %2" :: "s"(_la), "v"(voff), "s"(_gb) : "memory"); } } while (0)
; #define PG8_LDA(dst, b, h) do { _Pragma("unroll") for (int m = 0; m < 4; ++m) _Pragma("unroll") for (int k = 0; k < 2; ++k) dst[m][k] = *(const LAS bf16x8*)(lds + PG8_SA(b, h) + aoff + m * 2048 + k * 1024); } while (0)
; #define PG8_MMA(ai, bj, At, Bt) do { __builtin_amdgcn_s_setprio(1); _Pragma("unroll") for (int m = 0; m < 4; ++m) _Pragma("unroll") for (int n = 0; n < 2; ++n) _Pragma("unroll") for (int k = 0; k < 2; ++k) \
;         acc[ai][bj][m][n] = __builtin_amdgcn_mfma_f32_16x16x32_bf16(Bt[n][k], At[m][k], acc[ai][bj][m][n], 0, 0, 0); __builtin_amdgcn_s_setprio(0); } while (0)
; #define PG8_WAIT_V(n) asm volatile("s_waitcnt vmcnt(" #n ")" ::: "memory")
; #define PG8_WAIT_L(n) asm volatile("s_waitcnt lgkmcnt(" #n ")" ::: "memory")
; #define PG8_BAR __builtin_amdgcn_s_barrier()
; #define PG8_SCHED __builtin_amdgcn_sched_barrier(0)
; template <class Epi, class Sched>
; __device__ __forceinline__ void gemm_phase(LAS unsigned char* lds, const Sched& S, const Epi& E) {
;     ...
;             PG8_LDA(At, 1, 1); PG8_STAGE(PG8_SB(1, 0), b3, vB2, hB2 / 2); PG8_STAGE(PG8_SB(1, 1), b3 + hB2, vB2, hB2 / 2); PG8_STAGE(PG8_SA(1, 0), a3, vA2, hA2 / 2);
;             PG8_WAIT_V(8); PG8_WAIT_L(0); PG8_BAR; PG8_MMA(1, 0, At, B0); PG8_MMA(1, 1, At, B1); PG8_BAR; PG8_SCHED;
;         }
	s_add_u32 s82, s72, 0x80
	s_addc_u32 s83, s73, 0
	ds_read_b128 v[194:197], v154 offset:49152
	ds_read_b128 v[198:201], v154 offset:50176
	ds_read_b128 v[202:205], v154 offset:51200
	ds_read_b128 v[206:209], v154 offset:52224
	ds_read_b128 v[210:213], v154 offset:53248
	ds_read_b128 v[214:217], v154 offset:54272
	ds_read_b128 v[218:221], v154 offset:55296
	ds_read_b128 v[222:225], v154 offset:56320
	s_mov_b32 m0, s66
	s_nop 0
	global_load_lds_dwordx4 v150, s[82:83]
	s_add_u32 s82, s72, 0x20080
	s_addc_u32 s83, s73, 0
	s_mov_b32 m0, s67
	s_nop 0
	global_load_lds_dwordx4 v150, s[82:83]
	s_add_u32 s82, s72, 0x40080
	s_addc_u32 s83, s73, 0
	s_mov_b32 m0, s76
	s_nop 0
	global_load_lds_dwordx4 v150, s[82:83]
	s_add_u32 s72, s72, 0x60080
	s_addc_u32 s73, s73, 0
	s_mov_b32 m0, s77
	s_nop 0
	global_load_lds_dwordx4 v150, s[72:73]
	s_mov_b32 m0, s68
	s_nop 0
	global_load_lds_dwordx4 v128, s[22:23]
	s_add_u32 s16, s16, 0x20080
	s_addc_u32 s17, s17, 0
	s_mov_b32 m0, s69
	s_nop 0
	global_load_lds_dwordx4 v128, s[16:17]
	s_waitcnt vmcnt(8)
	s_waitcnt lgkmcnt(0)
	s_barrier
	s_setprio 1
	v_mfma_f32_16x16x32_bf16 v[60:63], v[138:141], v[194:197], v[60:63]
	v_mfma_f32_16x16x32_bf16 v[56:59], v[146:149], v[194:197], v[56:59]
	v_mfma_f32_16x16x32_bf16 v[52:55], v[138:141], v[202:205], v[52:55]
	v_mfma_f32_16x16x32_bf16 v[44:47], v[146:149], v[202:205], v[44:47]
	v_mfma_f32_16x16x32_bf16 v[36:39], v[138:141], v[210:213], v[36:39]
	v_mfma_f32_16x16x32_bf16 v[28:31], v[146:149], v[210:213], v[28:31]
	v_mfma_f32_16x16x32_bf16 v[20:23], v[138:141], v[218:221], v[20:23]
	v_mfma_f32_16x16x32_bf16 v[12:15], v[146:149], v[218:221], v[12:15]
	v_mfma_f32_16x16x32_bf16 v[60:63], v[142:145], v[198:201], v[60:63]
	v_mfma_f32_16x16x32_bf16 v[56:59], v[172:175], v[198:201], v[56:59]
	v_mfma_f32_16x16x32_bf16 v[52:55], v[142:145], v[206:209], v[52:55]
	v_mfma_f32_16x16x32_bf16 v[44:47], v[172:175], v[206:209], v[44:47]
	v_mfma_f32_16x16x32_bf16 v[36:39], v[142:145], v[214:217], v[36:39]
	v_mfma_f32_16x16x32_bf16 v[28:31], v[172:175], v[214:217], v[28:31]
	v_mfma_f32_16x16x32_bf16 v[20:23], v[142:145], v[222:225], v[20:23]
	v_mfma_f32_16x16x32_bf16 v[12:15], v[172:175], v[222:225], v[12:15]
	v_mfma_f32_16x16x32_bf16 v[48:51], v[178:181], v[194:197], v[48:51]
	v_mfma_f32_16x16x32_bf16 v[40:43], v[186:189], v[194:197], v[40:43]
	v_mfma_f32_16x16x32_bf16 v[32:35], v[178:181], v[202:205], v[32:35]
	v_mfma_f32_16x16x32_bf16 v[24:27], v[186:189], v[202:205], v[24:27]
	v_mfma_f32_16x16x32_bf16 v[16:19], v[178:181], v[210:213], v[16:19]
	v_mfma_f32_16x16x32_bf16 v[8:11], v[186:189], v[210:213], v[8:11]
	v_mfma_f32_16x16x32_bf16 v[4:7], v[178:181], v[218:221], v[4:7]
	v_mfma_f32_16x16x32_bf16 v[0:3], v[186:189], v[218:221], v[0:3]
	v_mfma_f32_16x16x32_bf16 v[48:51], v[182:185], v[198:201], v[48:51]
	v_mfma_f32_16x16x32_bf16 v[40:43], v[190:193], v[198:201], v[40:43]
	v_mfma_f32_16x16x32_bf16 v[32:35], v[182:185], v[206:209], v[32:35]
	v_mfma_f32_16x16x32_bf16 v[24:27], v[190:193], v[206:209], v[24:27]
	v_mfma_f32_16x16x32_bf16 v[16:19], v[182:185], v[214:217], v[16:19]
	v_mfma_f32_16x16x32_bf16 v[8:11], v[190:193], v[214:217], v[8:11]
	v_mfma_f32_16x16x32_bf16 v[4:7], v[182:185], v[222:225], v[4:7]
	v_mfma_f32_16x16x32_bf16 v[0:3], v[190:193], v[222:225], v[0:3]
	s_setprio 0
	s_barrier
	s_add_i32 s75, s75, 2
	s_add_u32 s62, s62, 0x100
	s_addc_u32 s63, s63, 0
	s_add_u32 s55, s55, 0x100
	s_addc_u32 s74, s74, 0
	s_cmp_gt_u32 s75, 13
	s_cbranch_scc0 .LBB0_582
	s_and_b64 vcc, exec, s[26:27]
	s_cbranch_vccz .LBB0_585
	s_barrier

; #define PG8_STAGE(bufoff, gbase, voff, p64) do { _Pragma("unroll") for (int _i = 0; _i < 2; ++_i) { \
;         const char* _gb = (const char*)(gbase) + (size_t)_i * (p64); const unsigned _la = ldsbase + (unsigned)(bufoff) + (unsigned)_i * 8192u; \
;         asm volatile("s_mov_b32 m0, %0\n\ts_nop 0\n\tglobal_load_lds_dwordx4 %1, %2" :: "s"(_la), "v"(voff), "s"(_gb) : "memory"); } } while (0)
; #define PG8_LDA(dst, b, h) do { _Pragma("unroll") for (int m = 0; m < 4; ++m) _Pragma("unroll") for (int k = 0; k < 2; ++k) dst[m][k] = *(const LAS bf16x8*)(lds + PG8_SA(b, h) + aoff + m * 2048 + k * 1024); } while (0)
; #define PG8_LDB(dst, b, h) do { _Pragma("unroll") for (int n = 0; n < 2; ++n) _Pragma("unroll") for (int k = 0; k < 2; ++k) dst[n][k] = *(const LAS bf16x8*)(lds + PG8_SB(b, h) + boff + n * 2048 + k * 1024); } while (0)
; #define PG8_MMA(ai, bj, At, Bt) do { __builtin_amdgcn_s_setprio(1); _Pragma("unroll") for (int m = 0; m < 4; ++m) _Pragma("unroll") for (int n = 0; n < 2; ++n) _Pragma("unroll") for (int k = 0; k < 2; ++k) \
;         acc[ai][bj][m][n] = __builtin_amdgcn_mfma_f32_16x16x32_bf16(Bt[n][k], At[m][k], acc[ai][bj][m][n], 0, 0, 0); __builtin_amdgcn_s_setprio(0); } while (0)
; #define PG8_WAIT_V(n) asm volatile("s_waitcnt vmcnt(" #n ")" ::: "memory")
; #define PG8_BAR __builtin_amdgcn_s_barrier()
; template <class Epi, class Sched>
; __device__ __forceinline__ void gemm_phase(LAS unsigned char* lds, const Sched& S, const Epi& E) {
;     ...
;             const bool last = (t == nt - 2);
;             const char* a1 = cA + (size_t)(t + 1) * kstep;
;             const char* a2 = last ? nA : cA + (size_t)(t + 2) * kstep; const char* b2 = last ? nB : cB + (size_t)(t + 2) * kstep;
;             const char* a3 = a2 + kstep; const char* b3 = b2 + kstep;
;             const unsigned vA2 = voffA, vB2 = voffB, hA2 = hA, hB2 = hB;
;             PG8_LDB(B0, 0, 0); PG8_LDB(B1, 0, 1); PG8_SCHED; PG8_LDA(At, 0, 0); PG8_STAGE(PG8_SA(1, 1), a1 + hA, voffA, hA / 2);
;             PG8_WAIT_V(8); PG8_WAIT_L(0); PG8_BAR; PG8_MMA(0, 0, At, B0); PG8_MMA(0, 1, At, B1); PG8_BAR; PG8_SCHED;
;             PG8_LDA(At, 0, 1); PG8_STAGE(PG8_SB(0, 0), b2, vB2, hB2 / 2); PG8_STAGE(PG8_SB(0, 1), b2 + hB2, vB2, hB2 / 2); PG8_STAGE(PG8_SA(0, 0), a2, vA2, hA2 / 2);
;             PG8_WAIT_V(8); PG8_WAIT_L(0); PG8_BAR; PG8_MMA(1, 0, At, B0); PG8_MMA(1, 1, At, B1); PG8_BAR; PG8_SCHED;
.LBB0_660:
	v_add_u32_e32 v130, 0x10000, v143
	ds_read_b128 v[146:149], v130
	ds_read_b128 v[150:153], v130 offset:1024
	ds_read_b128 v[172:175], v130 offset:2048
	ds_read_b128 v[178:181], v130 offset:3072
	v_add_u32_e32 v130, 0x14000, v143
	ds_read_b128 v[182:185], v130
	ds_read_b128 v[186:189], v130 offset:1024
	ds_read_b128 v[190:193], v130 offset:2048
	ds_read_b128 v[194:197], v130 offset:3072
	s_add_u32 s16, s58, 0x100
	s_addc_u32 s17, s59, 0
	s_cmp_eq_u32 s80, 4
	s_cselect_b32 s22, s40, s16
	s_cselect_b32 s23, s41, s17
	s_cselect_b32 s72, s54, s78
	s_cselect_b32 s73, s55, s79
	s_add_u32 s62, s22, 0x80
	s_addc_u32 s63, s23, 0
	ds_read_b128 v[198:201], v144
	ds_read_b128 v[202:205], v144 offset:1024
	ds_read_b128 v[206:209], v144 offset:2048
	ds_read_b128 v[210:213], v144 offset:3072
	ds_read_b128 v[214:217], v144 offset:4096
	ds_read_b128 v[218:221], v144 offset:5120
	ds_read_b128 v[222:225], v144 offset:6144
	ds_read_b128 v[226:229], v144 offset:7168
	s_add_u32 s82, s58, 0x20080
	s_addc_u32 s83, s59, 0
	s_mov_b32 m0, s66
	s_nop 0
	global_load_lds_dwordx4 v128, s[82:83]
	s_add_u32 s58, s58, 0x30080
	s_addc_u32 s59, s59, 0
	s_mov_b32 m0, s67
	s_nop 0
	global_load_lds_dwordx4 v128, s[58:59]
	s_waitcnt vmcnt(8)
	s_waitcnt lgkmcnt(0)
	s_barrier
	s_setprio 1
	v_mfma_f32_16x16x32_bf16 v[124:127], v[146:149], v[198:201], v[124:127]
	v_mfma_f32_16x16x32_bf16 v[120:123], v[172:175], v[198:201], v[120:123]
	v_mfma_f32_16x16x32_bf16 v[116:119], v[146:149], v[206:209], v[116:119]
	v_mfma_f32_16x16x32_bf16 v[108:111], v[172:175], v[206:209], v[108:111]
	v_mfma_f32_16x16x32_bf16 v[100:103], v[146:149], v[214:217], v[100:103]
	v_mfma_f32_16x16x32_bf16 v[92:95], v[172:175], v[214:217], v[92:95]
	v_mfma_f32_16x16x32_bf16 v[84:87], v[146:149], v[222:225], v[84:87]
	v_mfma_f32_16x16x32_bf16 v[76:79], v[172:175], v[222:225], v[76:79]
	v_mfma_f32_16x16x32_bf16 v[124:127], v[150:153], v[202:205], v[124:127]
	v_mfma_f32_16x16x32_bf16 v[120:123], v[178:181], v[202:205], v[120:123]
	v_mfma_f32_16x16x32_bf16 v[116:119], v[150:153], v[210:213], v[116:119]
	v_mfma_f32_16x16x32_bf16 v[108:111], v[178:181], v[210:213], v[108:111]
	v_mfma_f32_16x16x32_bf16 v[100:103], v[150:153], v[218:221], v[100:103]
	v_mfma_f32_16x16x32_bf16 v[92:95], v[178:181], v[218:221], v[92:95]
	v_mfma_f32_16x16x32_bf16 v[84:87], v[150:153], v[226:229], v[84:87]
	v_mfma_f32_16x16x32_bf16 v[76:79], v[178:181], v[226:229], v[76:79]
	v_mfma_f32_16x16x32_bf16 v[112:115], v[182:185], v[198:201], v[112:115]
	v_mfma_f32_16x16x32_bf16 v[104:107], v[190:193], v[198:201], v[104:107]
	v_mfma_f32_16x16x32_bf16 v[96:99], v[182:185], v[206:209], v[96:99]
	v_mfma_f32_16x16x32_bf16 v[88:91], v[190:193], v[206:209], v[88:91]
	v_mfma_f32_16x16x32_bf16 v[80:83], v[182:185], v[214:217], v[80:83]
	v_mfma_f32_16x16x32_bf16 v[72:75], v[190:193], v[214:217], v[72:75]
	v_mfma_f32_16x16x32_bf16 v[68:71], v[182:185], v[222:225], v[68:71]
	v_mfma_f32_16x16x32_bf16 v[64:67], v[190:193], v[222:225], v[64:67]
	v_mfma_f32_16x16x32_bf16 v[112:115], v[186:189], v[202:205], v[112:115]
	v_mfma_f32_16x16x32_bf16 v[104:107], v[194:197], v[202:205], v[104:107]
	v_mfma_f32_16x16x32_bf16 v[96:99], v[186:189], v[210:213], v[96:99]
	v_mfma_f32_16x16x32_bf16 v[88:91], v[194:197], v[210:213], v[88:91]
	v_mfma_f32_16x16x32_bf16 v[80:83], v[186:189], v[218:221], v[80:83]
	v_mfma_f32_16x16x32_bf16 v[72:75], v[194:197], v[218:221], v[72:75]
	v_mfma_f32_16x16x32_bf16 v[68:71], v[186:189], v[226:229], v[68:71]
	v_mfma_f32_16x16x32_bf16 v[64:67], v[194:197], v[226:229], v[64:67]
	s_setprio 0
	s_barrier
	s_add_u32 s58, s72, 0x10000
	ds_read_b128 v[198:201], v144 offset:16384
	ds_read_b128 v[202:205], v144 offset:17408
	ds_read_b128 v[206:209], v144 offset:18432
	ds_read_b128 v[210:213], v144 offset:19456
	ds_read_b128 v[214:217], v144 offset:20480
	ds_read_b128 v[218:221], v144 offset:21504
	ds_read_b128 v[222:225], v144 offset:22528
	ds_read_b128 v[226:229], v144 offset:23552
	s_mov_b32 m0, s33
	s_nop 0
	global_load_lds_dwordx4 v140, s[72:73]
	s_addc_u32 s59, s73, 0
	s_mov_b32 m0, s34
	s_nop 0
	global_load_lds_dwordx4 v140, s[58:59]
	s_add_u32 s58, s72, 0x20000
	s_addc_u32 s59, s73, 0
	s_mov_b32 m0, s35
	s_nop 0
	global_load_lds_dwordx4 v140, s[58:59]
	s_add_u32 s58, s72, 0x30000
	s_addc_u32 s59, s73, 0
	s_mov_b32 m0, s36
	s_nop 0
	global_load_lds_dwordx4 v140, s[58:59]
	s_mov_b32 m0, s24
	s_nop 0
	global_load_lds_dwordx4 v128, s[22:23]
	s_add_u32 s58, s22, 0x10000
	s_addc_u32 s59, s23, 0
	s_mov_b32 m0, s37
	s_nop 0
	global_load_lds_dwordx4 v128, s[58:59]
	s_waitcnt vmcnt(8)
	s_waitcnt lgkmcnt(0)
	s_barrier
; #define PG8_STAGE(bufoff, gbase, voff, p64) do { _Pragma("unroll") for (int _i = 0; _i < 2; ++_i) { \
;         const char* _gb = (const char*)(gbase) + (size_t)_i * (p64); const unsigned _la = ldsbase + (unsigned)(bufoff) + (unsigned)_i * 8192u; \
;         asm volatile("s_mov_b32 m0, %0\n\ts_nop 0\n\tglobal_load_lds_dwordx4 %1, %2" :: "s"(_la), "v"(voff), "s"(_gb) : "memory"); } } while (0)
; #define PG8_LDA(dst, b, h) do { _Pragma("unroll") for (int m = 0; m < 4; ++m) _Pragma("unroll") for (int k = 0; k < 2; ++k) dst[m][k] = *(const LAS bf16x8*)(lds + PG8_SA(b, h) + aoff + m * 2048 + k * 1024); } while (0)
; #define PG8_LDB(dst, b, h) do { _Pragma("unroll") for (int n = 0; n < 2; ++n) _Pragma("unroll") for (int k = 0; k < 2; ++k) dst[n][k] = *(const LAS bf16x8*)(lds + PG8_SB(b, h) + boff + n * 2048 + k * 1024); } while (0)
; #define PG8_MMA(ai, bj, At, Bt) do { __builtin_amdgcn_s_setprio(1); _Pragma("unroll") for (int m = 0; m < 4; ++m) _Pragma("unroll") for (int n = 0; n < 2; ++n) _Pragma("unroll") for (int k = 0; k < 2; ++k) \
;         acc[ai][bj][m][n] = __builtin_amdgcn_mfma_f32_16x16x32_bf16(Bt[n][k], At[m][k], acc[ai][bj][m][n], 0, 0, 0); __builtin_amdgcn_s_setprio(0); } while (0)
; #define PG8_WAIT_V(n) asm volatile("s_waitcnt vmcnt(" #n ")" ::: "memory")
; #define PG8_WAIT_L(n) asm volatile("s_waitcnt lgkmcnt(" #n ")" ::: "memory")
; #define PG8_BAR __builtin_amdgcn_s_barrier()
; #define PG8_SCHED __builtin_amdgcn_sched_barrier(0)
; template <class Epi, class Sched>
; __device__ __forceinline__ void gemm_phase(LAS unsigned char* lds, const Sched& S, const Epi& E) {
;     ...
;             PG8_WAIT_V(8); PG8_WAIT_L(0); PG8_BAR; PG8_MMA(1, 0, At, B0); PG8_MMA(1, 1, At, B1); PG8_BAR; PG8_SCHED;
;             PG8_LDB(B0, 1, 0); PG8_LDB(B1, 1, 1); PG8_SCHED; PG8_LDA(At, 1, 0); PG8_STAGE(PG8_SA(0, 1), a2 + hA2, vA2, hA2 / 2);
;             PG8_WAIT_V(8); PG8_WAIT_L(0); PG8_BAR; PG8_MMA(0, 0, At, B0); PG8_MMA(0, 1, At, B1); PG8_BAR; PG8_SCHED;
	s_setprio 1
	v_mfma_f32_16x16x32_bf16 v[60:63], v[146:149], v[198:201], v[60:63]
	v_mfma_f32_16x16x32_bf16 v[56:59], v[172:175], v[198:201], v[56:59]
	v_mfma_f32_16x16x32_bf16 v[52:55], v[146:149], v[206:209], v[52:55]
	v_mfma_f32_16x16x32_bf16 v[44:47], v[172:175], v[206:209], v[44:47]
	v_mfma_f32_16x16x32_bf16 v[36:39], v[146:149], v[214:217], v[36:39]
	v_mfma_f32_16x16x32_bf16 v[28:31], v[172:175], v[214:217], v[28:31]
	v_mfma_f32_16x16x32_bf16 v[20:23], v[146:149], v[222:225], v[20:23]
	v_mfma_f32_16x16x32_bf16 v[12:15], v[172:175], v[222:225], v[12:15]
	v_mfma_f32_16x16x32_bf16 v[60:63], v[150:153], v[202:205], v[60:63]
	v_mfma_f32_16x16x32_bf16 v[56:59], v[178:181], v[202:205], v[56:59]
	v_mfma_f32_16x16x32_bf16 v[52:55], v[150:153], v[210:213], v[52:55]
	v_mfma_f32_16x16x32_bf16 v[44:47], v[178:181], v[210:213], v[44:47]
	v_mfma_f32_16x16x32_bf16 v[36:39], v[150:153], v[218:221], v[36:39]
	v_mfma_f32_16x16x32_bf16 v[28:31], v[178:181], v[218:221], v[28:31]
	v_mfma_f32_16x16x32_bf16 v[20:23], v[150:153], v[226:229], v[20:23]
	v_mfma_f32_16x16x32_bf16 v[12:15], v[178:181], v[226:229], v[12:15]
	v_mfma_f32_16x16x32_bf16 v[48:51], v[182:185], v[198:201], v[48:51]
	v_mfma_f32_16x16x32_bf16 v[40:43], v[190:193], v[198:201], v[40:43]
	v_mfma_f32_16x16x32_bf16 v[32:35], v[182:185], v[206:209], v[32:35]
	v_mfma_f32_16x16x32_bf16 v[24:27], v[190:193], v[206:209], v[24:27]
	v_mfma_f32_16x16x32_bf16 v[16:19], v[182:185], v[214:217], v[16:19]
	v_mfma_f32_16x16x32_bf16 v[8:11], v[190:193], v[214:217], v[8:11]
	v_mfma_f32_16x16x32_bf16 v[4:7], v[182:185], v[222:225], v[4:7]
	v_mfma_f32_16x16x32_bf16 v[0:3], v[190:193], v[222:225], v[0:3]
	v_mfma_f32_16x16x32_bf16 v[48:51], v[186:189], v[202:205], v[48:51]
	v_mfma_f32_16x16x32_bf16 v[40:43], v[194:197], v[202:205], v[40:43]
	v_mfma_f32_16x16x32_bf16 v[32:35], v[186:189], v[210:213], v[32:35]
	v_mfma_f32_16x16x32_bf16 v[24:27], v[194:197], v[210:213], v[24:27]
	v_mfma_f32_16x16x32_bf16 v[16:19], v[186:189], v[218:221], v[16:19]
	v_mfma_f32_16x16x32_bf16 v[8:11], v[194:197], v[218:221], v[8:11]
	v_mfma_f32_16x16x32_bf16 v[4:7], v[186:189], v[226:229], v[4:7]
	v_mfma_f32_16x16x32_bf16 v[0:3], v[194:197], v[226:229], v[0:3]
	s_setprio 0
	s_barrier
	v_add_u32_e32 v130, 0x18000, v143
	ds_read_b128 v[146:149], v130
	ds_read_b128 v[150:153], v130 offset:1024
	ds_read_b128 v[172:175], v130 offset:2048
	ds_read_b128 v[178:181], v130 offset:3072
	v_add_u32_e32 v130, 0x1c000, v143
	ds_read_b128 v[182:185], v130
	ds_read_b128 v[186:189], v130 offset:1024
	ds_read_b128 v[190:193], v130 offset:2048
	ds_read_b128 v[194:197], v130 offset:3072
	ds_read_b128 v[198:201], v144 offset:32768
	ds_read_b128 v[202:205], v144 offset:33792
	ds_read_b128 v[206:209], v144 offset:34816
	ds_read_b128 v[210:213], v144 offset:35840
	ds_read_b128 v[214:217], v144 offset:36864
	ds_read_b128 v[218:221], v144 offset:37888
	ds_read_b128 v[222:225], v144 offset:38912
	ds_read_b128 v[226:229], v144 offset:39936
	s_add_u32 s58, s22, 0x20000
	s_addc_u32 s59, s23, 0
	s_mov_b32 m0, s42
	s_nop 0
	global_load_lds_dwordx4 v128, s[58:59]
	s_add_u32 s58, s22, 0x30000
	s_addc_u32 s59, s23, 0
	s_mov_b32 m0, s44
	s_nop 0
	global_load_lds_dwordx4 v128, s[58:59]
	s_waitcnt vmcnt(8)
	s_waitcnt lgkmcnt(0)
	s_barrier
	s_setprio 1
	v_mfma_f32_16x16x32_bf16 v[124:127], v[146:149], v[198:201], v[124:127]
	v_mfma_f32_16x16x32_bf16 v[120:123], v[172:175], v[198:201], v[120:123]
	v_mfma_f32_16x16x32_bf16 v[116:119], v[146:149], v[206:209], v[116:119]
	v_mfma_f32_16x16x32_bf16 v[108:111], v[172:175], v[206:209], v[108:111]
	v_mfma_f32_16x16x32_bf16 v[100:103], v[146:149], v[214:217], v[100:103]
	v_mfma_f32_16x16x32_bf16 v[92:95], v[172:175], v[214:217], v[92:95]
	v_mfma_f32_16x16x32_bf16 v[84:87], v[146:149], v[222:225], v[84:87]
	v_mfma_f32_16x16x32_bf16 v[76:79], v[172:175], v[222:225], v[76:79]
	v_mfma_f32_16x16x32_bf16 v[124:127], v[150:153], v[202:205], v[124:127]
	v_mfma_f32_16x16x32_bf16 v[120:123], v[178:181], v[202:205], v[120:123]
	v_mfma_f32_16x16x32_bf16 v[116:119], v[150:153], v[210:213], v[116:119]
	v_mfma_f32_16x16x32_bf16 v[108:111], v[178:181], v[210:213], v[108:111]
	v_mfma_f32_16x16x32_bf16 v[100:103], v[150:153], v[218:221], v[100:103]
	v_mfma_f32_16x16x32_bf16 v[92:95], v[178:181], v[218:221], v[92:95]
	v_mfma_f32_16x16x32_bf16 v[84:87], v[150:153], v[226:229], v[84:87]
	v_mfma_f32_16x16x32_bf16 v[76:79], v[178:181], v[226:229], v[76:79]
	v_mfma_f32_16x16x32_bf16 v[112:115], v[182:185], v[198:201], v[112:115]
	v_mfma_f32_16x16x32_bf16 v[104:107], v[190:193], v[198:201], v[104:107]
	v_mfma_f32_16x16x32_bf16 v[96:99], v[182:185], v[206:209], v[96:99]
	v_mfma_f32_16x16x32_bf16 v[88:91], v[190:193], v[206:209], v[88:91]
	v_mfma_f32_16x16x32_bf16 v[80:83], v[182:185], v[214:217], v[80:83]
	v_mfma_f32_16x16x32_bf16 v[72:75], v[190:193], v[214:217], v[72:75]
	v_mfma_f32_16x16x32_bf16 v[68:71], v[182:185], v[222:225], v[68:71]
	v_mfma_f32_16x16x32_bf16 v[64:67], v[190:193], v[222:225], v[64:67]
	v_mfma_f32_16x16x32_bf16 v[112:115], v[186:189], v[202:205], v[112:115]
	v_mfma_f32_16x16x32_bf16 v[104:107], v[194:197], v[202:205], v[104:107]
	v_mfma_f32_16x16x32_bf16 v[96:99], v[186:189], v[210:213], v[96:99]
	v_mfma_f32_16x16x32_bf16 v[88:91], v[194:197], v[210:213], v[88:91]
	v_mfma_f32_16x16x32_bf16 v[80:83], v[186:189], v[218:221], v[80:83]
	v_mfma_f32_16x16x32_bf16 v[72:75], v[194:197], v[218:221], v[72:75]
	v_mfma_f32_16x16x32_bf16 v[68:71], v[186:189], v[226:229], v[68:71]
	v_mfma_f32_16x16x32_bf16 v[64:67], v[194:197], v[226:229], v[64:67]
	s_setprio 0
	s_barrier
; #define PG8_STAGE(bufoff, gbase, voff, p64) do { _Pragma("unroll") for (int _i = 0; _i < 2; ++_i) { \
;         const char* _gb = (const char*)(gbase) + (size_t)_i * (p64); const unsigned _la = ldsbase + (unsigned)(bufoff) + (unsigned)_i * 8192u; \
;         asm volatile("s_mov_b32 m0, %0\n\ts_nop 0\n\tglobal_load_lds_dwordx4 %1, %2" :: "s"(_la), "v"(voff), "s"(_gb) : "memory"); } } while (0)
; #define PG8_LDA(dst, b, h) do { _Pragma("unroll") for (int m = 0; m < 4; ++m) _Pragma("unroll") for (int k = 0; k < 2; ++k) dst[m][k] = *(const LAS bf16x8*)(lds + PG8_SA(b, h) + aoff + m * 2048 + k * 1024); } while (0)
; #define PG8_MMA(ai, bj, At, Bt) do { __builtin_amdgcn_s_setprio(1); _Pragma("unroll") for (int m = 0; m < 4; ++m) _Pragma("unroll") for (int n = 0; n < 2; ++n) _Pragma("unroll") for (int k = 0; k < 2; ++k) \
;         acc[ai][bj][m][n] = __builtin_amdgcn_mfma_f32_16x16x32_bf16(Bt[n][k], At[m][k], acc[ai][bj][m][n], 0, 0, 0); __builtin_amdgcn_s_setprio(0); } while (0)
; #define PG8_WAIT_V(n) asm volatile("s_waitcnt vmcnt(" #n ")" ::: "memory")
; #define PG8_WAIT_L(n) asm volatile("s_waitcnt lgkmcnt(" #n ")" ::: "memory")
; #define PG8_BAR __builtin_amdgcn_s_barrier()
; #define PG8_SCHED __builtin_amdgcn_sched_barrier(0)
; template <class Epi, class Sched>
; __device__ __forceinline__ void gemm_phase(LAS unsigned char* lds, const Sched& S, const Epi& E) {
;     ...
;             PG8_LDA(At, 1, 1); PG8_STAGE(PG8_SB(1, 0), b3, vB2, hB2 / 2); PG8_STAGE(PG8_SB(1, 1), b3 + hB2, vB2, hB2 / 2); PG8_STAGE(PG8_SA(1, 0), a3, vA2, hA2 / 2);
;             PG8_WAIT_V(8); PG8_WAIT_L(0); PG8_BAR; PG8_MMA(1, 0, At, B0); PG8_MMA(1, 1, At, B1); PG8_BAR; PG8_SCHED;
;         }
	s_add_u32 s58, s72, 0x80
	s_addc_u32 s59, s73, 0
	ds_read_b128 v[198:201], v144 offset:49152
	ds_read_b128 v[202:205], v144 offset:50176
	ds_read_b128 v[206:209], v144 offset:51200
	ds_read_b128 v[210:213], v144 offset:52224
	ds_read_b128 v[214:217], v144 offset:53248
	ds_read_b128 v[218:221], v144 offset:54272
	ds_read_b128 v[222:225], v144 offset:55296
	ds_read_b128 v[226:229], v144 offset:56320
	s_mov_b32 m0, s48
	s_nop 0
	global_load_lds_dwordx4 v140, s[58:59]
	s_add_u32 s58, s72, 0x10080
	s_addc_u32 s59, s73, 0
	s_mov_b32 m0, s50
	s_nop 0
	global_load_lds_dwordx4 v140, s[58:59]
	s_add_u32 s58, s72, 0x20080
	s_addc_u32 s59, s73, 0
	s_mov_b32 m0, s64
	s_nop 0
	global_load_lds_dwordx4 v140, s[58:59]
	s_add_u32 s58, s72, 0x30080
	s_addc_u32 s59, s73, 0
	s_mov_b32 m0, s65
	s_nop 0
	global_load_lds_dwordx4 v140, s[58:59]
	s_mov_b32 m0, s51
	s_nop 0
	global_load_lds_dwordx4 v128, s[62:63]
	s_add_u32 s22, s22, 0x10080
	s_addc_u32 s23, s23, 0
	s_mov_b32 m0, s61
	s_nop 0
	global_load_lds_dwordx4 v128, s[22:23]
	s_waitcnt vmcnt(8)
	s_waitcnt lgkmcnt(0)
	s_barrier
	s_setprio 1
	v_mfma_f32_16x16x32_bf16 v[60:63], v[146:149], v[198:201], v[60:63]
	v_mfma_f32_16x16x32_bf16 v[56:59], v[172:175], v[198:201], v[56:59]
	v_mfma_f32_16x16x32_bf16 v[52:55], v[146:149], v[206:209], v[52:55]
	v_mfma_f32_16x16x32_bf16 v[44:47], v[172:175], v[206:209], v[44:47]
	v_mfma_f32_16x16x32_bf16 v[36:39], v[146:149], v[214:217], v[36:39]
	v_mfma_f32_16x16x32_bf16 v[28:31], v[172:175], v[214:217], v[28:31]
	v_mfma_f32_16x16x32_bf16 v[20:23], v[146:149], v[222:225], v[20:23]
	v_mfma_f32_16x16x32_bf16 v[12:15], v[172:175], v[222:225], v[12:15]
	v_mfma_f32_16x16x32_bf16 v[60:63], v[150:153], v[202:205], v[60:63]
	v_mfma_f32_16x16x32_bf16 v[56:59], v[178:181], v[202:205], v[56:59]
	v_mfma_f32_16x16x32_bf16 v[52:55], v[150:153], v[210:213], v[52:55]
	v_mfma_f32_16x16x32_bf16 v[44:47], v[178:181], v[210:213], v[44:47]
	v_mfma_f32_16x16x32_bf16 v[36:39], v[150:153], v[218:221], v[36:39]
	v_mfma_f32_16x16x32_bf16 v[28:31], v[178:181], v[218:221], v[28:31]
	v_mfma_f32_16x16x32_bf16 v[20:23], v[150:153], v[226:229], v[20:23]
	v_mfma_f32_16x16x32_bf16 v[12:15], v[178:181], v[226:229], v[12:15]
	v_mfma_f32_16x16x32_bf16 v[48:51], v[182:185], v[198:201], v[48:51]
	v_mfma_f32_16x16x32_bf16 v[40:43], v[190:193], v[198:201], v[40:43]
	v_mfma_f32_16x16x32_bf16 v[32:35], v[182:185], v[206:209], v[32:35]
	v_mfma_f32_16x16x32_bf16 v[24:27], v[190:193], v[206:209], v[24:27]
	v_mfma_f32_16x16x32_bf16 v[16:19], v[182:185], v[214:217], v[16:19]
	v_mfma_f32_16x16x32_bf16 v[8:11], v[190:193], v[214:217], v[8:11]
	v_mfma_f32_16x16x32_bf16 v[4:7], v[182:185], v[222:225], v[4:7]
	v_mfma_f32_16x16x32_bf16 v[0:3], v[190:193], v[222:225], v[0:3]
	v_mfma_f32_16x16x32_bf16 v[48:51], v[186:189], v[202:205], v[48:51]
	v_mfma_f32_16x16x32_bf16 v[40:43], v[194:197], v[202:205], v[40:43]
	v_mfma_f32_16x16x32_bf16 v[32:35], v[186:189], v[210:213], v[32:35]
	v_mfma_f32_16x16x32_bf16 v[24:27], v[194:197], v[210:213], v[24:27]
	v_mfma_f32_16x16x32_bf16 v[16:19], v[186:189], v[218:221], v[16:19]
	v_mfma_f32_16x16x32_bf16 v[8:11], v[194:197], v[218:221], v[8:11]
	v_mfma_f32_16x16x32_bf16 v[4:7], v[186:189], v[226:229], v[4:7]
	v_mfma_f32_16x16x32_bf16 v[0:3], v[194:197], v[226:229], v[0:3]
	s_setprio 0
	s_barrier
	s_add_i32 s80, s80, 2
	s_add_u32 s78, s78, 0x100
	s_addc_u32 s79, s79, 0
	s_cmp_gt_u32 s80, 5
	s_mov_b64 s[58:59], s[16:17]
	s_cbranch_scc0 .LBB0_660
	s_and_b64 vcc, exec, s[38:39]
	s_cbranch_vccz .LBB0_663
	s_barrier

; #define PG8_STAGE(bufoff, gbase, voff, p64) do { _Pragma("unroll") for (int _i = 0; _i < 2; ++_i) { \
;         const char* _gb = (const char*)(gbase) + (size_t)_i * (p64); const unsigned _la = ldsbase + (unsigned)(bufoff) + (unsigned)_i * 8192u; \
;         asm volatile("s_mov_b32 m0, %0\n\ts_nop 0\n\tglobal_load_lds_dwordx4 %1, %2" :: "s"(_la), "v"(voff), "s"(_gb) : "memory"); } } while (0)
; #define PG8_LDA(dst, b, h) do { _Pragma("unroll") for (int m = 0; m < 4; ++m) _Pragma("unroll") for (int k = 0; k < 2; ++k) dst[m][k] = *(const LAS bf16x8*)(lds + PG8_SA(b, h) + aoff + m * 2048 + k * 1024); } while (0)
; #define PG8_LDB(dst, b, h) do { _Pragma("unroll") for (int n = 0; n < 2; ++n) _Pragma("unroll") for (int k = 0; k < 2; ++k) dst[n][k] = *(const LAS bf16x8*)(lds + PG8_SB(b, h) + boff + n * 2048 + k * 1024); } while (0)
; #define PG8_MMA(ai, bj, At, Bt) do { __builtin_amdgcn_s_setprio(1); _Pragma("unroll") for (int m = 0; m < 4; ++m) _Pragma("unroll") for (int n = 0; n < 2; ++n) _Pragma("unroll") for (int k = 0; k < 2; ++k) \
;         acc[ai][bj][m][n] = __builtin_amdgcn_mfma_f32_16x16x32_bf16(Bt[n][k], At[m][k], acc[ai][bj][m][n], 0, 0, 0); __builtin_amdgcn_s_setprio(0); } while (0)
; #define PG8_WAIT_V(n) asm volatile("s_waitcnt vmcnt(" #n ")" ::: "memory")
; #define PG8_BAR __builtin_amdgcn_s_barrier()
; template <class Epi, class Sched>
; __device__ __forceinline__ void gemm_phase(LAS unsigned char* lds, const Sched& S, const Epi& E) {
;     ...
;             const bool last = (t == nt - 2);
;             const char* a1 = cA + (size_t)(t + 1) * kstep;
;             const char* a2 = last ? nA : cA + (size_t)(t + 2) * kstep; const char* b2 = last ? nB : cB + (size_t)(t + 2) * kstep;
;             const char* a3 = a2 + kstep; const char* b3 = b2 + kstep;
;             const unsigned vA2 = voffA, vB2 = voffB, hA2 = hA, hB2 = hB;
;             PG8_LDB(B0, 0, 0); PG8_LDB(B1, 0, 1); PG8_SCHED; PG8_LDA(At, 0, 0); PG8_STAGE(PG8_SA(1, 1), a1 + hA, voffA, hA / 2);
;             PG8_WAIT_V(8); PG8_WAIT_L(0); PG8_BAR; PG8_MMA(0, 0, At, B0); PG8_MMA(0, 1, At, B1); PG8_BAR; PG8_SCHED;
;             PG8_LDA(At, 0, 1); PG8_STAGE(PG8_SB(0, 0), b2, vB2, hB2 / 2); PG8_STAGE(PG8_SB(0, 1), b2 + hB2, vB2, hB2 / 2); PG8_STAGE(PG8_SA(0, 0), a2, vA2, hA2 / 2);
;             PG8_WAIT_V(8); PG8_WAIT_L(0); PG8_BAR; PG8_MMA(1, 0, At, B0); PG8_MMA(1, 1, At, B1); PG8_BAR; PG8_SCHED;
.LBB0_757:
	v_add_u32_e32 v128, 0x10000, v146
	ds_read_b128 v[130:133], v128
	ds_read_b128 v[134:137], v128 offset:1024
	ds_read_b128 v[138:141], v128 offset:2048
	ds_read_b128 v[148:151], v128 offset:3072
	v_add_u32_e32 v128, 0x14000, v146
	ds_read_b128 v[152:155], v128
	ds_read_b128 v[158:161], v128 offset:1024
	ds_read_b128 v[162:165], v128 offset:2048
	ds_read_b128 v[172:175], v128 offset:3072
	s_add_u32 s16, s56, 0xfffc0080
	s_addc_u32 s17, s57, -1
	s_cmp_eq_u32 s73, 12
	s_cselect_b32 s16, s40, s16
	s_cselect_b32 s17, s41, s17
	s_cselect_b32 s58, s54, s69
	s_cselect_b32 s59, s55, s72
	s_add_u32 s22, s16, 0x80
	s_addc_u32 s23, s17, 0
	ds_read_b128 v[178:181], v147
	ds_read_b128 v[182:185], v147 offset:1024
	ds_read_b128 v[186:189], v147 offset:2048
	ds_read_b128 v[190:193], v147 offset:3072
	ds_read_b128 v[194:197], v147 offset:4096
	ds_read_b128 v[198:201], v147 offset:5120
	ds_read_b128 v[202:205], v147 offset:6144
	ds_read_b128 v[206:209], v147 offset:7168
	s_mov_b32 m0, s62
	s_nop 0
	global_load_lds_dwordx4 v142, s[56:57]
	s_add_u32 s74, s56, 0x20000
	s_addc_u32 s75, s57, 0
	s_mov_b32 m0, s63
	s_nop 0
	global_load_lds_dwordx4 v142, s[74:75]
	s_waitcnt vmcnt(8)
	s_waitcnt lgkmcnt(0)
	s_barrier
	s_setprio 1
	v_mfma_f32_16x16x32_bf16 v[124:127], v[130:133], v[178:181], v[124:127]
	v_mfma_f32_16x16x32_bf16 v[116:119], v[138:141], v[178:181], v[116:119]
	v_mfma_f32_16x16x32_bf16 v[108:111], v[130:133], v[186:189], v[108:111]
	v_mfma_f32_16x16x32_bf16 v[100:103], v[138:141], v[186:189], v[100:103]
	v_mfma_f32_16x16x32_bf16 v[92:95], v[130:133], v[194:197], v[92:95]
	v_mfma_f32_16x16x32_bf16 v[84:87], v[138:141], v[194:197], v[84:87]
	v_mfma_f32_16x16x32_bf16 v[76:79], v[130:133], v[202:205], v[76:79]
	v_mfma_f32_16x16x32_bf16 v[68:71], v[138:141], v[202:205], v[68:71]
	v_mfma_f32_16x16x32_bf16 v[124:127], v[134:137], v[182:185], v[124:127]
	v_mfma_f32_16x16x32_bf16 v[116:119], v[148:151], v[182:185], v[116:119]
	v_mfma_f32_16x16x32_bf16 v[108:111], v[134:137], v[190:193], v[108:111]
	v_mfma_f32_16x16x32_bf16 v[100:103], v[148:151], v[190:193], v[100:103]
	v_mfma_f32_16x16x32_bf16 v[92:95], v[134:137], v[198:201], v[92:95]
	v_mfma_f32_16x16x32_bf16 v[84:87], v[148:151], v[198:201], v[84:87]
	v_mfma_f32_16x16x32_bf16 v[76:79], v[134:137], v[206:209], v[76:79]
	v_mfma_f32_16x16x32_bf16 v[68:71], v[148:151], v[206:209], v[68:71]
	v_mfma_f32_16x16x32_bf16 v[120:123], v[152:155], v[178:181], v[120:123]
	v_mfma_f32_16x16x32_bf16 v[112:115], v[162:165], v[178:181], v[112:115]
	v_mfma_f32_16x16x32_bf16 v[104:107], v[152:155], v[186:189], v[104:107]
	v_mfma_f32_16x16x32_bf16 v[96:99], v[162:165], v[186:189], v[96:99]
	v_mfma_f32_16x16x32_bf16 v[88:91], v[152:155], v[194:197], v[88:91]
	v_mfma_f32_16x16x32_bf16 v[80:83], v[162:165], v[194:197], v[80:83]
	v_mfma_f32_16x16x32_bf16 v[72:75], v[152:155], v[202:205], v[72:75]
	v_mfma_f32_16x16x32_bf16 v[64:67], v[162:165], v[202:205], v[64:67]
	v_mfma_f32_16x16x32_bf16 v[120:123], v[158:161], v[182:185], v[120:123]
	v_mfma_f32_16x16x32_bf16 v[112:115], v[172:175], v[182:185], v[112:115]
	v_mfma_f32_16x16x32_bf16 v[104:107], v[158:161], v[190:193], v[104:107]
	v_mfma_f32_16x16x32_bf16 v[96:99], v[172:175], v[190:193], v[96:99]
	v_mfma_f32_16x16x32_bf16 v[88:91], v[158:161], v[198:201], v[88:91]
	v_mfma_f32_16x16x32_bf16 v[80:83], v[172:175], v[198:201], v[80:83]
	v_mfma_f32_16x16x32_bf16 v[72:75], v[158:161], v[206:209], v[72:75]
	v_mfma_f32_16x16x32_bf16 v[64:67], v[172:175], v[206:209], v[64:67]
	s_setprio 0
	s_barrier
	s_add_u32 s74, s58, 0x20000
	ds_read_b128 v[178:181], v147 offset:16384
	ds_read_b128 v[182:185], v147 offset:17408
	ds_read_b128 v[186:189], v147 offset:18432
	ds_read_b128 v[190:193], v147 offset:19456
	ds_read_b128 v[194:197], v147 offset:20480
	ds_read_b128 v[198:201], v147 offset:21504
	ds_read_b128 v[202:205], v147 offset:22528
	ds_read_b128 v[206:209], v147 offset:23552
	s_mov_b32 m0, s20
	s_nop 0
	global_load_lds_dwordx4 v143, s[58:59]
	s_addc_u32 s75, s59, 0
	s_mov_b32 m0, s24
	s_nop 0
	global_load_lds_dwordx4 v143, s[74:75]
	s_add_u32 s74, s58, 0x40000
	s_addc_u32 s75, s59, 0
	s_mov_b32 m0, s33
	s_nop 0
	global_load_lds_dwordx4 v143, s[74:75]
	s_add_u32 s74, s58, 0x60000
	s_addc_u32 s75, s59, 0
	s_mov_b32 m0, s34
	s_nop 0
	global_load_lds_dwordx4 v143, s[74:75]
	s_mov_b32 m0, s15
	s_nop 0
	global_load_lds_dwordx4 v142, s[16:17]
	s_add_u32 s74, s16, 0x20000
	s_addc_u32 s75, s17, 0
	s_mov_b32 m0, s35
	s_nop 0
	global_load_lds_dwordx4 v142, s[74:75]
	s_waitcnt vmcnt(8)
	s_waitcnt lgkmcnt(0)
	s_barrier
; #define PG8_STAGE(bufoff, gbase, voff, p64) do { _Pragma("unroll") for (int _i = 0; _i < 2; ++_i) { \
;         const char* _gb = (const char*)(gbase) + (size_t)_i * (p64); const unsigned _la = ldsbase + (unsigned)(bufoff) + (unsigned)_i * 8192u; \
;         asm volatile("s_mov_b32 m0, %0\n\ts_nop 0\n\tglobal_load_lds_dwordx4 %1, %2" :: "s"(_la), "v"(voff), "s"(_gb) : "memory"); } } while (0)
; #define PG8_LDA(dst, b, h) do { _Pragma("unroll") for (int m = 0; m < 4; ++m) _Pragma("unroll") for (int k = 0; k < 2; ++k) dst[m][k] = *(const LAS bf16x8*)(lds + PG8_SA(b, h) + aoff + m * 2048 + k * 1024); } while (0)
; #define PG8_LDB(dst, b, h) do { _Pragma("unroll") for (int n = 0; n < 2; ++n) _Pragma("unroll") for (int k = 0; k < 2; ++k) dst[n][k] = *(const LAS bf16x8*)(lds + PG8_SB(b, h) + boff + n * 2048 + k * 1024); } while (0)
; #define PG8_MMA(ai, bj, At, Bt) do { __builtin_amdgcn_s_setprio(1); _Pragma("unroll") for (int m = 0; m < 4; ++m) _Pragma("unroll") for (int n = 0; n < 2; ++n) _Pragma("unroll") for (int k = 0; k < 2; ++k) \
;         acc[ai][bj][m][n] = __builtin_amdgcn_mfma_f32_16x16x32_bf16(Bt[n][k], At[m][k], acc[ai][bj][m][n], 0, 0, 0); __builtin_amdgcn_s_setprio(0); } while (0)
; #define PG8_WAIT_V(n) asm volatile("s_waitcnt vmcnt(" #n ")" ::: "memory")
; #define PG8_WAIT_L(n) asm volatile("s_waitcnt lgkmcnt(" #n ")" ::: "memory")
; #define PG8_BAR __builtin_amdgcn_s_barrier()
; #define PG8_SCHED __builtin_amdgcn_sched_barrier(0)
; template <class Epi, class Sched>
; __device__ __forceinline__ void gemm_phase(LAS unsigned char* lds, const Sched& S, const Epi& E) {
;     ...
;             PG8_WAIT_V(8); PG8_WAIT_L(0); PG8_BAR; PG8_MMA(1, 0, At, B0); PG8_MMA(1, 1, At, B1); PG8_BAR; PG8_SCHED;
;             PG8_LDB(B0, 1, 0); PG8_LDB(B1, 1, 1); PG8_SCHED; PG8_LDA(At, 1, 0); PG8_STAGE(PG8_SA(0, 1), a2 + hA2, vA2, hA2 / 2);
;             PG8_WAIT_V(8); PG8_WAIT_L(0); PG8_BAR; PG8_MMA(0, 0, At, B0); PG8_MMA(0, 1, At, B1); PG8_BAR; PG8_SCHED;
	s_setprio 1
	v_mfma_f32_16x16x32_bf16 v[60:63], v[130:133], v[178:181], v[60:63]
	v_mfma_f32_16x16x32_bf16 v[52:55], v[138:141], v[178:181], v[52:55]
	v_mfma_f32_16x16x32_bf16 v[44:47], v[130:133], v[186:189], v[44:47]
	v_mfma_f32_16x16x32_bf16 v[36:39], v[138:141], v[186:189], v[36:39]
	v_mfma_f32_16x16x32_bf16 v[28:31], v[130:133], v[194:197], v[28:31]
	v_mfma_f32_16x16x32_bf16 v[20:23], v[138:141], v[194:197], v[20:23]
	v_mfma_f32_16x16x32_bf16 v[12:15], v[130:133], v[202:205], v[12:15]
	v_mfma_f32_16x16x32_bf16 v[4:7], v[138:141], v[202:205], v[4:7]
	v_mfma_f32_16x16x32_bf16 v[60:63], v[134:137], v[182:185], v[60:63]
	v_mfma_f32_16x16x32_bf16 v[52:55], v[148:151], v[182:185], v[52:55]
	v_mfma_f32_16x16x32_bf16 v[44:47], v[134:137], v[190:193], v[44:47]
	v_mfma_f32_16x16x32_bf16 v[36:39], v[148:151], v[190:193], v[36:39]
	v_mfma_f32_16x16x32_bf16 v[28:31], v[134:137], v[198:201], v[28:31]
	v_mfma_f32_16x16x32_bf16 v[20:23], v[148:151], v[198:201], v[20:23]
	v_mfma_f32_16x16x32_bf16 v[12:15], v[134:137], v[206:209], v[12:15]
	v_mfma_f32_16x16x32_bf16 v[4:7], v[148:151], v[206:209], v[4:7]
	v_mfma_f32_16x16x32_bf16 v[56:59], v[152:155], v[178:181], v[56:59]
	v_mfma_f32_16x16x32_bf16 v[48:51], v[162:165], v[178:181], v[48:51]
	v_mfma_f32_16x16x32_bf16 v[40:43], v[152:155], v[186:189], v[40:43]
	v_mfma_f32_16x16x32_bf16 v[32:35], v[162:165], v[186:189], v[32:35]
	v_mfma_f32_16x16x32_bf16 v[24:27], v[152:155], v[194:197], v[24:27]
	v_mfma_f32_16x16x32_bf16 v[16:19], v[162:165], v[194:197], v[16:19]
	v_mfma_f32_16x16x32_bf16 v[8:11], v[152:155], v[202:205], v[8:11]
	v_mfma_f32_16x16x32_bf16 v[0:3], v[162:165], v[202:205], v[0:3]
	v_mfma_f32_16x16x32_bf16 v[56:59], v[158:161], v[182:185], v[56:59]
	v_mfma_f32_16x16x32_bf16 v[48:51], v[172:175], v[182:185], v[48:51]
	v_mfma_f32_16x16x32_bf16 v[40:43], v[158:161], v[190:193], v[40:43]
	v_mfma_f32_16x16x32_bf16 v[32:35], v[172:175], v[190:193], v[32:35]
	v_mfma_f32_16x16x32_bf16 v[24:27], v[158:161], v[198:201], v[24:27]
	v_mfma_f32_16x16x32_bf16 v[16:19], v[172:175], v[198:201], v[16:19]
	v_mfma_f32_16x16x32_bf16 v[8:11], v[158:161], v[206:209], v[8:11]
	v_mfma_f32_16x16x32_bf16 v[0:3], v[172:175], v[206:209], v[0:3]
	s_setprio 0
	s_barrier
	v_add_u32_e32 v128, 0x18000, v146
	ds_read_b128 v[130:133], v128
	ds_read_b128 v[134:137], v128 offset:1024
	ds_read_b128 v[138:141], v128 offset:2048
	ds_read_b128 v[148:151], v128 offset:3072
	v_add_u32_e32 v128, 0x1c000, v146
	ds_read_b128 v[152:155], v128
	ds_read_b128 v[158:161], v128 offset:1024
	ds_read_b128 v[162:165], v128 offset:2048
	ds_read_b128 v[172:175], v128 offset:3072
	ds_read_b128 v[178:181], v147 offset:32768
	ds_read_b128 v[182:185], v147 offset:33792
	ds_read_b128 v[186:189], v147 offset:34816
	ds_read_b128 v[190:193], v147 offset:35840
	ds_read_b128 v[194:197], v147 offset:36864
	ds_read_b128 v[198:201], v147 offset:37888
	ds_read_b128 v[202:205], v147 offset:38912
	ds_read_b128 v[206:209], v147 offset:39936
	s_add_u32 s74, s16, 0x40000
	s_addc_u32 s75, s17, 0
	s_mov_b32 m0, s36
	s_nop 0
	global_load_lds_dwordx4 v142, s[74:75]
	s_add_u32 s74, s16, 0x60000
	s_addc_u32 s75, s17, 0
	s_mov_b32 m0, s37
	s_nop 0
	global_load_lds_dwordx4 v142, s[74:75]
	s_waitcnt vmcnt(8)
	s_waitcnt lgkmcnt(0)
	s_barrier
	s_setprio 1
	v_mfma_f32_16x16x32_bf16 v[124:127], v[130:133], v[178:181], v[124:127]
	v_mfma_f32_16x16x32_bf16 v[116:119], v[138:141], v[178:181], v[116:119]
	v_mfma_f32_16x16x32_bf16 v[108:111], v[130:133], v[186:189], v[108:111]
	v_mfma_f32_16x16x32_bf16 v[100:103], v[138:141], v[186:189], v[100:103]
	v_mfma_f32_16x16x32_bf16 v[92:95], v[130:133], v[194:197], v[92:95]
	v_mfma_f32_16x16x32_bf16 v[84:87], v[138:141], v[194:197], v[84:87]
	v_mfma_f32_16x16x32_bf16 v[76:79], v[130:133], v[202:205], v[76:79]
	v_mfma_f32_16x16x32_bf16 v[68:71], v[138:141], v[202:205], v[68:71]
	v_mfma_f32_16x16x32_bf16 v[124:127], v[134:137], v[182:185], v[124:127]
	v_mfma_f32_16x16x32_bf16 v[116:119], v[148:151], v[182:185], v[116:119]
	v_mfma_f32_16x16x32_bf16 v[108:111], v[134:137], v[190:193], v[108:111]
	v_mfma_f32_16x16x32_bf16 v[100:103], v[148:151], v[190:193], v[100:103]
	v_mfma_f32_16x16x32_bf16 v[92:95], v[134:137], v[198:201], v[92:95]
	v_mfma_f32_16x16x32_bf16 v[84:87], v[148:151], v[198:201], v[84:87]
	v_mfma_f32_16x16x32_bf16 v[76:79], v[134:137], v[206:209], v[76:79]
	v_mfma_f32_16x16x32_bf16 v[68:71], v[148:151], v[206:209], v[68:71]
	v_mfma_f32_16x16x32_bf16 v[120:123], v[152:155], v[178:181], v[120:123]
	v_mfma_f32_16x16x32_bf16 v[112:115], v[162:165], v[178:181], v[112:115]
	v_mfma_f32_16x16x32_bf16 v[104:107], v[152:155], v[186:189], v[104:107]
	v_mfma_f32_16x16x32_bf16 v[96:99], v[162:165], v[186:189], v[96:99]
	v_mfma_f32_16x16x32_bf16 v[88:91], v[152:155], v[194:197], v[88:91]
	v_mfma_f32_16x16x32_bf16 v[80:83], v[162:165], v[194:197], v[80:83]
	v_mfma_f32_16x16x32_bf16 v[72:75], v[152:155], v[202:205], v[72:75]
	v_mfma_f32_16x16x32_bf16 v[64:67], v[162:165], v[202:205], v[64:67]
	v_mfma_f32_16x16x32_bf16 v[120:123], v[158:161], v[182:185], v[120:123]
	v_mfma_f32_16x16x32_bf16 v[112:115], v[172:175], v[182:185], v[112:115]
	v_mfma_f32_16x16x32_bf16 v[104:107], v[158:161], v[190:193], v[104:107]
	v_mfma_f32_16x16x32_bf16 v[96:99], v[172:175], v[190:193], v[96:99]
	v_mfma_f32_16x16x32_bf16 v[88:91], v[158:161], v[198:201], v[88:91]
	v_mfma_f32_16x16x32_bf16 v[80:83], v[172:175], v[198:201], v[80:83]
	v_mfma_f32_16x16x32_bf16 v[72:75], v[158:161], v[206:209], v[72:75]
	v_mfma_f32_16x16x32_bf16 v[64:67], v[172:175], v[206:209], v[64:67]
	s_setprio 0
	s_barrier
; #define PG8_STAGE(bufoff, gbase, voff, p64) do { _Pragma("unroll") for (int _i = 0; _i < 2; ++_i) { \
;         const char* _gb = (const char*)(gbase) + (size_t)_i * (p64); const unsigned _la = ldsbase + (unsigned)(bufoff) + (unsigned)_i * 8192u; \
;         asm volatile("s_mov_b32 m0, %0\n\ts_nop 0\n\tglobal_load_lds_dwordx4 %1, %2" :: "s"(_la), "v"(voff), "s"(_gb) : "memory"); } } while (0)
; #define PG8_LDA(dst, b, h) do { _Pragma("unroll") for (int m = 0; m < 4; ++m) _Pragma("unroll") for (int k = 0; k < 2; ++k) dst[m][k] = *(const LAS bf16x8*)(lds + PG8_SA(b, h) + aoff + m * 2048 + k * 1024); } while (0)
; #define PG8_MMA(ai, bj, At, Bt) do { __builtin_amdgcn_s_setprio(1); _Pragma("unroll") for (int m = 0; m < 4; ++m) _Pragma("unroll") for (int n = 0; n < 2; ++n) _Pragma("unroll") for (int k = 0; k < 2; ++k) \
;         acc[ai][bj][m][n] = __builtin_amdgcn_mfma_f32_16x16x32_bf16(Bt[n][k], At[m][k], acc[ai][bj][m][n], 0, 0, 0); __builtin_amdgcn_s_setprio(0); } while (0)
; #define PG8_WAIT_V(n) asm volatile("s_waitcnt vmcnt(" #n ")" ::: "memory")
; #define PG8_WAIT_L(n) asm volatile("s_waitcnt lgkmcnt(" #n ")" ::: "memory")
; #define PG8_BAR __builtin_amdgcn_s_barrier()
; #define PG8_SCHED __builtin_amdgcn_sched_barrier(0)
; template <class Epi, class Sched>
; __device__ __forceinline__ void gemm_phase(LAS unsigned char* lds, const Sched& S, const Epi& E) {
;     ...
;             PG8_LDA(At, 1, 1); PG8_STAGE(PG8_SB(1, 0), b3, vB2, hB2 / 2); PG8_STAGE(PG8_SB(1, 1), b3 + hB2, vB2, hB2 / 2); PG8_STAGE(PG8_SA(1, 0), a3, vA2, hA2 / 2);
;             PG8_WAIT_V(8); PG8_WAIT_L(0); PG8_BAR; PG8_MMA(1, 0, At, B0); PG8_MMA(1, 1, At, B1); PG8_BAR; PG8_SCHED;
;         }
	s_add_u32 s74, s58, 0x80
	s_addc_u32 s75, s59, 0
	ds_read_b128 v[178:181], v147 offset:49152
	ds_read_b128 v[182:185], v147 offset:50176
	ds_read_b128 v[186:189], v147 offset:51200
	ds_read_b128 v[190:193], v147 offset:52224
	ds_read_b128 v[194:197], v147 offset:53248
	ds_read_b128 v[198:201], v147 offset:54272
	ds_read_b128 v[202:205], v147 offset:55296
	ds_read_b128 v[206:209], v147 offset:56320
	s_mov_b32 m0, s45
	s_nop 0
	global_load_lds_dwordx4 v143, s[74:75]
	s_add_u32 s74, s58, 0x20080
	s_addc_u32 s75, s59, 0
	s_mov_b32 m0, s47
	s_nop 0
	global_load_lds_dwordx4 v143, s[74:75]
	s_add_u32 s74, s58, 0x40080
	s_addc_u32 s75, s59, 0
	s_mov_b32 m0, s51
	s_nop 0
	global_load_lds_dwordx4 v143, s[74:75]
	s_add_u32 s58, s58, 0x60080
	s_addc_u32 s59, s59, 0
	s_mov_b32 m0, s61
	s_nop 0
	global_load_lds_dwordx4 v143, s[58:59]
	s_mov_b32 m0, s48
	s_nop 0
	global_load_lds_dwordx4 v142, s[22:23]
	s_add_u32 s16, s16, 0x20080
	s_addc_u32 s17, s17, 0
	s_mov_b32 m0, s50
	s_nop 0
	global_load_lds_dwordx4 v142, s[16:17]
	s_waitcnt vmcnt(8)
	s_waitcnt lgkmcnt(0)
	s_barrier
	s_setprio 1
	v_mfma_f32_16x16x32_bf16 v[60:63], v[130:133], v[178:181], v[60:63]
	v_mfma_f32_16x16x32_bf16 v[52:55], v[138:141], v[178:181], v[52:55]
	v_mfma_f32_16x16x32_bf16 v[44:47], v[130:133], v[186:189], v[44:47]
	v_mfma_f32_16x16x32_bf16 v[36:39], v[138:141], v[186:189], v[36:39]
	v_mfma_f32_16x16x32_bf16 v[28:31], v[130:133], v[194:197], v[28:31]
	v_mfma_f32_16x16x32_bf16 v[20:23], v[138:141], v[194:197], v[20:23]
	v_mfma_f32_16x16x32_bf16 v[12:15], v[130:133], v[202:205], v[12:15]
	v_mfma_f32_16x16x32_bf16 v[4:7], v[138:141], v[202:205], v[4:7]
	v_mfma_f32_16x16x32_bf16 v[60:63], v[134:137], v[182:185], v[60:63]
	v_mfma_f32_16x16x32_bf16 v[52:55], v[148:151], v[182:185], v[52:55]
	v_mfma_f32_16x16x32_bf16 v[44:47], v[134:137], v[190:193], v[44:47]
	v_mfma_f32_16x16x32_bf16 v[36:39], v[148:151], v[190:193], v[36:39]
	v_mfma_f32_16x16x32_bf16 v[28:31], v[134:137], v[198:201], v[28:31]
	v_mfma_f32_16x16x32_bf16 v[20:23], v[148:151], v[198:201], v[20:23]
	v_mfma_f32_16x16x32_bf16 v[12:15], v[134:137], v[206:209], v[12:15]
	v_mfma_f32_16x16x32_bf16 v[4:7], v[148:151], v[206:209], v[4:7]
	v_mfma_f32_16x16x32_bf16 v[56:59], v[152:155], v[178:181], v[56:59]
	v_mfma_f32_16x16x32_bf16 v[48:51], v[162:165], v[178:181], v[48:51]
	v_mfma_f32_16x16x32_bf16 v[40:43], v[152:155], v[186:189], v[40:43]
	v_mfma_f32_16x16x32_bf16 v[32:35], v[162:165], v[186:189], v[32:35]
	v_mfma_f32_16x16x32_bf16 v[24:27], v[152:155], v[194:197], v[24:27]
	v_mfma_f32_16x16x32_bf16 v[16:19], v[162:165], v[194:197], v[16:19]
	v_mfma_f32_16x16x32_bf16 v[8:11], v[152:155], v[202:205], v[8:11]
	v_mfma_f32_16x16x32_bf16 v[0:3], v[162:165], v[202:205], v[0:3]
	v_mfma_f32_16x16x32_bf16 v[56:59], v[158:161], v[182:185], v[56:59]
	v_mfma_f32_16x16x32_bf16 v[48:51], v[172:175], v[182:185], v[48:51]
	v_mfma_f32_16x16x32_bf16 v[40:43], v[158:161], v[190:193], v[40:43]
	v_mfma_f32_16x16x32_bf16 v[32:35], v[172:175], v[190:193], v[32:35]
	v_mfma_f32_16x16x32_bf16 v[24:27], v[158:161], v[198:201], v[24:27]
	v_mfma_f32_16x16x32_bf16 v[16:19], v[172:175], v[198:201], v[16:19]
	v_mfma_f32_16x16x32_bf16 v[8:11], v[158:161], v[206:209], v[8:11]
	v_mfma_f32_16x16x32_bf16 v[0:3], v[172:175], v[206:209], v[0:3]
	s_setprio 0
	s_barrier
	s_add_i32 s73, s73, 2
	s_add_u32 s56, s56, 0x100
	s_addc_u32 s57, s57, 0
	s_add_u32 s69, s69, 0x100
	s_addc_u32 s72, s72, 0
	s_cmp_gt_u32 s73, 13
	s_cbranch_scc0 .LBB0_757
	s_and_b64 vcc, exec, s[38:39]
	s_cbranch_vccz .LBB0_760
	s_barrier

; #define PG8_STAGE(bufoff, gbase, voff, p64) do { _Pragma("unroll") for (int _i = 0; _i < 2; ++_i) { \
;         const char* _gb = (const char*)(gbase) + (size_t)_i * (p64); const unsigned _la = ldsbase + (unsigned)(bufoff) + (unsigned)_i * 8192u; \
;         asm volatile("s_mov_b32 m0, %0\n\ts_nop 0\n\tglobal_load_lds_dwordx4 %1, %2" :: "s"(_la), "v"(voff), "s"(_gb) : "memory"); } } while (0)
; #define PG8_LDA(dst, b, h) do { _Pragma("unroll") for (int m = 0; m < 4; ++m) _Pragma("unroll") for (int k = 0; k < 2; ++k) dst[m][k] = *(const LAS bf16x8*)(lds + PG8_SA(b, h) + aoff + m * 2048 + k * 1024); } while (0)
; #define PG8_LDB(dst, b, h) do { _Pragma("unroll") for (int n = 0; n < 2; ++n) _Pragma("unroll") for (int k = 0; k < 2; ++k) dst[n][k] = *(const LAS bf16x8*)(lds + PG8_SB(b, h) + boff + n * 2048 + k * 1024); } while (0)
; #define PG8_MMA(ai, bj, At, Bt) do { __builtin_amdgcn_s_setprio(1); _Pragma("unroll") for (int m = 0; m < 4; ++m) _Pragma("unroll") for (int n = 0; n < 2; ++n) _Pragma("unroll") for (int k = 0; k < 2; ++k) \
;         acc[ai][bj][m][n] = __builtin_amdgcn_mfma_f32_16x16x32_bf16(Bt[n][k], At[m][k], acc[ai][bj][m][n], 0, 0, 0); __builtin_amdgcn_s_setprio(0); } while (0)
; #define PG8_WAIT_V(n) asm volatile("s_waitcnt vmcnt(" #n ")" ::: "memory")
; #define PG8_BAR __builtin_amdgcn_s_barrier()
; template <class Epi, class Sched>
; __device__ __forceinline__ void gemm_phase(LAS unsigned char* lds, const Sched& S, const Epi& E) {
;     ...
;             const bool last = (t == nt - 2);
;             const char* a1 = cA + (size_t)(t + 1) * kstep;
;             const char* a2 = last ? nA : cA + (size_t)(t + 2) * kstep; const char* b2 = last ? nB : cB + (size_t)(t + 2) * kstep;
;             const char* a3 = a2 + kstep; const char* b3 = b2 + kstep;
;             const unsigned vA2 = voffA, vB2 = voffB, hA2 = hA, hB2 = hB;
;             PG8_LDB(B0, 0, 0); PG8_LDB(B1, 0, 1); PG8_SCHED; PG8_LDA(At, 0, 0); PG8_STAGE(PG8_SA(1, 1), a1 + hA, voffA, hA / 2);
;             PG8_WAIT_V(8); PG8_WAIT_L(0); PG8_BAR; PG8_MMA(0, 0, At, B0); PG8_MMA(0, 1, At, B1); PG8_BAR; PG8_SCHED;
;             PG8_LDA(At, 0, 1); PG8_STAGE(PG8_SB(0, 0), b2, vB2, hB2 / 2); PG8_STAGE(PG8_SB(0, 1), b2 + hB2, vB2, hB2 / 2); PG8_STAGE(PG8_SA(0, 0), a2, vA2, hA2 / 2);
;             PG8_WAIT_V(8); PG8_WAIT_L(0); PG8_BAR; PG8_MMA(1, 0, At, B0); PG8_MMA(1, 1, At, B1); PG8_BAR; PG8_SCHED;
.LBB0_844:
	v_add_u32_e32 v142, 0x10000, v175
	v_add_u32_e32 v154, 0x14000, v175
	ds_read_b128 v[130:133], v142
	ds_read_b128 v[134:137], v142 offset:1024
	ds_read_b128 v[138:141], v142 offset:2048
	ds_read_b128 v[142:145], v142 offset:3072
	ds_read_b128 v[146:149], v154
	ds_read_b128 v[150:153], v154 offset:1024
	ds_read_b128 v[158:161], v154 offset:2048
	ds_read_b128 v[162:165], v154 offset:3072
	s_add_i32 s80, s8, 2
	s_cmp_eq_u32 s73, s8
	s_cselect_b32 s8, s56, s76
	s_cselect_b32 s9, s57, s77
	s_cselect_b32 s22, s58, s78
	s_cselect_b32 s23, s59, s79
	s_add_u32 s16, s8, 0x80
	s_addc_u32 s17, s9, 0
	ds_read_b128 v[180:183], v177
	ds_read_b128 v[184:187], v177 offset:1024
	ds_read_b128 v[188:191], v177 offset:2048
	ds_read_b128 v[192:195], v177 offset:3072
	ds_read_b128 v[196:199], v177 offset:4096
	ds_read_b128 v[200:203], v177 offset:5120
	ds_read_b128 v[204:207], v177 offset:6144
	ds_read_b128 v[208:211], v177 offset:7168
	s_add_u32 s30, s76, 0x3ff80
	s_addc_u32 s31, s77, 0
	s_mov_b32 m0, s66
	s_nop 0
	global_load_lds_dwordx4 v172, s[30:31]
	s_add_u32 s30, s76, 0x5ff80
	s_addc_u32 s31, s77, 0
	s_mov_b32 m0, s67
	s_nop 0
	global_load_lds_dwordx4 v172, s[30:31]
	s_waitcnt vmcnt(8)
	s_waitcnt lgkmcnt(0)
	s_barrier
	s_setprio 1
	v_mfma_f32_16x16x32_bf16 v[124:127], v[130:133], v[180:183], v[124:127]
	v_mfma_f32_16x16x32_bf16 v[120:123], v[138:141], v[180:183], v[120:123]
	v_mfma_f32_16x16x32_bf16 v[116:119], v[130:133], v[188:191], v[116:119]
	v_mfma_f32_16x16x32_bf16 v[112:115], v[138:141], v[188:191], v[112:115]
	v_mfma_f32_16x16x32_bf16 v[108:111], v[130:133], v[196:199], v[108:111]
	v_mfma_f32_16x16x32_bf16 v[104:107], v[138:141], v[196:199], v[104:107]
	v_mfma_f32_16x16x32_bf16 v[100:103], v[130:133], v[204:207], v[100:103]
	v_mfma_f32_16x16x32_bf16 v[96:99], v[138:141], v[204:207], v[96:99]
	v_mfma_f32_16x16x32_bf16 v[124:127], v[134:137], v[184:187], v[124:127]
	v_mfma_f32_16x16x32_bf16 v[120:123], v[142:145], v[184:187], v[120:123]
	v_mfma_f32_16x16x32_bf16 v[116:119], v[134:137], v[192:195], v[116:119]
	v_mfma_f32_16x16x32_bf16 v[112:115], v[142:145], v[192:195], v[112:115]
	v_mfma_f32_16x16x32_bf16 v[108:111], v[134:137], v[200:203], v[108:111]
	v_mfma_f32_16x16x32_bf16 v[104:107], v[142:145], v[200:203], v[104:107]
	v_mfma_f32_16x16x32_bf16 v[100:103], v[134:137], v[208:211], v[100:103]
	v_mfma_f32_16x16x32_bf16 v[96:99], v[142:145], v[208:211], v[96:99]
	v_mfma_f32_16x16x32_bf16 v[92:95], v[146:149], v[180:183], v[92:95]
	v_mfma_f32_16x16x32_bf16 v[88:91], v[158:161], v[180:183], v[88:91]
	v_mfma_f32_16x16x32_bf16 v[84:87], v[146:149], v[188:191], v[84:87]
	v_mfma_f32_16x16x32_bf16 v[80:83], v[158:161], v[188:191], v[80:83]
	v_mfma_f32_16x16x32_bf16 v[76:79], v[146:149], v[196:199], v[76:79]
	v_mfma_f32_16x16x32_bf16 v[72:75], v[158:161], v[196:199], v[72:75]
	v_mfma_f32_16x16x32_bf16 v[68:71], v[146:149], v[204:207], v[68:71]
	v_mfma_f32_16x16x32_bf16 v[64:67], v[158:161], v[204:207], v[64:67]
	v_mfma_f32_16x16x32_bf16 v[92:95], v[150:153], v[184:187], v[92:95]
	v_mfma_f32_16x16x32_bf16 v[88:91], v[162:165], v[184:187], v[88:91]
	v_mfma_f32_16x16x32_bf16 v[84:87], v[150:153], v[192:195], v[84:87]
	v_mfma_f32_16x16x32_bf16 v[80:83], v[162:165], v[192:195], v[80:83]
	v_mfma_f32_16x16x32_bf16 v[76:79], v[150:153], v[200:203], v[76:79]
	v_mfma_f32_16x16x32_bf16 v[72:75], v[162:165], v[200:203], v[72:75]
	v_mfma_f32_16x16x32_bf16 v[68:71], v[150:153], v[208:211], v[68:71]
	v_mfma_f32_16x16x32_bf16 v[64:67], v[162:165], v[208:211], v[64:67]
	s_setprio 0
	s_barrier
	s_add_u32 s30, s22, 0x10000
	ds_read_b128 v[180:183], v177 offset:16384
	ds_read_b128 v[184:187], v177 offset:17408
	ds_read_b128 v[188:191], v177 offset:18432
	ds_read_b128 v[192:195], v177 offset:19456
	ds_read_b128 v[196:199], v177 offset:20480
	ds_read_b128 v[200:203], v177 offset:21504
	ds_read_b128 v[204:207], v177 offset:22528
	ds_read_b128 v[208:211], v177 offset:23552
	s_mov_b32 m0, s5
	s_nop 0
	global_load_lds_dwordx4 v128, s[22:23]
	s_addc_u32 s31, s23, 0
	s_mov_b32 m0, s12
	s_nop 0
	global_load_lds_dwordx4 v128, s[30:31]
	s_add_u32 s30, s22, 0x20000
	s_addc_u32 s31, s23, 0
	s_mov_b32 m0, s14
	s_nop 0
	global_load_lds_dwordx4 v128, s[30:31]
	s_add_u32 s30, s22, 0x30000
	s_addc_u32 s31, s23, 0
	s_mov_b32 m0, s15
	s_nop 0
	global_load_lds_dwordx4 v128, s[30:31]
	s_mov_b32 m0, s4
	s_nop 0
	global_load_lds_dwordx4 v172, s[8:9]
	s_add_u32 s30, s8, 0x20000
	s_addc_u32 s31, s9, 0
	s_mov_b32 m0, s24
	s_nop 0
	global_load_lds_dwordx4 v172, s[30:31]
	s_waitcnt vmcnt(8)
	s_waitcnt lgkmcnt(0)
	s_barrier
; #define PG8_STAGE(bufoff, gbase, voff, p64) do { _Pragma("unroll") for (int _i = 0; _i < 2; ++_i) { \
;         const char* _gb = (const char*)(gbase) + (size_t)_i * (p64); const unsigned _la = ldsbase + (unsigned)(bufoff) + (unsigned)_i * 8192u; \
;         asm volatile("s_mov_b32 m0, %0\n\ts_nop 0\n\tglobal_load_lds_dwordx4 %1, %2" :: "s"(_la), "v"(voff), "s"(_gb) : "memory"); } } while (0)
; #define PG8_LDA(dst, b, h) do { _Pragma("unroll") for (int m = 0; m < 4; ++m) _Pragma("unroll") for (int k = 0; k < 2; ++k) dst[m][k] = *(const LAS bf16x8*)(lds + PG8_SA(b, h) + aoff + m * 2048 + k * 1024); } while (0)
; #define PG8_LDB(dst, b, h) do { _Pragma("unroll") for (int n = 0; n < 2; ++n) _Pragma("unroll") for (int k = 0; k < 2; ++k) dst[n][k] = *(const LAS bf16x8*)(lds + PG8_SB(b, h) + boff + n * 2048 + k * 1024); } while (0)
; #define PG8_MMA(ai, bj, At, Bt) do { __builtin_amdgcn_s_setprio(1); _Pragma("unroll") for (int m = 0; m < 4; ++m) _Pragma("unroll") for (int n = 0; n < 2; ++n) _Pragma("unroll") for (int k = 0; k < 2; ++k) \
;         acc[ai][bj][m][n] = __builtin_amdgcn_mfma_f32_16x16x32_bf16(Bt[n][k], At[m][k], acc[ai][bj][m][n], 0, 0, 0); __builtin_amdgcn_s_setprio(0); } while (0)
; #define PG8_WAIT_V(n) asm volatile("s_waitcnt vmcnt(" #n ")" ::: "memory")
; #define PG8_WAIT_L(n) asm volatile("s_waitcnt lgkmcnt(" #n ")" ::: "memory")
; #define PG8_BAR __builtin_amdgcn_s_barrier()
; #define PG8_SCHED __builtin_amdgcn_sched_barrier(0)
; template <class Epi, class Sched>
; __device__ __forceinline__ void gemm_phase(LAS unsigned char* lds, const Sched& S, const Epi& E) {
;     ...
;             PG8_WAIT_V(8); PG8_WAIT_L(0); PG8_BAR; PG8_MMA(1, 0, At, B0); PG8_MMA(1, 1, At, B1); PG8_BAR; PG8_SCHED;
;             PG8_LDB(B0, 1, 0); PG8_LDB(B1, 1, 1); PG8_SCHED; PG8_LDA(At, 1, 0); PG8_STAGE(PG8_SA(0, 1), a2 + hA2, vA2, hA2 / 2);
;             PG8_WAIT_V(8); PG8_WAIT_L(0); PG8_BAR; PG8_MMA(0, 0, At, B0); PG8_MMA(0, 1, At, B1); PG8_BAR; PG8_SCHED;
	s_setprio 1
	v_mfma_f32_16x16x32_bf16 v[60:63], v[130:133], v[180:183], v[60:63]
	v_mfma_f32_16x16x32_bf16 v[56:59], v[138:141], v[180:183], v[56:59]
	v_mfma_f32_16x16x32_bf16 v[52:55], v[130:133], v[188:191], v[52:55]
	v_mfma_f32_16x16x32_bf16 v[48:51], v[138:141], v[188:191], v[48:51]
	v_mfma_f32_16x16x32_bf16 v[44:47], v[130:133], v[196:199], v[44:47]
	v_mfma_f32_16x16x32_bf16 v[40:43], v[138:141], v[196:199], v[40:43]
	v_mfma_f32_16x16x32_bf16 v[36:39], v[130:133], v[204:207], v[36:39]
	v_mfma_f32_16x16x32_bf16 v[32:35], v[138:141], v[204:207], v[32:35]
	v_mfma_f32_16x16x32_bf16 v[60:63], v[134:137], v[184:187], v[60:63]
	v_mfma_f32_16x16x32_bf16 v[56:59], v[142:145], v[184:187], v[56:59]
	v_mfma_f32_16x16x32_bf16 v[52:55], v[134:137], v[192:195], v[52:55]
	v_mfma_f32_16x16x32_bf16 v[48:51], v[142:145], v[192:195], v[48:51]
	v_mfma_f32_16x16x32_bf16 v[44:47], v[134:137], v[200:203], v[44:47]
	v_mfma_f32_16x16x32_bf16 v[40:43], v[142:145], v[200:203], v[40:43]
	v_mfma_f32_16x16x32_bf16 v[36:39], v[134:137], v[208:211], v[36:39]
	v_mfma_f32_16x16x32_bf16 v[32:35], v[142:145], v[208:211], v[32:35]
	v_mfma_f32_16x16x32_bf16 v[28:31], v[146:149], v[180:183], v[28:31]
	v_mfma_f32_16x16x32_bf16 v[24:27], v[158:161], v[180:183], v[24:27]
	v_mfma_f32_16x16x32_bf16 v[20:23], v[146:149], v[188:191], v[20:23]
	v_mfma_f32_16x16x32_bf16 v[16:19], v[158:161], v[188:191], v[16:19]
	v_mfma_f32_16x16x32_bf16 v[12:15], v[146:149], v[196:199], v[12:15]
	v_mfma_f32_16x16x32_bf16 v[8:11], v[158:161], v[196:199], v[8:11]
	v_mfma_f32_16x16x32_bf16 v[4:7], v[146:149], v[204:207], v[4:7]
	v_mfma_f32_16x16x32_bf16 v[0:3], v[158:161], v[204:207], v[0:3]
	v_mfma_f32_16x16x32_bf16 v[28:31], v[150:153], v[184:187], v[28:31]
	v_mfma_f32_16x16x32_bf16 v[24:27], v[162:165], v[184:187], v[24:27]
	v_mfma_f32_16x16x32_bf16 v[20:23], v[150:153], v[192:195], v[20:23]
	v_mfma_f32_16x16x32_bf16 v[16:19], v[162:165], v[192:195], v[16:19]
	v_mfma_f32_16x16x32_bf16 v[12:15], v[150:153], v[200:203], v[12:15]
	v_mfma_f32_16x16x32_bf16 v[8:11], v[162:165], v[200:203], v[8:11]
	v_mfma_f32_16x16x32_bf16 v[4:7], v[150:153], v[208:211], v[4:7]
	v_mfma_f32_16x16x32_bf16 v[0:3], v[162:165], v[208:211], v[0:3]
	s_setprio 0
	s_barrier
	v_add_u32_e32 v142, 0x18000, v175
	v_add_u32_e32 v154, 0x1c000, v175
	ds_read_b128 v[130:133], v142
	ds_read_b128 v[134:137], v142 offset:1024
	ds_read_b128 v[138:141], v142 offset:2048
	ds_read_b128 v[142:145], v142 offset:3072
	ds_read_b128 v[146:149], v154
	ds_read_b128 v[150:153], v154 offset:1024
	ds_read_b128 v[158:161], v154 offset:2048
	ds_read_b128 v[162:165], v154 offset:3072
	ds_read_b128 v[180:183], v177 offset:32768
	ds_read_b128 v[184:187], v177 offset:33792
	ds_read_b128 v[188:191], v177 offset:34816
	ds_read_b128 v[192:195], v177 offset:35840
	ds_read_b128 v[196:199], v177 offset:36864
	ds_read_b128 v[200:203], v177 offset:37888
	ds_read_b128 v[204:207], v177 offset:38912
	ds_read_b128 v[208:211], v177 offset:39936
	s_add_u32 s30, s8, 0x40000
	s_addc_u32 s31, s9, 0
	s_mov_b32 m0, s33
	s_nop 0
	global_load_lds_dwordx4 v172, s[30:31]
	s_add_u32 s30, s8, 0x60000
	s_addc_u32 s31, s9, 0
	s_mov_b32 m0, s34
	s_nop 0
	global_load_lds_dwordx4 v172, s[30:31]
	s_waitcnt vmcnt(8)
	s_waitcnt lgkmcnt(0)
	s_barrier
	s_setprio 1
	v_mfma_f32_16x16x32_bf16 v[124:127], v[130:133], v[180:183], v[124:127]
	v_mfma_f32_16x16x32_bf16 v[120:123], v[138:141], v[180:183], v[120:123]
	v_mfma_f32_16x16x32_bf16 v[116:119], v[130:133], v[188:191], v[116:119]
	v_mfma_f32_16x16x32_bf16 v[112:115], v[138:141], v[188:191], v[112:115]
	v_mfma_f32_16x16x32_bf16 v[108:111], v[130:133], v[196:199], v[108:111]
	v_mfma_f32_16x16x32_bf16 v[104:107], v[138:141], v[196:199], v[104:107]
	v_mfma_f32_16x16x32_bf16 v[100:103], v[130:133], v[204:207], v[100:103]
	v_mfma_f32_16x16x32_bf16 v[96:99], v[138:141], v[204:207], v[96:99]
	v_mfma_f32_16x16x32_bf16 v[124:127], v[134:137], v[184:187], v[124:127]
	v_mfma_f32_16x16x32_bf16 v[120:123], v[142:145], v[184:187], v[120:123]
	v_mfma_f32_16x16x32_bf16 v[116:119], v[134:137], v[192:195], v[116:119]
	v_mfma_f32_16x16x32_bf16 v[112:115], v[142:145], v[192:195], v[112:115]
	v_mfma_f32_16x16x32_bf16 v[108:111], v[134:137], v[200:203], v[108:111]
	v_mfma_f32_16x16x32_bf16 v[104:107], v[142:145], v[200:203], v[104:107]
	v_mfma_f32_16x16x32_bf16 v[100:103], v[134:137], v[208:211], v[100:103]
	v_mfma_f32_16x16x32_bf16 v[96:99], v[142:145], v[208:211], v[96:99]
	v_mfma_f32_16x16x32_bf16 v[92:95], v[146:149], v[180:183], v[92:95]
	v_mfma_f32_16x16x32_bf16 v[88:91], v[158:161], v[180:183], v[88:91]
	v_mfma_f32_16x16x32_bf16 v[84:87], v[146:149], v[188:191], v[84:87]
	v_mfma_f32_16x16x32_bf16 v[80:83], v[158:161], v[188:191], v[80:83]
	v_mfma_f32_16x16x32_bf16 v[76:79], v[146:149], v[196:199], v[76:79]
	v_mfma_f32_16x16x32_bf16 v[72:75], v[158:161], v[196:199], v[72:75]
	v_mfma_f32_16x16x32_bf16 v[68:71], v[146:149], v[204:207], v[68:71]
	v_mfma_f32_16x16x32_bf16 v[64:67], v[158:161], v[204:207], v[64:67]
	v_mfma_f32_16x16x32_bf16 v[92:95], v[150:153], v[184:187], v[92:95]
	v_mfma_f32_16x16x32_bf16 v[88:91], v[162:165], v[184:187], v[88:91]
	v_mfma_f32_16x16x32_bf16 v[84:87], v[150:153], v[192:195], v[84:87]
	v_mfma_f32_16x16x32_bf16 v[80:83], v[162:165], v[192:195], v[80:83]
	v_mfma_f32_16x16x32_bf16 v[76:79], v[150:153], v[200:203], v[76:79]
	v_mfma_f32_16x16x32_bf16 v[72:75], v[162:165], v[200:203], v[72:75]
	v_mfma_f32_16x16x32_bf16 v[68:71], v[150:153], v[208:211], v[68:71]
	v_mfma_f32_16x16x32_bf16 v[64:67], v[162:165], v[208:211], v[64:67]
	s_setprio 0
	s_barrier
; #define PG8_STAGE(bufoff, gbase, voff, p64) do { _Pragma("unroll") for (int _i = 0; _i < 2; ++_i) { \
;         const char* _gb = (const char*)(gbase) + (size_t)_i * (p64); const unsigned _la = ldsbase + (unsigned)(bufoff) + (unsigned)_i * 8192u; \
;         asm volatile("s_mov_b32 m0, %0\n\ts_nop 0\n\tglobal_load_lds_dwordx4 %1, %2" :: "s"(_la), "v"(voff), "s"(_gb) : "memory"); } } while (0)
; #define PG8_LDA(dst, b, h) do { _Pragma("unroll") for (int m = 0; m < 4; ++m) _Pragma("unroll") for (int k = 0; k < 2; ++k) dst[m][k] = *(const LAS bf16x8*)(lds + PG8_SA(b, h) + aoff + m * 2048 + k * 1024); } while (0)
; #define PG8_MMA(ai, bj, At, Bt) do { __builtin_amdgcn_s_setprio(1); _Pragma("unroll") for (int m = 0; m < 4; ++m) _Pragma("unroll") for (int n = 0; n < 2; ++n) _Pragma("unroll") for (int k = 0; k < 2; ++k) \
;         acc[ai][bj][m][n] = __builtin_amdgcn_mfma_f32_16x16x32_bf16(Bt[n][k], At[m][k], acc[ai][bj][m][n], 0, 0, 0); __builtin_amdgcn_s_setprio(0); } while (0)
; #define PG8_WAIT_V(n) asm volatile("s_waitcnt vmcnt(" #n ")" ::: "memory")
; #define PG8_WAIT_L(n) asm volatile("s_waitcnt lgkmcnt(" #n ")" ::: "memory")
; #define PG8_BAR __builtin_amdgcn_s_barrier()
; #define PG8_SCHED __builtin_amdgcn_sched_barrier(0)
; template <class Epi, class Sched>
; __device__ __forceinline__ void gemm_phase(LAS unsigned char* lds, const Sched& S, const Epi& E) {
;     ...
;             PG8_LDA(At, 1, 1); PG8_STAGE(PG8_SB(1, 0), b3, vB2, hB2 / 2); PG8_STAGE(PG8_SB(1, 1), b3 + hB2, vB2, hB2 / 2); PG8_STAGE(PG8_SA(1, 0), a3, vA2, hA2 / 2);
;             PG8_WAIT_V(8); PG8_WAIT_L(0); PG8_BAR; PG8_MMA(1, 0, At, B0); PG8_MMA(1, 1, At, B1); PG8_BAR; PG8_SCHED;
;         }
	s_add_u32 s30, s22, 0x80
	s_addc_u32 s31, s23, 0
	ds_read_b128 v[180:183], v177 offset:49152
	ds_read_b128 v[184:187], v177 offset:50176
	ds_read_b128 v[188:191], v177 offset:51200
	ds_read_b128 v[192:195], v177 offset:52224
	ds_read_b128 v[196:199], v177 offset:53248
	ds_read_b128 v[200:203], v177 offset:54272
	ds_read_b128 v[204:207], v177 offset:55296
	ds_read_b128 v[208:211], v177 offset:56320
	s_mov_b32 m0, s51
	s_nop 0
	global_load_lds_dwordx4 v128, s[30:31]
	s_add_u32 s30, s22, 0x10080
	s_addc_u32 s31, s23, 0
	s_mov_b32 m0, s61
	s_nop 0
	global_load_lds_dwordx4 v128, s[30:31]
	s_add_u32 s30, s22, 0x20080
	s_addc_u32 s31, s23, 0
	s_mov_b32 m0, s64
	s_nop 0
	global_load_lds_dwordx4 v128, s[30:31]
	s_add_u32 s22, s22, 0x30080
	s_addc_u32 s23, s23, 0
	s_mov_b32 m0, s65
	s_nop 0
	global_load_lds_dwordx4 v128, s[22:23]
	s_mov_b32 m0, s62
	s_nop 0
	global_load_lds_dwordx4 v172, s[16:17]
	s_add_u32 s8, s8, 0x20080
	s_addc_u32 s9, s9, 0
	s_mov_b32 m0, s63
	s_nop 0
	global_load_lds_dwordx4 v172, s[8:9]
	s_waitcnt vmcnt(8)
	s_waitcnt lgkmcnt(0)
	s_barrier
	s_setprio 1
	v_mfma_f32_16x16x32_bf16 v[60:63], v[130:133], v[180:183], v[60:63]
	v_mfma_f32_16x16x32_bf16 v[56:59], v[138:141], v[180:183], v[56:59]
	v_mfma_f32_16x16x32_bf16 v[52:55], v[130:133], v[188:191], v[52:55]
	v_mfma_f32_16x16x32_bf16 v[48:51], v[138:141], v[188:191], v[48:51]
	v_mfma_f32_16x16x32_bf16 v[44:47], v[130:133], v[196:199], v[44:47]
	v_mfma_f32_16x16x32_bf16 v[40:43], v[138:141], v[196:199], v[40:43]
	v_mfma_f32_16x16x32_bf16 v[36:39], v[130:133], v[204:207], v[36:39]
	v_mfma_f32_16x16x32_bf16 v[32:35], v[138:141], v[204:207], v[32:35]
	v_mfma_f32_16x16x32_bf16 v[60:63], v[134:137], v[184:187], v[60:63]
	v_mfma_f32_16x16x32_bf16 v[56:59], v[142:145], v[184:187], v[56:59]
	v_mfma_f32_16x16x32_bf16 v[52:55], v[134:137], v[192:195], v[52:55]
	v_mfma_f32_16x16x32_bf16 v[48:51], v[142:145], v[192:195], v[48:51]
	v_mfma_f32_16x16x32_bf16 v[44:47], v[134:137], v[200:203], v[44:47]
	v_mfma_f32_16x16x32_bf16 v[40:43], v[142:145], v[200:203], v[40:43]
	v_mfma_f32_16x16x32_bf16 v[36:39], v[134:137], v[208:211], v[36:39]
	v_mfma_f32_16x16x32_bf16 v[32:35], v[142:145], v[208:211], v[32:35]
	v_mfma_f32_16x16x32_bf16 v[28:31], v[146:149], v[180:183], v[28:31]
	v_mfma_f32_16x16x32_bf16 v[24:27], v[158:161], v[180:183], v[24:27]
	v_mfma_f32_16x16x32_bf16 v[20:23], v[146:149], v[188:191], v[20:23]
	v_mfma_f32_16x16x32_bf16 v[16:19], v[158:161], v[188:191], v[16:19]
	v_mfma_f32_16x16x32_bf16 v[12:15], v[146:149], v[196:199], v[12:15]
	v_mfma_f32_16x16x32_bf16 v[8:11], v[158:161], v[196:199], v[8:11]
	v_mfma_f32_16x16x32_bf16 v[4:7], v[146:149], v[204:207], v[4:7]
	v_mfma_f32_16x16x32_bf16 v[0:3], v[158:161], v[204:207], v[0:3]
	v_mfma_f32_16x16x32_bf16 v[28:31], v[150:153], v[184:187], v[28:31]
	v_mfma_f32_16x16x32_bf16 v[24:27], v[162:165], v[184:187], v[24:27]
	v_mfma_f32_16x16x32_bf16 v[20:23], v[150:153], v[192:195], v[20:23]
	v_mfma_f32_16x16x32_bf16 v[16:19], v[162:165], v[192:195], v[16:19]
	v_mfma_f32_16x16x32_bf16 v[12:15], v[150:153], v[200:203], v[12:15]
	v_mfma_f32_16x16x32_bf16 v[8:11], v[162:165], v[200:203], v[8:11]
	v_mfma_f32_16x16x32_bf16 v[4:7], v[150:153], v[208:211], v[4:7]
	v_mfma_f32_16x16x32_bf16 v[0:3], v[162:165], v[208:211], v[0:3]
	s_setprio 0
	s_barrier
	s_add_u32 s76, s76, 0x100
	s_addc_u32 s77, s77, 0
	s_add_u32 s78, s78, 0x100
	s_addc_u32 s79, s79, 0
	s_cmp_ge_u32 s80, s7
	s_mov_b32 s8, s80
	s_cbranch_scc0 .LBB0_844
	s_and_b64 vcc, exec, s[10:11]
	s_cbranch_vccz .LBB0_847
	s_barrier

; #define PG8_STAGE(bufoff, gbase, voff, p64) do { _Pragma("unroll") for (int _i = 0; _i < 2; ++_i) { \
;         const char* _gb = (const char*)(gbase) + (size_t)_i * (p64); const unsigned _la = ldsbase + (unsigned)(bufoff) + (unsigned)_i * 8192u; \
;         asm volatile("s_mov_b32 m0, %0\n\ts_nop 0\n\tglobal_load_lds_dwordx4 %1, %2" :: "s"(_la), "v"(voff), "s"(_gb) : "memory"); } } while (0)
; #define PG8_LDA(dst, b, h) do { _Pragma("unroll") for (int m = 0; m < 4; ++m) _Pragma("unroll") for (int k = 0; k < 2; ++k) dst[m][k] = *(const LAS bf16x8*)(lds + PG8_SA(b, h) + aoff + m * 2048 + k * 1024); } while (0)
; #define PG8_LDB(dst, b, h) do { _Pragma("unroll") for (int n = 0; n < 2; ++n) _Pragma("unroll") for (int k = 0; k < 2; ++k) dst[n][k] = *(const LAS bf16x8*)(lds + PG8_SB(b, h) + boff + n * 2048 + k * 1024); } while (0)
; #define PG8_WAIT_V(n) asm volatile("s_waitcnt vmcnt(" #n ")" ::: "memory")
; #define PG8_WAIT_L(n) asm volatile("s_waitcnt lgkmcnt(" #n ")" ::: "memory")
; #define PG8_BAR __builtin_amdgcn_s_barrier()
; template <class Epi, class Sched>
; __device__ __forceinline__ void gemm_phase(LAS unsigned char* lds, const Sched& S, const Epi& E) {
;     ...
;             const bool last = (t == nt - 2);
;             const char* a1 = cA + (size_t)(t + 1) * kstep;
;             const char* a2 = last ? nA : cA + (size_t)(t + 2) * kstep; const char* b2 = last ? nB : cB + (size_t)(t + 2) * kstep;
;             const char* a3 = a2 + kstep; const char* b3 = b2 + kstep;
;             const unsigned vA2 = voffA, vB2 = voffB, hA2 = hA, hB2 = hB;
;             PG8_LDB(B0, 0, 0); PG8_LDB(B1, 0, 1); PG8_SCHED; PG8_LDA(At, 0, 0); PG8_STAGE(PG8_SA(1, 1), a1 + hA, voffA, hA / 2);
;             PG8_WAIT_V(8); PG8_WAIT_L(0); PG8_BAR; PG8_MMA(0, 0, At, B0); PG8_MMA(0, 1, At, B1); PG8_BAR; PG8_SCHED;
;             PG8_LDA(At, 0, 1); PG8_STAGE(PG8_SB(0, 0), b2, vB2, hB2 / 2); PG8_STAGE(PG8_SB(0, 1), b2 + hB2, vB2, hB2 / 2); PG8_STAGE(PG8_SA(0, 0), a2, vA2, hA2 / 2);
;             PG8_WAIT_V(8); PG8_WAIT_L(0); PG8_BAR; PG8_MMA(1, 0, At, B0); PG8_MMA(1, 1, At, B1); PG8_BAR; PG8_SCHED;
;             PG8_LDB(B0, 1, 0); PG8_LDB(B1, 1, 1); PG8_SCHED; PG8_LDA(At, 1, 0); PG8_STAGE(PG8_SA(0, 1), a2 + hA2, vA2, hA2 / 2);
;             PG8_WAIT_V(8); PG8_WAIT_L(0); PG8_BAR; PG8_MMA(0, 0, At, B0); PG8_MMA(0, 1, At, B1); PG8_BAR; PG8_SCHED;
.LBB0_981:
	ds_read_b128 v[112:115], v162
	ds_read_b128 v[116:119], v162 offset:1024
	ds_read_b128 v[140:143], v162 offset:2048
	ds_read_b128 v[144:147], v162 offset:3072
	ds_read_b128 v[148:151], v163
	ds_read_b128 v[152:155], v163 offset:1024
	ds_read_b128 v[168:171], v163 offset:2048
	ds_read_b128 v[172:175], v163 offset:3072
	s_add_u32 s30, s26, 0xfffc0080
	s_addc_u32 s38, s27, -1
	s_cmp_eq_u32 s65, 12
	s_cselect_b32 s39, s23, s38
	s_cselect_b32 s38, s22, s30
	s_cselect_b32 s42, s24, s62
	s_cselect_b32 s43, s25, s63
	s_add_u32 s40, s38, 0x80
	s_addc_u32 s41, s39, 0
	ds_read_b128 v[178:181], v164
	ds_read_b128 v[182:185], v164 offset:1024
	ds_read_b128 v[186:189], v164 offset:2048
	ds_read_b128 v[190:193], v164 offset:3072
	ds_read_b128 v[194:197], v164 offset:4096
	ds_read_b128 v[198:201], v164 offset:5120
	ds_read_b128 v[202:205], v164 offset:6144
	ds_read_b128 v[206:209], v164 offset:7168
	s_mov_b32 m0, s58
	s_nop 0
	global_load_lds_dwordx4 v158, s[26:27]
	s_add_u32 s66, s26, 0x20000
	s_addc_u32 s67, s27, 0
	s_mov_b32 m0, s59
	s_nop 0
	global_load_lds_dwordx4 v158, s[66:67]
	s_waitcnt vmcnt(8)
	s_waitcnt lgkmcnt(0)
	s_barrier
	s_setprio 1
	v_mfma_f32_16x16x32_bf16 v[132:135], v[112:115], v[178:181], v[132:135]
	v_mfma_f32_16x16x32_bf16 v[128:131], v[140:143], v[178:181], v[128:131]
	v_mfma_f32_16x16x32_bf16 v[124:127], v[112:115], v[186:189], v[124:127]
	v_mfma_f32_16x16x32_bf16 v[120:123], v[140:143], v[186:189], v[120:123]
	v_mfma_f32_16x16x32_bf16 v[108:111], v[112:115], v[194:197], v[108:111]
	v_mfma_f32_16x16x32_bf16 v[104:107], v[140:143], v[194:197], v[104:107]
	v_mfma_f32_16x16x32_bf16 v[100:103], v[112:115], v[202:205], v[100:103]
	v_mfma_f32_16x16x32_bf16 v[96:99], v[140:143], v[202:205], v[96:99]
	v_mfma_f32_16x16x32_bf16 v[132:135], v[116:119], v[182:185], v[132:135]
	v_mfma_f32_16x16x32_bf16 v[128:131], v[144:147], v[182:185], v[128:131]
	v_mfma_f32_16x16x32_bf16 v[124:127], v[116:119], v[190:193], v[124:127]
	v_mfma_f32_16x16x32_bf16 v[120:123], v[144:147], v[190:193], v[120:123]
	v_mfma_f32_16x16x32_bf16 v[108:111], v[116:119], v[198:201], v[108:111]
	v_mfma_f32_16x16x32_bf16 v[104:107], v[144:147], v[198:201], v[104:107]
	v_mfma_f32_16x16x32_bf16 v[100:103], v[116:119], v[206:209], v[100:103]
	v_mfma_f32_16x16x32_bf16 v[96:99], v[144:147], v[206:209], v[96:99]
	v_mfma_f32_16x16x32_bf16 v[60:63], v[148:151], v[178:181], v[60:63]
	v_mfma_f32_16x16x32_bf16 v[56:59], v[168:171], v[178:181], v[56:59]
	v_mfma_f32_16x16x32_bf16 v[52:55], v[148:151], v[186:189], v[52:55]
	v_mfma_f32_16x16x32_bf16 v[48:51], v[168:171], v[186:189], v[48:51]
	v_mfma_f32_16x16x32_bf16 v[44:47], v[148:151], v[194:197], v[44:47]
	v_mfma_f32_16x16x32_bf16 v[40:43], v[168:171], v[194:197], v[40:43]
	v_mfma_f32_16x16x32_bf16 v[36:39], v[148:151], v[202:205], v[36:39]
	v_mfma_f32_16x16x32_bf16 v[32:35], v[168:171], v[202:205], v[32:35]
	v_mfma_f32_16x16x32_bf16 v[60:63], v[152:155], v[182:185], v[60:63]
	v_mfma_f32_16x16x32_bf16 v[56:59], v[172:175], v[182:185], v[56:59]
	v_mfma_f32_16x16x32_bf16 v[52:55], v[152:155], v[190:193], v[52:55]
	v_mfma_f32_16x16x32_bf16 v[48:51], v[172:175], v[190:193], v[48:51]
	v_mfma_f32_16x16x32_bf16 v[44:47], v[152:155], v[198:201], v[44:47]
	v_mfma_f32_16x16x32_bf16 v[40:43], v[172:175], v[198:201], v[40:43]
	v_mfma_f32_16x16x32_bf16 v[36:39], v[152:155], v[206:209], v[36:39]
	v_mfma_f32_16x16x32_bf16 v[32:35], v[172:175], v[206:209], v[32:35]
	s_setprio 0
	s_barrier
	s_add_u32 s66, s42, 0x20000
	ds_read_b128 v[178:181], v164 offset:16384
	ds_read_b128 v[182:185], v164 offset:17408
	ds_read_b128 v[186:189], v164 offset:18432
	ds_read_b128 v[190:193], v164 offset:19456
	ds_read_b128 v[194:197], v164 offset:20480
	ds_read_b128 v[198:201], v164 offset:21504
	ds_read_b128 v[202:205], v164 offset:22528
	ds_read_b128 v[206:209], v164 offset:23552
	s_mov_b32 m0, s35
	s_nop 0
	global_load_lds_dwordx4 v159, s[42:43]
	s_addc_u32 s67, s43, 0
	s_mov_b32 m0, s36
	s_nop 0
	global_load_lds_dwordx4 v159, s[66:67]
	s_add_u32 s66, s42, 0x40000
	s_addc_u32 s67, s43, 0
	s_mov_b32 m0, s37
	s_nop 0
	global_load_lds_dwordx4 v159, s[66:67]
	s_add_u32 s66, s42, 0x60000
	s_addc_u32 s67, s43, 0
	s_mov_b32 m0, s44
	s_nop 0
	global_load_lds_dwordx4 v159, s[66:67]
	s_mov_b32 m0, s34
	s_nop 0
	global_load_lds_dwordx4 v158, s[38:39]
	s_add_u32 s66, s38, 0x20000
	s_addc_u32 s67, s39, 0
	s_mov_b32 m0, s45
	s_nop 0
	global_load_lds_dwordx4 v158, s[66:67]
	s_waitcnt vmcnt(8)
	s_waitcnt lgkmcnt(0)
	s_barrier
	s_setprio 1
	v_mfma_f32_16x16x32_bf16 v[92:95], v[112:115], v[178:181], v[92:95]
	v_mfma_f32_16x16x32_bf16 v[88:91], v[140:143], v[178:181], v[88:91]
	v_mfma_f32_16x16x32_bf16 v[84:87], v[112:115], v[186:189], v[84:87]
	v_mfma_f32_16x16x32_bf16 v[80:83], v[140:143], v[186:189], v[80:83]
	v_mfma_f32_16x16x32_bf16 v[76:79], v[112:115], v[194:197], v[76:79]
	v_mfma_f32_16x16x32_bf16 v[72:75], v[140:143], v[194:197], v[72:75]
	v_mfma_f32_16x16x32_bf16 v[68:71], v[112:115], v[202:205], v[68:71]
	v_mfma_f32_16x16x32_bf16 v[64:67], v[140:143], v[202:205], v[64:67]
	v_mfma_f32_16x16x32_bf16 v[92:95], v[116:119], v[182:185], v[92:95]
	v_mfma_f32_16x16x32_bf16 v[88:91], v[144:147], v[182:185], v[88:91]
	v_mfma_f32_16x16x32_bf16 v[84:87], v[116:119], v[190:193], v[84:87]
	v_mfma_f32_16x16x32_bf16 v[80:83], v[144:147], v[190:193], v[80:83]
	v_mfma_f32_16x16x32_bf16 v[76:79], v[116:119], v[198:201], v[76:79]
	v_mfma_f32_16x16x32_bf16 v[72:75], v[144:147], v[198:201], v[72:75]
	v_mfma_f32_16x16x32_bf16 v[68:71], v[116:119], v[206:209], v[68:71]
	v_mfma_f32_16x16x32_bf16 v[64:67], v[144:147], v[206:209], v[64:67]
	v_mfma_f32_16x16x32_bf16 v[28:31], v[148:151], v[178:181], v[28:31]
	v_mfma_f32_16x16x32_bf16 v[24:27], v[168:171], v[178:181], v[24:27]
	v_mfma_f32_16x16x32_bf16 v[20:23], v[148:151], v[186:189], v[20:23]
	v_mfma_f32_16x16x32_bf16 v[16:19], v[168:171], v[186:189], v[16:19]
	v_mfma_f32_16x16x32_bf16 v[12:15], v[148:151], v[194:197], v[12:15]
	v_mfma_f32_16x16x32_bf16 v[8:11], v[168:171], v[194:197], v[8:11]
	v_mfma_f32_16x16x32_bf16 v[4:7], v[148:151], v[202:205], v[4:7]
	v_mfma_f32_16x16x32_bf16 v[0:3], v[168:171], v[202:205], v[0:3]
	v_mfma_f32_16x16x32_bf16 v[28:31], v[152:155], v[182:185], v[28:31]
	v_mfma_f32_16x16x32_bf16 v[24:27], v[172:175], v[182:185], v[24:27]
	v_mfma_f32_16x16x32_bf16 v[20:23], v[152:155], v[190:193], v[20:23]
	v_mfma_f32_16x16x32_bf16 v[16:19], v[172:175], v[190:193], v[16:19]
	v_mfma_f32_16x16x32_bf16 v[12:15], v[152:155], v[198:201], v[12:15]
	v_mfma_f32_16x16x32_bf16 v[8:11], v[172:175], v[198:201], v[8:11]
	v_mfma_f32_16x16x32_bf16 v[4:7], v[152:155], v[206:209], v[4:7]
	v_mfma_f32_16x16x32_bf16 v[0:3], v[172:175], v[206:209], v[0:3]
	s_setprio 0
	s_barrier
; #define PG8_STAGE(bufoff, gbase, voff, p64) do { _Pragma("unroll") for (int _i = 0; _i < 2; ++_i) { \
;         const char* _gb = (const char*)(gbase) + (size_t)_i * (p64); const unsigned _la = ldsbase + (unsigned)(bufoff) + (unsigned)_i * 8192u; \
;         asm volatile("s_mov_b32 m0, %0\n\ts_nop 0\n\tglobal_load_lds_dwordx4 %1, %2" :: "s"(_la), "v"(voff), "s"(_gb) : "memory"); } } while (0)
; #define PG8_LDA(dst, b, h) do { _Pragma("unroll") for (int m = 0; m < 4; ++m) _Pragma("unroll") for (int k = 0; k < 2; ++k) dst[m][k] = *(const LAS bf16x8*)(lds + PG8_SA(b, h) + aoff + m * 2048 + k * 1024); } while (0)
; #define PG8_LDB(dst, b, h) do { _Pragma("unroll") for (int n = 0; n < 2; ++n) _Pragma("unroll") for (int k = 0; k < 2; ++k) dst[n][k] = *(const LAS bf16x8*)(lds + PG8_SB(b, h) + boff + n * 2048 + k * 1024); } while (0)
; #define PG8_MMA(ai, bj, At, Bt) do { __builtin_amdgcn_s_setprio(1); _Pragma("unroll") for (int m = 0; m < 4; ++m) _Pragma("unroll") for (int n = 0; n < 2; ++n) _Pragma("unroll") for (int k = 0; k < 2; ++k) \
;         acc[ai][bj][m][n] = __builtin_amdgcn_mfma_f32_16x16x32_bf16(Bt[n][k], At[m][k], acc[ai][bj][m][n], 0, 0, 0); __builtin_amdgcn_s_setprio(0); } while (0)
; #define PG8_WAIT_V(n) asm volatile("s_waitcnt vmcnt(" #n ")" ::: "memory")
; #define PG8_WAIT_L(n) asm volatile("s_waitcnt lgkmcnt(" #n ")" ::: "memory")
; #define PG8_BAR __builtin_amdgcn_s_barrier()
; #define PG8_SCHED __builtin_amdgcn_sched_barrier(0)
; template <class Epi, class Sched>
; __device__ __forceinline__ void gemm_phase(LAS unsigned char* lds, const Sched& S, const Epi& E) {
;     ...
;             PG8_LDB(B0, 1, 0); PG8_LDB(B1, 1, 1); PG8_SCHED; PG8_LDA(At, 1, 0); PG8_STAGE(PG8_SA(0, 1), a2 + hA2, vA2, hA2 / 2);
;             PG8_WAIT_V(8); PG8_WAIT_L(0); PG8_BAR; PG8_MMA(0, 0, At, B0); PG8_MMA(0, 1, At, B1); PG8_BAR; PG8_SCHED;
;             PG8_LDA(At, 1, 1); PG8_STAGE(PG8_SB(1, 0), b3, vB2, hB2 / 2); PG8_STAGE(PG8_SB(1, 1), b3 + hB2, vB2, hB2 / 2); PG8_STAGE(PG8_SA(1, 0), a3, vA2, hA2 / 2);
;             PG8_WAIT_V(8); PG8_WAIT_L(0); PG8_BAR; PG8_MMA(1, 0, At, B0); PG8_MMA(1, 1, At, B1); PG8_BAR; PG8_SCHED;
;         }
	ds_read_b128 v[112:115], v165
	ds_read_b128 v[116:119], v165 offset:1024
	ds_read_b128 v[140:143], v165 offset:2048
	ds_read_b128 v[144:147], v165 offset:3072
	ds_read_b128 v[148:151], v166
	ds_read_b128 v[152:155], v166 offset:1024
	ds_read_b128 v[168:171], v166 offset:2048
	ds_read_b128 v[172:175], v166 offset:3072
	ds_read_b128 v[178:181], v164 offset:32768
	ds_read_b128 v[182:185], v164 offset:33792
	ds_read_b128 v[186:189], v164 offset:34816
	ds_read_b128 v[190:193], v164 offset:35840
	ds_read_b128 v[194:197], v164 offset:36864
	ds_read_b128 v[198:201], v164 offset:37888
	ds_read_b128 v[202:205], v164 offset:38912
	ds_read_b128 v[206:209], v164 offset:39936
	s_add_u32 s66, s38, 0x40000
	s_addc_u32 s67, s39, 0
	s_mov_b32 m0, s46
	s_nop 0
	global_load_lds_dwordx4 v158, s[66:67]
	s_add_u32 s66, s38, 0x60000
	s_addc_u32 s67, s39, 0
	s_mov_b32 m0, s47
	s_nop 0
	global_load_lds_dwordx4 v158, s[66:67]
	s_waitcnt vmcnt(8)
	s_waitcnt lgkmcnt(0)
	s_barrier
	s_setprio 1
	v_mfma_f32_16x16x32_bf16 v[132:135], v[112:115], v[178:181], v[132:135]
	v_mfma_f32_16x16x32_bf16 v[128:131], v[140:143], v[178:181], v[128:131]
	v_mfma_f32_16x16x32_bf16 v[124:127], v[112:115], v[186:189], v[124:127]
	v_mfma_f32_16x16x32_bf16 v[120:123], v[140:143], v[186:189], v[120:123]
	v_mfma_f32_16x16x32_bf16 v[108:111], v[112:115], v[194:197], v[108:111]
	v_mfma_f32_16x16x32_bf16 v[104:107], v[140:143], v[194:197], v[104:107]
	v_mfma_f32_16x16x32_bf16 v[100:103], v[112:115], v[202:205], v[100:103]
	v_mfma_f32_16x16x32_bf16 v[96:99], v[140:143], v[202:205], v[96:99]
	v_mfma_f32_16x16x32_bf16 v[132:135], v[116:119], v[182:185], v[132:135]
	v_mfma_f32_16x16x32_bf16 v[128:131], v[144:147], v[182:185], v[128:131]
	v_mfma_f32_16x16x32_bf16 v[124:127], v[116:119], v[190:193], v[124:127]
	v_mfma_f32_16x16x32_bf16 v[120:123], v[144:147], v[190:193], v[120:123]
	v_mfma_f32_16x16x32_bf16 v[108:111], v[116:119], v[198:201], v[108:111]
	v_mfma_f32_16x16x32_bf16 v[104:107], v[144:147], v[198:201], v[104:107]
	v_mfma_f32_16x16x32_bf16 v[100:103], v[116:119], v[206:209], v[100:103]
	v_mfma_f32_16x16x32_bf16 v[96:99], v[144:147], v[206:209], v[96:99]
	v_mfma_f32_16x16x32_bf16 v[60:63], v[148:151], v[178:181], v[60:63]
	v_mfma_f32_16x16x32_bf16 v[56:59], v[168:171], v[178:181], v[56:59]
	v_mfma_f32_16x16x32_bf16 v[52:55], v[148:151], v[186:189], v[52:55]
	v_mfma_f32_16x16x32_bf16 v[48:51], v[168:171], v[186:189], v[48:51]
	v_mfma_f32_16x16x32_bf16 v[44:47], v[148:151], v[194:197], v[44:47]
	v_mfma_f32_16x16x32_bf16 v[40:43], v[168:171], v[194:197], v[40:43]
	v_mfma_f32_16x16x32_bf16 v[36:39], v[148:151], v[202:205], v[36:39]
	v_mfma_f32_16x16x32_bf16 v[32:35], v[168:171], v[202:205], v[32:35]
	v_mfma_f32_16x16x32_bf16 v[60:63], v[152:155], v[182:185], v[60:63]
	v_mfma_f32_16x16x32_bf16 v[56:59], v[172:175], v[182:185], v[56:59]
	v_mfma_f32_16x16x32_bf16 v[52:55], v[152:155], v[190:193], v[52:55]
	v_mfma_f32_16x16x32_bf16 v[48:51], v[172:175], v[190:193], v[48:51]
	v_mfma_f32_16x16x32_bf16 v[44:47], v[152:155], v[198:201], v[44:47]
	v_mfma_f32_16x16x32_bf16 v[40:43], v[172:175], v[198:201], v[40:43]
	v_mfma_f32_16x16x32_bf16 v[36:39], v[152:155], v[206:209], v[36:39]
	v_mfma_f32_16x16x32_bf16 v[32:35], v[172:175], v[206:209], v[32:35]
	s_setprio 0
	s_barrier
	s_add_u32 s66, s42, 0x80
	s_addc_u32 s67, s43, 0
	ds_read_b128 v[178:181], v164 offset:49152
	ds_read_b128 v[182:185], v164 offset:50176
	ds_read_b128 v[186:189], v164 offset:51200
	ds_read_b128 v[190:193], v164 offset:52224
	ds_read_b128 v[194:197], v164 offset:53248
	ds_read_b128 v[198:201], v164 offset:54272
	ds_read_b128 v[202:205], v164 offset:55296
	ds_read_b128 v[206:209], v164 offset:56320
	s_mov_b32 m0, s52
	s_nop 0
	global_load_lds_dwordx4 v159, s[66:67]
	s_add_u32 s66, s42, 0x20080
	s_addc_u32 s67, s43, 0
	s_mov_b32 m0, s53
	s_nop 0
	global_load_lds_dwordx4 v159, s[66:67]
	s_add_u32 s66, s42, 0x40080
	s_addc_u32 s67, s43, 0
	s_mov_b32 m0, s56
	s_nop 0
	global_load_lds_dwordx4 v159, s[66:67]
	s_add_u32 s42, s42, 0x60080
	s_addc_u32 s43, s43, 0
	s_mov_b32 m0, s57
	s_nop 0
	global_load_lds_dwordx4 v159, s[42:43]
	s_mov_b32 m0, s54
	s_nop 0
	global_load_lds_dwordx4 v158, s[40:41]
	s_add_u32 s38, s38, 0x20080
	s_addc_u32 s39, s39, 0
	s_mov_b32 m0, s55
	s_nop 0
	global_load_lds_dwordx4 v158, s[38:39]
	s_waitcnt vmcnt(8)
	s_waitcnt lgkmcnt(0)
	s_barrier
	s_setprio 1
	v_mfma_f32_16x16x32_bf16 v[92:95], v[112:115], v[178:181], v[92:95]
	v_mfma_f32_16x16x32_bf16 v[88:91], v[140:143], v[178:181], v[88:91]
	v_mfma_f32_16x16x32_bf16 v[84:87], v[112:115], v[186:189], v[84:87]
	v_mfma_f32_16x16x32_bf16 v[80:83], v[140:143], v[186:189], v[80:83]
	v_mfma_f32_16x16x32_bf16 v[76:79], v[112:115], v[194:197], v[76:79]
	v_mfma_f32_16x16x32_bf16 v[72:75], v[140:143], v[194:197], v[72:75]
	v_mfma_f32_16x16x32_bf16 v[68:71], v[112:115], v[202:205], v[68:71]
	v_mfma_f32_16x16x32_bf16 v[64:67], v[140:143], v[202:205], v[64:67]
	v_mfma_f32_16x16x32_bf16 v[92:95], v[116:119], v[182:185], v[92:95]
	v_mfma_f32_16x16x32_bf16 v[88:91], v[144:147], v[182:185], v[88:91]
	v_mfma_f32_16x16x32_bf16 v[84:87], v[116:119], v[190:193], v[84:87]
	v_mfma_f32_16x16x32_bf16 v[80:83], v[144:147], v[190:193], v[80:83]
	v_mfma_f32_16x16x32_bf16 v[76:79], v[116:119], v[198:201], v[76:79]
	v_mfma_f32_16x16x32_bf16 v[72:75], v[144:147], v[198:201], v[72:75]
	v_mfma_f32_16x16x32_bf16 v[68:71], v[116:119], v[206:209], v[68:71]
	v_mfma_f32_16x16x32_bf16 v[64:67], v[144:147], v[206:209], v[64:67]
	v_mfma_f32_16x16x32_bf16 v[28:31], v[148:151], v[178:181], v[28:31]
	v_mfma_f32_16x16x32_bf16 v[24:27], v[168:171], v[178:181], v[24:27]
	v_mfma_f32_16x16x32_bf16 v[20:23], v[148:151], v[186:189], v[20:23]
	v_mfma_f32_16x16x32_bf16 v[16:19], v[168:171], v[186:189], v[16:19]
	v_mfma_f32_16x16x32_bf16 v[12:15], v[148:151], v[194:197], v[12:15]
	v_mfma_f32_16x16x32_bf16 v[8:11], v[168:171], v[194:197], v[8:11]
	v_mfma_f32_16x16x32_bf16 v[4:7], v[148:151], v[202:205], v[4:7]
	v_mfma_f32_16x16x32_bf16 v[0:3], v[168:171], v[202:205], v[0:3]
	v_mfma_f32_16x16x32_bf16 v[28:31], v[152:155], v[182:185], v[28:31]
	v_mfma_f32_16x16x32_bf16 v[24:27], v[172:175], v[182:185], v[24:27]
	v_mfma_f32_16x16x32_bf16 v[20:23], v[152:155], v[190:193], v[20:23]
	v_mfma_f32_16x16x32_bf16 v[16:19], v[172:175], v[190:193], v[16:19]
	v_mfma_f32_16x16x32_bf16 v[12:15], v[152:155], v[198:201], v[12:15]
	v_mfma_f32_16x16x32_bf16 v[8:11], v[172:175], v[198:201], v[8:11]
	v_mfma_f32_16x16x32_bf16 v[4:7], v[152:155], v[206:209], v[4:7]
	v_mfma_f32_16x16x32_bf16 v[0:3], v[172:175], v[206:209], v[0:3]
	s_setprio 0
	s_barrier
	s_add_i32 s65, s65, 2
	s_add_u32 s26, s26, 0x100
	s_addc_u32 s27, s27, 0
	s_add_u32 s62, s62, 0x100
	s_addc_u32 s63, s63, 0
	s_cmp_gt_u32 s65, 13
	s_cbranch_scc0 .LBB0_981
	s_and_b64 vcc, exec, s[14:15]
	s_cbranch_vccz .LBB0_984
	s_barrier

; #define PG8_STAGE(bufoff, gbase, voff, p64) do { _Pragma("unroll") for (int _i = 0; _i < 2; ++_i) { \
;         const char* _gb = (const char*)(gbase) + (size_t)_i * (p64); const unsigned _la = ldsbase + (unsigned)(bufoff) + (unsigned)_i * 8192u; \
;         asm volatile("s_mov_b32 m0, %0\n\ts_nop 0\n\tglobal_load_lds_dwordx4 %1, %2" :: "s"(_la), "v"(voff), "s"(_gb) : "memory"); } } while (0)
; #define PG8_LDA(dst, b, h) do { _Pragma("unroll") for (int m = 0; m < 4; ++m) _Pragma("unroll") for (int k = 0; k < 2; ++k) dst[m][k] = *(const LAS bf16x8*)(lds + PG8_SA(b, h) + aoff + m * 2048 + k * 1024); } while (0)
; #define PG8_LDB(dst, b, h) do { _Pragma("unroll") for (int n = 0; n < 2; ++n) _Pragma("unroll") for (int k = 0; k < 2; ++k) dst[n][k] = *(const LAS bf16x8*)(lds + PG8_SB(b, h) + boff + n * 2048 + k * 1024); } while (0)
; #define PG8_WAIT_V(n) asm volatile("s_waitcnt vmcnt(" #n ")" ::: "memory")
; #define PG8_WAIT_L(n) asm volatile("s_waitcnt lgkmcnt(" #n ")" ::: "memory")
; #define PG8_BAR __builtin_amdgcn_s_barrier()
; template <class Epi, class Sched>
; __device__ __forceinline__ void gemm_phase(LAS unsigned char* lds, const Sched& S, const Epi& E) {
;     ...
;             const bool last = (t == nt - 2);
;             const char* a1 = cA + (size_t)(t + 1) * kstep;
;             const char* a2 = last ? nA : cA + (size_t)(t + 2) * kstep; const char* b2 = last ? nB : cB + (size_t)(t + 2) * kstep;
;             const char* a3 = a2 + kstep; const char* b3 = b2 + kstep;
;             const unsigned vA2 = voffA, vB2 = voffB, hA2 = hA, hB2 = hB;
;             PG8_LDB(B0, 0, 0); PG8_LDB(B1, 0, 1); PG8_SCHED; PG8_LDA(At, 0, 0); PG8_STAGE(PG8_SA(1, 1), a1 + hA, voffA, hA / 2);
;             PG8_WAIT_V(8); PG8_WAIT_L(0); PG8_BAR; PG8_MMA(0, 0, At, B0); PG8_MMA(0, 1, At, B1); PG8_BAR; PG8_SCHED;
;             PG8_LDA(At, 0, 1); PG8_STAGE(PG8_SB(0, 0), b2, vB2, hB2 / 2); PG8_STAGE(PG8_SB(0, 1), b2 + hB2, vB2, hB2 / 2); PG8_STAGE(PG8_SA(0, 0), a2, vA2, hA2 / 2);
;             PG8_WAIT_V(8); PG8_WAIT_L(0); PG8_BAR; PG8_MMA(1, 0, At, B0); PG8_MMA(1, 1, At, B1); PG8_BAR; PG8_SCHED;
;             PG8_LDB(B0, 1, 0); PG8_LDB(B1, 1, 1); PG8_SCHED; PG8_LDA(At, 1, 0); PG8_STAGE(PG8_SA(0, 1), a2 + hA2, vA2, hA2 / 2);
;             PG8_WAIT_V(8); PG8_WAIT_L(0); PG8_BAR; PG8_MMA(0, 0, At, B0); PG8_MMA(0, 1, At, B1); PG8_BAR; PG8_SCHED;
.LBB0_1011:
	ds_read_b128 v[144:147], v138
	ds_read_b128 v[148:151], v138 offset:1024
	ds_read_b128 v[152:155], v138 offset:2048
	ds_read_b128 v[156:159], v138 offset:3072
	ds_read_b128 v[160:163], v139
	ds_read_b128 v[164:167], v139 offset:1024
	ds_read_b128 v[168:171], v139 offset:2048
	ds_read_b128 v[172:175], v139 offset:3072
	s_add_u32 s30, s26, 0xfffc0080
	s_addc_u32 s38, s27, -1
	s_cmp_eq_u32 s63, 12
	s_cselect_b32 s39, s23, s38
	s_cselect_b32 s38, s22, s30
	s_cselect_b32 s42, s24, s61
	s_cselect_b32 s43, s25, s62
	s_add_u32 s40, s38, 0x80
	s_addc_u32 s41, s39, 0
	ds_read_b128 v[178:181], v140
	ds_read_b128 v[182:185], v140 offset:1024
	ds_read_b128 v[186:189], v140 offset:2048
	ds_read_b128 v[190:193], v140 offset:3072
	ds_read_b128 v[194:197], v140 offset:4096
	ds_read_b128 v[198:201], v140 offset:5120
	ds_read_b128 v[202:205], v140 offset:6144
	ds_read_b128 v[206:209], v140 offset:7168
	s_mov_b32 m0, s57
	s_nop 0
	global_load_lds_dwordx4 v134, s[26:27]
	s_add_u32 s66, s26, 0x20000
	s_addc_u32 s67, s27, 0
	s_mov_b32 m0, s58
	s_nop 0
	global_load_lds_dwordx4 v134, s[66:67]
	s_waitcnt vmcnt(8)
	s_waitcnt lgkmcnt(0)
	s_barrier
	s_setprio 1
	v_mfma_f32_16x16x32_bf16 v[120:123], v[144:147], v[178:181], v[120:123]
	v_mfma_f32_16x16x32_bf16 v[116:119], v[152:155], v[178:181], v[116:119]
	v_mfma_f32_16x16x32_bf16 v[104:107], v[144:147], v[186:189], v[104:107]
	v_mfma_f32_16x16x32_bf16 v[100:103], v[152:155], v[186:189], v[100:103]
	v_mfma_f32_16x16x32_bf16 v[88:91], v[144:147], v[194:197], v[88:91]
	v_mfma_f32_16x16x32_bf16 v[84:87], v[152:155], v[194:197], v[84:87]
	v_mfma_f32_16x16x32_bf16 v[72:75], v[144:147], v[202:205], v[72:75]
	v_mfma_f32_16x16x32_bf16 v[68:71], v[152:155], v[202:205], v[68:71]
	v_mfma_f32_16x16x32_bf16 v[120:123], v[148:151], v[182:185], v[120:123]
	v_mfma_f32_16x16x32_bf16 v[116:119], v[156:159], v[182:185], v[116:119]
	v_mfma_f32_16x16x32_bf16 v[104:107], v[148:151], v[190:193], v[104:107]
	v_mfma_f32_16x16x32_bf16 v[100:103], v[156:159], v[190:193], v[100:103]
	v_mfma_f32_16x16x32_bf16 v[88:91], v[148:151], v[198:201], v[88:91]
	v_mfma_f32_16x16x32_bf16 v[84:87], v[156:159], v[198:201], v[84:87]
	v_mfma_f32_16x16x32_bf16 v[72:75], v[148:151], v[206:209], v[72:75]
	v_mfma_f32_16x16x32_bf16 v[68:71], v[156:159], v[206:209], v[68:71]
	v_mfma_f32_16x16x32_bf16 v[124:127], v[160:163], v[178:181], v[124:127]
	v_mfma_f32_16x16x32_bf16 v[112:115], v[168:171], v[178:181], v[112:115]
	v_mfma_f32_16x16x32_bf16 v[108:111], v[160:163], v[186:189], v[108:111]
	v_mfma_f32_16x16x32_bf16 v[96:99], v[168:171], v[186:189], v[96:99]
	v_mfma_f32_16x16x32_bf16 v[92:95], v[160:163], v[194:197], v[92:95]
	v_mfma_f32_16x16x32_bf16 v[80:83], v[168:171], v[194:197], v[80:83]
	v_mfma_f32_16x16x32_bf16 v[76:79], v[160:163], v[202:205], v[76:79]
	v_mfma_f32_16x16x32_bf16 v[64:67], v[168:171], v[202:205], v[64:67]
	v_mfma_f32_16x16x32_bf16 v[124:127], v[164:167], v[182:185], v[124:127]
	v_mfma_f32_16x16x32_bf16 v[112:115], v[172:175], v[182:185], v[112:115]
	v_mfma_f32_16x16x32_bf16 v[108:111], v[164:167], v[190:193], v[108:111]
	v_mfma_f32_16x16x32_bf16 v[96:99], v[172:175], v[190:193], v[96:99]
	v_mfma_f32_16x16x32_bf16 v[92:95], v[164:167], v[198:201], v[92:95]
	v_mfma_f32_16x16x32_bf16 v[80:83], v[172:175], v[198:201], v[80:83]
	v_mfma_f32_16x16x32_bf16 v[76:79], v[164:167], v[206:209], v[76:79]
	v_mfma_f32_16x16x32_bf16 v[64:67], v[172:175], v[206:209], v[64:67]
	s_setprio 0
	s_barrier
	s_add_u32 s66, s42, 0x20000
	ds_read_b128 v[178:181], v140 offset:16384
	ds_read_b128 v[182:185], v140 offset:17408
	ds_read_b128 v[186:189], v140 offset:18432
	ds_read_b128 v[190:193], v140 offset:19456
	ds_read_b128 v[194:197], v140 offset:20480
	ds_read_b128 v[198:201], v140 offset:21504
	ds_read_b128 v[202:205], v140 offset:22528
	ds_read_b128 v[206:209], v140 offset:23552
	s_mov_b32 m0, s35
	s_nop 0
	global_load_lds_dwordx4 v135, s[42:43]
	s_addc_u32 s67, s43, 0
	s_mov_b32 m0, s36
	s_nop 0
	global_load_lds_dwordx4 v135, s[66:67]
	s_add_u32 s66, s42, 0x40000
	s_addc_u32 s67, s43, 0
	s_mov_b32 m0, s37
	s_nop 0
	global_load_lds_dwordx4 v135, s[66:67]
	s_add_u32 s66, s42, 0x60000
	s_addc_u32 s67, s43, 0
	s_mov_b32 m0, s44
	s_nop 0
	global_load_lds_dwordx4 v135, s[66:67]
	s_mov_b32 m0, s34
	s_nop 0
	global_load_lds_dwordx4 v134, s[38:39]
	s_add_u32 s66, s38, 0x20000
	s_addc_u32 s67, s39, 0
	s_mov_b32 m0, s45
	s_nop 0
	global_load_lds_dwordx4 v134, s[66:67]
	s_waitcnt vmcnt(8)
	s_waitcnt lgkmcnt(0)
	s_barrier
	s_setprio 1
	v_mfma_f32_16x16x32_bf16 v[56:59], v[144:147], v[178:181], v[56:59]
	v_mfma_f32_16x16x32_bf16 v[52:55], v[152:155], v[178:181], v[52:55]
	v_mfma_f32_16x16x32_bf16 v[40:43], v[144:147], v[186:189], v[40:43]
	v_mfma_f32_16x16x32_bf16 v[36:39], v[152:155], v[186:189], v[36:39]
	v_mfma_f32_16x16x32_bf16 v[24:27], v[144:147], v[194:197], v[24:27]
	v_mfma_f32_16x16x32_bf16 v[20:23], v[152:155], v[194:197], v[20:23]
	v_mfma_f32_16x16x32_bf16 v[8:11], v[144:147], v[202:205], v[8:11]
	v_mfma_f32_16x16x32_bf16 v[4:7], v[152:155], v[202:205], v[4:7]
	v_mfma_f32_16x16x32_bf16 v[56:59], v[148:151], v[182:185], v[56:59]
	v_mfma_f32_16x16x32_bf16 v[52:55], v[156:159], v[182:185], v[52:55]
	v_mfma_f32_16x16x32_bf16 v[40:43], v[148:151], v[190:193], v[40:43]
	v_mfma_f32_16x16x32_bf16 v[36:39], v[156:159], v[190:193], v[36:39]
	v_mfma_f32_16x16x32_bf16 v[24:27], v[148:151], v[198:201], v[24:27]
	v_mfma_f32_16x16x32_bf16 v[20:23], v[156:159], v[198:201], v[20:23]
	v_mfma_f32_16x16x32_bf16 v[8:11], v[148:151], v[206:209], v[8:11]
	v_mfma_f32_16x16x32_bf16 v[4:7], v[156:159], v[206:209], v[4:7]
	v_mfma_f32_16x16x32_bf16 v[60:63], v[160:163], v[178:181], v[60:63]
	v_mfma_f32_16x16x32_bf16 v[48:51], v[168:171], v[178:181], v[48:51]
	v_mfma_f32_16x16x32_bf16 v[44:47], v[160:163], v[186:189], v[44:47]
	v_mfma_f32_16x16x32_bf16 v[32:35], v[168:171], v[186:189], v[32:35]
	v_mfma_f32_16x16x32_bf16 v[28:31], v[160:163], v[194:197], v[28:31]
	v_mfma_f32_16x16x32_bf16 v[16:19], v[168:171], v[194:197], v[16:19]
	v_mfma_f32_16x16x32_bf16 v[12:15], v[160:163], v[202:205], v[12:15]
	v_mfma_f32_16x16x32_bf16 v[0:3], v[168:171], v[202:205], v[0:3]
	v_mfma_f32_16x16x32_bf16 v[60:63], v[164:167], v[182:185], v[60:63]
	v_mfma_f32_16x16x32_bf16 v[48:51], v[172:175], v[182:185], v[48:51]
	v_mfma_f32_16x16x32_bf16 v[44:47], v[164:167], v[190:193], v[44:47]
	v_mfma_f32_16x16x32_bf16 v[32:35], v[172:175], v[190:193], v[32:35]
	v_mfma_f32_16x16x32_bf16 v[28:31], v[164:167], v[198:201], v[28:31]
	v_mfma_f32_16x16x32_bf16 v[16:19], v[172:175], v[198:201], v[16:19]
	v_mfma_f32_16x16x32_bf16 v[12:15], v[164:167], v[206:209], v[12:15]
	v_mfma_f32_16x16x32_bf16 v[0:3], v[172:175], v[206:209], v[0:3]
	s_setprio 0
	s_barrier
; #define PG8_STAGE(bufoff, gbase, voff, p64) do { _Pragma("unroll") for (int _i = 0; _i < 2; ++_i) { \
;         const char* _gb = (const char*)(gbase) + (size_t)_i * (p64); const unsigned _la = ldsbase + (unsigned)(bufoff) + (unsigned)_i * 8192u; \
;         asm volatile("s_mov_b32 m0, %0\n\ts_nop 0\n\tglobal_load_lds_dwordx4 %1, %2" :: "s"(_la), "v"(voff), "s"(_gb) : "memory"); } } while (0)
; #define PG8_LDA(dst, b, h) do { _Pragma("unroll") for (int m = 0; m < 4; ++m) _Pragma("unroll") for (int k = 0; k < 2; ++k) dst[m][k] = *(const LAS bf16x8*)(lds + PG8_SA(b, h) + aoff + m * 2048 + k * 1024); } while (0)
; #define PG8_LDB(dst, b, h) do { _Pragma("unroll") for (int n = 0; n < 2; ++n) _Pragma("unroll") for (int k = 0; k < 2; ++k) dst[n][k] = *(const LAS bf16x8*)(lds + PG8_SB(b, h) + boff + n * 2048 + k * 1024); } while (0)
; #define PG8_MMA(ai, bj, At, Bt) do { __builtin_amdgcn_s_setprio(1); _Pragma("unroll") for (int m = 0; m < 4; ++m) _Pragma("unroll") for (int n = 0; n < 2; ++n) _Pragma("unroll") for (int k = 0; k < 2; ++k) \
;         acc[ai][bj][m][n] = __builtin_amdgcn_mfma_f32_16x16x32_bf16(Bt[n][k], At[m][k], acc[ai][bj][m][n], 0, 0, 0); __builtin_amdgcn_s_setprio(0); } while (0)
; #define PG8_WAIT_V(n) asm volatile("s_waitcnt vmcnt(" #n ")" ::: "memory")
; #define PG8_WAIT_L(n) asm volatile("s_waitcnt lgkmcnt(" #n ")" ::: "memory")
; #define PG8_BAR __builtin_amdgcn_s_barrier()
; #define PG8_SCHED __builtin_amdgcn_sched_barrier(0)
; template <class Epi, class Sched>
; __device__ __forceinline__ void gemm_phase(LAS unsigned char* lds, const Sched& S, const Epi& E) {
;     ...
;             PG8_LDB(B0, 1, 0); PG8_LDB(B1, 1, 1); PG8_SCHED; PG8_LDA(At, 1, 0); PG8_STAGE(PG8_SA(0, 1), a2 + hA2, vA2, hA2 / 2);
;             PG8_WAIT_V(8); PG8_WAIT_L(0); PG8_BAR; PG8_MMA(0, 0, At, B0); PG8_MMA(0, 1, At, B1); PG8_BAR; PG8_SCHED;
;             PG8_LDA(At, 1, 1); PG8_STAGE(PG8_SB(1, 0), b3, vB2, hB2 / 2); PG8_STAGE(PG8_SB(1, 1), b3 + hB2, vB2, hB2 / 2); PG8_STAGE(PG8_SA(1, 0), a3, vA2, hA2 / 2);
;             PG8_WAIT_V(8); PG8_WAIT_L(0); PG8_BAR; PG8_MMA(1, 0, At, B0); PG8_MMA(1, 1, At, B1); PG8_BAR; PG8_SCHED;
;         }
	ds_read_b128 v[144:147], v141
	ds_read_b128 v[148:151], v141 offset:1024
	ds_read_b128 v[152:155], v141 offset:2048
	ds_read_b128 v[156:159], v141 offset:3072
	ds_read_b128 v[160:163], v142
	ds_read_b128 v[164:167], v142 offset:1024
	ds_read_b128 v[168:171], v142 offset:2048
	ds_read_b128 v[172:175], v142 offset:3072
	ds_read_b128 v[178:181], v140 offset:32768
	ds_read_b128 v[182:185], v140 offset:33792
	ds_read_b128 v[186:189], v140 offset:34816
	ds_read_b128 v[190:193], v140 offset:35840
	ds_read_b128 v[194:197], v140 offset:36864
	ds_read_b128 v[198:201], v140 offset:37888
	ds_read_b128 v[202:205], v140 offset:38912
	ds_read_b128 v[206:209], v140 offset:39936
	s_add_u32 s66, s38, 0x40000
	s_addc_u32 s67, s39, 0
	s_mov_b32 m0, s46
	s_nop 0
	global_load_lds_dwordx4 v134, s[66:67]
	s_add_u32 s66, s38, 0x60000
	s_addc_u32 s67, s39, 0
	s_mov_b32 m0, s47
	s_nop 0
	global_load_lds_dwordx4 v134, s[66:67]
	s_waitcnt vmcnt(8)
	s_waitcnt lgkmcnt(0)
	s_barrier
	s_setprio 1
	v_mfma_f32_16x16x32_bf16 v[120:123], v[144:147], v[178:181], v[120:123]
	v_mfma_f32_16x16x32_bf16 v[116:119], v[152:155], v[178:181], v[116:119]
	v_mfma_f32_16x16x32_bf16 v[104:107], v[144:147], v[186:189], v[104:107]
	v_mfma_f32_16x16x32_bf16 v[100:103], v[152:155], v[186:189], v[100:103]
	v_mfma_f32_16x16x32_bf16 v[88:91], v[144:147], v[194:197], v[88:91]
	v_mfma_f32_16x16x32_bf16 v[84:87], v[152:155], v[194:197], v[84:87]
	v_mfma_f32_16x16x32_bf16 v[72:75], v[144:147], v[202:205], v[72:75]
	v_mfma_f32_16x16x32_bf16 v[68:71], v[152:155], v[202:205], v[68:71]
	v_mfma_f32_16x16x32_bf16 v[120:123], v[148:151], v[182:185], v[120:123]
	v_mfma_f32_16x16x32_bf16 v[116:119], v[156:159], v[182:185], v[116:119]
	v_mfma_f32_16x16x32_bf16 v[104:107], v[148:151], v[190:193], v[104:107]
	v_mfma_f32_16x16x32_bf16 v[100:103], v[156:159], v[190:193], v[100:103]
	v_mfma_f32_16x16x32_bf16 v[88:91], v[148:151], v[198:201], v[88:91]
	v_mfma_f32_16x16x32_bf16 v[84:87], v[156:159], v[198:201], v[84:87]
	v_mfma_f32_16x16x32_bf16 v[72:75], v[148:151], v[206:209], v[72:75]
	v_mfma_f32_16x16x32_bf16 v[68:71], v[156:159], v[206:209], v[68:71]
	v_mfma_f32_16x16x32_bf16 v[124:127], v[160:163], v[178:181], v[124:127]
	v_mfma_f32_16x16x32_bf16 v[112:115], v[168:171], v[178:181], v[112:115]
	v_mfma_f32_16x16x32_bf16 v[108:111], v[160:163], v[186:189], v[108:111]
	v_mfma_f32_16x16x32_bf16 v[96:99], v[168:171], v[186:189], v[96:99]
	v_mfma_f32_16x16x32_bf16 v[92:95], v[160:163], v[194:197], v[92:95]
	v_mfma_f32_16x16x32_bf16 v[80:83], v[168:171], v[194:197], v[80:83]
	v_mfma_f32_16x16x32_bf16 v[76:79], v[160:163], v[202:205], v[76:79]
	v_mfma_f32_16x16x32_bf16 v[64:67], v[168:171], v[202:205], v[64:67]
	v_mfma_f32_16x16x32_bf16 v[124:127], v[164:167], v[182:185], v[124:127]
	v_mfma_f32_16x16x32_bf16 v[112:115], v[172:175], v[182:185], v[112:115]
	v_mfma_f32_16x16x32_bf16 v[108:111], v[164:167], v[190:193], v[108:111]
	v_mfma_f32_16x16x32_bf16 v[96:99], v[172:175], v[190:193], v[96:99]
	v_mfma_f32_16x16x32_bf16 v[92:95], v[164:167], v[198:201], v[92:95]
	v_mfma_f32_16x16x32_bf16 v[80:83], v[172:175], v[198:201], v[80:83]
	v_mfma_f32_16x16x32_bf16 v[76:79], v[164:167], v[206:209], v[76:79]
	v_mfma_f32_16x16x32_bf16 v[64:67], v[172:175], v[206:209], v[64:67]
	s_setprio 0
	s_barrier
	s_add_u32 s66, s42, 0x80
	s_addc_u32 s67, s43, 0
	ds_read_b128 v[178:181], v140 offset:49152
	ds_read_b128 v[182:185], v140 offset:50176
	ds_read_b128 v[186:189], v140 offset:51200
	ds_read_b128 v[190:193], v140 offset:52224
	ds_read_b128 v[194:197], v140 offset:53248
	ds_read_b128 v[198:201], v140 offset:54272
	ds_read_b128 v[202:205], v140 offset:55296
	ds_read_b128 v[206:209], v140 offset:56320
	s_mov_b32 m0, s51
	s_nop 0
	global_load_lds_dwordx4 v135, s[66:67]
	s_add_u32 s66, s42, 0x20080
	s_addc_u32 s67, s43, 0
	s_mov_b32 m0, s52
	s_nop 0
	global_load_lds_dwordx4 v135, s[66:67]
	s_add_u32 s66, s42, 0x40080
	s_addc_u32 s67, s43, 0
	s_mov_b32 m0, s55
	s_nop 0
	global_load_lds_dwordx4 v135, s[66:67]
	s_add_u32 s42, s42, 0x60080
	s_addc_u32 s43, s43, 0
	s_mov_b32 m0, s56
	s_nop 0
	global_load_lds_dwordx4 v135, s[42:43]
	s_mov_b32 m0, s53
	s_nop 0
	global_load_lds_dwordx4 v134, s[40:41]
	s_add_u32 s38, s38, 0x20080
	s_addc_u32 s39, s39, 0
	s_mov_b32 m0, s54
	s_nop 0
	global_load_lds_dwordx4 v134, s[38:39]
	s_waitcnt vmcnt(8)
	s_waitcnt lgkmcnt(0)
	s_barrier
	s_setprio 1
	v_mfma_f32_16x16x32_bf16 v[56:59], v[144:147], v[178:181], v[56:59]
	v_mfma_f32_16x16x32_bf16 v[52:55], v[152:155], v[178:181], v[52:55]
	v_mfma_f32_16x16x32_bf16 v[40:43], v[144:147], v[186:189], v[40:43]
	v_mfma_f32_16x16x32_bf16 v[36:39], v[152:155], v[186:189], v[36:39]
	v_mfma_f32_16x16x32_bf16 v[24:27], v[144:147], v[194:197], v[24:27]
	v_mfma_f32_16x16x32_bf16 v[20:23], v[152:155], v[194:197], v[20:23]
	v_mfma_f32_16x16x32_bf16 v[8:11], v[144:147], v[202:205], v[8:11]
	v_mfma_f32_16x16x32_bf16 v[4:7], v[152:155], v[202:205], v[4:7]
	v_mfma_f32_16x16x32_bf16 v[56:59], v[148:151], v[182:185], v[56:59]
	v_mfma_f32_16x16x32_bf16 v[52:55], v[156:159], v[182:185], v[52:55]
	v_mfma_f32_16x16x32_bf16 v[40:43], v[148:151], v[190:193], v[40:43]
	v_mfma_f32_16x16x32_bf16 v[36:39], v[156:159], v[190:193], v[36:39]
	v_mfma_f32_16x16x32_bf16 v[24:27], v[148:151], v[198:201], v[24:27]
	v_mfma_f32_16x16x32_bf16 v[20:23], v[156:159], v[198:201], v[20:23]
	v_mfma_f32_16x16x32_bf16 v[8:11], v[148:151], v[206:209], v[8:11]
	v_mfma_f32_16x16x32_bf16 v[4:7], v[156:159], v[206:209], v[4:7]
	v_mfma_f32_16x16x32_bf16 v[60:63], v[160:163], v[178:181], v[60:63]
	v_mfma_f32_16x16x32_bf16 v[48:51], v[168:171], v[178:181], v[48:51]
	v_mfma_f32_16x16x32_bf16 v[44:47], v[160:163], v[186:189], v[44:47]
	v_mfma_f32_16x16x32_bf16 v[32:35], v[168:171], v[186:189], v[32:35]
	v_mfma_f32_16x16x32_bf16 v[28:31], v[160:163], v[194:197], v[28:31]
	v_mfma_f32_16x16x32_bf16 v[16:19], v[168:171], v[194:197], v[16:19]
	v_mfma_f32_16x16x32_bf16 v[12:15], v[160:163], v[202:205], v[12:15]
	v_mfma_f32_16x16x32_bf16 v[0:3], v[168:171], v[202:205], v[0:3]
	v_mfma_f32_16x16x32_bf16 v[60:63], v[164:167], v[182:185], v[60:63]
	v_mfma_f32_16x16x32_bf16 v[48:51], v[172:175], v[182:185], v[48:51]
	v_mfma_f32_16x16x32_bf16 v[44:47], v[164:167], v[190:193], v[44:47]
	v_mfma_f32_16x16x32_bf16 v[32:35], v[172:175], v[190:193], v[32:35]
	v_mfma_f32_16x16x32_bf16 v[28:31], v[164:167], v[198:201], v[28:31]
	v_mfma_f32_16x16x32_bf16 v[16:19], v[172:175], v[198:201], v[16:19]
	v_mfma_f32_16x16x32_bf16 v[12:15], v[164:167], v[206:209], v[12:15]
	v_mfma_f32_16x16x32_bf16 v[0:3], v[172:175], v[206:209], v[0:3]
	s_setprio 0
	s_barrier
	s_add_i32 s63, s63, 2
	s_add_u32 s26, s26, 0x100
	s_addc_u32 s27, s27, 0
	s_add_u32 s61, s61, 0x100
	s_addc_u32 s62, s62, 0
	s_cmp_gt_u32 s63, 13
	s_cbranch_scc0 .LBB0_1011
	s_and_b64 vcc, exec, s[14:15]
	s_cbranch_vccz .LBB0_1014
	s_barrier

; #define PG8_STAGE(bufoff, gbase, voff, p64) do { _Pragma("unroll") for (int _i = 0; _i < 2; ++_i) { \
;         const char* _gb = (const char*)(gbase) + (size_t)_i * (p64); const unsigned _la = ldsbase + (unsigned)(bufoff) + (unsigned)_i * 8192u; \
;         asm volatile("s_mov_b32 m0, %0\n\ts_nop 0\n\tglobal_load_lds_dwordx4 %1, %2" :: "s"(_la), "v"(voff), "s"(_gb) : "memory"); } } while (0)
; #define PG8_LDA(dst, b, h) do { _Pragma("unroll") for (int m = 0; m < 4; ++m) _Pragma("unroll") for (int k = 0; k < 2; ++k) dst[m][k] = *(const LAS bf16x8*)(lds + PG8_SA(b, h) + aoff + m * 2048 + k * 1024); } while (0)
; #define PG8_LDB(dst, b, h) do { _Pragma("unroll") for (int n = 0; n < 2; ++n) _Pragma("unroll") for (int k = 0; k < 2; ++k) dst[n][k] = *(const LAS bf16x8*)(lds + PG8_SB(b, h) + boff + n * 2048 + k * 1024); } while (0)
; #define PG8_WAIT_V(n) asm volatile("s_waitcnt vmcnt(" #n ")" ::: "memory")
; #define PG8_WAIT_L(n) asm volatile("s_waitcnt lgkmcnt(" #n ")" ::: "memory")
; #define PG8_BAR __builtin_amdgcn_s_barrier()
; template <class Epi, class Sched>
; __device__ __forceinline__ void gemm_phase(LAS unsigned char* lds, const Sched& S, const Epi& E) {
;     ...
;             const bool last = (t == nt - 2);
;             const char* a1 = cA + (size_t)(t + 1) * kstep;
;             const char* a2 = last ? nA : cA + (size_t)(t + 2) * kstep; const char* b2 = last ? nB : cB + (size_t)(t + 2) * kstep;
;             const char* a3 = a2 + kstep; const char* b3 = b2 + kstep;
;             const unsigned vA2 = voffA, vB2 = voffB, hA2 = hA, hB2 = hB;
;             PG8_LDB(B0, 0, 0); PG8_LDB(B1, 0, 1); PG8_SCHED; PG8_LDA(At, 0, 0); PG8_STAGE(PG8_SA(1, 1), a1 + hA, voffA, hA / 2);
;             PG8_WAIT_V(8); PG8_WAIT_L(0); PG8_BAR; PG8_MMA(0, 0, At, B0); PG8_MMA(0, 1, At, B1); PG8_BAR; PG8_SCHED;
;             PG8_LDA(At, 0, 1); PG8_STAGE(PG8_SB(0, 0), b2, vB2, hB2 / 2); PG8_STAGE(PG8_SB(0, 1), b2 + hB2, vB2, hB2 / 2); PG8_STAGE(PG8_SA(0, 0), a2, vA2, hA2 / 2);
;             PG8_WAIT_V(8); PG8_WAIT_L(0); PG8_BAR; PG8_MMA(1, 0, At, B0); PG8_MMA(1, 1, At, B1); PG8_BAR; PG8_SCHED;
;             PG8_LDB(B0, 1, 0); PG8_LDB(B1, 1, 1); PG8_SCHED; PG8_LDA(At, 1, 0); PG8_STAGE(PG8_SA(0, 1), a2 + hA2, vA2, hA2 / 2);
;             PG8_WAIT_V(8); PG8_WAIT_L(0); PG8_BAR; PG8_MMA(0, 0, At, B0); PG8_MMA(0, 1, At, B1); PG8_BAR; PG8_SCHED;
.LBB0_1089:
	ds_read_b128 v[144:147], v138
	ds_read_b128 v[148:151], v138 offset:1024
	ds_read_b128 v[152:155], v138 offset:2048
	ds_read_b128 v[156:159], v138 offset:3072
	ds_read_b128 v[160:163], v139
	ds_read_b128 v[164:167], v139 offset:1024
	ds_read_b128 v[168:171], v139 offset:2048
	ds_read_b128 v[172:175], v139 offset:3072
	s_add_u32 s30, s38, 0xfff80080
	s_addc_u32 s40, s39, -1
	s_cmp_eq_u32 s62, 28
	s_cselect_b32 s41, s25, s40
	s_cselect_b32 s40, s24, s30
	s_cselect_b32 s44, s26, s60
	s_cselect_b32 s45, s27, s61
	s_add_u32 s42, s40, 0x80
	s_addc_u32 s43, s41, 0
	ds_read_b128 v[178:181], v140
	ds_read_b128 v[182:185], v140 offset:1024
	ds_read_b128 v[186:189], v140 offset:2048
	ds_read_b128 v[190:193], v140 offset:3072
	ds_read_b128 v[194:197], v140 offset:4096
	ds_read_b128 v[198:201], v140 offset:5120
	ds_read_b128 v[202:205], v140 offset:6144
	ds_read_b128 v[206:209], v140 offset:7168
	s_mov_b32 m0, s56
	s_nop 0
	global_load_lds_dwordx4 v134, s[38:39]
	s_add_u32 s66, s38, 0x40000
	s_addc_u32 s67, s39, 0
	s_mov_b32 m0, s57
	s_nop 0
	global_load_lds_dwordx4 v134, s[66:67]
	s_waitcnt vmcnt(8)
	s_waitcnt lgkmcnt(0)
	s_barrier
	s_setprio 1
	v_mfma_f32_16x16x32_bf16 v[124:127], v[144:147], v[178:181], v[124:127]
	v_mfma_f32_16x16x32_bf16 v[120:123], v[152:155], v[178:181], v[120:123]
	v_mfma_f32_16x16x32_bf16 v[116:119], v[144:147], v[186:189], v[116:119]
	v_mfma_f32_16x16x32_bf16 v[108:111], v[152:155], v[186:189], v[108:111]
	v_mfma_f32_16x16x32_bf16 v[100:103], v[144:147], v[194:197], v[100:103]
	v_mfma_f32_16x16x32_bf16 v[92:95], v[152:155], v[194:197], v[92:95]
	v_mfma_f32_16x16x32_bf16 v[84:87], v[144:147], v[202:205], v[84:87]
	v_mfma_f32_16x16x32_bf16 v[76:79], v[152:155], v[202:205], v[76:79]
	v_mfma_f32_16x16x32_bf16 v[124:127], v[148:151], v[182:185], v[124:127]
	v_mfma_f32_16x16x32_bf16 v[120:123], v[156:159], v[182:185], v[120:123]
	v_mfma_f32_16x16x32_bf16 v[116:119], v[148:151], v[190:193], v[116:119]
	v_mfma_f32_16x16x32_bf16 v[108:111], v[156:159], v[190:193], v[108:111]
	v_mfma_f32_16x16x32_bf16 v[100:103], v[148:151], v[198:201], v[100:103]
	v_mfma_f32_16x16x32_bf16 v[92:95], v[156:159], v[198:201], v[92:95]
	v_mfma_f32_16x16x32_bf16 v[84:87], v[148:151], v[206:209], v[84:87]
	v_mfma_f32_16x16x32_bf16 v[76:79], v[156:159], v[206:209], v[76:79]
	v_mfma_f32_16x16x32_bf16 v[112:115], v[160:163], v[178:181], v[112:115]
	v_mfma_f32_16x16x32_bf16 v[104:107], v[168:171], v[178:181], v[104:107]
	v_mfma_f32_16x16x32_bf16 v[96:99], v[160:163], v[186:189], v[96:99]
	v_mfma_f32_16x16x32_bf16 v[88:91], v[168:171], v[186:189], v[88:91]
	v_mfma_f32_16x16x32_bf16 v[80:83], v[160:163], v[194:197], v[80:83]
	v_mfma_f32_16x16x32_bf16 v[72:75], v[168:171], v[194:197], v[72:75]
	v_mfma_f32_16x16x32_bf16 v[68:71], v[160:163], v[202:205], v[68:71]
	v_mfma_f32_16x16x32_bf16 v[64:67], v[168:171], v[202:205], v[64:67]
	v_mfma_f32_16x16x32_bf16 v[112:115], v[164:167], v[182:185], v[112:115]
	v_mfma_f32_16x16x32_bf16 v[104:107], v[172:175], v[182:185], v[104:107]
	v_mfma_f32_16x16x32_bf16 v[96:99], v[164:167], v[190:193], v[96:99]
	v_mfma_f32_16x16x32_bf16 v[88:91], v[172:175], v[190:193], v[88:91]
	v_mfma_f32_16x16x32_bf16 v[80:83], v[164:167], v[198:201], v[80:83]
	v_mfma_f32_16x16x32_bf16 v[72:75], v[172:175], v[198:201], v[72:75]
	v_mfma_f32_16x16x32_bf16 v[68:71], v[164:167], v[206:209], v[68:71]
	v_mfma_f32_16x16x32_bf16 v[64:67], v[172:175], v[206:209], v[64:67]
	s_setprio 0
	s_barrier
	s_add_u32 s66, s44, 0x40000
	ds_read_b128 v[178:181], v140 offset:16384
	ds_read_b128 v[182:185], v140 offset:17408
	ds_read_b128 v[186:189], v140 offset:18432
	ds_read_b128 v[190:193], v140 offset:19456
	ds_read_b128 v[194:197], v140 offset:20480
	ds_read_b128 v[198:201], v140 offset:21504
	ds_read_b128 v[202:205], v140 offset:22528
	ds_read_b128 v[206:209], v140 offset:23552
	s_mov_b32 m0, s33
	s_nop 0
	global_load_lds_dwordx4 v135, s[44:45]
	s_addc_u32 s67, s45, 0
	s_mov_b32 m0, s34
	s_nop 0
	global_load_lds_dwordx4 v135, s[66:67]
	s_add_u32 s66, s44, 0x80000
	s_addc_u32 s67, s45, 0
	s_mov_b32 m0, s35
	s_nop 0
	global_load_lds_dwordx4 v135, s[66:67]
	s_add_u32 s66, s44, 0xc0000
	s_addc_u32 s67, s45, 0
	s_mov_b32 m0, s36
	s_nop 0
	global_load_lds_dwordx4 v135, s[66:67]
	s_mov_b32 m0, s31
	s_nop 0
	global_load_lds_dwordx4 v134, s[40:41]
	s_add_u32 s66, s40, 0x40000
	s_addc_u32 s67, s41, 0
	s_mov_b32 m0, s37
	s_nop 0
	global_load_lds_dwordx4 v134, s[66:67]
	s_waitcnt vmcnt(8)
	s_waitcnt lgkmcnt(0)
	s_barrier
	s_setprio 1
	v_mfma_f32_16x16x32_bf16 v[60:63], v[144:147], v[178:181], v[60:63]
	v_mfma_f32_16x16x32_bf16 v[56:59], v[152:155], v[178:181], v[56:59]
	v_mfma_f32_16x16x32_bf16 v[52:55], v[144:147], v[186:189], v[52:55]
	v_mfma_f32_16x16x32_bf16 v[44:47], v[152:155], v[186:189], v[44:47]
	v_mfma_f32_16x16x32_bf16 v[36:39], v[144:147], v[194:197], v[36:39]
	v_mfma_f32_16x16x32_bf16 v[28:31], v[152:155], v[194:197], v[28:31]
	v_mfma_f32_16x16x32_bf16 v[20:23], v[144:147], v[202:205], v[20:23]
	v_mfma_f32_16x16x32_bf16 v[12:15], v[152:155], v[202:205], v[12:15]
	v_mfma_f32_16x16x32_bf16 v[60:63], v[148:151], v[182:185], v[60:63]
	v_mfma_f32_16x16x32_bf16 v[56:59], v[156:159], v[182:185], v[56:59]
	v_mfma_f32_16x16x32_bf16 v[52:55], v[148:151], v[190:193], v[52:55]
	v_mfma_f32_16x16x32_bf16 v[44:47], v[156:159], v[190:193], v[44:47]
	v_mfma_f32_16x16x32_bf16 v[36:39], v[148:151], v[198:201], v[36:39]
	v_mfma_f32_16x16x32_bf16 v[28:31], v[156:159], v[198:201], v[28:31]
	v_mfma_f32_16x16x32_bf16 v[20:23], v[148:151], v[206:209], v[20:23]
	v_mfma_f32_16x16x32_bf16 v[12:15], v[156:159], v[206:209], v[12:15]
	v_mfma_f32_16x16x32_bf16 v[48:51], v[160:163], v[178:181], v[48:51]
	v_mfma_f32_16x16x32_bf16 v[40:43], v[168:171], v[178:181], v[40:43]
	v_mfma_f32_16x16x32_bf16 v[32:35], v[160:163], v[186:189], v[32:35]
	v_mfma_f32_16x16x32_bf16 v[24:27], v[168:171], v[186:189], v[24:27]
	v_mfma_f32_16x16x32_bf16 v[16:19], v[160:163], v[194:197], v[16:19]
	v_mfma_f32_16x16x32_bf16 v[8:11], v[168:171], v[194:197], v[8:11]
	v_mfma_f32_16x16x32_bf16 v[4:7], v[160:163], v[202:205], v[4:7]
	v_mfma_f32_16x16x32_bf16 v[0:3], v[168:171], v[202:205], v[0:3]
	v_mfma_f32_16x16x32_bf16 v[48:51], v[164:167], v[182:185], v[48:51]
	v_mfma_f32_16x16x32_bf16 v[40:43], v[172:175], v[182:185], v[40:43]
	v_mfma_f32_16x16x32_bf16 v[32:35], v[164:167], v[190:193], v[32:35]
	v_mfma_f32_16x16x32_bf16 v[24:27], v[172:175], v[190:193], v[24:27]
	v_mfma_f32_16x16x32_bf16 v[16:19], v[164:167], v[198:201], v[16:19]
	v_mfma_f32_16x16x32_bf16 v[8:11], v[172:175], v[198:201], v[8:11]
	v_mfma_f32_16x16x32_bf16 v[4:7], v[164:167], v[206:209], v[4:7]
	v_mfma_f32_16x16x32_bf16 v[0:3], v[172:175], v[206:209], v[0:3]
	s_setprio 0
	s_barrier
; #define PG8_STAGE(bufoff, gbase, voff, p64) do { _Pragma("unroll") for (int _i = 0; _i < 2; ++_i) { \
;         const char* _gb = (const char*)(gbase) + (size_t)_i * (p64); const unsigned _la = ldsbase + (unsigned)(bufoff) + (unsigned)_i * 8192u; \
;         asm volatile("s_mov_b32 m0, %0\n\ts_nop 0\n\tglobal_load_lds_dwordx4 %1, %2" :: "s"(_la), "v"(voff), "s"(_gb) : "memory"); } } while (0)
; #define PG8_LDA(dst, b, h) do { _Pragma("unroll") for (int m = 0; m < 4; ++m) _Pragma("unroll") for (int k = 0; k < 2; ++k) dst[m][k] = *(const LAS bf16x8*)(lds + PG8_SA(b, h) + aoff + m * 2048 + k * 1024); } while (0)
; #define PG8_LDB(dst, b, h) do { _Pragma("unroll") for (int n = 0; n < 2; ++n) _Pragma("unroll") for (int k = 0; k < 2; ++k) dst[n][k] = *(const LAS bf16x8*)(lds + PG8_SB(b, h) + boff + n * 2048 + k * 1024); } while (0)
; #define PG8_MMA(ai, bj, At, Bt) do { __builtin_amdgcn_s_setprio(1); _Pragma("unroll") for (int m = 0; m < 4; ++m) _Pragma("unroll") for (int n = 0; n < 2; ++n) _Pragma("unroll") for (int k = 0; k < 2; ++k) \
;         acc[ai][bj][m][n] = __builtin_amdgcn_mfma_f32_16x16x32_bf16(Bt[n][k], At[m][k], acc[ai][bj][m][n], 0, 0, 0); __builtin_amdgcn_s_setprio(0); } while (0)
; #define PG8_WAIT_V(n) asm volatile("s_waitcnt vmcnt(" #n ")" ::: "memory")
; #define PG8_WAIT_L(n) asm volatile("s_waitcnt lgkmcnt(" #n ")" ::: "memory")
; #define PG8_BAR __builtin_amdgcn_s_barrier()
; #define PG8_SCHED __builtin_amdgcn_sched_barrier(0)
; template <class Epi, class Sched>
; __device__ __forceinline__ void gemm_phase(LAS unsigned char* lds, const Sched& S, const Epi& E) {
;     ...
;             PG8_LDB(B0, 1, 0); PG8_LDB(B1, 1, 1); PG8_SCHED; PG8_LDA(At, 1, 0); PG8_STAGE(PG8_SA(0, 1), a2 + hA2, vA2, hA2 / 2);
;             PG8_WAIT_V(8); PG8_WAIT_L(0); PG8_BAR; PG8_MMA(0, 0, At, B0); PG8_MMA(0, 1, At, B1); PG8_BAR; PG8_SCHED;
;             PG8_LDA(At, 1, 1); PG8_STAGE(PG8_SB(1, 0), b3, vB2, hB2 / 2); PG8_STAGE(PG8_SB(1, 1), b3 + hB2, vB2, hB2 / 2); PG8_STAGE(PG8_SA(1, 0), a3, vA2, hA2 / 2);
;             PG8_WAIT_V(8); PG8_WAIT_L(0); PG8_BAR; PG8_MMA(1, 0, At, B0); PG8_MMA(1, 1, At, B1); PG8_BAR; PG8_SCHED;
;         }
	ds_read_b128 v[144:147], v141
	ds_read_b128 v[148:151], v141 offset:1024
	ds_read_b128 v[152:155], v141 offset:2048
	ds_read_b128 v[156:159], v141 offset:3072
	ds_read_b128 v[160:163], v142
	ds_read_b128 v[164:167], v142 offset:1024
	ds_read_b128 v[168:171], v142 offset:2048
	ds_read_b128 v[172:175], v142 offset:3072
	ds_read_b128 v[178:181], v140 offset:32768
	ds_read_b128 v[182:185], v140 offset:33792
	ds_read_b128 v[186:189], v140 offset:34816
	ds_read_b128 v[190:193], v140 offset:35840
	ds_read_b128 v[194:197], v140 offset:36864
	ds_read_b128 v[198:201], v140 offset:37888
	ds_read_b128 v[202:205], v140 offset:38912
	ds_read_b128 v[206:209], v140 offset:39936
	s_add_u32 s66, s40, 0x80000
	s_addc_u32 s67, s41, 0
	s_mov_b32 m0, s46
	s_nop 0
	global_load_lds_dwordx4 v134, s[66:67]
	s_add_u32 s66, s40, 0xc0000
	s_addc_u32 s67, s41, 0
	s_mov_b32 m0, s47
	s_nop 0
	global_load_lds_dwordx4 v134, s[66:67]
	s_waitcnt vmcnt(8)
	s_waitcnt lgkmcnt(0)
	s_barrier
	s_setprio 1
	v_mfma_f32_16x16x32_bf16 v[124:127], v[144:147], v[178:181], v[124:127]
	v_mfma_f32_16x16x32_bf16 v[120:123], v[152:155], v[178:181], v[120:123]
	v_mfma_f32_16x16x32_bf16 v[116:119], v[144:147], v[186:189], v[116:119]
	v_mfma_f32_16x16x32_bf16 v[108:111], v[152:155], v[186:189], v[108:111]
	v_mfma_f32_16x16x32_bf16 v[100:103], v[144:147], v[194:197], v[100:103]
	v_mfma_f32_16x16x32_bf16 v[92:95], v[152:155], v[194:197], v[92:95]
	v_mfma_f32_16x16x32_bf16 v[84:87], v[144:147], v[202:205], v[84:87]
	v_mfma_f32_16x16x32_bf16 v[76:79], v[152:155], v[202:205], v[76:79]
	v_mfma_f32_16x16x32_bf16 v[124:127], v[148:151], v[182:185], v[124:127]
	v_mfma_f32_16x16x32_bf16 v[120:123], v[156:159], v[182:185], v[120:123]
	v_mfma_f32_16x16x32_bf16 v[116:119], v[148:151], v[190:193], v[116:119]
	v_mfma_f32_16x16x32_bf16 v[108:111], v[156:159], v[190:193], v[108:111]
	v_mfma_f32_16x16x32_bf16 v[100:103], v[148:151], v[198:201], v[100:103]
	v_mfma_f32_16x16x32_bf16 v[92:95], v[156:159], v[198:201], v[92:95]
	v_mfma_f32_16x16x32_bf16 v[84:87], v[148:151], v[206:209], v[84:87]
	v_mfma_f32_16x16x32_bf16 v[76:79], v[156:159], v[206:209], v[76:79]
	v_mfma_f32_16x16x32_bf16 v[112:115], v[160:163], v[178:181], v[112:115]
	v_mfma_f32_16x16x32_bf16 v[104:107], v[168:171], v[178:181], v[104:107]
	v_mfma_f32_16x16x32_bf16 v[96:99], v[160:163], v[186:189], v[96:99]
	v_mfma_f32_16x16x32_bf16 v[88:91], v[168:171], v[186:189], v[88:91]
	v_mfma_f32_16x16x32_bf16 v[80:83], v[160:163], v[194:197], v[80:83]
	v_mfma_f32_16x16x32_bf16 v[72:75], v[168:171], v[194:197], v[72:75]
	v_mfma_f32_16x16x32_bf16 v[68:71], v[160:163], v[202:205], v[68:71]
	v_mfma_f32_16x16x32_bf16 v[64:67], v[168:171], v[202:205], v[64:67]
	v_mfma_f32_16x16x32_bf16 v[112:115], v[164:167], v[182:185], v[112:115]
	v_mfma_f32_16x16x32_bf16 v[104:107], v[172:175], v[182:185], v[104:107]
	v_mfma_f32_16x16x32_bf16 v[96:99], v[164:167], v[190:193], v[96:99]
	v_mfma_f32_16x16x32_bf16 v[88:91], v[172:175], v[190:193], v[88:91]
	v_mfma_f32_16x16x32_bf16 v[80:83], v[164:167], v[198:201], v[80:83]
	v_mfma_f32_16x16x32_bf16 v[72:75], v[172:175], v[198:201], v[72:75]
	v_mfma_f32_16x16x32_bf16 v[68:71], v[164:167], v[206:209], v[68:71]
	v_mfma_f32_16x16x32_bf16 v[64:67], v[172:175], v[206:209], v[64:67]
	s_setprio 0
	s_barrier
	s_add_u32 s66, s44, 0x80
	s_addc_u32 s67, s45, 0
	ds_read_b128 v[178:181], v140 offset:49152
	ds_read_b128 v[182:185], v140 offset:50176
	ds_read_b128 v[186:189], v140 offset:51200
	ds_read_b128 v[190:193], v140 offset:52224
	ds_read_b128 v[194:197], v140 offset:53248
	ds_read_b128 v[198:201], v140 offset:54272
	ds_read_b128 v[202:205], v140 offset:55296
	ds_read_b128 v[206:209], v140 offset:56320
	s_mov_b32 m0, s50
	s_nop 0
	global_load_lds_dwordx4 v135, s[66:67]
	s_add_u32 s66, s44, 0x40080
	s_addc_u32 s67, s45, 0
	s_mov_b32 m0, s51
	s_nop 0
	global_load_lds_dwordx4 v135, s[66:67]
	s_add_u32 s66, s44, 0x80080
	s_addc_u32 s67, s45, 0
	s_mov_b32 m0, s54
	s_nop 0
	global_load_lds_dwordx4 v135, s[66:67]
	s_add_u32 s44, s44, 0xc0080
	s_addc_u32 s45, s45, 0
	s_mov_b32 m0, s55
	s_nop 0
	global_load_lds_dwordx4 v135, s[44:45]
	s_mov_b32 m0, s52
	s_nop 0
	global_load_lds_dwordx4 v134, s[42:43]
	s_add_u32 s40, s40, 0x40080
	s_addc_u32 s41, s41, 0
	s_mov_b32 m0, s53
	s_nop 0
	global_load_lds_dwordx4 v134, s[40:41]
	s_waitcnt vmcnt(8)
	s_waitcnt lgkmcnt(0)
	s_barrier
	s_setprio 1
	v_mfma_f32_16x16x32_bf16 v[60:63], v[144:147], v[178:181], v[60:63]
	v_mfma_f32_16x16x32_bf16 v[56:59], v[152:155], v[178:181], v[56:59]
	v_mfma_f32_16x16x32_bf16 v[52:55], v[144:147], v[186:189], v[52:55]
	v_mfma_f32_16x16x32_bf16 v[44:47], v[152:155], v[186:189], v[44:47]
	v_mfma_f32_16x16x32_bf16 v[36:39], v[144:147], v[194:197], v[36:39]
	v_mfma_f32_16x16x32_bf16 v[28:31], v[152:155], v[194:197], v[28:31]
	v_mfma_f32_16x16x32_bf16 v[20:23], v[144:147], v[202:205], v[20:23]
	v_mfma_f32_16x16x32_bf16 v[12:15], v[152:155], v[202:205], v[12:15]
	v_mfma_f32_16x16x32_bf16 v[60:63], v[148:151], v[182:185], v[60:63]
	v_mfma_f32_16x16x32_bf16 v[56:59], v[156:159], v[182:185], v[56:59]
	v_mfma_f32_16x16x32_bf16 v[52:55], v[148:151], v[190:193], v[52:55]
	v_mfma_f32_16x16x32_bf16 v[44:47], v[156:159], v[190:193], v[44:47]
	v_mfma_f32_16x16x32_bf16 v[36:39], v[148:151], v[198:201], v[36:39]
	v_mfma_f32_16x16x32_bf16 v[28:31], v[156:159], v[198:201], v[28:31]
	v_mfma_f32_16x16x32_bf16 v[20:23], v[148:151], v[206:209], v[20:23]
	v_mfma_f32_16x16x32_bf16 v[12:15], v[156:159], v[206:209], v[12:15]
	v_mfma_f32_16x16x32_bf16 v[48:51], v[160:163], v[178:181], v[48:51]
	v_mfma_f32_16x16x32_bf16 v[40:43], v[168:171], v[178:181], v[40:43]
	v_mfma_f32_16x16x32_bf16 v[32:35], v[160:163], v[186:189], v[32:35]
	v_mfma_f32_16x16x32_bf16 v[24:27], v[168:171], v[186:189], v[24:27]
	v_mfma_f32_16x16x32_bf16 v[16:19], v[160:163], v[194:197], v[16:19]
	v_mfma_f32_16x16x32_bf16 v[8:11], v[168:171], v[194:197], v[8:11]
	v_mfma_f32_16x16x32_bf16 v[4:7], v[160:163], v[202:205], v[4:7]
	v_mfma_f32_16x16x32_bf16 v[0:3], v[168:171], v[202:205], v[0:3]
	v_mfma_f32_16x16x32_bf16 v[48:51], v[164:167], v[182:185], v[48:51]
	v_mfma_f32_16x16x32_bf16 v[40:43], v[172:175], v[182:185], v[40:43]
	v_mfma_f32_16x16x32_bf16 v[32:35], v[164:167], v[190:193], v[32:35]
	v_mfma_f32_16x16x32_bf16 v[24:27], v[172:175], v[190:193], v[24:27]
	v_mfma_f32_16x16x32_bf16 v[16:19], v[164:167], v[198:201], v[16:19]
	v_mfma_f32_16x16x32_bf16 v[8:11], v[172:175], v[198:201], v[8:11]
	v_mfma_f32_16x16x32_bf16 v[4:7], v[164:167], v[206:209], v[4:7]
	v_mfma_f32_16x16x32_bf16 v[0:3], v[172:175], v[206:209], v[0:3]
	s_setprio 0
	s_barrier
	s_add_i32 s62, s62, 2
	s_add_u32 s38, s38, 0x100
	s_addc_u32 s39, s39, 0
	s_add_u32 s60, s60, 0x100
	s_addc_u32 s61, s61, 0
	s_cmp_gt_u32 s62, 29
	s_cbranch_scc0 .LBB0_1089
	s_and_b64 vcc, exec, s[18:19]
	s_cbranch_vccz .LBB0_1092
	s_barrier

; #define PG8_STAGE(bufoff, gbase, voff, p64) do { _Pragma("unroll") for (int _i = 0; _i < 2; ++_i) { \
;         const char* _gb = (const char*)(gbase) + (size_t)_i * (p64); const unsigned _la = ldsbase + (unsigned)(bufoff) + (unsigned)_i * 8192u; \
;         asm volatile("s_mov_b32 m0, %0\n\ts_nop 0\n\tglobal_load_lds_dwordx4 %1, %2" :: "s"(_la), "v"(voff), "s"(_gb) : "memory"); } } while (0)
; #define PG8_LDA(dst, b, h) do { _Pragma("unroll") for (int m = 0; m < 4; ++m) _Pragma("unroll") for (int k = 0; k < 2; ++k) dst[m][k] = *(const LAS bf16x8*)(lds + PG8_SA(b, h) + aoff + m * 2048 + k * 1024); } while (0)
; #define PG8_LDB(dst, b, h) do { _Pragma("unroll") for (int n = 0; n < 2; ++n) _Pragma("unroll") for (int k = 0; k < 2; ++k) dst[n][k] = *(const LAS bf16x8*)(lds + PG8_SB(b, h) + boff + n * 2048 + k * 1024); } while (0)
; #define PG8_WAIT_V(n) asm volatile("s_waitcnt vmcnt(" #n ")" ::: "memory")
; #define PG8_WAIT_L(n) asm volatile("s_waitcnt lgkmcnt(" #n ")" ::: "memory")
; #define PG8_BAR __builtin_amdgcn_s_barrier()
; template <class Epi, class Sched>
; __device__ __forceinline__ void gemm_phase(LAS unsigned char* lds, const Sched& S, const Epi& E) {
;     ...
;             const bool last = (t == nt - 2);
;             const char* a1 = cA + (size_t)(t + 1) * kstep;
;             const char* a2 = last ? nA : cA + (size_t)(t + 2) * kstep; const char* b2 = last ? nB : cB + (size_t)(t + 2) * kstep;
;             const char* a3 = a2 + kstep; const char* b3 = b2 + kstep;
;             const unsigned vA2 = voffA, vB2 = voffB, hA2 = hA, hB2 = hB;
;             PG8_LDB(B0, 0, 0); PG8_LDB(B1, 0, 1); PG8_SCHED; PG8_LDA(At, 0, 0); PG8_STAGE(PG8_SA(1, 1), a1 + hA, voffA, hA / 2);
;             PG8_WAIT_V(8); PG8_WAIT_L(0); PG8_BAR; PG8_MMA(0, 0, At, B0); PG8_MMA(0, 1, At, B1); PG8_BAR; PG8_SCHED;
;             PG8_LDA(At, 0, 1); PG8_STAGE(PG8_SB(0, 0), b2, vB2, hB2 / 2); PG8_STAGE(PG8_SB(0, 1), b2 + hB2, vB2, hB2 / 2); PG8_STAGE(PG8_SA(0, 0), a2, vA2, hA2 / 2);
;             PG8_WAIT_V(8); PG8_WAIT_L(0); PG8_BAR; PG8_MMA(1, 0, At, B0); PG8_MMA(1, 1, At, B1); PG8_BAR; PG8_SCHED;
;             PG8_LDB(B0, 1, 0); PG8_LDB(B1, 1, 1); PG8_SCHED; PG8_LDA(At, 1, 0); PG8_STAGE(PG8_SA(0, 1), a2 + hA2, vA2, hA2 / 2);
;             PG8_WAIT_V(8); PG8_WAIT_L(0); PG8_BAR; PG8_MMA(0, 0, At, B0); PG8_MMA(0, 1, At, B1); PG8_BAR; PG8_SCHED;
.LBB0_1192:
	ds_read_b128 v[144:147], v138
	ds_read_b128 v[148:151], v138 offset:1024
	ds_read_b128 v[152:155], v138 offset:2048
	ds_read_b128 v[156:159], v138 offset:3072
	ds_read_b128 v[160:163], v139
	ds_read_b128 v[164:167], v139 offset:1024
	ds_read_b128 v[168:171], v139 offset:2048
	ds_read_b128 v[172:175], v139 offset:3072
	s_add_u32 s26, s24, 0xfffc0080
	s_addc_u32 s27, s25, -1
	s_cmp_eq_u32 s60, 12
	s_cselect_b32 s26, s20, s26
	s_cselect_b32 s27, s21, s27
	s_cselect_b32 s40, s22, s58
	s_cselect_b32 s41, s23, s59
	s_add_u32 s38, s26, 0x80
	s_addc_u32 s39, s27, 0
	ds_read_b128 v[178:181], v140
	ds_read_b128 v[182:185], v140 offset:1024
	ds_read_b128 v[186:189], v140 offset:2048
	ds_read_b128 v[190:193], v140 offset:3072
	ds_read_b128 v[194:197], v140 offset:4096
	ds_read_b128 v[198:201], v140 offset:5120
	ds_read_b128 v[202:205], v140 offset:6144
	ds_read_b128 v[206:209], v140 offset:7168
	s_mov_b32 m0, s54
	s_nop 0
	global_load_lds_dwordx4 v134, s[24:25]
	s_add_u32 s62, s24, 0x20000
	s_addc_u32 s63, s25, 0
	s_mov_b32 m0, s55
	s_nop 0
	global_load_lds_dwordx4 v134, s[62:63]
	s_waitcnt vmcnt(8)
	s_waitcnt lgkmcnt(0)
	s_barrier
	s_setprio 1
	v_mfma_f32_16x16x32_bf16 v[124:127], v[144:147], v[178:181], v[124:127]
	v_mfma_f32_16x16x32_bf16 v[120:123], v[152:155], v[178:181], v[120:123]
	v_mfma_f32_16x16x32_bf16 v[116:119], v[144:147], v[186:189], v[116:119]
	v_mfma_f32_16x16x32_bf16 v[108:111], v[152:155], v[186:189], v[108:111]
	v_mfma_f32_16x16x32_bf16 v[100:103], v[144:147], v[194:197], v[100:103]
	v_mfma_f32_16x16x32_bf16 v[92:95], v[152:155], v[194:197], v[92:95]
	v_mfma_f32_16x16x32_bf16 v[84:87], v[144:147], v[202:205], v[84:87]
	v_mfma_f32_16x16x32_bf16 v[76:79], v[152:155], v[202:205], v[76:79]
	v_mfma_f32_16x16x32_bf16 v[124:127], v[148:151], v[182:185], v[124:127]
	v_mfma_f32_16x16x32_bf16 v[120:123], v[156:159], v[182:185], v[120:123]
	v_mfma_f32_16x16x32_bf16 v[116:119], v[148:151], v[190:193], v[116:119]
	v_mfma_f32_16x16x32_bf16 v[108:111], v[156:159], v[190:193], v[108:111]
	v_mfma_f32_16x16x32_bf16 v[100:103], v[148:151], v[198:201], v[100:103]
	v_mfma_f32_16x16x32_bf16 v[92:95], v[156:159], v[198:201], v[92:95]
	v_mfma_f32_16x16x32_bf16 v[84:87], v[148:151], v[206:209], v[84:87]
	v_mfma_f32_16x16x32_bf16 v[76:79], v[156:159], v[206:209], v[76:79]
	v_mfma_f32_16x16x32_bf16 v[112:115], v[160:163], v[178:181], v[112:115]
	v_mfma_f32_16x16x32_bf16 v[104:107], v[168:171], v[178:181], v[104:107]
	v_mfma_f32_16x16x32_bf16 v[96:99], v[160:163], v[186:189], v[96:99]
	v_mfma_f32_16x16x32_bf16 v[88:91], v[168:171], v[186:189], v[88:91]
	v_mfma_f32_16x16x32_bf16 v[80:83], v[160:163], v[194:197], v[80:83]
	v_mfma_f32_16x16x32_bf16 v[72:75], v[168:171], v[194:197], v[72:75]
	v_mfma_f32_16x16x32_bf16 v[68:71], v[160:163], v[202:205], v[68:71]
	v_mfma_f32_16x16x32_bf16 v[64:67], v[168:171], v[202:205], v[64:67]
	v_mfma_f32_16x16x32_bf16 v[112:115], v[164:167], v[182:185], v[112:115]
	v_mfma_f32_16x16x32_bf16 v[104:107], v[172:175], v[182:185], v[104:107]
	v_mfma_f32_16x16x32_bf16 v[96:99], v[164:167], v[190:193], v[96:99]
	v_mfma_f32_16x16x32_bf16 v[88:91], v[172:175], v[190:193], v[88:91]
	v_mfma_f32_16x16x32_bf16 v[80:83], v[164:167], v[198:201], v[80:83]
	v_mfma_f32_16x16x32_bf16 v[72:75], v[172:175], v[198:201], v[72:75]
	v_mfma_f32_16x16x32_bf16 v[68:71], v[164:167], v[206:209], v[68:71]
	v_mfma_f32_16x16x32_bf16 v[64:67], v[172:175], v[206:209], v[64:67]
	s_setprio 0
	s_barrier
	s_add_u32 s62, s40, 0x20000
	ds_read_b128 v[178:181], v140 offset:16384
	ds_read_b128 v[182:185], v140 offset:17408
	ds_read_b128 v[186:189], v140 offset:18432
	ds_read_b128 v[190:193], v140 offset:19456
	ds_read_b128 v[194:197], v140 offset:20480
	ds_read_b128 v[198:201], v140 offset:21504
	ds_read_b128 v[202:205], v140 offset:22528
	ds_read_b128 v[206:209], v140 offset:23552
	s_mov_b32 m0, s35
	s_nop 0
	global_load_lds_dwordx4 v135, s[40:41]
	s_addc_u32 s63, s41, 0
	s_mov_b32 m0, s36
	s_nop 0
	global_load_lds_dwordx4 v135, s[62:63]
	s_add_u32 s62, s40, 0x40000
	s_addc_u32 s63, s41, 0
	s_mov_b32 m0, s37
	s_nop 0
	global_load_lds_dwordx4 v135, s[62:63]
	s_add_u32 s62, s40, 0x60000
	s_addc_u32 s63, s41, 0
	s_mov_b32 m0, s42
	s_nop 0
	global_load_lds_dwordx4 v135, s[62:63]
	s_mov_b32 m0, s34
	s_nop 0
	global_load_lds_dwordx4 v134, s[26:27]
	s_add_u32 s62, s26, 0x20000
	s_addc_u32 s63, s27, 0
	s_mov_b32 m0, s43
	s_nop 0
	global_load_lds_dwordx4 v134, s[62:63]
	s_waitcnt vmcnt(8)
	s_waitcnt lgkmcnt(0)
	s_barrier
	s_setprio 1
	v_mfma_f32_16x16x32_bf16 v[60:63], v[144:147], v[178:181], v[60:63]
	v_mfma_f32_16x16x32_bf16 v[56:59], v[152:155], v[178:181], v[56:59]
	v_mfma_f32_16x16x32_bf16 v[52:55], v[144:147], v[186:189], v[52:55]
	v_mfma_f32_16x16x32_bf16 v[44:47], v[152:155], v[186:189], v[44:47]
	v_mfma_f32_16x16x32_bf16 v[36:39], v[144:147], v[194:197], v[36:39]
	v_mfma_f32_16x16x32_bf16 v[28:31], v[152:155], v[194:197], v[28:31]
	v_mfma_f32_16x16x32_bf16 v[20:23], v[144:147], v[202:205], v[20:23]
	v_mfma_f32_16x16x32_bf16 v[12:15], v[152:155], v[202:205], v[12:15]
	v_mfma_f32_16x16x32_bf16 v[60:63], v[148:151], v[182:185], v[60:63]
	v_mfma_f32_16x16x32_bf16 v[56:59], v[156:159], v[182:185], v[56:59]
	v_mfma_f32_16x16x32_bf16 v[52:55], v[148:151], v[190:193], v[52:55]
	v_mfma_f32_16x16x32_bf16 v[44:47], v[156:159], v[190:193], v[44:47]
	v_mfma_f32_16x16x32_bf16 v[36:39], v[148:151], v[198:201], v[36:39]
	v_mfma_f32_16x16x32_bf16 v[28:31], v[156:159], v[198:201], v[28:31]
	v_mfma_f32_16x16x32_bf16 v[20:23], v[148:151], v[206:209], v[20:23]
	v_mfma_f32_16x16x32_bf16 v[12:15], v[156:159], v[206:209], v[12:15]
	v_mfma_f32_16x16x32_bf16 v[48:51], v[160:163], v[178:181], v[48:51]
	v_mfma_f32_16x16x32_bf16 v[40:43], v[168:171], v[178:181], v[40:43]
	v_mfma_f32_16x16x32_bf16 v[32:35], v[160:163], v[186:189], v[32:35]
	v_mfma_f32_16x16x32_bf16 v[24:27], v[168:171], v[186:189], v[24:27]
	v_mfma_f32_16x16x32_bf16 v[16:19], v[160:163], v[194:197], v[16:19]
	v_mfma_f32_16x16x32_bf16 v[8:11], v[168:171], v[194:197], v[8:11]
	v_mfma_f32_16x16x32_bf16 v[4:7], v[160:163], v[202:205], v[4:7]
	v_mfma_f32_16x16x32_bf16 v[0:3], v[168:171], v[202:205], v[0:3]
	v_mfma_f32_16x16x32_bf16 v[48:51], v[164:167], v[182:185], v[48:51]
	v_mfma_f32_16x16x32_bf16 v[40:43], v[172:175], v[182:185], v[40:43]
	v_mfma_f32_16x16x32_bf16 v[32:35], v[164:167], v[190:193], v[32:35]
	v_mfma_f32_16x16x32_bf16 v[24:27], v[172:175], v[190:193], v[24:27]
	v_mfma_f32_16x16x32_bf16 v[16:19], v[164:167], v[198:201], v[16:19]
	v_mfma_f32_16x16x32_bf16 v[8:11], v[172:175], v[198:201], v[8:11]
	v_mfma_f32_16x16x32_bf16 v[4:7], v[164:167], v[206:209], v[4:7]
	v_mfma_f32_16x16x32_bf16 v[0:3], v[172:175], v[206:209], v[0:3]
	s_setprio 0
	s_barrier
; #define PG8_STAGE(bufoff, gbase, voff, p64) do { _Pragma("unroll") for (int _i = 0; _i < 2; ++_i) { \
;         const char* _gb = (const char*)(gbase) + (size_t)_i * (p64); const unsigned _la = ldsbase + (unsigned)(bufoff) + (unsigned)_i * 8192u; \
;         asm volatile("s_mov_b32 m0, %0\n\ts_nop 0\n\tglobal_load_lds_dwordx4 %1, %2" :: "s"(_la), "v"(voff), "s"(_gb) : "memory"); } } while (0)
; #define PG8_LDA(dst, b, h) do { _Pragma("unroll") for (int m = 0; m < 4; ++m) _Pragma("unroll") for (int k = 0; k < 2; ++k) dst[m][k] = *(const LAS bf16x8*)(lds + PG8_SA(b, h) + aoff + m * 2048 + k * 1024); } while (0)
; #define PG8_LDB(dst, b, h) do { _Pragma("unroll") for (int n = 0; n < 2; ++n) _Pragma("unroll") for (int k = 0; k < 2; ++k) dst[n][k] = *(const LAS bf16x8*)(lds + PG8_SB(b, h) + boff + n * 2048 + k * 1024); } while (0)
; #define PG8_MMA(ai, bj, At, Bt) do { __builtin_amdgcn_s_setprio(1); _Pragma("unroll") for (int m = 0; m < 4; ++m) _Pragma("unroll") for (int n = 0; n < 2; ++n) _Pragma("unroll") for (int k = 0; k < 2; ++k) \
;         acc[ai][bj][m][n] = __builtin_amdgcn_mfma_f32_16x16x32_bf16(Bt[n][k], At[m][k], acc[ai][bj][m][n], 0, 0, 0); __builtin_amdgcn_s_setprio(0); } while (0)
; #define PG8_WAIT_V(n) asm volatile("s_waitcnt vmcnt(" #n ")" ::: "memory")
; #define PG8_WAIT_L(n) asm volatile("s_waitcnt lgkmcnt(" #n ")" ::: "memory")
; #define PG8_BAR __builtin_amdgcn_s_barrier()
; #define PG8_SCHED __builtin_amdgcn_sched_barrier(0)
; template <class Epi, class Sched>
; __device__ __forceinline__ void gemm_phase(LAS unsigned char* lds, const Sched& S, const Epi& E) {
;     ...
;             PG8_LDB(B0, 1, 0); PG8_LDB(B1, 1, 1); PG8_SCHED; PG8_LDA(At, 1, 0); PG8_STAGE(PG8_SA(0, 1), a2 + hA2, vA2, hA2 / 2);
;             PG8_WAIT_V(8); PG8_WAIT_L(0); PG8_BAR; PG8_MMA(0, 0, At, B0); PG8_MMA(0, 1, At, B1); PG8_BAR; PG8_SCHED;
;             PG8_LDA(At, 1, 1); PG8_STAGE(PG8_SB(1, 0), b3, vB2, hB2 / 2); PG8_STAGE(PG8_SB(1, 1), b3 + hB2, vB2, hB2 / 2); PG8_STAGE(PG8_SA(1, 0), a3, vA2, hA2 / 2);
;             PG8_WAIT_V(8); PG8_WAIT_L(0); PG8_BAR; PG8_MMA(1, 0, At, B0); PG8_MMA(1, 1, At, B1); PG8_BAR; PG8_SCHED;
;         }
	ds_read_b128 v[144:147], v141
	ds_read_b128 v[148:151], v141 offset:1024
	ds_read_b128 v[152:155], v141 offset:2048
	ds_read_b128 v[156:159], v141 offset:3072
	ds_read_b128 v[160:163], v142
	ds_read_b128 v[164:167], v142 offset:1024
	ds_read_b128 v[168:171], v142 offset:2048
	ds_read_b128 v[172:175], v142 offset:3072
	ds_read_b128 v[178:181], v140 offset:32768
	ds_read_b128 v[182:185], v140 offset:33792
	ds_read_b128 v[186:189], v140 offset:34816
	ds_read_b128 v[190:193], v140 offset:35840
	ds_read_b128 v[194:197], v140 offset:36864
	ds_read_b128 v[198:201], v140 offset:37888
	ds_read_b128 v[202:205], v140 offset:38912
	ds_read_b128 v[206:209], v140 offset:39936
	s_add_u32 s62, s26, 0x40000
	s_addc_u32 s63, s27, 0
	s_mov_b32 m0, s44
	s_nop 0
	global_load_lds_dwordx4 v134, s[62:63]
	s_add_u32 s62, s26, 0x60000
	s_addc_u32 s63, s27, 0
	s_mov_b32 m0, s45
	s_nop 0
	global_load_lds_dwordx4 v134, s[62:63]
	s_waitcnt vmcnt(8)
	s_waitcnt lgkmcnt(0)
	s_barrier
	s_setprio 1
	v_mfma_f32_16x16x32_bf16 v[124:127], v[144:147], v[178:181], v[124:127]
	v_mfma_f32_16x16x32_bf16 v[120:123], v[152:155], v[178:181], v[120:123]
	v_mfma_f32_16x16x32_bf16 v[116:119], v[144:147], v[186:189], v[116:119]
	v_mfma_f32_16x16x32_bf16 v[108:111], v[152:155], v[186:189], v[108:111]
	v_mfma_f32_16x16x32_bf16 v[100:103], v[144:147], v[194:197], v[100:103]
	v_mfma_f32_16x16x32_bf16 v[92:95], v[152:155], v[194:197], v[92:95]
	v_mfma_f32_16x16x32_bf16 v[84:87], v[144:147], v[202:205], v[84:87]
	v_mfma_f32_16x16x32_bf16 v[76:79], v[152:155], v[202:205], v[76:79]
	v_mfma_f32_16x16x32_bf16 v[124:127], v[148:151], v[182:185], v[124:127]
	v_mfma_f32_16x16x32_bf16 v[120:123], v[156:159], v[182:185], v[120:123]
	v_mfma_f32_16x16x32_bf16 v[116:119], v[148:151], v[190:193], v[116:119]
	v_mfma_f32_16x16x32_bf16 v[108:111], v[156:159], v[190:193], v[108:111]
	v_mfma_f32_16x16x32_bf16 v[100:103], v[148:151], v[198:201], v[100:103]
	v_mfma_f32_16x16x32_bf16 v[92:95], v[156:159], v[198:201], v[92:95]
	v_mfma_f32_16x16x32_bf16 v[84:87], v[148:151], v[206:209], v[84:87]
	v_mfma_f32_16x16x32_bf16 v[76:79], v[156:159], v[206:209], v[76:79]
	v_mfma_f32_16x16x32_bf16 v[112:115], v[160:163], v[178:181], v[112:115]
	v_mfma_f32_16x16x32_bf16 v[104:107], v[168:171], v[178:181], v[104:107]
	v_mfma_f32_16x16x32_bf16 v[96:99], v[160:163], v[186:189], v[96:99]
	v_mfma_f32_16x16x32_bf16 v[88:91], v[168:171], v[186:189], v[88:91]
	v_mfma_f32_16x16x32_bf16 v[80:83], v[160:163], v[194:197], v[80:83]
	v_mfma_f32_16x16x32_bf16 v[72:75], v[168:171], v[194:197], v[72:75]
	v_mfma_f32_16x16x32_bf16 v[68:71], v[160:163], v[202:205], v[68:71]
	v_mfma_f32_16x16x32_bf16 v[64:67], v[168:171], v[202:205], v[64:67]
	v_mfma_f32_16x16x32_bf16 v[112:115], v[164:167], v[182:185], v[112:115]
	v_mfma_f32_16x16x32_bf16 v[104:107], v[172:175], v[182:185], v[104:107]
	v_mfma_f32_16x16x32_bf16 v[96:99], v[164:167], v[190:193], v[96:99]
	v_mfma_f32_16x16x32_bf16 v[88:91], v[172:175], v[190:193], v[88:91]
	v_mfma_f32_16x16x32_bf16 v[80:83], v[164:167], v[198:201], v[80:83]
	v_mfma_f32_16x16x32_bf16 v[72:75], v[172:175], v[198:201], v[72:75]
	v_mfma_f32_16x16x32_bf16 v[68:71], v[164:167], v[206:209], v[68:71]
	v_mfma_f32_16x16x32_bf16 v[64:67], v[172:175], v[206:209], v[64:67]
	s_setprio 0
	s_barrier
	s_add_u32 s62, s40, 0x80
	s_addc_u32 s63, s41, 0
	ds_read_b128 v[178:181], v140 offset:49152
	ds_read_b128 v[182:185], v140 offset:50176
	ds_read_b128 v[186:189], v140 offset:51200
	ds_read_b128 v[190:193], v140 offset:52224
	ds_read_b128 v[194:197], v140 offset:53248
	ds_read_b128 v[198:201], v140 offset:54272
	ds_read_b128 v[202:205], v140 offset:55296
	ds_read_b128 v[206:209], v140 offset:56320
	s_mov_b32 m0, s48
	s_nop 0
	global_load_lds_dwordx4 v135, s[62:63]
	s_add_u32 s62, s40, 0x20080
	s_addc_u32 s63, s41, 0
	s_mov_b32 m0, s49
	s_nop 0
	global_load_lds_dwordx4 v135, s[62:63]
	s_add_u32 s62, s40, 0x40080
	s_addc_u32 s63, s41, 0
	s_mov_b32 m0, s52
	s_nop 0
	global_load_lds_dwordx4 v135, s[62:63]
	s_add_u32 s40, s40, 0x60080
	s_addc_u32 s41, s41, 0
	s_mov_b32 m0, s53
	s_nop 0
	global_load_lds_dwordx4 v135, s[40:41]
	s_mov_b32 m0, s50
	s_nop 0
	global_load_lds_dwordx4 v134, s[38:39]
	s_add_u32 s26, s26, 0x20080
	s_addc_u32 s27, s27, 0
	s_mov_b32 m0, s51
	s_nop 0
	global_load_lds_dwordx4 v134, s[26:27]
	s_waitcnt vmcnt(8)
	s_waitcnt lgkmcnt(0)
	s_barrier
	s_setprio 1
	v_mfma_f32_16x16x32_bf16 v[60:63], v[144:147], v[178:181], v[60:63]
	v_mfma_f32_16x16x32_bf16 v[56:59], v[152:155], v[178:181], v[56:59]
	v_mfma_f32_16x16x32_bf16 v[52:55], v[144:147], v[186:189], v[52:55]
	v_mfma_f32_16x16x32_bf16 v[44:47], v[152:155], v[186:189], v[44:47]
	v_mfma_f32_16x16x32_bf16 v[36:39], v[144:147], v[194:197], v[36:39]
	v_mfma_f32_16x16x32_bf16 v[28:31], v[152:155], v[194:197], v[28:31]
	v_mfma_f32_16x16x32_bf16 v[20:23], v[144:147], v[202:205], v[20:23]
	v_mfma_f32_16x16x32_bf16 v[12:15], v[152:155], v[202:205], v[12:15]
	v_mfma_f32_16x16x32_bf16 v[60:63], v[148:151], v[182:185], v[60:63]
	v_mfma_f32_16x16x32_bf16 v[56:59], v[156:159], v[182:185], v[56:59]
	v_mfma_f32_16x16x32_bf16 v[52:55], v[148:151], v[190:193], v[52:55]
	v_mfma_f32_16x16x32_bf16 v[44:47], v[156:159], v[190:193], v[44:47]
	v_mfma_f32_16x16x32_bf16 v[36:39], v[148:151], v[198:201], v[36:39]
	v_mfma_f32_16x16x32_bf16 v[28:31], v[156:159], v[198:201], v[28:31]
	v_mfma_f32_16x16x32_bf16 v[20:23], v[148:151], v[206:209], v[20:23]
	v_mfma_f32_16x16x32_bf16 v[12:15], v[156:159], v[206:209], v[12:15]
	v_mfma_f32_16x16x32_bf16 v[48:51], v[160:163], v[178:181], v[48:51]
	v_mfma_f32_16x16x32_bf16 v[40:43], v[168:171], v[178:181], v[40:43]
	v_mfma_f32_16x16x32_bf16 v[32:35], v[160:163], v[186:189], v[32:35]
	v_mfma_f32_16x16x32_bf16 v[24:27], v[168:171], v[186:189], v[24:27]
	v_mfma_f32_16x16x32_bf16 v[16:19], v[160:163], v[194:197], v[16:19]
	v_mfma_f32_16x16x32_bf16 v[8:11], v[168:171], v[194:197], v[8:11]
	v_mfma_f32_16x16x32_bf16 v[4:7], v[160:163], v[202:205], v[4:7]
	v_mfma_f32_16x16x32_bf16 v[0:3], v[168:171], v[202:205], v[0:3]
	v_mfma_f32_16x16x32_bf16 v[48:51], v[164:167], v[182:185], v[48:51]
	v_mfma_f32_16x16x32_bf16 v[40:43], v[172:175], v[182:185], v[40:43]
	v_mfma_f32_16x16x32_bf16 v[32:35], v[164:167], v[190:193], v[32:35]
	v_mfma_f32_16x16x32_bf16 v[24:27], v[172:175], v[190:193], v[24:27]
	v_mfma_f32_16x16x32_bf16 v[16:19], v[164:167], v[198:201], v[16:19]
	v_mfma_f32_16x16x32_bf16 v[8:11], v[172:175], v[198:201], v[8:11]
	v_mfma_f32_16x16x32_bf16 v[4:7], v[164:167], v[206:209], v[4:7]
	v_mfma_f32_16x16x32_bf16 v[0:3], v[172:175], v[206:209], v[0:3]
	s_setprio 0
	s_barrier
	s_add_i32 s60, s60, 2
	s_add_u32 s24, s24, 0x100
	s_addc_u32 s25, s25, 0
	s_add_u32 s58, s58, 0x100
	s_addc_u32 s59, s59, 0
	s_cmp_gt_u32 s60, 13
	s_cbranch_scc0 .LBB0_1192
	s_and_b64 vcc, exec, s[14:15]
	s_cbranch_vccz .LBB0_1195
	s_barrier

; #define PG8_STAGE(bufoff, gbase, voff, p64) do { _Pragma("unroll") for (int _i = 0; _i < 2; ++_i) { \
;         const char* _gb = (const char*)(gbase) + (size_t)_i * (p64); const unsigned _la = ldsbase + (unsigned)(bufoff) + (unsigned)_i * 8192u; \
;         asm volatile("s_mov_b32 m0, %0\n\ts_nop 0\n\tglobal_load_lds_dwordx4 %1, %2" :: "s"(_la), "v"(voff), "s"(_gb) : "memory"); } } while (0)
; #define PG8_LDA(dst, b, h) do { _Pragma("unroll") for (int m = 0; m < 4; ++m) _Pragma("unroll") for (int k = 0; k < 2; ++k) dst[m][k] = *(const LAS bf16x8*)(lds + PG8_SA(b, h) + aoff + m * 2048 + k * 1024); } while (0)
; #define PG8_LDB(dst, b, h) do { _Pragma("unroll") for (int n = 0; n < 2; ++n) _Pragma("unroll") for (int k = 0; k < 2; ++k) dst[n][k] = *(const LAS bf16x8*)(lds + PG8_SB(b, h) + boff + n * 2048 + k * 1024); } while (0)
; #define PG8_WAIT_V(n) asm volatile("s_waitcnt vmcnt(" #n ")" ::: "memory")
; #define PG8_WAIT_L(n) asm volatile("s_waitcnt lgkmcnt(" #n ")" ::: "memory")
; #define PG8_BAR __builtin_amdgcn_s_barrier()
; template <class Epi, class Sched>
; __device__ __forceinline__ void gemm_phase(LAS unsigned char* lds, const Sched& S, const Epi& E) {
;     ...
;             const bool last = (t == nt - 2);
;             const char* a1 = cA + (size_t)(t + 1) * kstep;
;             const char* a2 = last ? nA : cA + (size_t)(t + 2) * kstep; const char* b2 = last ? nB : cB + (size_t)(t + 2) * kstep;
;             const char* a3 = a2 + kstep; const char* b3 = b2 + kstep;
;             const unsigned vA2 = voffA, vB2 = voffB, hA2 = hA, hB2 = hB;
;             PG8_LDB(B0, 0, 0); PG8_LDB(B1, 0, 1); PG8_SCHED; PG8_LDA(At, 0, 0); PG8_STAGE(PG8_SA(1, 1), a1 + hA, voffA, hA / 2);
;             PG8_WAIT_V(8); PG8_WAIT_L(0); PG8_BAR; PG8_MMA(0, 0, At, B0); PG8_MMA(0, 1, At, B1); PG8_BAR; PG8_SCHED;
;             PG8_LDA(At, 0, 1); PG8_STAGE(PG8_SB(0, 0), b2, vB2, hB2 / 2); PG8_STAGE(PG8_SB(0, 1), b2 + hB2, vB2, hB2 / 2); PG8_STAGE(PG8_SA(0, 0), a2, vA2, hA2 / 2);
;             PG8_WAIT_V(8); PG8_WAIT_L(0); PG8_BAR; PG8_MMA(1, 0, At, B0); PG8_MMA(1, 1, At, B1); PG8_BAR; PG8_SCHED;
;             PG8_LDB(B0, 1, 0); PG8_LDB(B1, 1, 1); PG8_SCHED; PG8_LDA(At, 1, 0); PG8_STAGE(PG8_SA(0, 1), a2 + hA2, vA2, hA2 / 2);
;             PG8_WAIT_V(8); PG8_WAIT_L(0); PG8_BAR; PG8_MMA(0, 0, At, B0); PG8_MMA(0, 1, At, B1); PG8_BAR; PG8_SCHED;
.LBB0_1274:
	ds_read_b128 v[128:131], v156
	ds_read_b128 v[132:135], v156 offset:1024
	ds_read_b128 v[140:143], v156 offset:2048
	ds_read_b128 v[144:147], v156 offset:3072
	ds_read_b128 v[148:151], v157
	ds_read_b128 v[162:165], v157 offset:1024
	ds_read_b128 v[166:169], v157 offset:2048
	ds_read_b128 v[170:173], v157 offset:3072
	s_add_u32 s30, s38, 0xfffc0080
	s_addc_u32 s40, s39, -1
	s_cmp_eq_u32 s63, 12
	s_cselect_b32 s41, s25, s40
	s_cselect_b32 s40, s24, s30
	s_cselect_b32 s44, s26, s61
	s_cselect_b32 s45, s27, s62
	s_add_u32 s42, s40, 0x80
	s_addc_u32 s43, s41, 0
	ds_read_b128 v[178:181], v158
	ds_read_b128 v[182:185], v158 offset:1024
	ds_read_b128 v[186:189], v158 offset:2048
	ds_read_b128 v[190:193], v158 offset:3072
	ds_read_b128 v[194:197], v158 offset:4096
	ds_read_b128 v[198:201], v158 offset:5120
	ds_read_b128 v[202:205], v158 offset:6144
	ds_read_b128 v[206:209], v158 offset:7168
	s_mov_b32 m0, s57
	s_nop 0
	global_load_lds_dwordx4 v152, s[38:39]
	s_add_u32 s66, s38, 0x20000
	s_addc_u32 s67, s39, 0
	s_mov_b32 m0, s58
	s_nop 0
	global_load_lds_dwordx4 v152, s[66:67]
	s_waitcnt vmcnt(8)
	s_waitcnt lgkmcnt(0)
	s_barrier
	s_setprio 1
	v_mfma_f32_16x16x32_bf16 v[124:127], v[128:131], v[178:181], v[124:127]
	v_mfma_f32_16x16x32_bf16 v[116:119], v[140:143], v[178:181], v[116:119]
	v_mfma_f32_16x16x32_bf16 v[108:111], v[128:131], v[186:189], v[108:111]
	v_mfma_f32_16x16x32_bf16 v[100:103], v[140:143], v[186:189], v[100:103]
	v_mfma_f32_16x16x32_bf16 v[92:95], v[128:131], v[194:197], v[92:95]
	v_mfma_f32_16x16x32_bf16 v[84:87], v[140:143], v[194:197], v[84:87]
	v_mfma_f32_16x16x32_bf16 v[76:79], v[128:131], v[202:205], v[76:79]
	v_mfma_f32_16x16x32_bf16 v[68:71], v[140:143], v[202:205], v[68:71]
	v_mfma_f32_16x16x32_bf16 v[124:127], v[132:135], v[182:185], v[124:127]
	v_mfma_f32_16x16x32_bf16 v[116:119], v[144:147], v[182:185], v[116:119]
	v_mfma_f32_16x16x32_bf16 v[108:111], v[132:135], v[190:193], v[108:111]
	v_mfma_f32_16x16x32_bf16 v[100:103], v[144:147], v[190:193], v[100:103]
	v_mfma_f32_16x16x32_bf16 v[92:95], v[132:135], v[198:201], v[92:95]
	v_mfma_f32_16x16x32_bf16 v[84:87], v[144:147], v[198:201], v[84:87]
	v_mfma_f32_16x16x32_bf16 v[76:79], v[132:135], v[206:209], v[76:79]
	v_mfma_f32_16x16x32_bf16 v[68:71], v[144:147], v[206:209], v[68:71]
	v_mfma_f32_16x16x32_bf16 v[120:123], v[148:151], v[178:181], v[120:123]
	v_mfma_f32_16x16x32_bf16 v[112:115], v[166:169], v[178:181], v[112:115]
	v_mfma_f32_16x16x32_bf16 v[104:107], v[148:151], v[186:189], v[104:107]
	v_mfma_f32_16x16x32_bf16 v[96:99], v[166:169], v[186:189], v[96:99]
	v_mfma_f32_16x16x32_bf16 v[88:91], v[148:151], v[194:197], v[88:91]
	v_mfma_f32_16x16x32_bf16 v[80:83], v[166:169], v[194:197], v[80:83]
	v_mfma_f32_16x16x32_bf16 v[72:75], v[148:151], v[202:205], v[72:75]
	v_mfma_f32_16x16x32_bf16 v[64:67], v[166:169], v[202:205], v[64:67]
	v_mfma_f32_16x16x32_bf16 v[120:123], v[162:165], v[182:185], v[120:123]
	v_mfma_f32_16x16x32_bf16 v[112:115], v[170:173], v[182:185], v[112:115]
	v_mfma_f32_16x16x32_bf16 v[104:107], v[162:165], v[190:193], v[104:107]
	v_mfma_f32_16x16x32_bf16 v[96:99], v[170:173], v[190:193], v[96:99]
	v_mfma_f32_16x16x32_bf16 v[88:91], v[162:165], v[198:201], v[88:91]
	v_mfma_f32_16x16x32_bf16 v[80:83], v[170:173], v[198:201], v[80:83]
	v_mfma_f32_16x16x32_bf16 v[72:75], v[162:165], v[206:209], v[72:75]
	v_mfma_f32_16x16x32_bf16 v[64:67], v[170:173], v[206:209], v[64:67]
	s_setprio 0
	s_barrier
	s_add_u32 s66, s44, 0x20000
	ds_read_b128 v[178:181], v158 offset:16384
	ds_read_b128 v[182:185], v158 offset:17408
	ds_read_b128 v[186:189], v158 offset:18432
	ds_read_b128 v[190:193], v158 offset:19456
	ds_read_b128 v[194:197], v158 offset:20480
	ds_read_b128 v[198:201], v158 offset:21504
	ds_read_b128 v[202:205], v158 offset:22528
	ds_read_b128 v[206:209], v158 offset:23552
	s_mov_b32 m0, s35
	s_nop 0
	global_load_lds_dwordx4 v153, s[44:45]
	s_addc_u32 s67, s45, 0
	s_mov_b32 m0, s36
	s_nop 0
	global_load_lds_dwordx4 v153, s[66:67]
	s_add_u32 s66, s44, 0x40000
	s_addc_u32 s67, s45, 0
	s_mov_b32 m0, s37
	s_nop 0
	global_load_lds_dwordx4 v153, s[66:67]
	s_add_u32 s66, s44, 0x60000
	s_addc_u32 s67, s45, 0
	s_mov_b32 m0, s46
	s_nop 0
	global_load_lds_dwordx4 v153, s[66:67]
	s_mov_b32 m0, s34
	s_nop 0
	global_load_lds_dwordx4 v152, s[40:41]
	s_add_u32 s66, s40, 0x20000
	s_addc_u32 s67, s41, 0
	s_mov_b32 m0, s47
	s_nop 0
	global_load_lds_dwordx4 v152, s[66:67]
	s_waitcnt vmcnt(8)
	s_waitcnt lgkmcnt(0)
	s_barrier
	s_setprio 1
	v_mfma_f32_16x16x32_bf16 v[60:63], v[128:131], v[178:181], v[60:63]
	v_mfma_f32_16x16x32_bf16 v[52:55], v[140:143], v[178:181], v[52:55]
	v_mfma_f32_16x16x32_bf16 v[44:47], v[128:131], v[186:189], v[44:47]
	v_mfma_f32_16x16x32_bf16 v[36:39], v[140:143], v[186:189], v[36:39]
	v_mfma_f32_16x16x32_bf16 v[28:31], v[128:131], v[194:197], v[28:31]
	v_mfma_f32_16x16x32_bf16 v[20:23], v[140:143], v[194:197], v[20:23]
	v_mfma_f32_16x16x32_bf16 v[12:15], v[128:131], v[202:205], v[12:15]
	v_mfma_f32_16x16x32_bf16 v[4:7], v[140:143], v[202:205], v[4:7]
	v_mfma_f32_16x16x32_bf16 v[60:63], v[132:135], v[182:185], v[60:63]
	v_mfma_f32_16x16x32_bf16 v[52:55], v[144:147], v[182:185], v[52:55]
	v_mfma_f32_16x16x32_bf16 v[44:47], v[132:135], v[190:193], v[44:47]
	v_mfma_f32_16x16x32_bf16 v[36:39], v[144:147], v[190:193], v[36:39]
	v_mfma_f32_16x16x32_bf16 v[28:31], v[132:135], v[198:201], v[28:31]
	v_mfma_f32_16x16x32_bf16 v[20:23], v[144:147], v[198:201], v[20:23]
	v_mfma_f32_16x16x32_bf16 v[12:15], v[132:135], v[206:209], v[12:15]
	v_mfma_f32_16x16x32_bf16 v[4:7], v[144:147], v[206:209], v[4:7]
	v_mfma_f32_16x16x32_bf16 v[56:59], v[148:151], v[178:181], v[56:59]
	v_mfma_f32_16x16x32_bf16 v[48:51], v[166:169], v[178:181], v[48:51]
	v_mfma_f32_16x16x32_bf16 v[40:43], v[148:151], v[186:189], v[40:43]
	v_mfma_f32_16x16x32_bf16 v[32:35], v[166:169], v[186:189], v[32:35]
	v_mfma_f32_16x16x32_bf16 v[24:27], v[148:151], v[194:197], v[24:27]
	v_mfma_f32_16x16x32_bf16 v[16:19], v[166:169], v[194:197], v[16:19]
	v_mfma_f32_16x16x32_bf16 v[8:11], v[148:151], v[202:205], v[8:11]
	v_mfma_f32_16x16x32_bf16 v[0:3], v[166:169], v[202:205], v[0:3]
	v_mfma_f32_16x16x32_bf16 v[56:59], v[162:165], v[182:185], v[56:59]
	v_mfma_f32_16x16x32_bf16 v[48:51], v[170:173], v[182:185], v[48:51]
	v_mfma_f32_16x16x32_bf16 v[40:43], v[162:165], v[190:193], v[40:43]
	v_mfma_f32_16x16x32_bf16 v[32:35], v[170:173], v[190:193], v[32:35]
	v_mfma_f32_16x16x32_bf16 v[24:27], v[162:165], v[198:201], v[24:27]
	v_mfma_f32_16x16x32_bf16 v[16:19], v[170:173], v[198:201], v[16:19]
	v_mfma_f32_16x16x32_bf16 v[8:11], v[162:165], v[206:209], v[8:11]
	v_mfma_f32_16x16x32_bf16 v[0:3], v[170:173], v[206:209], v[0:3]
	s_setprio 0
	s_barrier
; #define PG8_STAGE(bufoff, gbase, voff, p64) do { _Pragma("unroll") for (int _i = 0; _i < 2; ++_i) { \
;         const char* _gb = (const char*)(gbase) + (size_t)_i * (p64); const unsigned _la = ldsbase + (unsigned)(bufoff) + (unsigned)_i * 8192u; \
;         asm volatile("s_mov_b32 m0, %0\n\ts_nop 0\n\tglobal_load_lds_dwordx4 %1, %2" :: "s"(_la), "v"(voff), "s"(_gb) : "memory"); } } while (0)
; #define PG8_LDA(dst, b, h) do { _Pragma("unroll") for (int m = 0; m < 4; ++m) _Pragma("unroll") for (int k = 0; k < 2; ++k) dst[m][k] = *(const LAS bf16x8*)(lds + PG8_SA(b, h) + aoff + m * 2048 + k * 1024); } while (0)
; #define PG8_LDB(dst, b, h) do { _Pragma("unroll") for (int n = 0; n < 2; ++n) _Pragma("unroll") for (int k = 0; k < 2; ++k) dst[n][k] = *(const LAS bf16x8*)(lds + PG8_SB(b, h) + boff + n * 2048 + k * 1024); } while (0)
; #define PG8_MMA(ai, bj, At, Bt) do { __builtin_amdgcn_s_setprio(1); _Pragma("unroll") for (int m = 0; m < 4; ++m) _Pragma("unroll") for (int n = 0; n < 2; ++n) _Pragma("unroll") for (int k = 0; k < 2; ++k) \
;         acc[ai][bj][m][n] = __builtin_amdgcn_mfma_f32_16x16x32_bf16(Bt[n][k], At[m][k], acc[ai][bj][m][n], 0, 0, 0); __builtin_amdgcn_s_setprio(0); } while (0)
; #define PG8_WAIT_V(n) asm volatile("s_waitcnt vmcnt(" #n ")" ::: "memory")
; #define PG8_WAIT_L(n) asm volatile("s_waitcnt lgkmcnt(" #n ")" ::: "memory")
; #define PG8_BAR __builtin_amdgcn_s_barrier()
; #define PG8_SCHED __builtin_amdgcn_sched_barrier(0)
; template <class Epi, class Sched>
; __device__ __forceinline__ void gemm_phase(LAS unsigned char* lds, const Sched& S, const Epi& E) {
;     ...
;             PG8_LDB(B0, 1, 0); PG8_LDB(B1, 1, 1); PG8_SCHED; PG8_LDA(At, 1, 0); PG8_STAGE(PG8_SA(0, 1), a2 + hA2, vA2, hA2 / 2);
;             PG8_WAIT_V(8); PG8_WAIT_L(0); PG8_BAR; PG8_MMA(0, 0, At, B0); PG8_MMA(0, 1, At, B1); PG8_BAR; PG8_SCHED;
;             PG8_LDA(At, 1, 1); PG8_STAGE(PG8_SB(1, 0), b3, vB2, hB2 / 2); PG8_STAGE(PG8_SB(1, 1), b3 + hB2, vB2, hB2 / 2); PG8_STAGE(PG8_SA(1, 0), a3, vA2, hA2 / 2);
;             PG8_WAIT_V(8); PG8_WAIT_L(0); PG8_BAR; PG8_MMA(1, 0, At, B0); PG8_MMA(1, 1, At, B1); PG8_BAR; PG8_SCHED;
;         }
;         if (wr == 0) PG8_BAR;
	ds_read_b128 v[128:131], v159
	ds_read_b128 v[132:135], v159 offset:1024
	ds_read_b128 v[140:143], v159 offset:2048
	ds_read_b128 v[144:147], v159 offset:3072
	ds_read_b128 v[148:151], v160
	ds_read_b128 v[162:165], v160 offset:1024
	ds_read_b128 v[166:169], v160 offset:2048
	ds_read_b128 v[170:173], v160 offset:3072
	ds_read_b128 v[178:181], v158 offset:32768
	ds_read_b128 v[182:185], v158 offset:33792
	ds_read_b128 v[186:189], v158 offset:34816
	ds_read_b128 v[190:193], v158 offset:35840
	ds_read_b128 v[194:197], v158 offset:36864
	ds_read_b128 v[198:201], v158 offset:37888
	ds_read_b128 v[202:205], v158 offset:38912
	ds_read_b128 v[206:209], v158 offset:39936
	s_add_u32 s66, s40, 0x40000
	s_addc_u32 s67, s41, 0
	s_mov_b32 m0, s48
	s_nop 0
	global_load_lds_dwordx4 v152, s[66:67]
	s_add_u32 s66, s40, 0x60000
	s_addc_u32 s67, s41, 0
	s_mov_b32 m0, s49
	s_nop 0
	global_load_lds_dwordx4 v152, s[66:67]
	s_waitcnt vmcnt(8)
	s_waitcnt lgkmcnt(0)
	s_barrier
	s_setprio 1
	v_mfma_f32_16x16x32_bf16 v[124:127], v[128:131], v[178:181], v[124:127]
	v_mfma_f32_16x16x32_bf16 v[116:119], v[140:143], v[178:181], v[116:119]
	v_mfma_f32_16x16x32_bf16 v[108:111], v[128:131], v[186:189], v[108:111]
	v_mfma_f32_16x16x32_bf16 v[100:103], v[140:143], v[186:189], v[100:103]
	v_mfma_f32_16x16x32_bf16 v[92:95], v[128:131], v[194:197], v[92:95]
	v_mfma_f32_16x16x32_bf16 v[84:87], v[140:143], v[194:197], v[84:87]
	v_mfma_f32_16x16x32_bf16 v[76:79], v[128:131], v[202:205], v[76:79]
	v_mfma_f32_16x16x32_bf16 v[68:71], v[140:143], v[202:205], v[68:71]
	v_mfma_f32_16x16x32_bf16 v[124:127], v[132:135], v[182:185], v[124:127]
	v_mfma_f32_16x16x32_bf16 v[116:119], v[144:147], v[182:185], v[116:119]
	v_mfma_f32_16x16x32_bf16 v[108:111], v[132:135], v[190:193], v[108:111]
	v_mfma_f32_16x16x32_bf16 v[100:103], v[144:147], v[190:193], v[100:103]
	v_mfma_f32_16x16x32_bf16 v[92:95], v[132:135], v[198:201], v[92:95]
	v_mfma_f32_16x16x32_bf16 v[84:87], v[144:147], v[198:201], v[84:87]
	v_mfma_f32_16x16x32_bf16 v[76:79], v[132:135], v[206:209], v[76:79]
	v_mfma_f32_16x16x32_bf16 v[68:71], v[144:147], v[206:209], v[68:71]
	v_mfma_f32_16x16x32_bf16 v[120:123], v[148:151], v[178:181], v[120:123]
	v_mfma_f32_16x16x32_bf16 v[112:115], v[166:169], v[178:181], v[112:115]
	v_mfma_f32_16x16x32_bf16 v[104:107], v[148:151], v[186:189], v[104:107]
	v_mfma_f32_16x16x32_bf16 v[96:99], v[166:169], v[186:189], v[96:99]
	v_mfma_f32_16x16x32_bf16 v[88:91], v[148:151], v[194:197], v[88:91]
	v_mfma_f32_16x16x32_bf16 v[80:83], v[166:169], v[194:197], v[80:83]
	v_mfma_f32_16x16x32_bf16 v[72:75], v[148:151], v[202:205], v[72:75]
	v_mfma_f32_16x16x32_bf16 v[64:67], v[166:169], v[202:205], v[64:67]
	v_mfma_f32_16x16x32_bf16 v[120:123], v[162:165], v[182:185], v[120:123]
	v_mfma_f32_16x16x32_bf16 v[112:115], v[170:173], v[182:185], v[112:115]
	v_mfma_f32_16x16x32_bf16 v[104:107], v[162:165], v[190:193], v[104:107]
	v_mfma_f32_16x16x32_bf16 v[96:99], v[170:173], v[190:193], v[96:99]
	v_mfma_f32_16x16x32_bf16 v[88:91], v[162:165], v[198:201], v[88:91]
	v_mfma_f32_16x16x32_bf16 v[80:83], v[170:173], v[198:201], v[80:83]
	v_mfma_f32_16x16x32_bf16 v[72:75], v[162:165], v[206:209], v[72:75]
	v_mfma_f32_16x16x32_bf16 v[64:67], v[170:173], v[206:209], v[64:67]
	s_setprio 0
	s_barrier
	s_add_u32 s66, s44, 0x80
	s_addc_u32 s67, s45, 0
	ds_read_b128 v[178:181], v158 offset:49152
	ds_read_b128 v[182:185], v158 offset:50176
	ds_read_b128 v[186:189], v158 offset:51200
	ds_read_b128 v[190:193], v158 offset:52224
	ds_read_b128 v[194:197], v158 offset:53248
	ds_read_b128 v[198:201], v158 offset:54272
	ds_read_b128 v[202:205], v158 offset:55296
	ds_read_b128 v[206:209], v158 offset:56320
	s_mov_b32 m0, s51
	s_nop 0
	global_load_lds_dwordx4 v153, s[66:67]
	s_add_u32 s66, s44, 0x20080
	s_addc_u32 s67, s45, 0
	s_mov_b32 m0, s52
	s_nop 0
	global_load_lds_dwordx4 v153, s[66:67]
	s_add_u32 s66, s44, 0x40080
	s_addc_u32 s67, s45, 0
	s_mov_b32 m0, s55
	s_nop 0
	global_load_lds_dwordx4 v153, s[66:67]
	s_add_u32 s44, s44, 0x60080
	s_addc_u32 s45, s45, 0
	s_mov_b32 m0, s56
	s_nop 0
	global_load_lds_dwordx4 v153, s[44:45]
	s_mov_b32 m0, s53
	s_nop 0
	global_load_lds_dwordx4 v152, s[42:43]
	s_add_u32 s40, s40, 0x20080
	s_addc_u32 s41, s41, 0
	s_mov_b32 m0, s54
	s_nop 0
	global_load_lds_dwordx4 v152, s[40:41]
	s_waitcnt vmcnt(8)
	s_waitcnt lgkmcnt(0)
	s_barrier
	s_setprio 1
	v_mfma_f32_16x16x32_bf16 v[60:63], v[128:131], v[178:181], v[60:63]
	v_mfma_f32_16x16x32_bf16 v[52:55], v[140:143], v[178:181], v[52:55]
	v_mfma_f32_16x16x32_bf16 v[44:47], v[128:131], v[186:189], v[44:47]
	v_mfma_f32_16x16x32_bf16 v[36:39], v[140:143], v[186:189], v[36:39]
	v_mfma_f32_16x16x32_bf16 v[28:31], v[128:131], v[194:197], v[28:31]
	v_mfma_f32_16x16x32_bf16 v[20:23], v[140:143], v[194:197], v[20:23]
	v_mfma_f32_16x16x32_bf16 v[12:15], v[128:131], v[202:205], v[12:15]
	v_mfma_f32_16x16x32_bf16 v[4:7], v[140:143], v[202:205], v[4:7]
	v_mfma_f32_16x16x32_bf16 v[60:63], v[132:135], v[182:185], v[60:63]
	v_mfma_f32_16x16x32_bf16 v[52:55], v[144:147], v[182:185], v[52:55]
	v_mfma_f32_16x16x32_bf16 v[44:47], v[132:135], v[190:193], v[44:47]
	v_mfma_f32_16x16x32_bf16 v[36:39], v[144:147], v[190:193], v[36:39]
	v_mfma_f32_16x16x32_bf16 v[28:31], v[132:135], v[198:201], v[28:31]
	v_mfma_f32_16x16x32_bf16 v[20:23], v[144:147], v[198:201], v[20:23]
	v_mfma_f32_16x16x32_bf16 v[12:15], v[132:135], v[206:209], v[12:15]
	v_mfma_f32_16x16x32_bf16 v[4:7], v[144:147], v[206:209], v[4:7]
	v_mfma_f32_16x16x32_bf16 v[56:59], v[148:151], v[178:181], v[56:59]
	v_mfma_f32_16x16x32_bf16 v[48:51], v[166:169], v[178:181], v[48:51]
	v_mfma_f32_16x16x32_bf16 v[40:43], v[148:151], v[186:189], v[40:43]
	v_mfma_f32_16x16x32_bf16 v[32:35], v[166:169], v[186:189], v[32:35]
	v_mfma_f32_16x16x32_bf16 v[24:27], v[148:151], v[194:197], v[24:27]
	v_mfma_f32_16x16x32_bf16 v[16:19], v[166:169], v[194:197], v[16:19]
	v_mfma_f32_16x16x32_bf16 v[8:11], v[148:151], v[202:205], v[8:11]
	v_mfma_f32_16x16x32_bf16 v[0:3], v[166:169], v[202:205], v[0:3]
	v_mfma_f32_16x16x32_bf16 v[56:59], v[162:165], v[182:185], v[56:59]
	v_mfma_f32_16x16x32_bf16 v[48:51], v[170:173], v[182:185], v[48:51]
	v_mfma_f32_16x16x32_bf16 v[40:43], v[162:165], v[190:193], v[40:43]
	v_mfma_f32_16x16x32_bf16 v[32:35], v[170:173], v[190:193], v[32:35]
	v_mfma_f32_16x16x32_bf16 v[24:27], v[162:165], v[198:201], v[24:27]
	v_mfma_f32_16x16x32_bf16 v[16:19], v[170:173], v[198:201], v[16:19]
	v_mfma_f32_16x16x32_bf16 v[8:11], v[162:165], v[206:209], v[8:11]
	v_mfma_f32_16x16x32_bf16 v[0:3], v[170:173], v[206:209], v[0:3]
	s_setprio 0
	s_barrier
	s_add_i32 s63, s63, 2
	s_add_u32 s38, s38, 0x100
	s_addc_u32 s39, s39, 0
	s_add_u32 s61, s61, 0x100
	s_addc_u32 s62, s62, 0
	s_cmp_gt_u32 s63, 13
	s_cbranch_scc0 .LBB0_1274
	s_and_b64 vcc, exec, s[18:19]
	s_cbranch_vccz .LBB0_1277
	s_barrier

; #define PG8_STAGE(bufoff, gbase, voff, p64) do { _Pragma("unroll") for (int _i = 0; _i < 2; ++_i) { \
;         const char* _gb = (const char*)(gbase) + (size_t)_i * (p64); const unsigned _la = ldsbase + (unsigned)(bufoff) + (unsigned)_i * 8192u; \
;         asm volatile("s_mov_b32 m0, %0\n\ts_nop 0\n\tglobal_load_lds_dwordx4 %1, %2" :: "s"(_la), "v"(voff), "s"(_gb) : "memory"); } } while (0)
; #define PG8_LDA(dst, b, h) do { _Pragma("unroll") for (int m = 0; m < 4; ++m) _Pragma("unroll") for (int k = 0; k < 2; ++k) dst[m][k] = *(const LAS bf16x8*)(lds + PG8_SA(b, h) + aoff + m * 2048 + k * 1024); } while (0)
; #define PG8_LDB(dst, b, h) do { _Pragma("unroll") for (int n = 0; n < 2; ++n) _Pragma("unroll") for (int k = 0; k < 2; ++k) dst[n][k] = *(const LAS bf16x8*)(lds + PG8_SB(b, h) + boff + n * 2048 + k * 1024); } while (0)
; #define PG8_MMA(ai, bj, At, Bt) do { __builtin_amdgcn_s_setprio(1); _Pragma("unroll") for (int m = 0; m < 4; ++m) _Pragma("unroll") for (int n = 0; n < 2; ++n) _Pragma("unroll") for (int k = 0; k < 2; ++k) \
;         acc[ai][bj][m][n] = __builtin_amdgcn_mfma_f32_16x16x32_bf16(Bt[n][k], At[m][k], acc[ai][bj][m][n], 0, 0, 0); __builtin_amdgcn_s_setprio(0); } while (0)
; #define PG8_WAIT_V(n) asm volatile("s_waitcnt vmcnt(" #n ")" ::: "memory")
; template <class Epi, class Sched>
; __device__ __forceinline__ void gemm_phase(LAS unsigned char* lds, const Sched& S, const Epi& E) {
;     ...
;         for (int t = 0; t < nt; t += 2) {
;             const bool last = (t == nt - 2);
;             const char* a1 = cA + (size_t)(t + 1) * kstep;
;             const char* a2 = last ? nA : cA + (size_t)(t + 2) * kstep; const char* b2 = last ? nB : cB + (size_t)(t + 2) * kstep;
;             const char* a3 = a2 + kstep; const char* b3 = b2 + kstep;
;             const unsigned vA2 = voffA, vB2 = voffB, hA2 = hA, hB2 = hB;
;             PG8_LDB(B0, 0, 0); PG8_LDB(B1, 0, 1); PG8_SCHED; PG8_LDA(At, 0, 0); PG8_STAGE(PG8_SA(1, 1), a1 + hA, voffA, hA / 2);
;             PG8_WAIT_V(8); PG8_WAIT_L(0); PG8_BAR; PG8_MMA(0, 0, At, B0); PG8_MMA(0, 1, At, B1); PG8_BAR; PG8_SCHED;
;             PG8_LDA(At, 0, 1); PG8_STAGE(PG8_SB(0, 0), b2, vB2, hB2 / 2); PG8_STAGE(PG8_SB(0, 1), b2 + hB2, vB2, hB2 / 2); PG8_STAGE(PG8_SA(0, 0), a2, vA2, hA2 / 2);
;             PG8_WAIT_V(8); PG8_WAIT_L(0); PG8_BAR; PG8_MMA(1, 0, At, B0); PG8_MMA(1, 1, At, B1); PG8_BAR; PG8_SCHED;
.LBB0_1352:
	ds_read_b128 v[128:131], v174
	ds_read_b128 v[132:135], v174 offset:1024
	ds_read_b128 v[136:139], v174 offset:2048
	ds_read_b128 v[144:147], v174 offset:3072
	ds_read_b128 v[148:151], v175
	ds_read_b128 v[152:155], v175 offset:1024
	ds_read_b128 v[156:159], v175 offset:2048
	ds_read_b128 v[160:163], v175 offset:3072
	s_add_u32 s24, s22, 0xfffc0080
	s_addc_u32 s25, s23, -1
	s_cmp_eq_u32 s61, 12
	s_cselect_b32 s24, s18, s24
	s_cselect_b32 s25, s19, s25
	s_cselect_b32 s38, s20, s59
	s_cselect_b32 s39, s21, s60
	s_add_u32 s26, s24, 0x80
	s_addc_u32 s27, s25, 0
	ds_read_b128 v[164:167], v177
	ds_read_b128 v[180:183], v177 offset:1024
	ds_read_b128 v[184:187], v177 offset:2048
	ds_read_b128 v[188:191], v177 offset:3072
	ds_read_b128 v[192:195], v177 offset:4096
	ds_read_b128 v[196:199], v177 offset:5120
	ds_read_b128 v[200:203], v177 offset:6144
	ds_read_b128 v[204:207], v177 offset:7168
	s_mov_b32 m0, s54
	s_nop 0
	global_load_lds_dwordx4 v170, s[22:23]
	s_add_u32 s62, s22, 0x20000
	s_addc_u32 s63, s23, 0
	s_mov_b32 m0, s55
	s_nop 0
	global_load_lds_dwordx4 v170, s[62:63]
	s_waitcnt vmcnt(8)
	s_waitcnt lgkmcnt(0)
	s_barrier
	s_setprio 1
	v_mfma_f32_16x16x32_bf16 v[84:87], v[128:131], v[164:167], v[84:87]
	v_mfma_f32_16x16x32_bf16 v[76:79], v[136:139], v[164:167], v[76:79]
	v_mfma_f32_16x16x32_bf16 v[124:127], v[128:131], v[184:187], v[124:127]
	v_mfma_f32_16x16x32_bf16 v[120:123], v[136:139], v[184:187], v[120:123]
	v_mfma_f32_16x16x32_bf16 v[116:119], v[128:131], v[192:195], v[116:119]
	v_mfma_f32_16x16x32_bf16 v[112:115], v[136:139], v[192:195], v[112:115]
	v_mfma_f32_16x16x32_bf16 v[108:111], v[128:131], v[200:203], v[108:111]
	v_mfma_f32_16x16x32_bf16 v[104:107], v[136:139], v[200:203], v[104:107]
	v_mfma_f32_16x16x32_bf16 v[84:87], v[132:135], v[180:183], v[84:87]
	v_mfma_f32_16x16x32_bf16 v[76:79], v[144:147], v[180:183], v[76:79]
	v_mfma_f32_16x16x32_bf16 v[124:127], v[132:135], v[188:191], v[124:127]
	v_mfma_f32_16x16x32_bf16 v[120:123], v[144:147], v[188:191], v[120:123]
	v_mfma_f32_16x16x32_bf16 v[116:119], v[132:135], v[196:199], v[116:119]
	v_mfma_f32_16x16x32_bf16 v[112:115], v[144:147], v[196:199], v[112:115]
	v_mfma_f32_16x16x32_bf16 v[108:111], v[132:135], v[204:207], v[108:111]
	v_mfma_f32_16x16x32_bf16 v[104:107], v[144:147], v[204:207], v[104:107]
	v_mfma_f32_16x16x32_bf16 v[60:63], v[148:151], v[164:167], v[60:63]
	v_mfma_f32_16x16x32_bf16 v[56:59], v[156:159], v[164:167], v[56:59]
	v_mfma_f32_16x16x32_bf16 v[52:55], v[148:151], v[184:187], v[52:55]
	v_mfma_f32_16x16x32_bf16 v[48:51], v[156:159], v[184:187], v[48:51]
	v_mfma_f32_16x16x32_bf16 v[44:47], v[148:151], v[192:195], v[44:47]
	v_mfma_f32_16x16x32_bf16 v[40:43], v[156:159], v[192:195], v[40:43]
	v_mfma_f32_16x16x32_bf16 v[36:39], v[148:151], v[200:203], v[36:39]
	v_mfma_f32_16x16x32_bf16 v[32:35], v[156:159], v[200:203], v[32:35]
	v_mfma_f32_16x16x32_bf16 v[60:63], v[152:155], v[180:183], v[60:63]
	v_mfma_f32_16x16x32_bf16 v[56:59], v[160:163], v[180:183], v[56:59]
	v_mfma_f32_16x16x32_bf16 v[52:55], v[152:155], v[188:191], v[52:55]
	v_mfma_f32_16x16x32_bf16 v[48:51], v[160:163], v[188:191], v[48:51]
	v_mfma_f32_16x16x32_bf16 v[44:47], v[152:155], v[196:199], v[44:47]
	v_mfma_f32_16x16x32_bf16 v[40:43], v[160:163], v[196:199], v[40:43]
	v_mfma_f32_16x16x32_bf16 v[36:39], v[152:155], v[204:207], v[36:39]
	v_mfma_f32_16x16x32_bf16 v[32:35], v[160:163], v[204:207], v[32:35]
	s_setprio 0
	s_barrier
	s_add_u32 s62, s38, 0x20000
	ds_read_b128 v[164:167], v177 offset:16384
	ds_read_b128 v[180:183], v177 offset:17408
	ds_read_b128 v[184:187], v177 offset:18432
	ds_read_b128 v[188:191], v177 offset:19456
	ds_read_b128 v[192:195], v177 offset:20480
	ds_read_b128 v[196:199], v177 offset:21504
	ds_read_b128 v[200:203], v177 offset:22528
	ds_read_b128 v[204:207], v177 offset:23552
	s_mov_b32 m0, s35
	s_nop 0
	global_load_lds_dwordx4 v171, s[38:39]
	s_addc_u32 s63, s39, 0
	s_mov_b32 m0, s36
	s_nop 0
	global_load_lds_dwordx4 v171, s[62:63]
	s_add_u32 s62, s38, 0x40000
	s_addc_u32 s63, s39, 0
	s_mov_b32 m0, s37
	s_nop 0
	global_load_lds_dwordx4 v171, s[62:63]
	s_add_u32 s62, s38, 0x60000
	s_addc_u32 s63, s39, 0
	s_mov_b32 m0, s40
	s_nop 0
	global_load_lds_dwordx4 v171, s[62:63]
	s_mov_b32 m0, s34
	s_nop 0
	global_load_lds_dwordx4 v170, s[24:25]
	s_add_u32 s62, s24, 0x20000
	s_addc_u32 s63, s25, 0
	s_mov_b32 m0, s41
	s_nop 0
	global_load_lds_dwordx4 v170, s[62:63]
	s_waitcnt vmcnt(8)
	s_waitcnt lgkmcnt(0)
	s_barrier
	s_setprio 1
	v_mfma_f32_16x16x32_bf16 v[100:103], v[128:131], v[164:167], v[100:103]
	v_mfma_f32_16x16x32_bf16 v[96:99], v[136:139], v[164:167], v[96:99]
	v_mfma_f32_16x16x32_bf16 v[92:95], v[128:131], v[184:187], v[92:95]
	v_mfma_f32_16x16x32_bf16 v[88:91], v[136:139], v[184:187], v[88:91]
	v_mfma_f32_16x16x32_bf16 v[80:83], v[128:131], v[192:195], v[80:83]
	v_mfma_f32_16x16x32_bf16 v[72:75], v[136:139], v[192:195], v[72:75]
	v_mfma_f32_16x16x32_bf16 v[68:71], v[128:131], v[200:203], v[68:71]
	v_mfma_f32_16x16x32_bf16 v[64:67], v[136:139], v[200:203], v[64:67]
	v_mfma_f32_16x16x32_bf16 v[100:103], v[132:135], v[180:183], v[100:103]
	v_mfma_f32_16x16x32_bf16 v[96:99], v[144:147], v[180:183], v[96:99]
	v_mfma_f32_16x16x32_bf16 v[92:95], v[132:135], v[188:191], v[92:95]
	v_mfma_f32_16x16x32_bf16 v[88:91], v[144:147], v[188:191], v[88:91]
	v_mfma_f32_16x16x32_bf16 v[80:83], v[132:135], v[196:199], v[80:83]
	v_mfma_f32_16x16x32_bf16 v[72:75], v[144:147], v[196:199], v[72:75]
	v_mfma_f32_16x16x32_bf16 v[68:71], v[132:135], v[204:207], v[68:71]
	v_mfma_f32_16x16x32_bf16 v[64:67], v[144:147], v[204:207], v[64:67]
	v_mfma_f32_16x16x32_bf16 v[28:31], v[148:151], v[164:167], v[28:31]
	v_mfma_f32_16x16x32_bf16 v[24:27], v[156:159], v[164:167], v[24:27]
	v_mfma_f32_16x16x32_bf16 v[20:23], v[148:151], v[184:187], v[20:23]
	v_mfma_f32_16x16x32_bf16 v[16:19], v[156:159], v[184:187], v[16:19]
	v_mfma_f32_16x16x32_bf16 v[12:15], v[148:151], v[192:195], v[12:15]
	v_mfma_f32_16x16x32_bf16 v[8:11], v[156:159], v[192:195], v[8:11]
	v_mfma_f32_16x16x32_bf16 v[4:7], v[148:151], v[200:203], v[4:7]
	v_mfma_f32_16x16x32_bf16 v[0:3], v[156:159], v[200:203], v[0:3]
	v_mfma_f32_16x16x32_bf16 v[28:31], v[152:155], v[180:183], v[28:31]
	v_mfma_f32_16x16x32_bf16 v[24:27], v[160:163], v[180:183], v[24:27]
	v_mfma_f32_16x16x32_bf16 v[20:23], v[152:155], v[188:191], v[20:23]
	v_mfma_f32_16x16x32_bf16 v[16:19], v[160:163], v[188:191], v[16:19]
	v_mfma_f32_16x16x32_bf16 v[12:15], v[152:155], v[196:199], v[12:15]
	v_mfma_f32_16x16x32_bf16 v[8:11], v[160:163], v[196:199], v[8:11]
	v_mfma_f32_16x16x32_bf16 v[4:7], v[152:155], v[204:207], v[4:7]
	v_mfma_f32_16x16x32_bf16 v[0:3], v[160:163], v[204:207], v[0:3]
	s_setprio 0
	s_barrier
; #define PG8_STAGE(bufoff, gbase, voff, p64) do { _Pragma("unroll") for (int _i = 0; _i < 2; ++_i) { \
;         const char* _gb = (const char*)(gbase) + (size_t)_i * (p64); const unsigned _la = ldsbase + (unsigned)(bufoff) + (unsigned)_i * 8192u; \
;         asm volatile("s_mov_b32 m0, %0\n\ts_nop 0\n\tglobal_load_lds_dwordx4 %1, %2" :: "s"(_la), "v"(voff), "s"(_gb) : "memory"); } } while (0)
; #define PG8_LDA(dst, b, h) do { _Pragma("unroll") for (int m = 0; m < 4; ++m) _Pragma("unroll") for (int k = 0; k < 2; ++k) dst[m][k] = *(const LAS bf16x8*)(lds + PG8_SA(b, h) + aoff + m * 2048 + k * 1024); } while (0)
; #define PG8_LDB(dst, b, h) do { _Pragma("unroll") for (int n = 0; n < 2; ++n) _Pragma("unroll") for (int k = 0; k < 2; ++k) dst[n][k] = *(const LAS bf16x8*)(lds + PG8_SB(b, h) + boff + n * 2048 + k * 1024); } while (0)
; #define PG8_MMA(ai, bj, At, Bt) do { __builtin_amdgcn_s_setprio(1); _Pragma("unroll") for (int m = 0; m < 4; ++m) _Pragma("unroll") for (int n = 0; n < 2; ++n) _Pragma("unroll") for (int k = 0; k < 2; ++k) \
;         acc[ai][bj][m][n] = __builtin_amdgcn_mfma_f32_16x16x32_bf16(Bt[n][k], At[m][k], acc[ai][bj][m][n], 0, 0, 0); __builtin_amdgcn_s_setprio(0); } while (0)
; #define PG8_WAIT_V(n) asm volatile("s_waitcnt vmcnt(" #n ")" ::: "memory")
; #define PG8_WAIT_L(n) asm volatile("s_waitcnt lgkmcnt(" #n ")" ::: "memory")
; #define PG8_BAR __builtin_amdgcn_s_barrier()
; #define PG8_SCHED __builtin_amdgcn_sched_barrier(0)
; template <class Epi, class Sched>
; __device__ __forceinline__ void gemm_phase(LAS unsigned char* lds, const Sched& S, const Epi& E) {
;     ...
;             PG8_LDB(B0, 1, 0); PG8_LDB(B1, 1, 1); PG8_SCHED; PG8_LDA(At, 1, 0); PG8_STAGE(PG8_SA(0, 1), a2 + hA2, vA2, hA2 / 2);
;             PG8_WAIT_V(8); PG8_WAIT_L(0); PG8_BAR; PG8_MMA(0, 0, At, B0); PG8_MMA(0, 1, At, B1); PG8_BAR; PG8_SCHED;
;             PG8_LDA(At, 1, 1); PG8_STAGE(PG8_SB(1, 0), b3, vB2, hB2 / 2); PG8_STAGE(PG8_SB(1, 1), b3 + hB2, vB2, hB2 / 2); PG8_STAGE(PG8_SA(1, 0), a3, vA2, hA2 / 2);
;             PG8_WAIT_V(8); PG8_WAIT_L(0); PG8_BAR; PG8_MMA(1, 0, At, B0); PG8_MMA(1, 1, At, B1); PG8_BAR; PG8_SCHED;
;         }
;         if (wr == 0) PG8_BAR;
	ds_read_b128 v[128:131], v178
	ds_read_b128 v[132:135], v178 offset:1024
	ds_read_b128 v[136:139], v178 offset:2048
	ds_read_b128 v[144:147], v178 offset:3072
	ds_read_b128 v[148:151], v179
	ds_read_b128 v[152:155], v179 offset:1024
	ds_read_b128 v[156:159], v179 offset:2048
	ds_read_b128 v[160:163], v179 offset:3072
	ds_read_b128 v[164:167], v177 offset:32768
	ds_read_b128 v[180:183], v177 offset:33792
	ds_read_b128 v[184:187], v177 offset:34816
	ds_read_b128 v[188:191], v177 offset:35840
	ds_read_b128 v[192:195], v177 offset:36864
	ds_read_b128 v[196:199], v177 offset:37888
	ds_read_b128 v[200:203], v177 offset:38912
	ds_read_b128 v[204:207], v177 offset:39936
	s_add_u32 s62, s24, 0x40000
	s_addc_u32 s63, s25, 0
	s_mov_b32 m0, s42
	s_nop 0
	global_load_lds_dwordx4 v170, s[62:63]
	s_add_u32 s62, s24, 0x60000
	s_addc_u32 s63, s25, 0
	s_mov_b32 m0, s43
	s_nop 0
	global_load_lds_dwordx4 v170, s[62:63]
	s_waitcnt vmcnt(8)
	s_waitcnt lgkmcnt(0)
	s_barrier
	s_setprio 1
	v_mfma_f32_16x16x32_bf16 v[84:87], v[128:131], v[164:167], v[84:87]
	v_mfma_f32_16x16x32_bf16 v[76:79], v[136:139], v[164:167], v[76:79]
	v_mfma_f32_16x16x32_bf16 v[124:127], v[128:131], v[184:187], v[124:127]
	v_mfma_f32_16x16x32_bf16 v[120:123], v[136:139], v[184:187], v[120:123]
	v_mfma_f32_16x16x32_bf16 v[116:119], v[128:131], v[192:195], v[116:119]
	v_mfma_f32_16x16x32_bf16 v[112:115], v[136:139], v[192:195], v[112:115]
	v_mfma_f32_16x16x32_bf16 v[108:111], v[128:131], v[200:203], v[108:111]
	v_mfma_f32_16x16x32_bf16 v[104:107], v[136:139], v[200:203], v[104:107]
	v_mfma_f32_16x16x32_bf16 v[84:87], v[132:135], v[180:183], v[84:87]
	v_mfma_f32_16x16x32_bf16 v[76:79], v[144:147], v[180:183], v[76:79]
	v_mfma_f32_16x16x32_bf16 v[124:127], v[132:135], v[188:191], v[124:127]
	v_mfma_f32_16x16x32_bf16 v[120:123], v[144:147], v[188:191], v[120:123]
	v_mfma_f32_16x16x32_bf16 v[116:119], v[132:135], v[196:199], v[116:119]
	v_mfma_f32_16x16x32_bf16 v[112:115], v[144:147], v[196:199], v[112:115]
	v_mfma_f32_16x16x32_bf16 v[108:111], v[132:135], v[204:207], v[108:111]
	v_mfma_f32_16x16x32_bf16 v[104:107], v[144:147], v[204:207], v[104:107]
	v_mfma_f32_16x16x32_bf16 v[60:63], v[148:151], v[164:167], v[60:63]
	v_mfma_f32_16x16x32_bf16 v[56:59], v[156:159], v[164:167], v[56:59]
	v_mfma_f32_16x16x32_bf16 v[52:55], v[148:151], v[184:187], v[52:55]
	v_mfma_f32_16x16x32_bf16 v[48:51], v[156:159], v[184:187], v[48:51]
	v_mfma_f32_16x16x32_bf16 v[44:47], v[148:151], v[192:195], v[44:47]
	v_mfma_f32_16x16x32_bf16 v[40:43], v[156:159], v[192:195], v[40:43]
	v_mfma_f32_16x16x32_bf16 v[36:39], v[148:151], v[200:203], v[36:39]
	v_mfma_f32_16x16x32_bf16 v[32:35], v[156:159], v[200:203], v[32:35]
	v_mfma_f32_16x16x32_bf16 v[60:63], v[152:155], v[180:183], v[60:63]
	v_mfma_f32_16x16x32_bf16 v[56:59], v[160:163], v[180:183], v[56:59]
	v_mfma_f32_16x16x32_bf16 v[52:55], v[152:155], v[188:191], v[52:55]
	v_mfma_f32_16x16x32_bf16 v[48:51], v[160:163], v[188:191], v[48:51]
	v_mfma_f32_16x16x32_bf16 v[44:47], v[152:155], v[196:199], v[44:47]
	v_mfma_f32_16x16x32_bf16 v[40:43], v[160:163], v[196:199], v[40:43]
	v_mfma_f32_16x16x32_bf16 v[36:39], v[152:155], v[204:207], v[36:39]
	v_mfma_f32_16x16x32_bf16 v[32:35], v[160:163], v[204:207], v[32:35]
	s_setprio 0
	s_barrier
	s_add_u32 s62, s38, 0x80
	s_addc_u32 s63, s39, 0
	ds_read_b128 v[164:167], v177 offset:49152
	ds_read_b128 v[180:183], v177 offset:50176
	ds_read_b128 v[184:187], v177 offset:51200
	ds_read_b128 v[188:191], v177 offset:52224
	ds_read_b128 v[192:195], v177 offset:53248
	ds_read_b128 v[196:199], v177 offset:54272
	ds_read_b128 v[200:203], v177 offset:55296
	ds_read_b128 v[204:207], v177 offset:56320
	s_mov_b32 m0, s48
	s_nop 0
	global_load_lds_dwordx4 v171, s[62:63]
	s_add_u32 s62, s38, 0x20080
	s_addc_u32 s63, s39, 0
	s_mov_b32 m0, s49
	s_nop 0
	global_load_lds_dwordx4 v171, s[62:63]
	s_add_u32 s62, s38, 0x40080
	s_addc_u32 s63, s39, 0
	s_mov_b32 m0, s52
	s_nop 0
	global_load_lds_dwordx4 v171, s[62:63]
	s_add_u32 s38, s38, 0x60080
	s_addc_u32 s39, s39, 0
	s_mov_b32 m0, s53
	s_nop 0
	global_load_lds_dwordx4 v171, s[38:39]
	s_mov_b32 m0, s50
	s_nop 0
	global_load_lds_dwordx4 v170, s[26:27]
	s_add_u32 s24, s24, 0x20080
	s_addc_u32 s25, s25, 0
	s_mov_b32 m0, s51
	s_nop 0
	global_load_lds_dwordx4 v170, s[24:25]
	s_waitcnt vmcnt(8)
	s_waitcnt lgkmcnt(0)
	s_barrier
	s_setprio 1
	v_mfma_f32_16x16x32_bf16 v[100:103], v[128:131], v[164:167], v[100:103]
	v_mfma_f32_16x16x32_bf16 v[96:99], v[136:139], v[164:167], v[96:99]
	v_mfma_f32_16x16x32_bf16 v[92:95], v[128:131], v[184:187], v[92:95]
	v_mfma_f32_16x16x32_bf16 v[88:91], v[136:139], v[184:187], v[88:91]
	v_mfma_f32_16x16x32_bf16 v[80:83], v[128:131], v[192:195], v[80:83]
	v_mfma_f32_16x16x32_bf16 v[72:75], v[136:139], v[192:195], v[72:75]
	v_mfma_f32_16x16x32_bf16 v[68:71], v[128:131], v[200:203], v[68:71]
	v_mfma_f32_16x16x32_bf16 v[64:67], v[136:139], v[200:203], v[64:67]
	v_mfma_f32_16x16x32_bf16 v[100:103], v[132:135], v[180:183], v[100:103]
	v_mfma_f32_16x16x32_bf16 v[96:99], v[144:147], v[180:183], v[96:99]
	v_mfma_f32_16x16x32_bf16 v[92:95], v[132:135], v[188:191], v[92:95]
	v_mfma_f32_16x16x32_bf16 v[88:91], v[144:147], v[188:191], v[88:91]
	v_mfma_f32_16x16x32_bf16 v[80:83], v[132:135], v[196:199], v[80:83]
	v_mfma_f32_16x16x32_bf16 v[72:75], v[144:147], v[196:199], v[72:75]
	v_mfma_f32_16x16x32_bf16 v[68:71], v[132:135], v[204:207], v[68:71]
	v_mfma_f32_16x16x32_bf16 v[64:67], v[144:147], v[204:207], v[64:67]
	v_mfma_f32_16x16x32_bf16 v[28:31], v[148:151], v[164:167], v[28:31]
	v_mfma_f32_16x16x32_bf16 v[24:27], v[156:159], v[164:167], v[24:27]
	v_mfma_f32_16x16x32_bf16 v[20:23], v[148:151], v[184:187], v[20:23]
	v_mfma_f32_16x16x32_bf16 v[16:19], v[156:159], v[184:187], v[16:19]
	v_mfma_f32_16x16x32_bf16 v[12:15], v[148:151], v[192:195], v[12:15]
	v_mfma_f32_16x16x32_bf16 v[8:11], v[156:159], v[192:195], v[8:11]
	v_mfma_f32_16x16x32_bf16 v[4:7], v[148:151], v[200:203], v[4:7]
	v_mfma_f32_16x16x32_bf16 v[0:3], v[156:159], v[200:203], v[0:3]
	v_mfma_f32_16x16x32_bf16 v[28:31], v[152:155], v[180:183], v[28:31]
	v_mfma_f32_16x16x32_bf16 v[24:27], v[160:163], v[180:183], v[24:27]
	v_mfma_f32_16x16x32_bf16 v[20:23], v[152:155], v[188:191], v[20:23]
	v_mfma_f32_16x16x32_bf16 v[16:19], v[160:163], v[188:191], v[16:19]
	v_mfma_f32_16x16x32_bf16 v[12:15], v[152:155], v[196:199], v[12:15]
	v_mfma_f32_16x16x32_bf16 v[8:11], v[160:163], v[196:199], v[8:11]
	v_mfma_f32_16x16x32_bf16 v[4:7], v[152:155], v[204:207], v[4:7]
	v_mfma_f32_16x16x32_bf16 v[0:3], v[160:163], v[204:207], v[0:3]
	s_setprio 0
	s_barrier
	s_add_i32 s61, s61, 2
	s_add_u32 s22, s22, 0x100
	s_addc_u32 s23, s23, 0
	s_add_u32 s59, s59, 0x100
	s_addc_u32 s60, s60, 0
	s_cmp_gt_u32 s61, 13
	s_cbranch_scc0 .LBB0_1352
	s_and_b64 vcc, exec, s[12:13]
	s_cbranch_vccz .LBB0_1355
	s_barrier

; #define PG8_STAGE(bufoff, gbase, voff, p64) do { _Pragma("unroll") for (int _i = 0; _i < 2; ++_i) { \
;         const char* _gb = (const char*)(gbase) + (size_t)_i * (p64); const unsigned _la = ldsbase + (unsigned)(bufoff) + (unsigned)_i * 8192u; \
;         asm volatile("s_mov_b32 m0, %0\n\ts_nop 0\n\tglobal_load_lds_dwordx4 %1, %2" :: "s"(_la), "v"(voff), "s"(_gb) : "memory"); } } while (0)
; #define PG8_LDA(dst, b, h) do { _Pragma("unroll") for (int m = 0; m < 4; ++m) _Pragma("unroll") for (int k = 0; k < 2; ++k) dst[m][k] = *(const LAS bf16x8*)(lds + PG8_SA(b, h) + aoff + m * 2048 + k * 1024); } while (0)
; #define PG8_LDB(dst, b, h) do { _Pragma("unroll") for (int n = 0; n < 2; ++n) _Pragma("unroll") for (int k = 0; k < 2; ++k) dst[n][k] = *(const LAS bf16x8*)(lds + PG8_SB(b, h) + boff + n * 2048 + k * 1024); } while (0)
; #define PG8_MMA(ai, bj, At, Bt) do { __builtin_amdgcn_s_setprio(1); _Pragma("unroll") for (int m = 0; m < 4; ++m) _Pragma("unroll") for (int n = 0; n < 2; ++n) _Pragma("unroll") for (int k = 0; k < 2; ++k) \
;         acc[ai][bj][m][n] = __builtin_amdgcn_mfma_f32_16x16x32_bf16(Bt[n][k], At[m][k], acc[ai][bj][m][n], 0, 0, 0); __builtin_amdgcn_s_setprio(0); } while (0)
; #define PG8_WAIT_V(n) asm volatile("s_waitcnt vmcnt(" #n ")" ::: "memory")
; template <class Epi, class Sched>
; __device__ __forceinline__ void gemm_phase(LAS unsigned char* lds, const Sched& S, const Epi& E) {
;     ...
;         for (int t = 0; t < nt; t += 2) {
;             const bool last = (t == nt - 2);
;             const char* a1 = cA + (size_t)(t + 1) * kstep;
;             const char* a2 = last ? nA : cA + (size_t)(t + 2) * kstep; const char* b2 = last ? nB : cB + (size_t)(t + 2) * kstep;
;             const char* a3 = a2 + kstep; const char* b3 = b2 + kstep;
;             const unsigned vA2 = voffA, vB2 = voffB, hA2 = hA, hB2 = hB;
;             PG8_LDB(B0, 0, 0); PG8_LDB(B1, 0, 1); PG8_SCHED; PG8_LDA(At, 0, 0); PG8_STAGE(PG8_SA(1, 1), a1 + hA, voffA, hA / 2);
;             PG8_WAIT_V(8); PG8_WAIT_L(0); PG8_BAR; PG8_MMA(0, 0, At, B0); PG8_MMA(0, 1, At, B1); PG8_BAR; PG8_SCHED;
;             PG8_LDA(At, 0, 1); PG8_STAGE(PG8_SB(0, 0), b2, vB2, hB2 / 2); PG8_STAGE(PG8_SB(0, 1), b2 + hB2, vB2, hB2 / 2); PG8_STAGE(PG8_SA(0, 0), a2, vA2, hA2 / 2);
;             PG8_WAIT_V(8); PG8_WAIT_L(0); PG8_BAR; PG8_MMA(1, 0, At, B0); PG8_MMA(1, 1, At, B1); PG8_BAR; PG8_SCHED;
.LBB0_1485:
	ds_read_b128 v[144:147], v138
	ds_read_b128 v[148:151], v138 offset:1024
	ds_read_b128 v[152:155], v138 offset:2048
	ds_read_b128 v[156:159], v138 offset:3072
	ds_read_b128 v[160:163], v139
	ds_read_b128 v[164:167], v139 offset:1024
	ds_read_b128 v[168:171], v139 offset:2048
	ds_read_b128 v[172:175], v139 offset:3072
	s_add_u32 s26, s24, 0xfffc0080
	s_addc_u32 s27, s25, -1
	s_cmp_eq_u32 s61, 12
	s_cselect_b32 s26, s20, s26
	s_cselect_b32 s27, s21, s27
	s_cselect_b32 s40, s22, s59
	s_cselect_b32 s41, s23, s60
	s_add_u32 s38, s26, 0x80
	s_addc_u32 s39, s27, 0
	ds_read_b128 v[178:181], v140
	ds_read_b128 v[182:185], v140 offset:1024
	ds_read_b128 v[186:189], v140 offset:2048
	ds_read_b128 v[190:193], v140 offset:3072
	ds_read_b128 v[194:197], v140 offset:4096
	ds_read_b128 v[198:201], v140 offset:5120
	ds_read_b128 v[202:205], v140 offset:6144
	ds_read_b128 v[206:209], v140 offset:7168
	s_mov_b32 m0, s54
	s_nop 0
	global_load_lds_dwordx4 v134, s[24:25]
	s_add_u32 s62, s24, 0x20000
	s_addc_u32 s63, s25, 0
	s_mov_b32 m0, s55
	s_nop 0
	global_load_lds_dwordx4 v134, s[62:63]
	s_waitcnt vmcnt(8)
	s_waitcnt lgkmcnt(0)
	s_barrier
	s_setprio 1
	v_mfma_f32_16x16x32_bf16 v[124:127], v[144:147], v[178:181], v[124:127]
	v_mfma_f32_16x16x32_bf16 v[120:123], v[152:155], v[178:181], v[120:123]
	v_mfma_f32_16x16x32_bf16 v[108:111], v[144:147], v[186:189], v[108:111]
	v_mfma_f32_16x16x32_bf16 v[104:107], v[152:155], v[186:189], v[104:107]
	v_mfma_f32_16x16x32_bf16 v[92:95], v[144:147], v[194:197], v[92:95]
	v_mfma_f32_16x16x32_bf16 v[88:91], v[152:155], v[194:197], v[88:91]
	v_mfma_f32_16x16x32_bf16 v[76:79], v[144:147], v[202:205], v[76:79]
	v_mfma_f32_16x16x32_bf16 v[72:75], v[152:155], v[202:205], v[72:75]
	v_mfma_f32_16x16x32_bf16 v[124:127], v[148:151], v[182:185], v[124:127]
	v_mfma_f32_16x16x32_bf16 v[120:123], v[156:159], v[182:185], v[120:123]
	v_mfma_f32_16x16x32_bf16 v[108:111], v[148:151], v[190:193], v[108:111]
	v_mfma_f32_16x16x32_bf16 v[104:107], v[156:159], v[190:193], v[104:107]
	v_mfma_f32_16x16x32_bf16 v[92:95], v[148:151], v[198:201], v[92:95]
	v_mfma_f32_16x16x32_bf16 v[88:91], v[156:159], v[198:201], v[88:91]
	v_mfma_f32_16x16x32_bf16 v[76:79], v[148:151], v[206:209], v[76:79]
	v_mfma_f32_16x16x32_bf16 v[72:75], v[156:159], v[206:209], v[72:75]
	v_mfma_f32_16x16x32_bf16 v[116:119], v[160:163], v[178:181], v[116:119]
	v_mfma_f32_16x16x32_bf16 v[112:115], v[168:171], v[178:181], v[112:115]
	v_mfma_f32_16x16x32_bf16 v[100:103], v[160:163], v[186:189], v[100:103]
	v_mfma_f32_16x16x32_bf16 v[96:99], v[168:171], v[186:189], v[96:99]
	v_mfma_f32_16x16x32_bf16 v[84:87], v[160:163], v[194:197], v[84:87]
	v_mfma_f32_16x16x32_bf16 v[80:83], v[168:171], v[194:197], v[80:83]
	v_mfma_f32_16x16x32_bf16 v[68:71], v[160:163], v[202:205], v[68:71]
	v_mfma_f32_16x16x32_bf16 v[64:67], v[168:171], v[202:205], v[64:67]
	v_mfma_f32_16x16x32_bf16 v[116:119], v[164:167], v[182:185], v[116:119]
	v_mfma_f32_16x16x32_bf16 v[112:115], v[172:175], v[182:185], v[112:115]
	v_mfma_f32_16x16x32_bf16 v[100:103], v[164:167], v[190:193], v[100:103]
	v_mfma_f32_16x16x32_bf16 v[96:99], v[172:175], v[190:193], v[96:99]
	v_mfma_f32_16x16x32_bf16 v[84:87], v[164:167], v[198:201], v[84:87]
	v_mfma_f32_16x16x32_bf16 v[80:83], v[172:175], v[198:201], v[80:83]
	v_mfma_f32_16x16x32_bf16 v[68:71], v[164:167], v[206:209], v[68:71]
	v_mfma_f32_16x16x32_bf16 v[64:67], v[172:175], v[206:209], v[64:67]
	s_setprio 0
	s_barrier
	s_add_u32 s62, s40, 0x20000
	ds_read_b128 v[178:181], v140 offset:16384
	ds_read_b128 v[182:185], v140 offset:17408
	ds_read_b128 v[186:189], v140 offset:18432
	ds_read_b128 v[190:193], v140 offset:19456
	ds_read_b128 v[194:197], v140 offset:20480
	ds_read_b128 v[198:201], v140 offset:21504
	ds_read_b128 v[202:205], v140 offset:22528
	ds_read_b128 v[206:209], v140 offset:23552
	s_mov_b32 m0, s36
	s_nop 0
	global_load_lds_dwordx4 v135, s[40:41]
	s_addc_u32 s63, s41, 0
	s_mov_b32 m0, s37
	s_nop 0
	global_load_lds_dwordx4 v135, s[62:63]
	s_add_u32 s62, s40, 0x40000
	s_addc_u32 s63, s41, 0
	s_mov_b32 m0, s42
	s_nop 0
	global_load_lds_dwordx4 v135, s[62:63]
	s_add_u32 s62, s40, 0x60000
	s_addc_u32 s63, s41, 0
	s_mov_b32 m0, s43
	s_nop 0
	global_load_lds_dwordx4 v135, s[62:63]
	s_mov_b32 m0, s34
	s_nop 0
	global_load_lds_dwordx4 v134, s[26:27]
	s_add_u32 s62, s26, 0x20000
	s_addc_u32 s63, s27, 0
	s_mov_b32 m0, s44
	s_nop 0
	global_load_lds_dwordx4 v134, s[62:63]
	s_waitcnt vmcnt(8)
	s_waitcnt lgkmcnt(0)
	s_barrier
	s_setprio 1
	v_mfma_f32_16x16x32_bf16 v[60:63], v[144:147], v[178:181], v[60:63]
	v_mfma_f32_16x16x32_bf16 v[56:59], v[152:155], v[178:181], v[56:59]
	v_mfma_f32_16x16x32_bf16 v[44:47], v[144:147], v[186:189], v[44:47]
	v_mfma_f32_16x16x32_bf16 v[40:43], v[152:155], v[186:189], v[40:43]
	v_mfma_f32_16x16x32_bf16 v[28:31], v[144:147], v[194:197], v[28:31]
	v_mfma_f32_16x16x32_bf16 v[24:27], v[152:155], v[194:197], v[24:27]
	v_mfma_f32_16x16x32_bf16 v[12:15], v[144:147], v[202:205], v[12:15]
	v_mfma_f32_16x16x32_bf16 v[8:11], v[152:155], v[202:205], v[8:11]
	v_mfma_f32_16x16x32_bf16 v[60:63], v[148:151], v[182:185], v[60:63]
	v_mfma_f32_16x16x32_bf16 v[56:59], v[156:159], v[182:185], v[56:59]
	v_mfma_f32_16x16x32_bf16 v[44:47], v[148:151], v[190:193], v[44:47]
	v_mfma_f32_16x16x32_bf16 v[40:43], v[156:159], v[190:193], v[40:43]
	v_mfma_f32_16x16x32_bf16 v[28:31], v[148:151], v[198:201], v[28:31]
	v_mfma_f32_16x16x32_bf16 v[24:27], v[156:159], v[198:201], v[24:27]
	v_mfma_f32_16x16x32_bf16 v[12:15], v[148:151], v[206:209], v[12:15]
	v_mfma_f32_16x16x32_bf16 v[8:11], v[156:159], v[206:209], v[8:11]
	v_mfma_f32_16x16x32_bf16 v[52:55], v[160:163], v[178:181], v[52:55]
	v_mfma_f32_16x16x32_bf16 v[48:51], v[168:171], v[178:181], v[48:51]
	v_mfma_f32_16x16x32_bf16 v[36:39], v[160:163], v[186:189], v[36:39]
	v_mfma_f32_16x16x32_bf16 v[32:35], v[168:171], v[186:189], v[32:35]
	v_mfma_f32_16x16x32_bf16 v[20:23], v[160:163], v[194:197], v[20:23]
	v_mfma_f32_16x16x32_bf16 v[16:19], v[168:171], v[194:197], v[16:19]
	v_mfma_f32_16x16x32_bf16 v[4:7], v[160:163], v[202:205], v[4:7]
	v_mfma_f32_16x16x32_bf16 v[0:3], v[168:171], v[202:205], v[0:3]
	v_mfma_f32_16x16x32_bf16 v[52:55], v[164:167], v[182:185], v[52:55]
	v_mfma_f32_16x16x32_bf16 v[48:51], v[172:175], v[182:185], v[48:51]
	v_mfma_f32_16x16x32_bf16 v[36:39], v[164:167], v[190:193], v[36:39]
	v_mfma_f32_16x16x32_bf16 v[32:35], v[172:175], v[190:193], v[32:35]
	v_mfma_f32_16x16x32_bf16 v[20:23], v[164:167], v[198:201], v[20:23]
	v_mfma_f32_16x16x32_bf16 v[16:19], v[172:175], v[198:201], v[16:19]
	v_mfma_f32_16x16x32_bf16 v[4:7], v[164:167], v[206:209], v[4:7]
	v_mfma_f32_16x16x32_bf16 v[0:3], v[172:175], v[206:209], v[0:3]
	s_setprio 0
	s_barrier
; #define PG8_STAGE(bufoff, gbase, voff, p64) do { _Pragma("unroll") for (int _i = 0; _i < 2; ++_i) { \
;         const char* _gb = (const char*)(gbase) + (size_t)_i * (p64); const unsigned _la = ldsbase + (unsigned)(bufoff) + (unsigned)_i * 8192u; \
;         asm volatile("s_mov_b32 m0, %0\n\ts_nop 0\n\tglobal_load_lds_dwordx4 %1, %2" :: "s"(_la), "v"(voff), "s"(_gb) : "memory"); } } while (0)
; #define PG8_LDA(dst, b, h) do { _Pragma("unroll") for (int m = 0; m < 4; ++m) _Pragma("unroll") for (int k = 0; k < 2; ++k) dst[m][k] = *(const LAS bf16x8*)(lds + PG8_SA(b, h) + aoff + m * 2048 + k * 1024); } while (0)
; #define PG8_LDB(dst, b, h) do { _Pragma("unroll") for (int n = 0; n < 2; ++n) _Pragma("unroll") for (int k = 0; k < 2; ++k) dst[n][k] = *(const LAS bf16x8*)(lds + PG8_SB(b, h) + boff + n * 2048 + k * 1024); } while (0)
; #define PG8_MMA(ai, bj, At, Bt) do { __builtin_amdgcn_s_setprio(1); _Pragma("unroll") for (int m = 0; m < 4; ++m) _Pragma("unroll") for (int n = 0; n < 2; ++n) _Pragma("unroll") for (int k = 0; k < 2; ++k) \
;         acc[ai][bj][m][n] = __builtin_amdgcn_mfma_f32_16x16x32_bf16(Bt[n][k], At[m][k], acc[ai][bj][m][n], 0, 0, 0); __builtin_amdgcn_s_setprio(0); } while (0)
; #define PG8_WAIT_V(n) asm volatile("s_waitcnt vmcnt(" #n ")" ::: "memory")
; #define PG8_WAIT_L(n) asm volatile("s_waitcnt lgkmcnt(" #n ")" ::: "memory")
; #define PG8_BAR __builtin_amdgcn_s_barrier()
; #define PG8_SCHED __builtin_amdgcn_sched_barrier(0)
; template <class Epi, class Sched>
; __device__ __forceinline__ void gemm_phase(LAS unsigned char* lds, const Sched& S, const Epi& E) {
;     ...
;             PG8_LDB(B0, 1, 0); PG8_LDB(B1, 1, 1); PG8_SCHED; PG8_LDA(At, 1, 0); PG8_STAGE(PG8_SA(0, 1), a2 + hA2, vA2, hA2 / 2);
;             PG8_WAIT_V(8); PG8_WAIT_L(0); PG8_BAR; PG8_MMA(0, 0, At, B0); PG8_MMA(0, 1, At, B1); PG8_BAR; PG8_SCHED;
;             PG8_LDA(At, 1, 1); PG8_STAGE(PG8_SB(1, 0), b3, vB2, hB2 / 2); PG8_STAGE(PG8_SB(1, 1), b3 + hB2, vB2, hB2 / 2); PG8_STAGE(PG8_SA(1, 0), a3, vA2, hA2 / 2);
;             PG8_WAIT_V(8); PG8_WAIT_L(0); PG8_BAR; PG8_MMA(1, 0, At, B0); PG8_MMA(1, 1, At, B1); PG8_BAR; PG8_SCHED;
;         }
;         if (wr == 0) PG8_BAR;
	ds_read_b128 v[144:147], v141
	ds_read_b128 v[148:151], v141 offset:1024
	ds_read_b128 v[152:155], v141 offset:2048
	ds_read_b128 v[156:159], v141 offset:3072
	ds_read_b128 v[160:163], v142
	ds_read_b128 v[164:167], v142 offset:1024
	ds_read_b128 v[168:171], v142 offset:2048
	ds_read_b128 v[172:175], v142 offset:3072
	ds_read_b128 v[178:181], v140 offset:32768
	ds_read_b128 v[182:185], v140 offset:33792
	ds_read_b128 v[186:189], v140 offset:34816
	ds_read_b128 v[190:193], v140 offset:35840
	ds_read_b128 v[194:197], v140 offset:36864
	ds_read_b128 v[198:201], v140 offset:37888
	ds_read_b128 v[202:205], v140 offset:38912
	ds_read_b128 v[206:209], v140 offset:39936
	s_add_u32 s62, s26, 0x40000
	s_addc_u32 s63, s27, 0
	s_mov_b32 m0, s45
	s_nop 0
	global_load_lds_dwordx4 v134, s[62:63]
	s_add_u32 s62, s26, 0x60000
	s_addc_u32 s63, s27, 0
	s_mov_b32 m0, s46
	s_nop 0
	global_load_lds_dwordx4 v134, s[62:63]
	s_waitcnt vmcnt(8)
	s_waitcnt lgkmcnt(0)
	s_barrier
	s_setprio 1
	v_mfma_f32_16x16x32_bf16 v[124:127], v[144:147], v[178:181], v[124:127]
	v_mfma_f32_16x16x32_bf16 v[120:123], v[152:155], v[178:181], v[120:123]
	v_mfma_f32_16x16x32_bf16 v[108:111], v[144:147], v[186:189], v[108:111]
	v_mfma_f32_16x16x32_bf16 v[104:107], v[152:155], v[186:189], v[104:107]
	v_mfma_f32_16x16x32_bf16 v[92:95], v[144:147], v[194:197], v[92:95]
	v_mfma_f32_16x16x32_bf16 v[88:91], v[152:155], v[194:197], v[88:91]
	v_mfma_f32_16x16x32_bf16 v[76:79], v[144:147], v[202:205], v[76:79]
	v_mfma_f32_16x16x32_bf16 v[72:75], v[152:155], v[202:205], v[72:75]
	v_mfma_f32_16x16x32_bf16 v[124:127], v[148:151], v[182:185], v[124:127]
	v_mfma_f32_16x16x32_bf16 v[120:123], v[156:159], v[182:185], v[120:123]
	v_mfma_f32_16x16x32_bf16 v[108:111], v[148:151], v[190:193], v[108:111]
	v_mfma_f32_16x16x32_bf16 v[104:107], v[156:159], v[190:193], v[104:107]
	v_mfma_f32_16x16x32_bf16 v[92:95], v[148:151], v[198:201], v[92:95]
	v_mfma_f32_16x16x32_bf16 v[88:91], v[156:159], v[198:201], v[88:91]
	v_mfma_f32_16x16x32_bf16 v[76:79], v[148:151], v[206:209], v[76:79]
	v_mfma_f32_16x16x32_bf16 v[72:75], v[156:159], v[206:209], v[72:75]
	v_mfma_f32_16x16x32_bf16 v[116:119], v[160:163], v[178:181], v[116:119]
	v_mfma_f32_16x16x32_bf16 v[112:115], v[168:171], v[178:181], v[112:115]
	v_mfma_f32_16x16x32_bf16 v[100:103], v[160:163], v[186:189], v[100:103]
	v_mfma_f32_16x16x32_bf16 v[96:99], v[168:171], v[186:189], v[96:99]
	v_mfma_f32_16x16x32_bf16 v[84:87], v[160:163], v[194:197], v[84:87]
	v_mfma_f32_16x16x32_bf16 v[80:83], v[168:171], v[194:197], v[80:83]
	v_mfma_f32_16x16x32_bf16 v[68:71], v[160:163], v[202:205], v[68:71]
	v_mfma_f32_16x16x32_bf16 v[64:67], v[168:171], v[202:205], v[64:67]
	v_mfma_f32_16x16x32_bf16 v[116:119], v[164:167], v[182:185], v[116:119]
	v_mfma_f32_16x16x32_bf16 v[112:115], v[172:175], v[182:185], v[112:115]
	v_mfma_f32_16x16x32_bf16 v[100:103], v[164:167], v[190:193], v[100:103]
	v_mfma_f32_16x16x32_bf16 v[96:99], v[172:175], v[190:193], v[96:99]
	v_mfma_f32_16x16x32_bf16 v[84:87], v[164:167], v[198:201], v[84:87]
	v_mfma_f32_16x16x32_bf16 v[80:83], v[172:175], v[198:201], v[80:83]
	v_mfma_f32_16x16x32_bf16 v[68:71], v[164:167], v[206:209], v[68:71]
	v_mfma_f32_16x16x32_bf16 v[64:67], v[172:175], v[206:209], v[64:67]
	s_setprio 0
	s_barrier
	s_add_u32 s62, s40, 0x80
	s_addc_u32 s63, s41, 0
	ds_read_b128 v[178:181], v140 offset:49152
	ds_read_b128 v[182:185], v140 offset:50176
	ds_read_b128 v[186:189], v140 offset:51200
	ds_read_b128 v[190:193], v140 offset:52224
	ds_read_b128 v[194:197], v140 offset:53248
	ds_read_b128 v[198:201], v140 offset:54272
	ds_read_b128 v[202:205], v140 offset:55296
	ds_read_b128 v[206:209], v140 offset:56320
	s_mov_b32 m0, s48
	s_nop 0
	global_load_lds_dwordx4 v135, s[62:63]
	s_add_u32 s62, s40, 0x20080
	s_addc_u32 s63, s41, 0
	s_mov_b32 m0, s49
	s_nop 0
	global_load_lds_dwordx4 v135, s[62:63]
	s_add_u32 s62, s40, 0x40080
	s_addc_u32 s63, s41, 0
	s_mov_b32 m0, s52
	s_nop 0
	global_load_lds_dwordx4 v135, s[62:63]
	s_add_u32 s40, s40, 0x60080
	s_addc_u32 s41, s41, 0
	s_mov_b32 m0, s53
	s_nop 0
	global_load_lds_dwordx4 v135, s[40:41]
	s_mov_b32 m0, s50
	s_nop 0
	global_load_lds_dwordx4 v134, s[38:39]
	s_add_u32 s26, s26, 0x20080
	s_addc_u32 s27, s27, 0
	s_mov_b32 m0, s51
	s_nop 0
	global_load_lds_dwordx4 v134, s[26:27]
	s_waitcnt vmcnt(8)
	s_waitcnt lgkmcnt(0)
	s_barrier
	s_setprio 1
	v_mfma_f32_16x16x32_bf16 v[60:63], v[144:147], v[178:181], v[60:63]
	v_mfma_f32_16x16x32_bf16 v[56:59], v[152:155], v[178:181], v[56:59]
	v_mfma_f32_16x16x32_bf16 v[44:47], v[144:147], v[186:189], v[44:47]
	v_mfma_f32_16x16x32_bf16 v[40:43], v[152:155], v[186:189], v[40:43]
	v_mfma_f32_16x16x32_bf16 v[28:31], v[144:147], v[194:197], v[28:31]
	v_mfma_f32_16x16x32_bf16 v[24:27], v[152:155], v[194:197], v[24:27]
	v_mfma_f32_16x16x32_bf16 v[12:15], v[144:147], v[202:205], v[12:15]
	v_mfma_f32_16x16x32_bf16 v[8:11], v[152:155], v[202:205], v[8:11]
	v_mfma_f32_16x16x32_bf16 v[60:63], v[148:151], v[182:185], v[60:63]
	v_mfma_f32_16x16x32_bf16 v[56:59], v[156:159], v[182:185], v[56:59]
	v_mfma_f32_16x16x32_bf16 v[44:47], v[148:151], v[190:193], v[44:47]
	v_mfma_f32_16x16x32_bf16 v[40:43], v[156:159], v[190:193], v[40:43]
	v_mfma_f32_16x16x32_bf16 v[28:31], v[148:151], v[198:201], v[28:31]
	v_mfma_f32_16x16x32_bf16 v[24:27], v[156:159], v[198:201], v[24:27]
	v_mfma_f32_16x16x32_bf16 v[12:15], v[148:151], v[206:209], v[12:15]
	v_mfma_f32_16x16x32_bf16 v[8:11], v[156:159], v[206:209], v[8:11]
	v_mfma_f32_16x16x32_bf16 v[52:55], v[160:163], v[178:181], v[52:55]
	v_mfma_f32_16x16x32_bf16 v[48:51], v[168:171], v[178:181], v[48:51]
	v_mfma_f32_16x16x32_bf16 v[36:39], v[160:163], v[186:189], v[36:39]
	v_mfma_f32_16x16x32_bf16 v[32:35], v[168:171], v[186:189], v[32:35]
	v_mfma_f32_16x16x32_bf16 v[20:23], v[160:163], v[194:197], v[20:23]
	v_mfma_f32_16x16x32_bf16 v[16:19], v[168:171], v[194:197], v[16:19]
	v_mfma_f32_16x16x32_bf16 v[4:7], v[160:163], v[202:205], v[4:7]
	v_mfma_f32_16x16x32_bf16 v[0:3], v[168:171], v[202:205], v[0:3]
	v_mfma_f32_16x16x32_bf16 v[52:55], v[164:167], v[182:185], v[52:55]
	v_mfma_f32_16x16x32_bf16 v[48:51], v[172:175], v[182:185], v[48:51]
	v_mfma_f32_16x16x32_bf16 v[36:39], v[164:167], v[190:193], v[36:39]
	v_mfma_f32_16x16x32_bf16 v[32:35], v[172:175], v[190:193], v[32:35]
	v_mfma_f32_16x16x32_bf16 v[20:23], v[164:167], v[198:201], v[20:23]
	v_mfma_f32_16x16x32_bf16 v[16:19], v[172:175], v[198:201], v[16:19]
	v_mfma_f32_16x16x32_bf16 v[4:7], v[164:167], v[206:209], v[4:7]
	v_mfma_f32_16x16x32_bf16 v[0:3], v[172:175], v[206:209], v[0:3]
	s_setprio 0
	s_barrier
	s_add_i32 s61, s61, 2
	s_add_u32 s24, s24, 0x100
	s_addc_u32 s25, s25, 0
	s_add_u32 s59, s59, 0x100
	s_addc_u32 s60, s60, 0
	s_cmp_gt_u32 s61, 13
	s_cbranch_scc0 .LBB0_1485
	s_and_b64 vcc, exec, s[14:15]
	s_cbranch_vccz .LBB0_1488
	s_barrier

; #define PG8_STAGE(bufoff, gbase, voff, p64) do { _Pragma("unroll") for (int _i = 0; _i < 2; ++_i) { \
;         const char* _gb = (const char*)(gbase) + (size_t)_i * (p64); const unsigned _la = ldsbase + (unsigned)(bufoff) + (unsigned)_i * 8192u; \
;         asm volatile("s_mov_b32 m0, %0\n\ts_nop 0\n\tglobal_load_lds_dwordx4 %1, %2" :: "s"(_la), "v"(voff), "s"(_gb) : "memory"); } } while (0)
; #define PG8_LDA(dst, b, h) do { _Pragma("unroll") for (int m = 0; m < 4; ++m) _Pragma("unroll") for (int k = 0; k < 2; ++k) dst[m][k] = *(const LAS bf16x8*)(lds + PG8_SA(b, h) + aoff + m * 2048 + k * 1024); } while (0)
; #define PG8_LDB(dst, b, h) do { _Pragma("unroll") for (int n = 0; n < 2; ++n) _Pragma("unroll") for (int k = 0; k < 2; ++k) dst[n][k] = *(const LAS bf16x8*)(lds + PG8_SB(b, h) + boff + n * 2048 + k * 1024); } while (0)
; #define PG8_MMA(ai, bj, At, Bt) do { __builtin_amdgcn_s_setprio(1); _Pragma("unroll") for (int m = 0; m < 4; ++m) _Pragma("unroll") for (int n = 0; n < 2; ++n) _Pragma("unroll") for (int k = 0; k < 2; ++k) \
;         acc[ai][bj][m][n] = __builtin_amdgcn_mfma_f32_16x16x32_bf16(Bt[n][k], At[m][k], acc[ai][bj][m][n], 0, 0, 0); __builtin_amdgcn_s_setprio(0); } while (0)
; #define PG8_WAIT_V(n) asm volatile("s_waitcnt vmcnt(" #n ")" ::: "memory")
; template <class Epi, class Sched>
; __device__ __forceinline__ void gemm_phase(LAS unsigned char* lds, const Sched& S, const Epi& E) {
;     ...
;         for (int t = 0; t < nt; t += 2) {
;             const bool last = (t == nt - 2);
;             const char* a1 = cA + (size_t)(t + 1) * kstep;
;             const char* a2 = last ? nA : cA + (size_t)(t + 2) * kstep; const char* b2 = last ? nB : cB + (size_t)(t + 2) * kstep;
;             const char* a3 = a2 + kstep; const char* b3 = b2 + kstep;
;             const unsigned vA2 = voffA, vB2 = voffB, hA2 = hA, hB2 = hB;
;             PG8_LDB(B0, 0, 0); PG8_LDB(B1, 0, 1); PG8_SCHED; PG8_LDA(At, 0, 0); PG8_STAGE(PG8_SA(1, 1), a1 + hA, voffA, hA / 2);
;             PG8_WAIT_V(8); PG8_WAIT_L(0); PG8_BAR; PG8_MMA(0, 0, At, B0); PG8_MMA(0, 1, At, B1); PG8_BAR; PG8_SCHED;
;             PG8_LDA(At, 0, 1); PG8_STAGE(PG8_SB(0, 0), b2, vB2, hB2 / 2); PG8_STAGE(PG8_SB(0, 1), b2 + hB2, vB2, hB2 / 2); PG8_STAGE(PG8_SA(0, 0), a2, vA2, hA2 / 2);
;             PG8_WAIT_V(8); PG8_WAIT_L(0); PG8_BAR; PG8_MMA(1, 0, At, B0); PG8_MMA(1, 1, At, B1); PG8_BAR; PG8_SCHED;
.LBB0_1559:
	ds_read_b128 v[128:131], v179
	ds_read_b128 v[132:135], v179 offset:1024
	ds_read_b128 v[136:139], v179 offset:2048
	ds_read_b128 v[140:143], v179 offset:3072
	ds_read_b128 v[150:153], v180
	ds_read_b128 v[154:157], v180 offset:1024
	ds_read_b128 v[158:161], v180 offset:2048
	ds_read_b128 v[162:165], v180 offset:3072
	s_add_u32 s24, s22, 0xfff50080
	s_addc_u32 s25, s23, -1
	s_cmp_eq_u32 s61, 40
	s_cselect_b32 s24, s18, s24
	s_cselect_b32 s25, s19, s25
	s_cselect_b32 s38, s20, s59
	s_cselect_b32 s39, s21, s60
	s_add_u32 s26, s24, 0x80
	s_addc_u32 s27, s25, 0
	ds_read_b128 v[166:169], v181
	ds_read_b128 v[170:173], v181 offset:1024
	ds_read_b128 v[184:187], v181 offset:2048
	ds_read_b128 v[188:191], v181 offset:3072
	ds_read_b128 v[192:195], v181 offset:4096
	ds_read_b128 v[196:199], v181 offset:5120
	ds_read_b128 v[200:203], v181 offset:6144
	ds_read_b128 v[204:207], v181 offset:7168
	s_mov_b32 m0, s54
	s_nop 0
	global_load_lds_dwordx4 v144, s[22:23]
	s_add_u32 s62, s22, 0x58000
	s_addc_u32 s63, s23, 0
	s_mov_b32 m0, s55
	s_nop 0
	global_load_lds_dwordx4 v144, s[62:63]
	s_waitcnt vmcnt(8)
	s_waitcnt lgkmcnt(0)
	s_barrier
	s_setprio 1
	v_mfma_f32_16x16x32_bf16 v[124:127], v[128:131], v[166:169], v[124:127]
	v_mfma_f32_16x16x32_bf16 v[120:123], v[136:139], v[166:169], v[120:123]
	v_mfma_f32_16x16x32_bf16 v[116:119], v[128:131], v[184:187], v[116:119]
	v_mfma_f32_16x16x32_bf16 v[112:115], v[136:139], v[184:187], v[112:115]
	v_mfma_f32_16x16x32_bf16 v[108:111], v[128:131], v[192:195], v[108:111]
	v_mfma_f32_16x16x32_bf16 v[104:107], v[136:139], v[192:195], v[104:107]
	v_mfma_f32_16x16x32_bf16 v[100:103], v[128:131], v[200:203], v[100:103]
	v_mfma_f32_16x16x32_bf16 v[96:99], v[136:139], v[200:203], v[96:99]
	v_mfma_f32_16x16x32_bf16 v[124:127], v[132:135], v[170:173], v[124:127]
	v_mfma_f32_16x16x32_bf16 v[120:123], v[140:143], v[170:173], v[120:123]
	v_mfma_f32_16x16x32_bf16 v[116:119], v[132:135], v[188:191], v[116:119]
	v_mfma_f32_16x16x32_bf16 v[112:115], v[140:143], v[188:191], v[112:115]
	v_mfma_f32_16x16x32_bf16 v[108:111], v[132:135], v[196:199], v[108:111]
	v_mfma_f32_16x16x32_bf16 v[104:107], v[140:143], v[196:199], v[104:107]
	v_mfma_f32_16x16x32_bf16 v[100:103], v[132:135], v[204:207], v[100:103]
	v_mfma_f32_16x16x32_bf16 v[96:99], v[140:143], v[204:207], v[96:99]
	v_mfma_f32_16x16x32_bf16 v[60:63], v[150:153], v[166:169], v[60:63]
	v_mfma_f32_16x16x32_bf16 v[56:59], v[158:161], v[166:169], v[56:59]
	v_mfma_f32_16x16x32_bf16 v[52:55], v[150:153], v[184:187], v[52:55]
	v_mfma_f32_16x16x32_bf16 v[48:51], v[158:161], v[184:187], v[48:51]
	v_mfma_f32_16x16x32_bf16 v[44:47], v[150:153], v[192:195], v[44:47]
	v_mfma_f32_16x16x32_bf16 v[40:43], v[158:161], v[192:195], v[40:43]
	v_mfma_f32_16x16x32_bf16 v[36:39], v[150:153], v[200:203], v[36:39]
	v_mfma_f32_16x16x32_bf16 v[32:35], v[158:161], v[200:203], v[32:35]
	v_mfma_f32_16x16x32_bf16 v[60:63], v[154:157], v[170:173], v[60:63]
	v_mfma_f32_16x16x32_bf16 v[56:59], v[162:165], v[170:173], v[56:59]
	v_mfma_f32_16x16x32_bf16 v[52:55], v[154:157], v[188:191], v[52:55]
	v_mfma_f32_16x16x32_bf16 v[48:51], v[162:165], v[188:191], v[48:51]
	v_mfma_f32_16x16x32_bf16 v[44:47], v[154:157], v[196:199], v[44:47]
	v_mfma_f32_16x16x32_bf16 v[40:43], v[162:165], v[196:199], v[40:43]
	v_mfma_f32_16x16x32_bf16 v[36:39], v[154:157], v[204:207], v[36:39]
	v_mfma_f32_16x16x32_bf16 v[32:35], v[162:165], v[204:207], v[32:35]
	s_setprio 0
	s_barrier
	s_add_u32 s62, s38, 0x58000
	ds_read_b128 v[166:169], v181 offset:16384
	ds_read_b128 v[170:173], v181 offset:17408
	ds_read_b128 v[184:187], v181 offset:18432
	ds_read_b128 v[188:191], v181 offset:19456
	ds_read_b128 v[192:195], v181 offset:20480
	ds_read_b128 v[196:199], v181 offset:21504
	ds_read_b128 v[200:203], v181 offset:22528
	ds_read_b128 v[204:207], v181 offset:23552
	s_mov_b32 m0, s35
	s_nop 0
	global_load_lds_dwordx4 v145, s[38:39]
	s_addc_u32 s63, s39, 0
	s_mov_b32 m0, s36
	s_nop 0
	global_load_lds_dwordx4 v145, s[62:63]
	s_add_u32 s62, s38, 0xb0000
	s_addc_u32 s63, s39, 0
	s_mov_b32 m0, s37
	s_nop 0
	global_load_lds_dwordx4 v145, s[62:63]
	s_add_u32 s62, s38, 0x108000
	s_addc_u32 s63, s39, 0
	s_mov_b32 m0, s40
	s_nop 0
	global_load_lds_dwordx4 v145, s[62:63]
	s_mov_b32 m0, s34
	s_nop 0
	global_load_lds_dwordx4 v144, s[24:25]
	s_add_u32 s62, s24, 0x58000
	s_addc_u32 s63, s25, 0
	s_mov_b32 m0, s41
	s_nop 0
	global_load_lds_dwordx4 v144, s[62:63]
	s_waitcnt vmcnt(8)
	s_waitcnt lgkmcnt(0)
	s_barrier
	s_setprio 1
	v_mfma_f32_16x16x32_bf16 v[92:95], v[128:131], v[166:169], v[92:95]
	v_mfma_f32_16x16x32_bf16 v[88:91], v[136:139], v[166:169], v[88:91]
	v_mfma_f32_16x16x32_bf16 v[84:87], v[128:131], v[184:187], v[84:87]
	v_mfma_f32_16x16x32_bf16 v[80:83], v[136:139], v[184:187], v[80:83]
	v_mfma_f32_16x16x32_bf16 v[76:79], v[128:131], v[192:195], v[76:79]
	v_mfma_f32_16x16x32_bf16 v[72:75], v[136:139], v[192:195], v[72:75]
	v_mfma_f32_16x16x32_bf16 v[68:71], v[128:131], v[200:203], v[68:71]
	v_mfma_f32_16x16x32_bf16 v[64:67], v[136:139], v[200:203], v[64:67]
	v_mfma_f32_16x16x32_bf16 v[92:95], v[132:135], v[170:173], v[92:95]
	v_mfma_f32_16x16x32_bf16 v[88:91], v[140:143], v[170:173], v[88:91]
	v_mfma_f32_16x16x32_bf16 v[84:87], v[132:135], v[188:191], v[84:87]
	v_mfma_f32_16x16x32_bf16 v[80:83], v[140:143], v[188:191], v[80:83]
	v_mfma_f32_16x16x32_bf16 v[76:79], v[132:135], v[196:199], v[76:79]
	v_mfma_f32_16x16x32_bf16 v[72:75], v[140:143], v[196:199], v[72:75]
	v_mfma_f32_16x16x32_bf16 v[68:71], v[132:135], v[204:207], v[68:71]
	v_mfma_f32_16x16x32_bf16 v[64:67], v[140:143], v[204:207], v[64:67]
	v_mfma_f32_16x16x32_bf16 v[28:31], v[150:153], v[166:169], v[28:31]
	v_mfma_f32_16x16x32_bf16 v[24:27], v[158:161], v[166:169], v[24:27]
	v_mfma_f32_16x16x32_bf16 v[20:23], v[150:153], v[184:187], v[20:23]
	v_mfma_f32_16x16x32_bf16 v[16:19], v[158:161], v[184:187], v[16:19]
	v_mfma_f32_16x16x32_bf16 v[12:15], v[150:153], v[192:195], v[12:15]
	v_mfma_f32_16x16x32_bf16 v[8:11], v[158:161], v[192:195], v[8:11]
	v_mfma_f32_16x16x32_bf16 v[4:7], v[150:153], v[200:203], v[4:7]
	v_mfma_f32_16x16x32_bf16 v[0:3], v[158:161], v[200:203], v[0:3]
	v_mfma_f32_16x16x32_bf16 v[28:31], v[154:157], v[170:173], v[28:31]
	v_mfma_f32_16x16x32_bf16 v[24:27], v[162:165], v[170:173], v[24:27]
	v_mfma_f32_16x16x32_bf16 v[20:23], v[154:157], v[188:191], v[20:23]
	v_mfma_f32_16x16x32_bf16 v[16:19], v[162:165], v[188:191], v[16:19]
	v_mfma_f32_16x16x32_bf16 v[12:15], v[154:157], v[196:199], v[12:15]
	v_mfma_f32_16x16x32_bf16 v[8:11], v[162:165], v[196:199], v[8:11]
	v_mfma_f32_16x16x32_bf16 v[4:7], v[154:157], v[204:207], v[4:7]
	v_mfma_f32_16x16x32_bf16 v[0:3], v[162:165], v[204:207], v[0:3]
	s_setprio 0
	s_barrier
; #define PG8_STAGE(bufoff, gbase, voff, p64) do { _Pragma("unroll") for (int _i = 0; _i < 2; ++_i) { \
;         const char* _gb = (const char*)(gbase) + (size_t)_i * (p64); const unsigned _la = ldsbase + (unsigned)(bufoff) + (unsigned)_i * 8192u; \
;         asm volatile("s_mov_b32 m0, %0\n\ts_nop 0\n\tglobal_load_lds_dwordx4 %1, %2" :: "s"(_la), "v"(voff), "s"(_gb) : "memory"); } } while (0)
; #define PG8_LDA(dst, b, h) do { _Pragma("unroll") for (int m = 0; m < 4; ++m) _Pragma("unroll") for (int k = 0; k < 2; ++k) dst[m][k] = *(const LAS bf16x8*)(lds + PG8_SA(b, h) + aoff + m * 2048 + k * 1024); } while (0)
; #define PG8_LDB(dst, b, h) do { _Pragma("unroll") for (int n = 0; n < 2; ++n) _Pragma("unroll") for (int k = 0; k < 2; ++k) dst[n][k] = *(const LAS bf16x8*)(lds + PG8_SB(b, h) + boff + n * 2048 + k * 1024); } while (0)
; #define PG8_MMA(ai, bj, At, Bt) do { __builtin_amdgcn_s_setprio(1); _Pragma("unroll") for (int m = 0; m < 4; ++m) _Pragma("unroll") for (int n = 0; n < 2; ++n) _Pragma("unroll") for (int k = 0; k < 2; ++k) \
;         acc[ai][bj][m][n] = __builtin_amdgcn_mfma_f32_16x16x32_bf16(Bt[n][k], At[m][k], acc[ai][bj][m][n], 0, 0, 0); __builtin_amdgcn_s_setprio(0); } while (0)
; #define PG8_WAIT_V(n) asm volatile("s_waitcnt vmcnt(" #n ")" ::: "memory")
; #define PG8_WAIT_L(n) asm volatile("s_waitcnt lgkmcnt(" #n ")" ::: "memory")
; #define PG8_BAR __builtin_amdgcn_s_barrier()
; #define PG8_SCHED __builtin_amdgcn_sched_barrier(0)
; template <class Epi, class Sched>
; __device__ __forceinline__ void gemm_phase(LAS unsigned char* lds, const Sched& S, const Epi& E) {
;     ...
;             PG8_LDB(B0, 1, 0); PG8_LDB(B1, 1, 1); PG8_SCHED; PG8_LDA(At, 1, 0); PG8_STAGE(PG8_SA(0, 1), a2 + hA2, vA2, hA2 / 2);
;             PG8_WAIT_V(8); PG8_WAIT_L(0); PG8_BAR; PG8_MMA(0, 0, At, B0); PG8_MMA(0, 1, At, B1); PG8_BAR; PG8_SCHED;
;             PG8_LDA(At, 1, 1); PG8_STAGE(PG8_SB(1, 0), b3, vB2, hB2 / 2); PG8_STAGE(PG8_SB(1, 1), b3 + hB2, vB2, hB2 / 2); PG8_STAGE(PG8_SA(1, 0), a3, vA2, hA2 / 2);
;             PG8_WAIT_V(8); PG8_WAIT_L(0); PG8_BAR; PG8_MMA(1, 0, At, B0); PG8_MMA(1, 1, At, B1); PG8_BAR; PG8_SCHED;
;         }
;         if (wr == 0) PG8_BAR;
	ds_read_b128 v[128:131], v182
	ds_read_b128 v[132:135], v182 offset:1024
	ds_read_b128 v[136:139], v182 offset:2048
	ds_read_b128 v[140:143], v182 offset:3072
	ds_read_b128 v[150:153], v183
	ds_read_b128 v[154:157], v183 offset:1024
	ds_read_b128 v[158:161], v183 offset:2048
	ds_read_b128 v[162:165], v183 offset:3072
	ds_read_b128 v[166:169], v181 offset:32768
	ds_read_b128 v[170:173], v181 offset:33792
	ds_read_b128 v[184:187], v181 offset:34816
	ds_read_b128 v[188:191], v181 offset:35840
	ds_read_b128 v[192:195], v181 offset:36864
	ds_read_b128 v[196:199], v181 offset:37888
	ds_read_b128 v[200:203], v181 offset:38912
	ds_read_b128 v[204:207], v181 offset:39936
	s_add_u32 s62, s24, 0xb0000
	s_addc_u32 s63, s25, 0
	s_mov_b32 m0, s42
	s_nop 0
	global_load_lds_dwordx4 v144, s[62:63]
	s_add_u32 s62, s24, 0x108000
	s_addc_u32 s63, s25, 0
	s_mov_b32 m0, s43
	s_nop 0
	global_load_lds_dwordx4 v144, s[62:63]
	s_waitcnt vmcnt(8)
	s_waitcnt lgkmcnt(0)
	s_barrier
	s_setprio 1
	v_mfma_f32_16x16x32_bf16 v[124:127], v[128:131], v[166:169], v[124:127]
	v_mfma_f32_16x16x32_bf16 v[120:123], v[136:139], v[166:169], v[120:123]
	v_mfma_f32_16x16x32_bf16 v[116:119], v[128:131], v[184:187], v[116:119]
	v_mfma_f32_16x16x32_bf16 v[112:115], v[136:139], v[184:187], v[112:115]
	v_mfma_f32_16x16x32_bf16 v[108:111], v[128:131], v[192:195], v[108:111]
	v_mfma_f32_16x16x32_bf16 v[104:107], v[136:139], v[192:195], v[104:107]
	v_mfma_f32_16x16x32_bf16 v[100:103], v[128:131], v[200:203], v[100:103]
	v_mfma_f32_16x16x32_bf16 v[96:99], v[136:139], v[200:203], v[96:99]
	v_mfma_f32_16x16x32_bf16 v[124:127], v[132:135], v[170:173], v[124:127]
	v_mfma_f32_16x16x32_bf16 v[120:123], v[140:143], v[170:173], v[120:123]
	v_mfma_f32_16x16x32_bf16 v[116:119], v[132:135], v[188:191], v[116:119]
	v_mfma_f32_16x16x32_bf16 v[112:115], v[140:143], v[188:191], v[112:115]
	v_mfma_f32_16x16x32_bf16 v[108:111], v[132:135], v[196:199], v[108:111]
	v_mfma_f32_16x16x32_bf16 v[104:107], v[140:143], v[196:199], v[104:107]
	v_mfma_f32_16x16x32_bf16 v[100:103], v[132:135], v[204:207], v[100:103]
	v_mfma_f32_16x16x32_bf16 v[96:99], v[140:143], v[204:207], v[96:99]
	v_mfma_f32_16x16x32_bf16 v[60:63], v[150:153], v[166:169], v[60:63]
	v_mfma_f32_16x16x32_bf16 v[56:59], v[158:161], v[166:169], v[56:59]
	v_mfma_f32_16x16x32_bf16 v[52:55], v[150:153], v[184:187], v[52:55]
	v_mfma_f32_16x16x32_bf16 v[48:51], v[158:161], v[184:187], v[48:51]
	v_mfma_f32_16x16x32_bf16 v[44:47], v[150:153], v[192:195], v[44:47]
	v_mfma_f32_16x16x32_bf16 v[40:43], v[158:161], v[192:195], v[40:43]
	v_mfma_f32_16x16x32_bf16 v[36:39], v[150:153], v[200:203], v[36:39]
	v_mfma_f32_16x16x32_bf16 v[32:35], v[158:161], v[200:203], v[32:35]
	v_mfma_f32_16x16x32_bf16 v[60:63], v[154:157], v[170:173], v[60:63]
	v_mfma_f32_16x16x32_bf16 v[56:59], v[162:165], v[170:173], v[56:59]
	v_mfma_f32_16x16x32_bf16 v[52:55], v[154:157], v[188:191], v[52:55]
	v_mfma_f32_16x16x32_bf16 v[48:51], v[162:165], v[188:191], v[48:51]
	v_mfma_f32_16x16x32_bf16 v[44:47], v[154:157], v[196:199], v[44:47]
	v_mfma_f32_16x16x32_bf16 v[40:43], v[162:165], v[196:199], v[40:43]
	v_mfma_f32_16x16x32_bf16 v[36:39], v[154:157], v[204:207], v[36:39]
	v_mfma_f32_16x16x32_bf16 v[32:35], v[162:165], v[204:207], v[32:35]
	s_setprio 0
	s_barrier
	s_add_u32 s62, s38, 0x80
	s_addc_u32 s63, s39, 0
	ds_read_b128 v[166:169], v181 offset:49152
	ds_read_b128 v[170:173], v181 offset:50176
	ds_read_b128 v[184:187], v181 offset:51200
	ds_read_b128 v[188:191], v181 offset:52224
	ds_read_b128 v[192:195], v181 offset:53248
	ds_read_b128 v[196:199], v181 offset:54272
	ds_read_b128 v[200:203], v181 offset:55296
	ds_read_b128 v[204:207], v181 offset:56320
	s_mov_b32 m0, s48
	s_nop 0
	global_load_lds_dwordx4 v145, s[62:63]
	s_add_u32 s62, s38, 0x58080
	s_addc_u32 s63, s39, 0
	s_mov_b32 m0, s49
	s_nop 0
	global_load_lds_dwordx4 v145, s[62:63]
	s_add_u32 s62, s38, 0xb0080
	s_addc_u32 s63, s39, 0
	s_mov_b32 m0, s52
	s_nop 0
	global_load_lds_dwordx4 v145, s[62:63]
	s_add_u32 s38, s38, 0x108080
	s_addc_u32 s39, s39, 0
	s_mov_b32 m0, s53
	s_nop 0
	global_load_lds_dwordx4 v145, s[38:39]
	s_mov_b32 m0, s50
	s_nop 0
	global_load_lds_dwordx4 v144, s[26:27]
	s_add_u32 s24, s24, 0x58080
	s_addc_u32 s25, s25, 0
	s_mov_b32 m0, s51
	s_nop 0
	global_load_lds_dwordx4 v144, s[24:25]
	s_waitcnt vmcnt(8)
	s_waitcnt lgkmcnt(0)
	s_barrier
	s_setprio 1
	v_mfma_f32_16x16x32_bf16 v[92:95], v[128:131], v[166:169], v[92:95]
	v_mfma_f32_16x16x32_bf16 v[88:91], v[136:139], v[166:169], v[88:91]
	v_mfma_f32_16x16x32_bf16 v[84:87], v[128:131], v[184:187], v[84:87]
	v_mfma_f32_16x16x32_bf16 v[80:83], v[136:139], v[184:187], v[80:83]
	v_mfma_f32_16x16x32_bf16 v[76:79], v[128:131], v[192:195], v[76:79]
	v_mfma_f32_16x16x32_bf16 v[72:75], v[136:139], v[192:195], v[72:75]
	v_mfma_f32_16x16x32_bf16 v[68:71], v[128:131], v[200:203], v[68:71]
	v_mfma_f32_16x16x32_bf16 v[64:67], v[136:139], v[200:203], v[64:67]
	v_mfma_f32_16x16x32_bf16 v[92:95], v[132:135], v[170:173], v[92:95]
	v_mfma_f32_16x16x32_bf16 v[88:91], v[140:143], v[170:173], v[88:91]
	v_mfma_f32_16x16x32_bf16 v[84:87], v[132:135], v[188:191], v[84:87]
	v_mfma_f32_16x16x32_bf16 v[80:83], v[140:143], v[188:191], v[80:83]
	v_mfma_f32_16x16x32_bf16 v[76:79], v[132:135], v[196:199], v[76:79]
	v_mfma_f32_16x16x32_bf16 v[72:75], v[140:143], v[196:199], v[72:75]
	v_mfma_f32_16x16x32_bf16 v[68:71], v[132:135], v[204:207], v[68:71]
	v_mfma_f32_16x16x32_bf16 v[64:67], v[140:143], v[204:207], v[64:67]
	v_mfma_f32_16x16x32_bf16 v[28:31], v[150:153], v[166:169], v[28:31]
	v_mfma_f32_16x16x32_bf16 v[24:27], v[158:161], v[166:169], v[24:27]
	v_mfma_f32_16x16x32_bf16 v[20:23], v[150:153], v[184:187], v[20:23]
	v_mfma_f32_16x16x32_bf16 v[16:19], v[158:161], v[184:187], v[16:19]
	v_mfma_f32_16x16x32_bf16 v[12:15], v[150:153], v[192:195], v[12:15]
	v_mfma_f32_16x16x32_bf16 v[8:11], v[158:161], v[192:195], v[8:11]
	v_mfma_f32_16x16x32_bf16 v[4:7], v[150:153], v[200:203], v[4:7]
	v_mfma_f32_16x16x32_bf16 v[0:3], v[158:161], v[200:203], v[0:3]
	v_mfma_f32_16x16x32_bf16 v[28:31], v[154:157], v[170:173], v[28:31]
	v_mfma_f32_16x16x32_bf16 v[24:27], v[162:165], v[170:173], v[24:27]
	v_mfma_f32_16x16x32_bf16 v[20:23], v[154:157], v[188:191], v[20:23]
	v_mfma_f32_16x16x32_bf16 v[16:19], v[162:165], v[188:191], v[16:19]
	v_mfma_f32_16x16x32_bf16 v[12:15], v[154:157], v[196:199], v[12:15]
	v_mfma_f32_16x16x32_bf16 v[8:11], v[162:165], v[196:199], v[8:11]
	v_mfma_f32_16x16x32_bf16 v[4:7], v[154:157], v[204:207], v[4:7]
	v_mfma_f32_16x16x32_bf16 v[0:3], v[162:165], v[204:207], v[0:3]
	s_setprio 0
	s_barrier
	s_add_i32 s61, s61, 2
	s_add_u32 s22, s22, 0x100
	s_addc_u32 s23, s23, 0
	s_add_u32 s59, s59, 0x100
	s_addc_u32 s60, s60, 0
	s_cmp_gt_u32 s61, 41
	s_cbranch_scc0 .LBB0_1559
	s_and_b64 vcc, exec, s[12:13]
	s_cbranch_vccz .LBB0_1562
	s_barrier
